# v20: GEMM K-loops all LDS-DMA pieces in scalar-base form (s_nop slots kept)
# speedup vs baseline: 1.0065x; 1.0062x over previous
.LBB0_144:
	s_lshl_b32 s1, s1, 5
	s_add_i32 s67, s2, 0x18000
	s_mov_b64 s[20:21], 0x80
	s_and_b32 s1, s1, 0x60
	v_lshl_add_u64 v[6:7], v[6:7], 0, s[20:21]
	s_mov_b32 m0, s67
	s_add_i32 s72, s2, 0x1a000
	s_lshl_b32 s5, s0, 13
	s_lshl_b32 s7, s1, 7
	s_waitcnt vmcnt(2)
	s_barrier
	global_load_lds_dwordx4 v[6:7], off
	v_lshl_add_u64 v[4:5], v[4:5], 0, s[20:21]
	s_mov_b32 m0, s72
	s_add_i32 s73, s2, 0x8000
	s_add_i32 s74, s2, 0xa000
	global_load_lds_dwordx4 v[4:5], off
	v_lshl_add_u64 v[0:1], v[0:1], 0, s[20:21]
	s_mov_b32 m0, s73
	s_add_u32 s22, s12, 0x40080
	global_load_lds_dwordx4 v[0:1], off
	v_lshl_add_u64 v[0:1], v[2:3], 0, s[20:21]
	s_mov_b32 m0, s74
	s_addc_u32 s23, s13, 0
	s_add_i32 s75, s2, 0x1c000
	global_load_lds_dwordx4 v[0:1], off
	s_mov_b32 m0, s75
	s_add_i32 s78, s2, 0x1e000
	global_load_lds_dwordx4 v132, s[22:23]
	s_mov_b32 m0, s78
	s_cmpk_lt_u32 s14, 0x100
	global_load_lds_dwordx4 v134, s[22:23]
	v_bfe_u32 v1, v8, 4, 2
	v_and_b32_e32 v0, 15, v8
	v_lshlrev_b32_e32 v2, 4, v1
	v_lshl_or_b32 v129, s0, 6, v0
	v_lshl_or_b32 v0, v0, 6, v2
	v_lshlrev_b32_e32 v2, 2, v8
	v_lshl_or_b32 v149, v1, 2, s1
	v_lshlrev_b32_e32 v1, 14, v9
	v_and_b32_e32 v2, 32, v2
	v_and_b32_e32 v1, 0xffff8000, v1
	v_bitop3_b32 v145, v0, s5, v2 bitop3:0xde
	v_bitop3_b32 v0, v0, s7, v2 bitop3:0xde
	v_lshl_add_u32 v1, v10, 11, v1
	v_and_b32_e32 v2, 1, v9
	v_lshl_or_b32 v1, v2, 6, v1
	v_lshl_add_u32 v138, v11, 1, v1
	v_lshlrev_b32_e32 v1, 14, v12
	v_and_b32_e32 v1, 0xffff8000, v1
	s_waitcnt vmcnt(6)
	v_lshl_add_u32 v1, v13, 11, v1
	v_and_b32_e32 v2, 1, v12
	v_lshl_or_b32 v1, v2, 6, v1
	s_cselect_b64 s[22:23], -1, 0
	v_lshrrev_b32_e32 v155, 1, v149
	v_or_b32_e32 v160, 16, v129
	v_or_b32_e32 v161, 32, v129
	v_or_b32_e32 v162, 48, v129
	s_ashr_i32 s79, s82, 31
	s_ashr_i32 s83, s3, 31
	v_mov_b32_e32 v139, v137
	v_lshl_add_u32 v140, v14, 1, v1
	v_mov_b32_e32 v141, v137
	s_mov_b32 s84, 0
	v_mov_b64_e32 v[142:143], 0x400
	v_mov_b64_e32 v[150:151], 0x3ff
	v_or_b32_e32 v163, 0x10000, v0
	v_add_u32_e32 v164, 0x10400, v0
	v_add_u32_e32 v165, 0x10800, v0
	v_add_u32_e32 v167, 0x10c00, v0
	v_or_b32_e32 v168, 0x14000, v0
	v_add_u32_e32 v169, 0x14400, v0
	v_add_u32_e32 v170, 0x14800, v0
	v_add_u32_e32 v171, 0x14c00, v0
	s_add_i32 s85, s2, 0xc000
	s_add_i32 s86, s2, 0xe000
	v_or_b32_e32 v172, 0x18000, v0
	v_add_u32_e32 v173, 0x18400, v0
	v_add_u32_e32 v174, 0x18800, v0
	v_add_u32_e32 v175, 0x18c00, v0
	v_or_b32_e32 v176, 0x1c000, v0
	v_add_u32_e32 v177, 0x1c400, v0
	v_add_u32_e32 v178, 0x1c800, v0
	v_add_u32_e32 v179, 0x1cc00, v0
	s_mov_b32 s87, 0x3e0f83e1
	s_movk_i32 s14, 0xff
	s_movk_i32 s15, 0x3ff
	s_mov_b32 s24, 0x3d800000
	s_barrier
	s_branch .LBB0_147

.LBB0_154:
	ds_read_b128 v[180:183], v163
	ds_read_b128 v[184:187], v164
	ds_read_b128 v[188:191], v165
	ds_read_b128 v[196:199], v167
	ds_read_b128 v[200:203], v168
	ds_read_b128 v[204:207], v169
	ds_read_b128 v[208:211], v170
	ds_read_b128 v[212:215], v171
	s_add_u32 s12, s10, 0xfffc0080
	s_addc_u32 s13, s11, -1
	s_cmp_eq_u32 s54, 12
	s_cselect_b32 s37, s5, s13
	s_cselect_b32 s36, s7, s12
	s_cselect_b32 s13, s27, s39
	s_cselect_b32 s12, s29, s38
	s_mov_b32 m0, s85
	ds_read_b128 v[216:219], v145
	ds_read_b128 v[220:223], v145 offset:1024
	ds_read_b128 v[224:227], v145 offset:2048
	ds_read_b128 v[228:231], v145 offset:3072
	ds_read_b128 v[232:235], v145 offset:4096
	ds_read_b128 v[236:239], v145 offset:5120
	ds_read_b128 v[240:243], v145 offset:6144
	ds_read_b128 v[244:247], v145 offset:7168
	global_load_lds_dwordx4 v138, s[10:11]
	s_mov_b32 m0, s86
	s_nop 0
	global_load_lds_dwordx4 v140, s[10:11]
	s_waitcnt vmcnt(8)
	s_waitcnt lgkmcnt(0)
	s_barrier
	s_setprio 1
	s_waitcnt lgkmcnt(0)
	v_mfma_f32_16x16x32_bf16 v[124:127], v[180:183], v[216:219], v[124:127]
	v_mfma_f32_16x16x32_bf16 v[120:123], v[188:191], v[216:219], v[120:123]
	v_mfma_f32_16x16x32_bf16 v[108:111], v[180:183], v[224:227], v[108:111]
	v_mfma_f32_16x16x32_bf16 v[104:107], v[188:191], v[224:227], v[104:107]
	v_mfma_f32_16x16x32_bf16 v[92:95], v[180:183], v[232:235], v[92:95]
	v_mfma_f32_16x16x32_bf16 v[88:91], v[188:191], v[232:235], v[88:91]
	v_mfma_f32_16x16x32_bf16 v[76:79], v[180:183], v[240:243], v[76:79]
	v_mfma_f32_16x16x32_bf16 v[72:75], v[188:191], v[240:243], v[72:75]
	v_mfma_f32_16x16x32_bf16 v[124:127], v[184:187], v[220:223], v[124:127]
	v_mfma_f32_16x16x32_bf16 v[120:123], v[196:199], v[220:223], v[120:123]
	v_mfma_f32_16x16x32_bf16 v[108:111], v[184:187], v[228:231], v[108:111]
	v_mfma_f32_16x16x32_bf16 v[104:107], v[196:199], v[228:231], v[104:107]
	v_mfma_f32_16x16x32_bf16 v[92:95], v[184:187], v[236:239], v[92:95]
	v_mfma_f32_16x16x32_bf16 v[88:91], v[196:199], v[236:239], v[88:91]
	v_mfma_f32_16x16x32_bf16 v[76:79], v[184:187], v[244:247], v[76:79]
	v_mfma_f32_16x16x32_bf16 v[72:75], v[196:199], v[244:247], v[72:75]
	s_setprio 0
	s_setprio 1
	v_mfma_f32_16x16x32_bf16 v[116:119], v[200:203], v[216:219], v[116:119]
	v_mfma_f32_16x16x32_bf16 v[112:115], v[208:211], v[216:219], v[112:115]
	v_mfma_f32_16x16x32_bf16 v[100:103], v[200:203], v[224:227], v[100:103]
	v_mfma_f32_16x16x32_bf16 v[96:99], v[208:211], v[224:227], v[96:99]
	v_mfma_f32_16x16x32_bf16 v[84:87], v[200:203], v[232:235], v[84:87]
	v_mfma_f32_16x16x32_bf16 v[80:83], v[208:211], v[232:235], v[80:83]
	v_mfma_f32_16x16x32_bf16 v[68:71], v[200:203], v[240:243], v[68:71]
	v_mfma_f32_16x16x32_bf16 v[64:67], v[208:211], v[240:243], v[64:67]
	v_mfma_f32_16x16x32_bf16 v[116:119], v[204:207], v[220:223], v[116:119]
	v_mfma_f32_16x16x32_bf16 v[112:115], v[212:215], v[220:223], v[112:115]
	v_mfma_f32_16x16x32_bf16 v[100:103], v[204:207], v[228:231], v[100:103]
	v_mfma_f32_16x16x32_bf16 v[96:99], v[212:215], v[228:231], v[96:99]
	v_mfma_f32_16x16x32_bf16 v[84:87], v[204:207], v[236:239], v[84:87]
	v_mfma_f32_16x16x32_bf16 v[80:83], v[212:215], v[236:239], v[80:83]
	v_mfma_f32_16x16x32_bf16 v[68:71], v[204:207], v[244:247], v[68:71]
	v_mfma_f32_16x16x32_bf16 v[64:67], v[212:215], v[244:247], v[64:67]
	s_setprio 0
	s_barrier
	s_add_u32 s98, s12, s20
	s_addc_u32 s99, s13, s21
	s_add_u32 s100, s36, s20
	s_addc_u32 s101, s37, s21
	s_mov_b32 m0, s25
	s_add_u32 s56, s12, 0x40000
	ds_read_b128 v[216:219], v145 offset:16384
	ds_read_b128 v[220:223], v145 offset:17408
	ds_read_b128 v[224:227], v145 offset:18432
	ds_read_b128 v[228:231], v145 offset:19456
	ds_read_b128 v[232:235], v145 offset:20480
	ds_read_b128 v[236:239], v145 offset:21504
	ds_read_b128 v[240:243], v145 offset:22528
	ds_read_b128 v[244:247], v145 offset:23552
	global_load_lds_dwordx4 v132, s[12:13]
	s_mov_b32 m0, s33
	s_addc_u32 s57, s13, 0
	global_load_lds_dwordx4 v134, s[12:13]
	s_mov_b32 m0, s62
	s_nop 0
	global_load_lds_dwordx4 v132, s[56:57]
	s_mov_b32 m0, s63
	s_nop 0
	global_load_lds_dwordx4 v134, s[56:57]
	s_mov_b32 m0, s2
	s_nop 0
	global_load_lds_dwordx4 v132, s[36:37]
	s_mov_b32 m0, s64
	s_nop 0
	global_load_lds_dwordx4 v134, s[36:37]
	s_waitcnt vmcnt(8)
	s_waitcnt lgkmcnt(0)
	s_barrier
	s_setprio 1
	s_waitcnt lgkmcnt(0)
	v_mfma_f32_16x16x32_bf16 v[60:63], v[180:183], v[216:219], v[60:63]
	v_mfma_f32_16x16x32_bf16 v[56:59], v[188:191], v[216:219], v[56:59]
	v_mfma_f32_16x16x32_bf16 v[44:47], v[180:183], v[224:227], v[44:47]
	v_mfma_f32_16x16x32_bf16 v[40:43], v[188:191], v[224:227], v[40:43]
	v_mfma_f32_16x16x32_bf16 v[28:31], v[180:183], v[232:235], v[28:31]
	v_mfma_f32_16x16x32_bf16 v[24:27], v[188:191], v[232:235], v[24:27]
	v_mfma_f32_16x16x32_bf16 v[12:15], v[180:183], v[240:243], v[12:15]
	v_mfma_f32_16x16x32_bf16 v[8:11], v[188:191], v[240:243], v[8:11]
	v_mfma_f32_16x16x32_bf16 v[60:63], v[184:187], v[220:223], v[60:63]
	v_mfma_f32_16x16x32_bf16 v[56:59], v[196:199], v[220:223], v[56:59]
	v_mfma_f32_16x16x32_bf16 v[44:47], v[184:187], v[228:231], v[44:47]
	v_mfma_f32_16x16x32_bf16 v[40:43], v[196:199], v[228:231], v[40:43]
	v_mfma_f32_16x16x32_bf16 v[28:31], v[184:187], v[236:239], v[28:31]
	v_mfma_f32_16x16x32_bf16 v[24:27], v[196:199], v[236:239], v[24:27]
	v_mfma_f32_16x16x32_bf16 v[12:15], v[184:187], v[244:247], v[12:15]
	v_mfma_f32_16x16x32_bf16 v[8:11], v[196:199], v[244:247], v[8:11]
	s_setprio 0
	s_setprio 1
	v_mfma_f32_16x16x32_bf16 v[52:55], v[200:203], v[216:219], v[52:55]
	v_mfma_f32_16x16x32_bf16 v[48:51], v[208:211], v[216:219], v[48:51]
	v_mfma_f32_16x16x32_bf16 v[36:39], v[200:203], v[224:227], v[36:39]
	v_mfma_f32_16x16x32_bf16 v[32:35], v[208:211], v[224:227], v[32:35]
	v_mfma_f32_16x16x32_bf16 v[20:23], v[200:203], v[232:235], v[20:23]
	v_mfma_f32_16x16x32_bf16 v[16:19], v[208:211], v[232:235], v[16:19]
	v_mfma_f32_16x16x32_bf16 v[4:7], v[200:203], v[240:243], v[4:7]
	v_mfma_f32_16x16x32_bf16 v[0:3], v[208:211], v[240:243], v[0:3]
	v_mfma_f32_16x16x32_bf16 v[52:55], v[204:207], v[220:223], v[52:55]
	v_mfma_f32_16x16x32_bf16 v[48:51], v[212:215], v[220:223], v[48:51]
	v_mfma_f32_16x16x32_bf16 v[36:39], v[204:207], v[228:231], v[36:39]
	v_mfma_f32_16x16x32_bf16 v[32:35], v[212:215], v[228:231], v[32:35]
	v_mfma_f32_16x16x32_bf16 v[20:23], v[204:207], v[236:239], v[20:23]
	v_mfma_f32_16x16x32_bf16 v[16:19], v[212:215], v[236:239], v[16:19]
	v_mfma_f32_16x16x32_bf16 v[4:7], v[204:207], v[244:247], v[4:7]
	v_mfma_f32_16x16x32_bf16 v[0:3], v[212:215], v[244:247], v[0:3]
	s_setprio 0
	s_barrier
	ds_read_b128 v[180:183], v172
	ds_read_b128 v[184:187], v173
	ds_read_b128 v[188:191], v174
	ds_read_b128 v[196:199], v175
	ds_read_b128 v[200:203], v176
	ds_read_b128 v[204:207], v177
	ds_read_b128 v[208:211], v178
	ds_read_b128 v[212:215], v179
	s_add_u32 s36, s36, 0x40000
	s_addc_u32 s37, s37, 0
	s_mov_b32 m0, s65
	ds_read_b128 v[216:219], v145 offset:32768
	ds_read_b128 v[220:223], v145 offset:33792
	ds_read_b128 v[224:227], v145 offset:34816
	ds_read_b128 v[228:231], v145 offset:35840
	ds_read_b128 v[232:235], v145 offset:36864
	ds_read_b128 v[236:239], v145 offset:37888
	ds_read_b128 v[240:243], v145 offset:38912
	ds_read_b128 v[244:247], v145 offset:39936
	global_load_lds_dwordx4 v132, s[36:37]
	s_mov_b32 m0, s66
	s_nop 0
	global_load_lds_dwordx4 v134, s[36:37]
	s_waitcnt vmcnt(8)
	s_waitcnt lgkmcnt(0)
	s_barrier
	s_setprio 1
	s_waitcnt lgkmcnt(0)
	v_mfma_f32_16x16x32_bf16 v[124:127], v[180:183], v[216:219], v[124:127]
	v_mfma_f32_16x16x32_bf16 v[120:123], v[188:191], v[216:219], v[120:123]
	v_mfma_f32_16x16x32_bf16 v[108:111], v[180:183], v[224:227], v[108:111]
	v_mfma_f32_16x16x32_bf16 v[104:107], v[188:191], v[224:227], v[104:107]
	v_mfma_f32_16x16x32_bf16 v[92:95], v[180:183], v[232:235], v[92:95]
	v_mfma_f32_16x16x32_bf16 v[88:91], v[188:191], v[232:235], v[88:91]
	v_mfma_f32_16x16x32_bf16 v[76:79], v[180:183], v[240:243], v[76:79]
	v_mfma_f32_16x16x32_bf16 v[72:75], v[188:191], v[240:243], v[72:75]
	v_mfma_f32_16x16x32_bf16 v[124:127], v[184:187], v[220:223], v[124:127]
	v_mfma_f32_16x16x32_bf16 v[120:123], v[196:199], v[220:223], v[120:123]
	v_mfma_f32_16x16x32_bf16 v[108:111], v[184:187], v[228:231], v[108:111]
	v_mfma_f32_16x16x32_bf16 v[104:107], v[196:199], v[228:231], v[104:107]
	v_mfma_f32_16x16x32_bf16 v[92:95], v[184:187], v[236:239], v[92:95]
	v_mfma_f32_16x16x32_bf16 v[88:91], v[196:199], v[236:239], v[88:91]
	v_mfma_f32_16x16x32_bf16 v[76:79], v[184:187], v[244:247], v[76:79]
	v_mfma_f32_16x16x32_bf16 v[72:75], v[196:199], v[244:247], v[72:75]
	s_setprio 0
	s_setprio 1
	v_mfma_f32_16x16x32_bf16 v[116:119], v[200:203], v[216:219], v[116:119]
	v_mfma_f32_16x16x32_bf16 v[112:115], v[208:211], v[216:219], v[112:115]
	v_mfma_f32_16x16x32_bf16 v[100:103], v[200:203], v[224:227], v[100:103]
	v_mfma_f32_16x16x32_bf16 v[96:99], v[208:211], v[224:227], v[96:99]
	v_mfma_f32_16x16x32_bf16 v[84:87], v[200:203], v[232:235], v[84:87]
	v_mfma_f32_16x16x32_bf16 v[80:83], v[208:211], v[232:235], v[80:83]
	v_mfma_f32_16x16x32_bf16 v[68:71], v[200:203], v[240:243], v[68:71]
	v_mfma_f32_16x16x32_bf16 v[64:67], v[208:211], v[240:243], v[64:67]
	v_mfma_f32_16x16x32_bf16 v[116:119], v[204:207], v[220:223], v[116:119]
	v_mfma_f32_16x16x32_bf16 v[112:115], v[212:215], v[220:223], v[112:115]
	v_mfma_f32_16x16x32_bf16 v[100:103], v[204:207], v[228:231], v[100:103]
	v_mfma_f32_16x16x32_bf16 v[96:99], v[212:215], v[228:231], v[96:99]
	v_mfma_f32_16x16x32_bf16 v[84:87], v[204:207], v[236:239], v[84:87]
	v_mfma_f32_16x16x32_bf16 v[80:83], v[212:215], v[236:239], v[80:83]
	v_mfma_f32_16x16x32_bf16 v[68:71], v[204:207], v[244:247], v[68:71]
	v_mfma_f32_16x16x32_bf16 v[64:67], v[212:215], v[244:247], v[64:67]
	s_setprio 0
	s_barrier
	s_mov_b32 m0, s67
	s_add_u32 s12, s12, 0x40080
	ds_read_b128 v[216:219], v145 offset:49152
	ds_read_b128 v[220:223], v145 offset:50176
	ds_read_b128 v[224:227], v145 offset:51200
	ds_read_b128 v[228:231], v145 offset:52224
	ds_read_b128 v[232:235], v145 offset:53248
	ds_read_b128 v[236:239], v145 offset:54272
	ds_read_b128 v[240:243], v145 offset:55296
	ds_read_b128 v[244:247], v145 offset:56320
	global_load_lds_dwordx4 v132, s[98:99]
	s_mov_b32 m0, s72
	s_addc_u32 s13, s13, 0
	global_load_lds_dwordx4 v134, s[98:99]
	s_mov_b32 m0, s75
	s_nop 0
	global_load_lds_dwordx4 v132, s[12:13]
	s_mov_b32 m0, s78
	s_nop 0
	global_load_lds_dwordx4 v134, s[12:13]
	s_mov_b32 m0, s73
	s_nop 0
	global_load_lds_dwordx4 v132, s[100:101]
	s_mov_b32 m0, s74
	s_nop 0
	global_load_lds_dwordx4 v134, s[100:101]
	s_waitcnt vmcnt(8)
	s_waitcnt lgkmcnt(0)
	s_barrier
	s_setprio 1
	s_waitcnt lgkmcnt(0)
	v_mfma_f32_16x16x32_bf16 v[60:63], v[180:183], v[216:219], v[60:63]
	v_mfma_f32_16x16x32_bf16 v[56:59], v[188:191], v[216:219], v[56:59]
	v_mfma_f32_16x16x32_bf16 v[44:47], v[180:183], v[224:227], v[44:47]
	v_mfma_f32_16x16x32_bf16 v[40:43], v[188:191], v[224:227], v[40:43]
	v_mfma_f32_16x16x32_bf16 v[28:31], v[180:183], v[232:235], v[28:31]
	v_mfma_f32_16x16x32_bf16 v[24:27], v[188:191], v[232:235], v[24:27]
	v_mfma_f32_16x16x32_bf16 v[12:15], v[180:183], v[240:243], v[12:15]
	v_mfma_f32_16x16x32_bf16 v[8:11], v[188:191], v[240:243], v[8:11]
	v_mfma_f32_16x16x32_bf16 v[60:63], v[184:187], v[220:223], v[60:63]
	v_mfma_f32_16x16x32_bf16 v[56:59], v[196:199], v[220:223], v[56:59]
	v_mfma_f32_16x16x32_bf16 v[44:47], v[184:187], v[228:231], v[44:47]
	v_mfma_f32_16x16x32_bf16 v[40:43], v[196:199], v[228:231], v[40:43]
	v_mfma_f32_16x16x32_bf16 v[28:31], v[184:187], v[236:239], v[28:31]
	v_mfma_f32_16x16x32_bf16 v[24:27], v[196:199], v[236:239], v[24:27]
	v_mfma_f32_16x16x32_bf16 v[12:15], v[184:187], v[244:247], v[12:15]
	v_mfma_f32_16x16x32_bf16 v[8:11], v[196:199], v[244:247], v[8:11]
	s_setprio 0
	s_setprio 1
	v_mfma_f32_16x16x32_bf16 v[52:55], v[200:203], v[216:219], v[52:55]
	v_mfma_f32_16x16x32_bf16 v[48:51], v[208:211], v[216:219], v[48:51]
	v_mfma_f32_16x16x32_bf16 v[36:39], v[200:203], v[224:227], v[36:39]
	v_mfma_f32_16x16x32_bf16 v[32:35], v[208:211], v[224:227], v[32:35]
	v_mfma_f32_16x16x32_bf16 v[20:23], v[200:203], v[232:235], v[20:23]
	v_mfma_f32_16x16x32_bf16 v[16:19], v[208:211], v[232:235], v[16:19]
	v_mfma_f32_16x16x32_bf16 v[4:7], v[200:203], v[240:243], v[4:7]
	v_mfma_f32_16x16x32_bf16 v[0:3], v[208:211], v[240:243], v[0:3]
	v_mfma_f32_16x16x32_bf16 v[52:55], v[204:207], v[220:223], v[52:55]
	v_mfma_f32_16x16x32_bf16 v[48:51], v[212:215], v[220:223], v[48:51]
	v_mfma_f32_16x16x32_bf16 v[36:39], v[204:207], v[228:231], v[36:39]
	v_mfma_f32_16x16x32_bf16 v[32:35], v[212:215], v[228:231], v[32:35]
	v_mfma_f32_16x16x32_bf16 v[20:23], v[204:207], v[236:239], v[20:23]
	v_mfma_f32_16x16x32_bf16 v[16:19], v[212:215], v[236:239], v[16:19]
	v_mfma_f32_16x16x32_bf16 v[4:7], v[204:207], v[244:247], v[4:7]
	v_mfma_f32_16x16x32_bf16 v[0:3], v[212:215], v[244:247], v[0:3]
	s_setprio 0
	s_barrier
	s_add_i32 s54, s54, 2
	s_add_u32 s10, s10, 0x100
	s_addc_u32 s11, s11, 0
	s_add_u32 s38, s38, 0x100
	s_addc_u32 s39, s39, 0
	s_cmp_gt_u32 s54, 13
	s_cbranch_scc0 .LBB0_154
	s_and_b64 vcc, exec, s[22:23]
	s_cbranch_vccz .LBB0_157
	s_barrier

.LBB0_241:
	s_lshl_b32 s11, s16, 5
	s_add_i32 s64, s31, 0x18000
	s_mov_b64 s[16:17], 0x80
	s_and_b32 s11, s11, 0x60
	v_lshl_add_u64 v[6:7], v[6:7], 0, s[16:17]
	s_mov_b32 m0, s64
	s_add_i32 s65, s31, 0x1a000
	s_lshl_b32 s7, s5, 13
	s_lshl_b32 s20, s11, 7
	s_waitcnt vmcnt(2)
	s_barrier
	global_load_lds_dwordx4 v[6:7], off
	v_lshl_add_u64 v[4:5], v[4:5], 0, s[16:17]
	s_mov_b32 m0, s65
	s_add_i32 s66, s31, 0x8000
	s_add_i32 s67, s31, 0xa000
	global_load_lds_dwordx4 v[4:5], off
	v_lshl_add_u64 v[0:1], v[0:1], 0, s[16:17]
	s_mov_b32 m0, s66
	s_add_u32 s18, s14, 0x40080
	global_load_lds_dwordx4 v[0:1], off
	v_lshl_add_u64 v[0:1], v[2:3], 0, s[16:17]
	s_mov_b32 m0, s67
	s_addc_u32 s19, s15, 0
	s_add_i32 s72, s31, 0x1c000
	global_load_lds_dwordx4 v[0:1], off
	s_mov_b32 m0, s72
	s_add_i32 s73, s31, 0x1e000
	global_load_lds_dwordx4 v132, s[18:19]
	s_mov_b32 m0, s73
	s_cmpk_lt_u32 s4, 0x100
	global_load_lds_dwordx4 v134, s[18:19]
	v_bfe_u32 v1, v8, 4, 2
	v_and_b32_e32 v0, 15, v8
	v_lshlrev_b32_e32 v2, 4, v1
	v_lshl_or_b32 v129, s5, 6, v0
	v_lshl_or_b32 v0, v0, 6, v2
	v_lshlrev_b32_e32 v2, 2, v8
	v_lshl_or_b32 v164, v1, 2, s11
	v_lshlrev_b32_e32 v1, 14, v9
	v_and_b32_e32 v2, 32, v2
	v_and_b32_e32 v1, 0xffff8000, v1
	v_bitop3_b32 v145, v0, s7, v2 bitop3:0xde
	v_bitop3_b32 v0, v0, s20, v2 bitop3:0xde
	v_lshl_add_u32 v1, v10, 11, v1
	v_and_b32_e32 v2, 1, v9
	v_lshl_or_b32 v1, v2, 6, v1
	v_lshl_add_u32 v138, v11, 1, v1
	v_lshlrev_b32_e32 v1, 14, v12
	v_and_b32_e32 v1, 0xffff8000, v1
	s_waitcnt vmcnt(6)
	v_lshl_add_u32 v1, v13, 11, v1
	v_and_b32_e32 v2, 1, v12
	v_lshl_or_b32 v1, v2, 6, v1
	s_cselect_b64 s[18:19], -1, 0
	s_ashr_i32 s74, s82, 31
	s_mov_b32 s75, s82
	s_ashr_i32 s78, s3, 31
	v_mov_b32_e32 v139, v137
	v_lshl_add_u32 v140, v14, 1, v1
	v_mov_b32_e32 v141, v137
	s_mov_b32 s79, 0
	v_mov_b64_e32 v[142:143], 0x400
	v_mov_b64_e32 v[150:151], 0x3ff
	v_or_b32_e32 v165, 0x10000, v0
	v_add_u32_e32 v167, 0x10400, v0
	v_add_u32_e32 v168, 0x10800, v0
	v_add_u32_e32 v169, 0x10c00, v0
	v_or_b32_e32 v170, 0x14000, v0
	v_add_u32_e32 v171, 0x14400, v0
	v_add_u32_e32 v172, 0x14800, v0
	v_add_u32_e32 v173, 0x14c00, v0
	s_add_i32 s82, s31, 0xc000
	s_add_i32 s83, s31, 0xe000
	v_or_b32_e32 v174, 0x18000, v0
	v_add_u32_e32 v175, 0x18400, v0
	v_add_u32_e32 v176, 0x18800, v0
	v_add_u32_e32 v177, 0x18c00, v0
	v_or_b32_e32 v178, 0x1c000, v0
	v_add_u32_e32 v179, 0x1c400, v0
	v_add_u32_e32 v180, 0x1c800, v0
	v_add_u32_e32 v181, 0x1cc00, v0
	s_brev_b32 s84, -4
	s_barrier
	s_branch .LBB0_244

.LBB0_251:
	ds_read_b128 v[160:163], v165
	ds_read_b128 v[182:185], v167
	ds_read_b128 v[186:189], v168
	ds_read_b128 v[190:193], v169
	ds_read_b128 v[196:199], v170
	ds_read_b128 v[200:203], v171
	ds_read_b128 v[204:207], v172
	ds_read_b128 v[208:211], v173
	s_add_u32 s14, s12, 0xfffc0080
	s_addc_u32 s15, s13, -1
	s_cmp_eq_u32 s54, 12
	s_cselect_b32 s29, s7, s15
	s_cselect_b32 s28, s11, s14
	s_cselect_b32 s15, s21, s39
	s_cselect_b32 s14, s23, s38
	s_mov_b32 m0, s82
	ds_read_b128 v[212:215], v145
	ds_read_b128 v[216:219], v145 offset:1024
	ds_read_b128 v[220:223], v145 offset:2048
	ds_read_b128 v[224:227], v145 offset:3072
	ds_read_b128 v[228:231], v145 offset:4096
	ds_read_b128 v[232:235], v145 offset:5120
	ds_read_b128 v[236:239], v145 offset:6144
	ds_read_b128 v[240:243], v145 offset:7168
	global_load_lds_dwordx4 v138, s[12:13]
	s_mov_b32 m0, s83
	s_nop 0
	global_load_lds_dwordx4 v140, s[12:13]
	s_waitcnt vmcnt(8)
	s_waitcnt lgkmcnt(0)
	s_barrier
	s_setprio 1
	s_waitcnt lgkmcnt(0)
	v_mfma_f32_16x16x32_bf16 v[124:127], v[160:163], v[212:215], v[124:127]
	v_mfma_f32_16x16x32_bf16 v[120:123], v[186:189], v[212:215], v[120:123]
	v_mfma_f32_16x16x32_bf16 v[108:111], v[160:163], v[220:223], v[108:111]
	v_mfma_f32_16x16x32_bf16 v[104:107], v[186:189], v[220:223], v[104:107]
	v_mfma_f32_16x16x32_bf16 v[92:95], v[160:163], v[228:231], v[92:95]
	v_mfma_f32_16x16x32_bf16 v[88:91], v[186:189], v[228:231], v[88:91]
	v_mfma_f32_16x16x32_bf16 v[76:79], v[160:163], v[236:239], v[76:79]
	v_mfma_f32_16x16x32_bf16 v[72:75], v[186:189], v[236:239], v[72:75]
	v_mfma_f32_16x16x32_bf16 v[124:127], v[182:185], v[216:219], v[124:127]
	v_mfma_f32_16x16x32_bf16 v[120:123], v[190:193], v[216:219], v[120:123]
	v_mfma_f32_16x16x32_bf16 v[108:111], v[182:185], v[224:227], v[108:111]
	v_mfma_f32_16x16x32_bf16 v[104:107], v[190:193], v[224:227], v[104:107]
	v_mfma_f32_16x16x32_bf16 v[92:95], v[182:185], v[232:235], v[92:95]
	v_mfma_f32_16x16x32_bf16 v[88:91], v[190:193], v[232:235], v[88:91]
	v_mfma_f32_16x16x32_bf16 v[76:79], v[182:185], v[240:243], v[76:79]
	v_mfma_f32_16x16x32_bf16 v[72:75], v[190:193], v[240:243], v[72:75]
	s_setprio 0
	s_setprio 1
	v_mfma_f32_16x16x32_bf16 v[116:119], v[196:199], v[212:215], v[116:119]
	v_mfma_f32_16x16x32_bf16 v[112:115], v[204:207], v[212:215], v[112:115]
	v_mfma_f32_16x16x32_bf16 v[100:103], v[196:199], v[220:223], v[100:103]
	v_mfma_f32_16x16x32_bf16 v[96:99], v[204:207], v[220:223], v[96:99]
	v_mfma_f32_16x16x32_bf16 v[84:87], v[196:199], v[228:231], v[84:87]
	v_mfma_f32_16x16x32_bf16 v[80:83], v[204:207], v[228:231], v[80:83]
	v_mfma_f32_16x16x32_bf16 v[68:71], v[196:199], v[236:239], v[68:71]
	v_mfma_f32_16x16x32_bf16 v[64:67], v[204:207], v[236:239], v[64:67]
	v_mfma_f32_16x16x32_bf16 v[116:119], v[200:203], v[216:219], v[116:119]
	v_mfma_f32_16x16x32_bf16 v[112:115], v[208:211], v[216:219], v[112:115]
	v_mfma_f32_16x16x32_bf16 v[100:103], v[200:203], v[224:227], v[100:103]
	v_mfma_f32_16x16x32_bf16 v[96:99], v[208:211], v[224:227], v[96:99]
	v_mfma_f32_16x16x32_bf16 v[84:87], v[200:203], v[232:235], v[84:87]
	v_mfma_f32_16x16x32_bf16 v[80:83], v[208:211], v[232:235], v[80:83]
	v_mfma_f32_16x16x32_bf16 v[68:71], v[200:203], v[240:243], v[68:71]
	v_mfma_f32_16x16x32_bf16 v[64:67], v[208:211], v[240:243], v[64:67]
	s_setprio 0
	s_barrier
	s_add_u32 s98, s14, s16
	s_addc_u32 s99, s15, s17
	s_add_u32 s100, s28, s16
	s_addc_u32 s101, s29, s17
	s_mov_b32 m0, s33
	s_add_u32 s56, s14, 0x40000
	ds_read_b128 v[212:215], v145 offset:16384
	ds_read_b128 v[216:219], v145 offset:17408
	ds_read_b128 v[220:223], v145 offset:18432
	ds_read_b128 v[224:227], v145 offset:19456
	ds_read_b128 v[228:231], v145 offset:20480
	ds_read_b128 v[232:235], v145 offset:21504
	ds_read_b128 v[236:239], v145 offset:22528
	ds_read_b128 v[240:243], v145 offset:23552
	global_load_lds_dwordx4 v132, s[14:15]
	s_mov_b32 m0, s34
	s_addc_u32 s57, s15, 0
	global_load_lds_dwordx4 v134, s[14:15]
	s_mov_b32 m0, s35
	s_nop 0
	global_load_lds_dwordx4 v132, s[56:57]
	s_mov_b32 m0, s36
	s_nop 0
	global_load_lds_dwordx4 v134, s[56:57]
	s_mov_b32 m0, s31
	s_nop 0
	global_load_lds_dwordx4 v132, s[28:29]
	s_mov_b32 m0, s37
	s_nop 0
	global_load_lds_dwordx4 v134, s[28:29]
	s_waitcnt vmcnt(8)
	s_waitcnt lgkmcnt(0)
	s_barrier
	s_setprio 1
	s_waitcnt lgkmcnt(0)
	v_mfma_f32_16x16x32_bf16 v[60:63], v[160:163], v[212:215], v[60:63]
	v_mfma_f32_16x16x32_bf16 v[56:59], v[186:189], v[212:215], v[56:59]
	v_mfma_f32_16x16x32_bf16 v[44:47], v[160:163], v[220:223], v[44:47]
	v_mfma_f32_16x16x32_bf16 v[40:43], v[186:189], v[220:223], v[40:43]
	v_mfma_f32_16x16x32_bf16 v[28:31], v[160:163], v[228:231], v[28:31]
	v_mfma_f32_16x16x32_bf16 v[24:27], v[186:189], v[228:231], v[24:27]
	v_mfma_f32_16x16x32_bf16 v[12:15], v[160:163], v[236:239], v[12:15]
	v_mfma_f32_16x16x32_bf16 v[8:11], v[186:189], v[236:239], v[8:11]
	v_mfma_f32_16x16x32_bf16 v[60:63], v[182:185], v[216:219], v[60:63]
	v_mfma_f32_16x16x32_bf16 v[56:59], v[190:193], v[216:219], v[56:59]
	v_mfma_f32_16x16x32_bf16 v[44:47], v[182:185], v[224:227], v[44:47]
	v_mfma_f32_16x16x32_bf16 v[40:43], v[190:193], v[224:227], v[40:43]
	v_mfma_f32_16x16x32_bf16 v[28:31], v[182:185], v[232:235], v[28:31]
	v_mfma_f32_16x16x32_bf16 v[24:27], v[190:193], v[232:235], v[24:27]
	v_mfma_f32_16x16x32_bf16 v[12:15], v[182:185], v[240:243], v[12:15]
	v_mfma_f32_16x16x32_bf16 v[8:11], v[190:193], v[240:243], v[8:11]
	s_setprio 0
	s_setprio 1
	v_mfma_f32_16x16x32_bf16 v[52:55], v[196:199], v[212:215], v[52:55]
	v_mfma_f32_16x16x32_bf16 v[48:51], v[204:207], v[212:215], v[48:51]
	v_mfma_f32_16x16x32_bf16 v[36:39], v[196:199], v[220:223], v[36:39]
	v_mfma_f32_16x16x32_bf16 v[32:35], v[204:207], v[220:223], v[32:35]
	v_mfma_f32_16x16x32_bf16 v[20:23], v[196:199], v[228:231], v[20:23]
	v_mfma_f32_16x16x32_bf16 v[16:19], v[204:207], v[228:231], v[16:19]
	v_mfma_f32_16x16x32_bf16 v[4:7], v[196:199], v[236:239], v[4:7]
	v_mfma_f32_16x16x32_bf16 v[0:3], v[204:207], v[236:239], v[0:3]
	v_mfma_f32_16x16x32_bf16 v[52:55], v[200:203], v[216:219], v[52:55]
	v_mfma_f32_16x16x32_bf16 v[48:51], v[208:211], v[216:219], v[48:51]
	v_mfma_f32_16x16x32_bf16 v[36:39], v[200:203], v[224:227], v[36:39]
	v_mfma_f32_16x16x32_bf16 v[32:35], v[208:211], v[224:227], v[32:35]
	v_mfma_f32_16x16x32_bf16 v[20:23], v[200:203], v[232:235], v[20:23]
	v_mfma_f32_16x16x32_bf16 v[16:19], v[208:211], v[232:235], v[16:19]
	v_mfma_f32_16x16x32_bf16 v[4:7], v[200:203], v[240:243], v[4:7]
	v_mfma_f32_16x16x32_bf16 v[0:3], v[208:211], v[240:243], v[0:3]
	s_setprio 0
	s_barrier
	ds_read_b128 v[160:163], v174
	ds_read_b128 v[182:185], v175
	ds_read_b128 v[186:189], v176
	ds_read_b128 v[190:193], v177
	ds_read_b128 v[196:199], v178
	ds_read_b128 v[200:203], v179
	ds_read_b128 v[204:207], v180
	ds_read_b128 v[208:211], v181
	s_add_u32 s28, s28, 0x40000
	s_addc_u32 s29, s29, 0
	s_mov_b32 m0, s62
	ds_read_b128 v[212:215], v145 offset:32768
	ds_read_b128 v[216:219], v145 offset:33792
	ds_read_b128 v[220:223], v145 offset:34816
	ds_read_b128 v[224:227], v145 offset:35840
	ds_read_b128 v[228:231], v145 offset:36864
	ds_read_b128 v[232:235], v145 offset:37888
	ds_read_b128 v[236:239], v145 offset:38912
	ds_read_b128 v[240:243], v145 offset:39936
	global_load_lds_dwordx4 v132, s[28:29]
	s_mov_b32 m0, s63
	s_nop 0
	global_load_lds_dwordx4 v134, s[28:29]
	s_waitcnt vmcnt(8)
	s_waitcnt lgkmcnt(0)
	s_barrier
	s_setprio 1
	s_waitcnt lgkmcnt(0)
	v_mfma_f32_16x16x32_bf16 v[124:127], v[160:163], v[212:215], v[124:127]
	v_mfma_f32_16x16x32_bf16 v[120:123], v[186:189], v[212:215], v[120:123]
	v_mfma_f32_16x16x32_bf16 v[108:111], v[160:163], v[220:223], v[108:111]
	v_mfma_f32_16x16x32_bf16 v[104:107], v[186:189], v[220:223], v[104:107]
	v_mfma_f32_16x16x32_bf16 v[92:95], v[160:163], v[228:231], v[92:95]
	v_mfma_f32_16x16x32_bf16 v[88:91], v[186:189], v[228:231], v[88:91]
	v_mfma_f32_16x16x32_bf16 v[76:79], v[160:163], v[236:239], v[76:79]
	v_mfma_f32_16x16x32_bf16 v[72:75], v[186:189], v[236:239], v[72:75]
	v_mfma_f32_16x16x32_bf16 v[124:127], v[182:185], v[216:219], v[124:127]
	v_mfma_f32_16x16x32_bf16 v[120:123], v[190:193], v[216:219], v[120:123]
	v_mfma_f32_16x16x32_bf16 v[108:111], v[182:185], v[224:227], v[108:111]
	v_mfma_f32_16x16x32_bf16 v[104:107], v[190:193], v[224:227], v[104:107]
	v_mfma_f32_16x16x32_bf16 v[92:95], v[182:185], v[232:235], v[92:95]
	v_mfma_f32_16x16x32_bf16 v[88:91], v[190:193], v[232:235], v[88:91]
	v_mfma_f32_16x16x32_bf16 v[76:79], v[182:185], v[240:243], v[76:79]
	v_mfma_f32_16x16x32_bf16 v[72:75], v[190:193], v[240:243], v[72:75]
	s_setprio 0
	s_setprio 1
	v_mfma_f32_16x16x32_bf16 v[116:119], v[196:199], v[212:215], v[116:119]
	v_mfma_f32_16x16x32_bf16 v[112:115], v[204:207], v[212:215], v[112:115]
	v_mfma_f32_16x16x32_bf16 v[100:103], v[196:199], v[220:223], v[100:103]
	v_mfma_f32_16x16x32_bf16 v[96:99], v[204:207], v[220:223], v[96:99]
	v_mfma_f32_16x16x32_bf16 v[84:87], v[196:199], v[228:231], v[84:87]
	v_mfma_f32_16x16x32_bf16 v[80:83], v[204:207], v[228:231], v[80:83]
	v_mfma_f32_16x16x32_bf16 v[68:71], v[196:199], v[236:239], v[68:71]
	v_mfma_f32_16x16x32_bf16 v[64:67], v[204:207], v[236:239], v[64:67]
	v_mfma_f32_16x16x32_bf16 v[116:119], v[200:203], v[216:219], v[116:119]
	v_mfma_f32_16x16x32_bf16 v[112:115], v[208:211], v[216:219], v[112:115]
	v_mfma_f32_16x16x32_bf16 v[100:103], v[200:203], v[224:227], v[100:103]
	v_mfma_f32_16x16x32_bf16 v[96:99], v[208:211], v[224:227], v[96:99]
	v_mfma_f32_16x16x32_bf16 v[84:87], v[200:203], v[232:235], v[84:87]
	v_mfma_f32_16x16x32_bf16 v[80:83], v[208:211], v[232:235], v[80:83]
	v_mfma_f32_16x16x32_bf16 v[68:71], v[200:203], v[240:243], v[68:71]
	v_mfma_f32_16x16x32_bf16 v[64:67], v[208:211], v[240:243], v[64:67]
	s_setprio 0
	s_barrier
	s_mov_b32 m0, s64
	s_add_u32 s14, s14, 0x40080
	ds_read_b128 v[212:215], v145 offset:49152
	ds_read_b128 v[216:219], v145 offset:50176
	ds_read_b128 v[220:223], v145 offset:51200
	ds_read_b128 v[224:227], v145 offset:52224
	ds_read_b128 v[228:231], v145 offset:53248
	ds_read_b128 v[232:235], v145 offset:54272
	ds_read_b128 v[236:239], v145 offset:55296
	ds_read_b128 v[240:243], v145 offset:56320
	global_load_lds_dwordx4 v132, s[98:99]
	s_mov_b32 m0, s65
	s_addc_u32 s15, s15, 0
	global_load_lds_dwordx4 v134, s[98:99]
	s_mov_b32 m0, s72
	s_nop 0
	global_load_lds_dwordx4 v132, s[14:15]
	s_mov_b32 m0, s73
	s_nop 0
	global_load_lds_dwordx4 v134, s[14:15]
	s_mov_b32 m0, s66
	s_nop 0
	global_load_lds_dwordx4 v132, s[100:101]
	s_mov_b32 m0, s67
	s_nop 0
	global_load_lds_dwordx4 v134, s[100:101]
	s_waitcnt vmcnt(8)
	s_waitcnt lgkmcnt(0)
	s_barrier
	s_setprio 1
	s_waitcnt lgkmcnt(0)
	v_mfma_f32_16x16x32_bf16 v[60:63], v[160:163], v[212:215], v[60:63]
	v_mfma_f32_16x16x32_bf16 v[56:59], v[186:189], v[212:215], v[56:59]
	v_mfma_f32_16x16x32_bf16 v[44:47], v[160:163], v[220:223], v[44:47]
	v_mfma_f32_16x16x32_bf16 v[40:43], v[186:189], v[220:223], v[40:43]
	v_mfma_f32_16x16x32_bf16 v[28:31], v[160:163], v[228:231], v[28:31]
	v_mfma_f32_16x16x32_bf16 v[24:27], v[186:189], v[228:231], v[24:27]
	v_mfma_f32_16x16x32_bf16 v[12:15], v[160:163], v[236:239], v[12:15]
	v_mfma_f32_16x16x32_bf16 v[8:11], v[186:189], v[236:239], v[8:11]
	v_mfma_f32_16x16x32_bf16 v[60:63], v[182:185], v[216:219], v[60:63]
	v_mfma_f32_16x16x32_bf16 v[56:59], v[190:193], v[216:219], v[56:59]
	v_mfma_f32_16x16x32_bf16 v[44:47], v[182:185], v[224:227], v[44:47]
	v_mfma_f32_16x16x32_bf16 v[40:43], v[190:193], v[224:227], v[40:43]
	v_mfma_f32_16x16x32_bf16 v[28:31], v[182:185], v[232:235], v[28:31]
	v_mfma_f32_16x16x32_bf16 v[24:27], v[190:193], v[232:235], v[24:27]
	v_mfma_f32_16x16x32_bf16 v[12:15], v[182:185], v[240:243], v[12:15]
	v_mfma_f32_16x16x32_bf16 v[8:11], v[190:193], v[240:243], v[8:11]
	s_setprio 0
	s_setprio 1
	v_mfma_f32_16x16x32_bf16 v[52:55], v[196:199], v[212:215], v[52:55]
	v_mfma_f32_16x16x32_bf16 v[48:51], v[204:207], v[212:215], v[48:51]
	v_mfma_f32_16x16x32_bf16 v[36:39], v[196:199], v[220:223], v[36:39]
	v_mfma_f32_16x16x32_bf16 v[32:35], v[204:207], v[220:223], v[32:35]
	v_mfma_f32_16x16x32_bf16 v[20:23], v[196:199], v[228:231], v[20:23]
	v_mfma_f32_16x16x32_bf16 v[16:19], v[204:207], v[228:231], v[16:19]
	v_mfma_f32_16x16x32_bf16 v[4:7], v[196:199], v[236:239], v[4:7]
	v_mfma_f32_16x16x32_bf16 v[0:3], v[204:207], v[236:239], v[0:3]
	v_mfma_f32_16x16x32_bf16 v[52:55], v[200:203], v[216:219], v[52:55]
	v_mfma_f32_16x16x32_bf16 v[48:51], v[208:211], v[216:219], v[48:51]
	v_mfma_f32_16x16x32_bf16 v[36:39], v[200:203], v[224:227], v[36:39]
	v_mfma_f32_16x16x32_bf16 v[32:35], v[208:211], v[224:227], v[32:35]
	v_mfma_f32_16x16x32_bf16 v[20:23], v[200:203], v[232:235], v[20:23]
	v_mfma_f32_16x16x32_bf16 v[16:19], v[208:211], v[232:235], v[16:19]
	v_mfma_f32_16x16x32_bf16 v[4:7], v[200:203], v[240:243], v[4:7]
	v_mfma_f32_16x16x32_bf16 v[0:3], v[208:211], v[240:243], v[0:3]
	s_setprio 0
	s_barrier
	s_add_i32 s54, s54, 2
	s_add_u32 s12, s12, 0x100
	s_addc_u32 s13, s13, 0
	s_add_u32 s38, s38, 0x100
	s_addc_u32 s39, s39, 0
	s_cmp_gt_u32 s54, 13
	s_cbranch_scc0 .LBB0_251
	s_and_b64 vcc, exec, s[18:19]
	s_cbranch_vccz .LBB0_254
	s_barrier

.LBB0_576:
	s_lshl_b32 s9, s14, 5
	s_add_i32 s64, s29, 0x18000
	s_mov_b64 s[16:17], 0x80
	s_and_b32 s9, s9, 0x60
	v_lshl_add_u64 v[6:7], v[6:7], 0, s[16:17]
	s_mov_b32 m0, s64
	s_add_i32 s65, s29, 0x1a000
	s_lshl_b32 s7, s5, 13
	s_lshl_b32 s18, s9, 7
	s_waitcnt vmcnt(2)
	s_barrier
	global_load_lds_dwordx4 v[6:7], off
	v_lshl_add_u64 v[4:5], v[4:5], 0, s[16:17]
	s_mov_b32 m0, s65
	s_add_i32 s66, s29, 0x8000
	s_add_i32 s67, s29, 0xa000
	global_load_lds_dwordx4 v[4:5], off
	v_lshl_add_u64 v[0:1], v[0:1], 0, s[16:17]
	s_mov_b32 m0, s66
	s_add_u32 s14, s12, 0x40080
	global_load_lds_dwordx4 v[0:1], off
	v_lshl_add_u64 v[0:1], v[2:3], 0, s[16:17]
	s_mov_b32 m0, s67
	s_addc_u32 s15, s13, 0
	s_add_i32 s72, s29, 0x1c000
	global_load_lds_dwordx4 v[0:1], off
	s_mov_b32 m0, s72
	s_add_i32 s73, s29, 0x1e000
	global_load_lds_dwordx4 v132, s[14:15]
	s_mov_b32 m0, s73
	s_cmpk_lt_u32 s4, 0x100
	global_load_lds_dwordx4 v134, s[14:15]
	v_bfe_u32 v1, v8, 4, 2
	v_and_b32_e32 v0, 15, v8
	v_lshlrev_b32_e32 v2, 4, v1
	v_lshl_or_b32 v129, s5, 6, v0
	v_lshl_or_b32 v0, v0, 6, v2
	v_lshlrev_b32_e32 v2, 2, v8
	v_lshl_or_b32 v164, v1, 2, s9
	v_lshlrev_b32_e32 v1, 14, v9
	v_and_b32_e32 v2, 32, v2
	v_and_b32_e32 v1, 0xffff8000, v1
	v_bitop3_b32 v145, v0, s7, v2 bitop3:0xde
	v_bitop3_b32 v0, v0, s18, v2 bitop3:0xde
	v_lshl_add_u32 v1, v10, 11, v1
	v_and_b32_e32 v2, 1, v9
	v_lshl_or_b32 v1, v2, 6, v1
	v_lshl_add_u32 v138, v11, 1, v1
	v_lshlrev_b32_e32 v1, 14, v12
	v_and_b32_e32 v1, 0xffff8000, v1
	s_waitcnt vmcnt(6)
	v_lshl_add_u32 v1, v13, 11, v1
	v_and_b32_e32 v2, 1, v12
	v_lshl_or_b32 v1, v2, 6, v1
	s_cselect_b64 s[18:19], -1, 0
	s_ashr_i32 s74, s82, 31
	s_mov_b32 s75, s82
	s_ashr_i32 s78, s3, 31
	v_mov_b32_e32 v139, v137
	v_lshl_add_u32 v140, v14, 1, v1
	v_mov_b32_e32 v141, v137
	s_mov_b32 s79, 0
	v_mov_b64_e32 v[142:143], 0x400
	v_mov_b64_e32 v[150:151], 0x3ff
	v_or_b32_e32 v165, 0x10000, v0
	v_add_u32_e32 v167, 0x10400, v0
	v_add_u32_e32 v168, 0x10800, v0
	v_add_u32_e32 v169, 0x10c00, v0
	v_or_b32_e32 v170, 0x14000, v0
	v_add_u32_e32 v171, 0x14400, v0
	v_add_u32_e32 v172, 0x14800, v0
	v_add_u32_e32 v173, 0x14c00, v0
	s_add_i32 s82, s29, 0xc000
	s_add_i32 s83, s29, 0xe000
	v_or_b32_e32 v174, 0x18000, v0
	v_add_u32_e32 v175, 0x18400, v0
	v_add_u32_e32 v176, 0x18800, v0
	v_add_u32_e32 v177, 0x18c00, v0
	v_or_b32_e32 v178, 0x1c000, v0
	v_add_u32_e32 v179, 0x1c400, v0
	v_add_u32_e32 v180, 0x1c800, v0
	v_add_u32_e32 v181, 0x1cc00, v0
	s_brev_b32 s84, -4
	s_barrier
	s_branch .LBB0_579

.LBB0_586:
	ds_read_b128 v[160:163], v165
	ds_read_b128 v[182:185], v167
	ds_read_b128 v[186:189], v168
	ds_read_b128 v[190:193], v169
	ds_read_b128 v[196:199], v170
	ds_read_b128 v[200:203], v171
	ds_read_b128 v[204:207], v172
	ds_read_b128 v[208:211], v173
	s_add_u32 s12, s10, 0xfffc0080
	s_addc_u32 s13, s11, -1
	s_cmp_eq_u32 s54, 12
	s_cselect_b32 s15, s7, s13
	s_cselect_b32 s14, s9, s12
	s_cselect_b32 s13, s21, s39
	s_cselect_b32 s12, s23, s38
	s_mov_b32 m0, s82
	ds_read_b128 v[212:215], v145
	ds_read_b128 v[216:219], v145 offset:1024
	ds_read_b128 v[220:223], v145 offset:2048
	ds_read_b128 v[224:227], v145 offset:3072
	ds_read_b128 v[228:231], v145 offset:4096
	ds_read_b128 v[232:235], v145 offset:5120
	ds_read_b128 v[236:239], v145 offset:6144
	ds_read_b128 v[240:243], v145 offset:7168
	global_load_lds_dwordx4 v138, s[10:11]
	s_mov_b32 m0, s83
	s_nop 0
	global_load_lds_dwordx4 v140, s[10:11]
	s_waitcnt vmcnt(8)
	s_waitcnt lgkmcnt(0)
	s_barrier
	s_setprio 1
	s_waitcnt lgkmcnt(0)
	v_mfma_f32_16x16x32_bf16 v[124:127], v[160:163], v[212:215], v[124:127]
	v_mfma_f32_16x16x32_bf16 v[120:123], v[186:189], v[212:215], v[120:123]
	v_mfma_f32_16x16x32_bf16 v[108:111], v[160:163], v[220:223], v[108:111]
	v_mfma_f32_16x16x32_bf16 v[104:107], v[186:189], v[220:223], v[104:107]
	v_mfma_f32_16x16x32_bf16 v[92:95], v[160:163], v[228:231], v[92:95]
	v_mfma_f32_16x16x32_bf16 v[88:91], v[186:189], v[228:231], v[88:91]
	v_mfma_f32_16x16x32_bf16 v[76:79], v[160:163], v[236:239], v[76:79]
	v_mfma_f32_16x16x32_bf16 v[72:75], v[186:189], v[236:239], v[72:75]
	v_mfma_f32_16x16x32_bf16 v[124:127], v[182:185], v[216:219], v[124:127]
	v_mfma_f32_16x16x32_bf16 v[120:123], v[190:193], v[216:219], v[120:123]
	v_mfma_f32_16x16x32_bf16 v[108:111], v[182:185], v[224:227], v[108:111]
	v_mfma_f32_16x16x32_bf16 v[104:107], v[190:193], v[224:227], v[104:107]
	v_mfma_f32_16x16x32_bf16 v[92:95], v[182:185], v[232:235], v[92:95]
	v_mfma_f32_16x16x32_bf16 v[88:91], v[190:193], v[232:235], v[88:91]
	v_mfma_f32_16x16x32_bf16 v[76:79], v[182:185], v[240:243], v[76:79]
	v_mfma_f32_16x16x32_bf16 v[72:75], v[190:193], v[240:243], v[72:75]
	s_setprio 0
	s_setprio 1
	v_mfma_f32_16x16x32_bf16 v[116:119], v[196:199], v[212:215], v[116:119]
	v_mfma_f32_16x16x32_bf16 v[112:115], v[204:207], v[212:215], v[112:115]
	v_mfma_f32_16x16x32_bf16 v[100:103], v[196:199], v[220:223], v[100:103]
	v_mfma_f32_16x16x32_bf16 v[96:99], v[204:207], v[220:223], v[96:99]
	v_mfma_f32_16x16x32_bf16 v[84:87], v[196:199], v[228:231], v[84:87]
	v_mfma_f32_16x16x32_bf16 v[80:83], v[204:207], v[228:231], v[80:83]
	v_mfma_f32_16x16x32_bf16 v[68:71], v[196:199], v[236:239], v[68:71]
	v_mfma_f32_16x16x32_bf16 v[64:67], v[204:207], v[236:239], v[64:67]
	v_mfma_f32_16x16x32_bf16 v[116:119], v[200:203], v[216:219], v[116:119]
	v_mfma_f32_16x16x32_bf16 v[112:115], v[208:211], v[216:219], v[112:115]
	v_mfma_f32_16x16x32_bf16 v[100:103], v[200:203], v[224:227], v[100:103]
	v_mfma_f32_16x16x32_bf16 v[96:99], v[208:211], v[224:227], v[96:99]
	v_mfma_f32_16x16x32_bf16 v[84:87], v[200:203], v[232:235], v[84:87]
	v_mfma_f32_16x16x32_bf16 v[80:83], v[208:211], v[232:235], v[80:83]
	v_mfma_f32_16x16x32_bf16 v[68:71], v[200:203], v[240:243], v[68:71]
	v_mfma_f32_16x16x32_bf16 v[64:67], v[208:211], v[240:243], v[64:67]
	s_setprio 0
	s_barrier
	s_add_u32 s98, s12, s16
	s_addc_u32 s99, s13, s17
	s_add_u32 s100, s14, s16
	s_addc_u32 s101, s15, s17
	s_mov_b32 m0, s30
	s_add_u32 s56, s12, 0x40000
	ds_read_b128 v[212:215], v145 offset:16384
	ds_read_b128 v[216:219], v145 offset:17408
	ds_read_b128 v[220:223], v145 offset:18432
	ds_read_b128 v[224:227], v145 offset:19456
	ds_read_b128 v[228:231], v145 offset:20480
	ds_read_b128 v[232:235], v145 offset:21504
	ds_read_b128 v[236:239], v145 offset:22528
	ds_read_b128 v[240:243], v145 offset:23552
	global_load_lds_dwordx4 v132, s[12:13]
	s_mov_b32 m0, s31
	s_addc_u32 s57, s13, 0
	global_load_lds_dwordx4 v134, s[12:13]
	s_mov_b32 m0, s33
	s_nop 0
	global_load_lds_dwordx4 v132, s[56:57]
	s_mov_b32 m0, s34
	s_nop 0
	global_load_lds_dwordx4 v134, s[56:57]
	s_mov_b32 m0, s29
	s_nop 0
	global_load_lds_dwordx4 v132, s[14:15]
	s_mov_b32 m0, s35
	s_nop 0
	global_load_lds_dwordx4 v134, s[14:15]
	s_waitcnt vmcnt(8)
	s_waitcnt lgkmcnt(0)
	s_barrier
	s_setprio 1
	s_waitcnt lgkmcnt(0)
	v_mfma_f32_16x16x32_bf16 v[60:63], v[160:163], v[212:215], v[60:63]
	v_mfma_f32_16x16x32_bf16 v[56:59], v[186:189], v[212:215], v[56:59]
	v_mfma_f32_16x16x32_bf16 v[44:47], v[160:163], v[220:223], v[44:47]
	v_mfma_f32_16x16x32_bf16 v[40:43], v[186:189], v[220:223], v[40:43]
	v_mfma_f32_16x16x32_bf16 v[28:31], v[160:163], v[228:231], v[28:31]
	v_mfma_f32_16x16x32_bf16 v[24:27], v[186:189], v[228:231], v[24:27]
	v_mfma_f32_16x16x32_bf16 v[12:15], v[160:163], v[236:239], v[12:15]
	v_mfma_f32_16x16x32_bf16 v[8:11], v[186:189], v[236:239], v[8:11]
	v_mfma_f32_16x16x32_bf16 v[60:63], v[182:185], v[216:219], v[60:63]
	v_mfma_f32_16x16x32_bf16 v[56:59], v[190:193], v[216:219], v[56:59]
	v_mfma_f32_16x16x32_bf16 v[44:47], v[182:185], v[224:227], v[44:47]
	v_mfma_f32_16x16x32_bf16 v[40:43], v[190:193], v[224:227], v[40:43]
	v_mfma_f32_16x16x32_bf16 v[28:31], v[182:185], v[232:235], v[28:31]
	v_mfma_f32_16x16x32_bf16 v[24:27], v[190:193], v[232:235], v[24:27]
	v_mfma_f32_16x16x32_bf16 v[12:15], v[182:185], v[240:243], v[12:15]
	v_mfma_f32_16x16x32_bf16 v[8:11], v[190:193], v[240:243], v[8:11]
	s_setprio 0
	s_setprio 1
	v_mfma_f32_16x16x32_bf16 v[52:55], v[196:199], v[212:215], v[52:55]
	v_mfma_f32_16x16x32_bf16 v[48:51], v[204:207], v[212:215], v[48:51]
	v_mfma_f32_16x16x32_bf16 v[36:39], v[196:199], v[220:223], v[36:39]
	v_mfma_f32_16x16x32_bf16 v[32:35], v[204:207], v[220:223], v[32:35]
	v_mfma_f32_16x16x32_bf16 v[20:23], v[196:199], v[228:231], v[20:23]
	v_mfma_f32_16x16x32_bf16 v[16:19], v[204:207], v[228:231], v[16:19]
	v_mfma_f32_16x16x32_bf16 v[4:7], v[196:199], v[236:239], v[4:7]
	v_mfma_f32_16x16x32_bf16 v[0:3], v[204:207], v[236:239], v[0:3]
	v_mfma_f32_16x16x32_bf16 v[52:55], v[200:203], v[216:219], v[52:55]
	v_mfma_f32_16x16x32_bf16 v[48:51], v[208:211], v[216:219], v[48:51]
	v_mfma_f32_16x16x32_bf16 v[36:39], v[200:203], v[224:227], v[36:39]
	v_mfma_f32_16x16x32_bf16 v[32:35], v[208:211], v[224:227], v[32:35]
	v_mfma_f32_16x16x32_bf16 v[20:23], v[200:203], v[232:235], v[20:23]
	v_mfma_f32_16x16x32_bf16 v[16:19], v[208:211], v[232:235], v[16:19]
	v_mfma_f32_16x16x32_bf16 v[4:7], v[200:203], v[240:243], v[4:7]
	v_mfma_f32_16x16x32_bf16 v[0:3], v[208:211], v[240:243], v[0:3]
	s_setprio 0
	s_barrier
	ds_read_b128 v[160:163], v174
	ds_read_b128 v[182:185], v175
	ds_read_b128 v[186:189], v176
	ds_read_b128 v[190:193], v177
	ds_read_b128 v[196:199], v178
	ds_read_b128 v[200:203], v179
	ds_read_b128 v[204:207], v180
	ds_read_b128 v[208:211], v181
	s_add_u32 s14, s14, 0x40000
	s_addc_u32 s15, s15, 0
	s_mov_b32 m0, s36
	ds_read_b128 v[212:215], v145 offset:32768
	ds_read_b128 v[216:219], v145 offset:33792
	ds_read_b128 v[220:223], v145 offset:34816
	ds_read_b128 v[224:227], v145 offset:35840
	ds_read_b128 v[228:231], v145 offset:36864
	ds_read_b128 v[232:235], v145 offset:37888
	ds_read_b128 v[236:239], v145 offset:38912
	ds_read_b128 v[240:243], v145 offset:39936
	global_load_lds_dwordx4 v132, s[14:15]
	s_mov_b32 m0, s37
	s_nop 0
	global_load_lds_dwordx4 v134, s[14:15]
	s_waitcnt vmcnt(8)
	s_waitcnt lgkmcnt(0)
	s_barrier
	s_setprio 1
	s_waitcnt lgkmcnt(0)
	v_mfma_f32_16x16x32_bf16 v[124:127], v[160:163], v[212:215], v[124:127]
	v_mfma_f32_16x16x32_bf16 v[120:123], v[186:189], v[212:215], v[120:123]
	v_mfma_f32_16x16x32_bf16 v[108:111], v[160:163], v[220:223], v[108:111]
	v_mfma_f32_16x16x32_bf16 v[104:107], v[186:189], v[220:223], v[104:107]
	v_mfma_f32_16x16x32_bf16 v[92:95], v[160:163], v[228:231], v[92:95]
	v_mfma_f32_16x16x32_bf16 v[88:91], v[186:189], v[228:231], v[88:91]
	v_mfma_f32_16x16x32_bf16 v[76:79], v[160:163], v[236:239], v[76:79]
	v_mfma_f32_16x16x32_bf16 v[72:75], v[186:189], v[236:239], v[72:75]
	v_mfma_f32_16x16x32_bf16 v[124:127], v[182:185], v[216:219], v[124:127]
	v_mfma_f32_16x16x32_bf16 v[120:123], v[190:193], v[216:219], v[120:123]
	v_mfma_f32_16x16x32_bf16 v[108:111], v[182:185], v[224:227], v[108:111]
	v_mfma_f32_16x16x32_bf16 v[104:107], v[190:193], v[224:227], v[104:107]
	v_mfma_f32_16x16x32_bf16 v[92:95], v[182:185], v[232:235], v[92:95]
	v_mfma_f32_16x16x32_bf16 v[88:91], v[190:193], v[232:235], v[88:91]
	v_mfma_f32_16x16x32_bf16 v[76:79], v[182:185], v[240:243], v[76:79]
	v_mfma_f32_16x16x32_bf16 v[72:75], v[190:193], v[240:243], v[72:75]
	s_setprio 0
	s_setprio 1
	v_mfma_f32_16x16x32_bf16 v[116:119], v[196:199], v[212:215], v[116:119]
	v_mfma_f32_16x16x32_bf16 v[112:115], v[204:207], v[212:215], v[112:115]
	v_mfma_f32_16x16x32_bf16 v[100:103], v[196:199], v[220:223], v[100:103]
	v_mfma_f32_16x16x32_bf16 v[96:99], v[204:207], v[220:223], v[96:99]
	v_mfma_f32_16x16x32_bf16 v[84:87], v[196:199], v[228:231], v[84:87]
	v_mfma_f32_16x16x32_bf16 v[80:83], v[204:207], v[228:231], v[80:83]
	v_mfma_f32_16x16x32_bf16 v[68:71], v[196:199], v[236:239], v[68:71]
	v_mfma_f32_16x16x32_bf16 v[64:67], v[204:207], v[236:239], v[64:67]
	v_mfma_f32_16x16x32_bf16 v[116:119], v[200:203], v[216:219], v[116:119]
	v_mfma_f32_16x16x32_bf16 v[112:115], v[208:211], v[216:219], v[112:115]
	v_mfma_f32_16x16x32_bf16 v[100:103], v[200:203], v[224:227], v[100:103]
	v_mfma_f32_16x16x32_bf16 v[96:99], v[208:211], v[224:227], v[96:99]
	v_mfma_f32_16x16x32_bf16 v[84:87], v[200:203], v[232:235], v[84:87]
	v_mfma_f32_16x16x32_bf16 v[80:83], v[208:211], v[232:235], v[80:83]
	v_mfma_f32_16x16x32_bf16 v[68:71], v[200:203], v[240:243], v[68:71]
	v_mfma_f32_16x16x32_bf16 v[64:67], v[208:211], v[240:243], v[64:67]
	s_setprio 0
	s_barrier
	s_mov_b32 m0, s64
	s_add_u32 s12, s12, 0x40080
	ds_read_b128 v[212:215], v145 offset:49152
	ds_read_b128 v[216:219], v145 offset:50176
	ds_read_b128 v[220:223], v145 offset:51200
	ds_read_b128 v[224:227], v145 offset:52224
	ds_read_b128 v[228:231], v145 offset:53248
	ds_read_b128 v[232:235], v145 offset:54272
	ds_read_b128 v[236:239], v145 offset:55296
	ds_read_b128 v[240:243], v145 offset:56320
	global_load_lds_dwordx4 v132, s[98:99]
	s_mov_b32 m0, s65
	s_addc_u32 s13, s13, 0
	global_load_lds_dwordx4 v134, s[98:99]
	s_mov_b32 m0, s72
	s_nop 0
	global_load_lds_dwordx4 v132, s[12:13]
	s_mov_b32 m0, s73
	s_nop 0
	global_load_lds_dwordx4 v134, s[12:13]
	s_mov_b32 m0, s66
	s_nop 0
	global_load_lds_dwordx4 v132, s[100:101]
	s_mov_b32 m0, s67
	s_nop 0
	global_load_lds_dwordx4 v134, s[100:101]
	s_waitcnt vmcnt(8)
	s_waitcnt lgkmcnt(0)
	s_barrier
	s_setprio 1
	s_waitcnt lgkmcnt(0)
	v_mfma_f32_16x16x32_bf16 v[60:63], v[160:163], v[212:215], v[60:63]
	v_mfma_f32_16x16x32_bf16 v[56:59], v[186:189], v[212:215], v[56:59]
	v_mfma_f32_16x16x32_bf16 v[44:47], v[160:163], v[220:223], v[44:47]
	v_mfma_f32_16x16x32_bf16 v[40:43], v[186:189], v[220:223], v[40:43]
	v_mfma_f32_16x16x32_bf16 v[28:31], v[160:163], v[228:231], v[28:31]
	v_mfma_f32_16x16x32_bf16 v[24:27], v[186:189], v[228:231], v[24:27]
	v_mfma_f32_16x16x32_bf16 v[12:15], v[160:163], v[236:239], v[12:15]
	v_mfma_f32_16x16x32_bf16 v[8:11], v[186:189], v[236:239], v[8:11]
	v_mfma_f32_16x16x32_bf16 v[60:63], v[182:185], v[216:219], v[60:63]
	v_mfma_f32_16x16x32_bf16 v[56:59], v[190:193], v[216:219], v[56:59]
	v_mfma_f32_16x16x32_bf16 v[44:47], v[182:185], v[224:227], v[44:47]
	v_mfma_f32_16x16x32_bf16 v[40:43], v[190:193], v[224:227], v[40:43]
	v_mfma_f32_16x16x32_bf16 v[28:31], v[182:185], v[232:235], v[28:31]
	v_mfma_f32_16x16x32_bf16 v[24:27], v[190:193], v[232:235], v[24:27]
	v_mfma_f32_16x16x32_bf16 v[12:15], v[182:185], v[240:243], v[12:15]
	v_mfma_f32_16x16x32_bf16 v[8:11], v[190:193], v[240:243], v[8:11]
	s_setprio 0
	s_setprio 1
	v_mfma_f32_16x16x32_bf16 v[52:55], v[196:199], v[212:215], v[52:55]
	v_mfma_f32_16x16x32_bf16 v[48:51], v[204:207], v[212:215], v[48:51]
	v_mfma_f32_16x16x32_bf16 v[36:39], v[196:199], v[220:223], v[36:39]
	v_mfma_f32_16x16x32_bf16 v[32:35], v[204:207], v[220:223], v[32:35]
	v_mfma_f32_16x16x32_bf16 v[20:23], v[196:199], v[228:231], v[20:23]
	v_mfma_f32_16x16x32_bf16 v[16:19], v[204:207], v[228:231], v[16:19]
	v_mfma_f32_16x16x32_bf16 v[4:7], v[196:199], v[236:239], v[4:7]
	v_mfma_f32_16x16x32_bf16 v[0:3], v[204:207], v[236:239], v[0:3]
	v_mfma_f32_16x16x32_bf16 v[52:55], v[200:203], v[216:219], v[52:55]
	v_mfma_f32_16x16x32_bf16 v[48:51], v[208:211], v[216:219], v[48:51]
	v_mfma_f32_16x16x32_bf16 v[36:39], v[200:203], v[224:227], v[36:39]
	v_mfma_f32_16x16x32_bf16 v[32:35], v[208:211], v[224:227], v[32:35]
	v_mfma_f32_16x16x32_bf16 v[20:23], v[200:203], v[232:235], v[20:23]
	v_mfma_f32_16x16x32_bf16 v[16:19], v[208:211], v[232:235], v[16:19]
	v_mfma_f32_16x16x32_bf16 v[4:7], v[200:203], v[240:243], v[4:7]
	v_mfma_f32_16x16x32_bf16 v[0:3], v[208:211], v[240:243], v[0:3]
	s_setprio 0
	s_barrier
	s_add_i32 s54, s54, 2
	s_add_u32 s10, s10, 0x100
	s_addc_u32 s11, s11, 0
	s_add_u32 s38, s38, 0x100
	s_addc_u32 s39, s39, 0
	s_cmp_gt_u32 s54, 13
	s_cbranch_scc0 .LBB0_586
	s_and_b64 vcc, exec, s[18:19]
	s_cbranch_vccz .LBB0_589
	s_barrier

.LBB0_846:
	s_lshl_b32 s1, s7, 5
	s_add_i32 s75, s40, 0x18000
	s_mov_b64 s[14:15], 0x80
	s_and_b32 s20, s1, 0x60
	v_lshl_add_u64 v[6:7], v[6:7], 0, s[14:15]
	s_mov_b32 m0, s75
	s_add_i32 s78, s40, 0x1a000
	s_lshl_b32 s18, s5, 13
	s_lshl_b32 s7, s20, 7
	s_waitcnt vmcnt(2)
	s_barrier
	global_load_lds_dwordx4 v[6:7], off
	v_lshl_add_u64 v[4:5], v[4:5], 0, s[14:15]
	s_mov_b32 m0, s78
	s_add_i32 s79, s40, 0x8000
	s_add_i32 s82, s40, 0xa000
	global_load_lds_dwordx4 v[4:5], off
	v_lshl_add_u64 v[0:1], v[0:1], 0, s[14:15]
	s_mov_b32 m0, s79
	s_add_u32 s16, s28, 0x80080
	global_load_lds_dwordx4 v[0:1], off
	v_lshl_add_u64 v[0:1], v[2:3], 0, s[14:15]
	s_mov_b32 m0, s82
	s_addc_u32 s17, s29, 0
	s_add_i32 s83, s40, 0x1c000
	global_load_lds_dwordx4 v[0:1], off
	s_mov_b32 m0, s83
	s_add_i32 s84, s40, 0x1e000
	global_load_lds_dwordx4 v132, s[16:17]
	s_mov_b32 m0, s84
	s_sext_i32_i8 s1, s6
	global_load_lds_dwordx4 v134, s[16:17]
	v_bfe_u32 v0, v8, 4, 2
	v_lshlrev_b32_e32 v2, 4, v0
	v_lshl_or_b32 v153, v0, 2, s20
	v_lshlrev_b32_e32 v0, 14, v9
	v_and_b32_e32 v1, 15, v8
	v_and_b32_e32 v0, 0x7fff8000, v0
	v_lshl_or_b32 v129, s5, 6, v1
	v_lshl_or_b32 v1, v1, 6, v2
	v_lshlrev_b32_e32 v2, 2, v8
	v_lshl_add_u32 v0, v10, 11, v0
	v_and_b32_e32 v2, 32, v2
	v_or_b32_e32 v0, v0, v11
	v_bitop3_b32 v152, v1, s18, v2 bitop3:0xde
	v_bitop3_b32 v2, v1, s7, v2 bitop3:0xde
	s_mov_b64 s[6:7], 0x80080
	v_add_lshl_u32 v0, v0, v12, 1
	v_mov_b32_e32 v1, v133
	v_lshl_add_u64 v[136:137], v[0:1], 0, s[6:7]
	v_lshlrev_b32_e32 v0, 14, v13
	v_and_b32_e32 v0, 0x7fff8000, v0
	v_lshl_add_u32 v0, v14, 11, v0
	s_waitcnt vmcnt(6)
	v_or_b32_e32 v0, v0, v15
	s_cmpk_lt_u32 s4, 0x100
	v_readlane_b32 s4, v255, 11
	v_add_lshl_u32 v0, v0, v16, 1
	s_movk_i32 s85, 0x100
	s_cselect_b64 s[16:17], -1, 0
	s_ashr_i32 s86, s4, 31
	s_mov_b32 s87, s4
	v_lshl_add_u64 v[138:139], v[0:1], 0, s[6:7]
	s_mov_b32 s54, 0
	v_mov_b64_e32 v[140:141], 0x1ff
	v_or_b32_e32 v160, 0x10000, v2
	v_add_u32_e32 v161, 0x10400, v2
	v_add_u32_e32 v162, 0x10800, v2
	v_add_u32_e32 v163, 0x10c00, v2
	v_or_b32_e32 v164, 0x14000, v2
	v_add_u32_e32 v165, 0x14400, v2
	v_add_u32_e32 v167, 0x14800, v2
	v_add_u32_e32 v168, 0x14c00, v2
	s_add_i32 s55, s40, 0xc000
	s_add_i32 s36, s40, 0xe000
	v_or_b32_e32 v169, 0x18000, v2
	v_add_u32_e32 v170, 0x18400, v2
	v_add_u32_e32 v171, 0x18800, v2
	v_add_u32_e32 v172, 0x18c00, v2
	v_or_b32_e32 v173, 0x1c000, v2
	v_add_u32_e32 v174, 0x1c400, v2
	v_add_u32_e32 v175, 0x1c800, v2
	v_add_u32_e32 v176, 0x1cc00, v2
	s_mov_b32 s38, 0x3e0f83e1
	s_movk_i32 s39, 0xdf00
	s_mov_b32 s18, 0x3fd744fd
	v_mov_b32_e32 v177, 0xffffff00
	s_barrier
	v_readlane_b32 s5, v255, 12
	s_branch .LBB0_849

.LBB0_856:
	ds_read_b128 v[178:181], v160
	ds_read_b128 v[182:185], v161
	ds_read_b128 v[186:189], v162
	ds_read_b128 v[190:193], v163
	ds_read_b128 v[198:201], v164
	ds_read_b128 v[202:205], v165
	ds_read_b128 v[206:209], v167
	ds_read_b128 v[210:213], v168
	s_add_u32 s28, s10, 0x100
	s_addc_u32 s29, s11, 0
	s_cmp_eq_u32 s56, 28
	s_cselect_b32 s35, s4, s29
	s_cselect_b32 s34, s5, s28
	s_cselect_b32 s31, s21, vcc_hi
	s_cselect_b32 s30, s23, vcc_lo
	s_mov_b32 m0, s55
	ds_read_b128 v[214:217], v152
	ds_read_b128 v[218:221], v152 offset:1024
	ds_read_b128 v[222:225], v152 offset:2048
	ds_read_b128 v[226:229], v152 offset:3072
	ds_read_b128 v[230:233], v152 offset:4096
	ds_read_b128 v[234:237], v152 offset:5120
	ds_read_b128 v[238:241], v152 offset:6144
	ds_read_b128 v[242:245], v152 offset:7168
	global_load_lds_dwordx4 v136, s[10:11]
	s_mov_b32 m0, s36
	s_nop 0
	global_load_lds_dwordx4 v138, s[10:11]
	s_waitcnt vmcnt(8)
	s_waitcnt lgkmcnt(0)
	s_barrier
	s_setprio 1
	s_waitcnt lgkmcnt(0)
	v_mfma_f32_16x16x32_bf16 v[124:127], v[178:181], v[214:217], v[124:127]
	v_mfma_f32_16x16x32_bf16 v[120:123], v[186:189], v[214:217], v[120:123]
	v_mfma_f32_16x16x32_bf16 v[108:111], v[178:181], v[222:225], v[108:111]
	v_mfma_f32_16x16x32_bf16 v[104:107], v[186:189], v[222:225], v[104:107]
	v_mfma_f32_16x16x32_bf16 v[92:95], v[178:181], v[230:233], v[92:95]
	v_mfma_f32_16x16x32_bf16 v[88:91], v[186:189], v[230:233], v[88:91]
	v_mfma_f32_16x16x32_bf16 v[76:79], v[178:181], v[238:241], v[76:79]
	v_mfma_f32_16x16x32_bf16 v[72:75], v[186:189], v[238:241], v[72:75]
	v_mfma_f32_16x16x32_bf16 v[124:127], v[182:185], v[218:221], v[124:127]
	v_mfma_f32_16x16x32_bf16 v[120:123], v[190:193], v[218:221], v[120:123]
	v_mfma_f32_16x16x32_bf16 v[108:111], v[182:185], v[226:229], v[108:111]
	v_mfma_f32_16x16x32_bf16 v[104:107], v[190:193], v[226:229], v[104:107]
	v_mfma_f32_16x16x32_bf16 v[92:95], v[182:185], v[234:237], v[92:95]
	v_mfma_f32_16x16x32_bf16 v[88:91], v[190:193], v[234:237], v[88:91]
	v_mfma_f32_16x16x32_bf16 v[76:79], v[182:185], v[242:245], v[76:79]
	v_mfma_f32_16x16x32_bf16 v[72:75], v[190:193], v[242:245], v[72:75]
	s_setprio 0
	s_setprio 1
	v_mfma_f32_16x16x32_bf16 v[116:119], v[198:201], v[214:217], v[116:119]
	v_mfma_f32_16x16x32_bf16 v[112:115], v[206:209], v[214:217], v[112:115]
	v_mfma_f32_16x16x32_bf16 v[100:103], v[198:201], v[222:225], v[100:103]
	v_mfma_f32_16x16x32_bf16 v[96:99], v[206:209], v[222:225], v[96:99]
	v_mfma_f32_16x16x32_bf16 v[84:87], v[198:201], v[230:233], v[84:87]
	v_mfma_f32_16x16x32_bf16 v[80:83], v[206:209], v[230:233], v[80:83]
	v_mfma_f32_16x16x32_bf16 v[68:71], v[198:201], v[238:241], v[68:71]
	v_mfma_f32_16x16x32_bf16 v[64:67], v[206:209], v[238:241], v[64:67]
	v_mfma_f32_16x16x32_bf16 v[116:119], v[202:205], v[218:221], v[116:119]
	v_mfma_f32_16x16x32_bf16 v[112:115], v[210:213], v[218:221], v[112:115]
	v_mfma_f32_16x16x32_bf16 v[100:103], v[202:205], v[226:229], v[100:103]
	v_mfma_f32_16x16x32_bf16 v[96:99], v[210:213], v[226:229], v[96:99]
	v_mfma_f32_16x16x32_bf16 v[84:87], v[202:205], v[234:237], v[84:87]
	v_mfma_f32_16x16x32_bf16 v[80:83], v[210:213], v[234:237], v[80:83]
	v_mfma_f32_16x16x32_bf16 v[68:71], v[202:205], v[242:245], v[68:71]
	v_mfma_f32_16x16x32_bf16 v[64:67], v[210:213], v[242:245], v[64:67]
	s_setprio 0
	s_barrier
	s_add_u32 s98, s30, s14
	s_addc_u32 s99, s31, s15
	s_add_u32 s100, s34, s14
	s_addc_u32 s101, s35, s15
	s_mov_b32 m0, s37
	s_add_u32 s10, s30, 0x80000
	ds_read_b128 v[214:217], v152 offset:16384
	ds_read_b128 v[218:221], v152 offset:17408
	ds_read_b128 v[222:225], v152 offset:18432
	ds_read_b128 v[226:229], v152 offset:19456
	ds_read_b128 v[230:233], v152 offset:20480
	ds_read_b128 v[234:237], v152 offset:21504
	ds_read_b128 v[238:241], v152 offset:22528
	ds_read_b128 v[242:245], v152 offset:23552
	global_load_lds_dwordx4 v132, s[30:31]
	s_mov_b32 m0, s41
	s_addc_u32 s11, s31, 0
	global_load_lds_dwordx4 v134, s[30:31]
	s_mov_b32 m0, s42
	s_nop 0
	global_load_lds_dwordx4 v132, s[10:11]
	s_mov_b32 m0, s43
	s_nop 0
	global_load_lds_dwordx4 v134, s[10:11]
	s_mov_b32 m0, s40
	s_nop 0
	global_load_lds_dwordx4 v132, s[34:35]
	s_mov_b32 m0, s72
	s_nop 0
	global_load_lds_dwordx4 v134, s[34:35]
	s_waitcnt vmcnt(8)
	s_waitcnt lgkmcnt(0)
	s_barrier
	s_setprio 1
	s_waitcnt lgkmcnt(0)
	v_mfma_f32_16x16x32_bf16 v[60:63], v[178:181], v[214:217], v[60:63]
	v_mfma_f32_16x16x32_bf16 v[56:59], v[186:189], v[214:217], v[56:59]
	v_mfma_f32_16x16x32_bf16 v[44:47], v[178:181], v[222:225], v[44:47]
	v_mfma_f32_16x16x32_bf16 v[40:43], v[186:189], v[222:225], v[40:43]
	v_mfma_f32_16x16x32_bf16 v[28:31], v[178:181], v[230:233], v[28:31]
	v_mfma_f32_16x16x32_bf16 v[24:27], v[186:189], v[230:233], v[24:27]
	v_mfma_f32_16x16x32_bf16 v[16:19], v[178:181], v[238:241], v[16:19]
	v_mfma_f32_16x16x32_bf16 v[8:11], v[186:189], v[238:241], v[8:11]
	v_mfma_f32_16x16x32_bf16 v[60:63], v[182:185], v[218:221], v[60:63]
	v_mfma_f32_16x16x32_bf16 v[56:59], v[190:193], v[218:221], v[56:59]
	v_mfma_f32_16x16x32_bf16 v[44:47], v[182:185], v[226:229], v[44:47]
	v_mfma_f32_16x16x32_bf16 v[40:43], v[190:193], v[226:229], v[40:43]
	v_mfma_f32_16x16x32_bf16 v[28:31], v[182:185], v[234:237], v[28:31]
	v_mfma_f32_16x16x32_bf16 v[24:27], v[190:193], v[234:237], v[24:27]
	v_mfma_f32_16x16x32_bf16 v[16:19], v[182:185], v[242:245], v[16:19]
	v_mfma_f32_16x16x32_bf16 v[8:11], v[190:193], v[242:245], v[8:11]
	s_setprio 0
	s_setprio 1
	v_mfma_f32_16x16x32_bf16 v[52:55], v[198:201], v[214:217], v[52:55]
	v_mfma_f32_16x16x32_bf16 v[48:51], v[206:209], v[214:217], v[48:51]
	v_mfma_f32_16x16x32_bf16 v[36:39], v[198:201], v[222:225], v[36:39]
	v_mfma_f32_16x16x32_bf16 v[32:35], v[206:209], v[222:225], v[32:35]
	v_mfma_f32_16x16x32_bf16 v[20:23], v[198:201], v[230:233], v[20:23]
	v_mfma_f32_16x16x32_bf16 v[12:15], v[206:209], v[230:233], v[12:15]
	v_mfma_f32_16x16x32_bf16 v[4:7], v[198:201], v[238:241], v[4:7]
	v_mfma_f32_16x16x32_bf16 v[0:3], v[206:209], v[238:241], v[0:3]
	v_mfma_f32_16x16x32_bf16 v[52:55], v[202:205], v[218:221], v[52:55]
	v_mfma_f32_16x16x32_bf16 v[48:51], v[210:213], v[218:221], v[48:51]
	v_mfma_f32_16x16x32_bf16 v[36:39], v[202:205], v[226:229], v[36:39]
	v_mfma_f32_16x16x32_bf16 v[32:35], v[210:213], v[226:229], v[32:35]
	v_mfma_f32_16x16x32_bf16 v[20:23], v[202:205], v[234:237], v[20:23]
	v_mfma_f32_16x16x32_bf16 v[12:15], v[210:213], v[234:237], v[12:15]
	v_mfma_f32_16x16x32_bf16 v[4:7], v[202:205], v[242:245], v[4:7]
	v_mfma_f32_16x16x32_bf16 v[0:3], v[210:213], v[242:245], v[0:3]
	s_setprio 0
	s_barrier
	ds_read_b128 v[178:181], v169
	ds_read_b128 v[182:185], v170
	ds_read_b128 v[186:189], v171
	ds_read_b128 v[190:193], v172
	ds_read_b128 v[198:201], v173
	ds_read_b128 v[202:205], v174
	ds_read_b128 v[206:209], v175
	ds_read_b128 v[210:213], v176
	s_add_u32 s10, s34, 0x80000
	s_addc_u32 s11, s35, 0
	s_mov_b32 m0, s73
	ds_read_b128 v[214:217], v152 offset:32768
	ds_read_b128 v[218:221], v152 offset:33792
	ds_read_b128 v[222:225], v152 offset:34816
	ds_read_b128 v[226:229], v152 offset:35840
	ds_read_b128 v[230:233], v152 offset:36864
	ds_read_b128 v[234:237], v152 offset:37888
	ds_read_b128 v[238:241], v152 offset:38912
	ds_read_b128 v[242:245], v152 offset:39936
	global_load_lds_dwordx4 v132, s[10:11]
	s_mov_b32 m0, s74
	s_nop 0
	global_load_lds_dwordx4 v134, s[10:11]
	s_waitcnt vmcnt(8)
	s_waitcnt lgkmcnt(0)
	s_barrier
	s_setprio 1
	s_waitcnt lgkmcnt(0)
	v_mfma_f32_16x16x32_bf16 v[124:127], v[178:181], v[214:217], v[124:127]
	v_mfma_f32_16x16x32_bf16 v[120:123], v[186:189], v[214:217], v[120:123]
	v_mfma_f32_16x16x32_bf16 v[108:111], v[178:181], v[222:225], v[108:111]
	v_mfma_f32_16x16x32_bf16 v[104:107], v[186:189], v[222:225], v[104:107]
	v_mfma_f32_16x16x32_bf16 v[92:95], v[178:181], v[230:233], v[92:95]
	v_mfma_f32_16x16x32_bf16 v[88:91], v[186:189], v[230:233], v[88:91]
	v_mfma_f32_16x16x32_bf16 v[76:79], v[178:181], v[238:241], v[76:79]
	v_mfma_f32_16x16x32_bf16 v[72:75], v[186:189], v[238:241], v[72:75]
	v_mfma_f32_16x16x32_bf16 v[124:127], v[182:185], v[218:221], v[124:127]
	v_mfma_f32_16x16x32_bf16 v[120:123], v[190:193], v[218:221], v[120:123]
	v_mfma_f32_16x16x32_bf16 v[108:111], v[182:185], v[226:229], v[108:111]
	v_mfma_f32_16x16x32_bf16 v[104:107], v[190:193], v[226:229], v[104:107]
	v_mfma_f32_16x16x32_bf16 v[92:95], v[182:185], v[234:237], v[92:95]
	v_mfma_f32_16x16x32_bf16 v[88:91], v[190:193], v[234:237], v[88:91]
	v_mfma_f32_16x16x32_bf16 v[76:79], v[182:185], v[242:245], v[76:79]
	v_mfma_f32_16x16x32_bf16 v[72:75], v[190:193], v[242:245], v[72:75]
	s_setprio 0
	s_setprio 1
	v_mfma_f32_16x16x32_bf16 v[116:119], v[198:201], v[214:217], v[116:119]
	v_mfma_f32_16x16x32_bf16 v[112:115], v[206:209], v[214:217], v[112:115]
	v_mfma_f32_16x16x32_bf16 v[100:103], v[198:201], v[222:225], v[100:103]
	v_mfma_f32_16x16x32_bf16 v[96:99], v[206:209], v[222:225], v[96:99]
	v_mfma_f32_16x16x32_bf16 v[84:87], v[198:201], v[230:233], v[84:87]
	v_mfma_f32_16x16x32_bf16 v[80:83], v[206:209], v[230:233], v[80:83]
	v_mfma_f32_16x16x32_bf16 v[68:71], v[198:201], v[238:241], v[68:71]
	v_mfma_f32_16x16x32_bf16 v[64:67], v[206:209], v[238:241], v[64:67]
	v_mfma_f32_16x16x32_bf16 v[116:119], v[202:205], v[218:221], v[116:119]
	v_mfma_f32_16x16x32_bf16 v[112:115], v[210:213], v[218:221], v[112:115]
	v_mfma_f32_16x16x32_bf16 v[100:103], v[202:205], v[226:229], v[100:103]
	v_mfma_f32_16x16x32_bf16 v[96:99], v[210:213], v[226:229], v[96:99]
	v_mfma_f32_16x16x32_bf16 v[84:87], v[202:205], v[234:237], v[84:87]
	v_mfma_f32_16x16x32_bf16 v[80:83], v[210:213], v[234:237], v[80:83]
	v_mfma_f32_16x16x32_bf16 v[68:71], v[202:205], v[242:245], v[68:71]
	v_mfma_f32_16x16x32_bf16 v[64:67], v[210:213], v[242:245], v[64:67]
	s_setprio 0
	s_barrier
	s_mov_b32 m0, s75
	s_add_u32 s10, s30, 0x80080
	ds_read_b128 v[214:217], v152 offset:49152
	ds_read_b128 v[218:221], v152 offset:50176
	ds_read_b128 v[222:225], v152 offset:51200
	ds_read_b128 v[226:229], v152 offset:52224
	ds_read_b128 v[230:233], v152 offset:53248
	ds_read_b128 v[234:237], v152 offset:54272
	ds_read_b128 v[238:241], v152 offset:55296
	ds_read_b128 v[242:245], v152 offset:56320
	global_load_lds_dwordx4 v132, s[98:99]
	s_mov_b32 m0, s78
	s_addc_u32 s11, s31, 0
	global_load_lds_dwordx4 v134, s[98:99]
	s_mov_b32 m0, s83
	s_nop 0
	global_load_lds_dwordx4 v132, s[10:11]
	s_mov_b32 m0, s84
	s_nop 0
	global_load_lds_dwordx4 v134, s[10:11]
	s_mov_b32 m0, s79
	s_nop 0
	global_load_lds_dwordx4 v132, s[100:101]
	s_mov_b32 m0, s82
	s_nop 0
	global_load_lds_dwordx4 v134, s[100:101]
	s_waitcnt vmcnt(8)
	s_waitcnt lgkmcnt(0)
	s_barrier
	s_setprio 1
	s_waitcnt lgkmcnt(0)
	v_mfma_f32_16x16x32_bf16 v[60:63], v[178:181], v[214:217], v[60:63]
	v_mfma_f32_16x16x32_bf16 v[56:59], v[186:189], v[214:217], v[56:59]
	v_mfma_f32_16x16x32_bf16 v[44:47], v[178:181], v[222:225], v[44:47]
	v_mfma_f32_16x16x32_bf16 v[40:43], v[186:189], v[222:225], v[40:43]
	v_mfma_f32_16x16x32_bf16 v[28:31], v[178:181], v[230:233], v[28:31]
	v_mfma_f32_16x16x32_bf16 v[24:27], v[186:189], v[230:233], v[24:27]
	v_mfma_f32_16x16x32_bf16 v[16:19], v[178:181], v[238:241], v[16:19]
	v_mfma_f32_16x16x32_bf16 v[8:11], v[186:189], v[238:241], v[8:11]
	v_mfma_f32_16x16x32_bf16 v[60:63], v[182:185], v[218:221], v[60:63]
	v_mfma_f32_16x16x32_bf16 v[56:59], v[190:193], v[218:221], v[56:59]
	v_mfma_f32_16x16x32_bf16 v[44:47], v[182:185], v[226:229], v[44:47]
	v_mfma_f32_16x16x32_bf16 v[40:43], v[190:193], v[226:229], v[40:43]
	v_mfma_f32_16x16x32_bf16 v[28:31], v[182:185], v[234:237], v[28:31]
	v_mfma_f32_16x16x32_bf16 v[24:27], v[190:193], v[234:237], v[24:27]
	v_mfma_f32_16x16x32_bf16 v[16:19], v[182:185], v[242:245], v[16:19]
	v_mfma_f32_16x16x32_bf16 v[8:11], v[190:193], v[242:245], v[8:11]
	s_setprio 0
	s_setprio 1
	v_mfma_f32_16x16x32_bf16 v[52:55], v[198:201], v[214:217], v[52:55]
	v_mfma_f32_16x16x32_bf16 v[48:51], v[206:209], v[214:217], v[48:51]
	v_mfma_f32_16x16x32_bf16 v[36:39], v[198:201], v[222:225], v[36:39]
	v_mfma_f32_16x16x32_bf16 v[32:35], v[206:209], v[222:225], v[32:35]
	v_mfma_f32_16x16x32_bf16 v[20:23], v[198:201], v[230:233], v[20:23]
	v_mfma_f32_16x16x32_bf16 v[12:15], v[206:209], v[230:233], v[12:15]
	v_mfma_f32_16x16x32_bf16 v[4:7], v[198:201], v[238:241], v[4:7]
	v_mfma_f32_16x16x32_bf16 v[0:3], v[206:209], v[238:241], v[0:3]
	v_mfma_f32_16x16x32_bf16 v[52:55], v[202:205], v[218:221], v[52:55]
	v_mfma_f32_16x16x32_bf16 v[48:51], v[210:213], v[218:221], v[48:51]
	v_mfma_f32_16x16x32_bf16 v[36:39], v[202:205], v[226:229], v[36:39]
	v_mfma_f32_16x16x32_bf16 v[32:35], v[210:213], v[226:229], v[32:35]
	v_mfma_f32_16x16x32_bf16 v[20:23], v[202:205], v[234:237], v[20:23]
	v_mfma_f32_16x16x32_bf16 v[12:15], v[210:213], v[234:237], v[12:15]
	v_mfma_f32_16x16x32_bf16 v[4:7], v[202:205], v[242:245], v[4:7]
	v_mfma_f32_16x16x32_bf16 v[0:3], v[210:213], v[242:245], v[0:3]
	s_setprio 0
	s_barrier
	s_add_i32 s56, s56, 2
	s_add_u32 vcc_lo, vcc_lo, 0x100
	s_addc_u32 vcc_hi, vcc_hi, 0
	s_cmp_gt_u32 s56, 29
	s_mov_b64 s[10:11], s[28:29]
	s_cbranch_scc0 .LBB0_856
	s_and_b64 vcc, exec, s[16:17]
	s_cbranch_vccz .LBB0_859
	s_barrier

.LBB0_1090:
	s_lshl_b32 s8, s8, 5
	s_and_b32 s37, s8, 0x60
	s_add_i32 s40, s2, 0x18000
	s_mov_b64 s[8:9], 0x80
	v_lshl_add_u64 v[6:7], v[6:7], 0, s[8:9]
	s_mov_b32 m0, s40
	s_add_i32 s41, s2, 0x1a000
	s_lshl_b32 s11, s5, 13
	s_lshl_b32 s14, s37, 7
	s_waitcnt vmcnt(2)
	s_barrier
	global_load_lds_dwordx4 v[6:7], off
	v_lshl_add_u64 v[4:5], v[4:5], 0, s[8:9]
	s_mov_b32 m0, s41
	s_add_i32 s47, s2, 0x8000
	s_add_i32 s52, s2, 0xa000
	global_load_lds_dwordx4 v[4:5], off
	v_lshl_add_u64 v[0:1], v[0:1], 0, s[8:9]
	s_mov_b32 m0, s47
	s_add_u32 s12, s48, 0x40080
	global_load_lds_dwordx4 v[0:1], off
	v_lshl_add_u64 v[0:1], v[2:3], 0, s[8:9]
	s_mov_b32 m0, s52
	s_addc_u32 s13, s49, 0
	s_add_i32 s53, s2, 0x1c000
	global_load_lds_dwordx4 v[0:1], off
	s_mov_b32 m0, s53
	s_add_i32 s60, s2, 0x1e000
	global_load_lds_dwordx4 v130, s[12:13]
	s_mov_b32 m0, s60
	s_cmpk_lt_u32 s4, 0x100
	global_load_lds_dwordx4 v128, s[12:13]
	v_bfe_u32 v1, v8, 4, 2
	v_and_b32_e32 v0, 15, v8
	v_lshlrev_b32_e32 v2, 4, v1
	v_lshl_or_b32 v140, s5, 6, v0
	v_lshl_or_b32 v0, v0, 6, v2
	v_lshlrev_b32_e32 v2, 2, v8
	v_lshlrev_b32_e32 v142, 2, v1
	v_lshlrev_b32_e32 v1, 14, v12
	v_and_b32_e32 v2, 32, v2
	v_and_b32_e32 v1, 0xffff8000, v1
	v_bitop3_b32 v141, v0, s11, v2 bitop3:0xde
	v_bitop3_b32 v0, v0, s14, v2 bitop3:0xde
	v_lshl_add_u32 v1, v13, 11, v1
	v_and_b32_e32 v2, 1, v12
	v_lshl_or_b32 v1, v2, 6, v1
	v_lshl_add_u32 v132, v14, 1, v1
	v_lshlrev_b32_e32 v1, 14, v9
	v_and_b32_e32 v1, 0xffff8000, v1
	s_waitcnt vmcnt(6)
	v_lshl_add_u32 v1, v10, 11, v1
	v_and_b32_e32 v2, 1, v9
	v_lshl_or_b32 v1, v2, 6, v1
	s_sext_i32_i16 s38, s10
	s_cselect_b64 s[12:13], -1, 0
	s_ashr_i32 s61, s82, 31
	s_mov_b32 s64, s82
	v_mov_b32_e32 v133, v131
	v_lshl_add_u32 v134, v11, 1, v1
	v_mov_b32_e32 v135, v131
	v_mov_b64_e32 v[136:137], 0xb58
	v_mov_b64_e32 v[138:139], 0xb57
	v_or_b32_e32 v143, 0x10000, v0
	v_add_u32_e32 v153, 0x10400, v0
	v_add_u32_e32 v159, 0x10800, v0
	v_add_u32_e32 v160, 0x10c00, v0
	v_or_b32_e32 v161, 0x14000, v0
	v_add_u32_e32 v162, 0x14400, v0
	v_add_u32_e32 v163, 0x14800, v0
	v_add_u32_e32 v164, 0x14c00, v0
	s_add_i32 s65, s2, 0xc000
	s_add_i32 s67, s2, 0xe000
	v_or_b32_e32 v165, 0x18000, v0
	v_add_u32_e32 v166, 0x18400, v0
	v_add_u32_e32 v167, 0x18800, v0
	v_add_u32_e32 v168, 0x18c00, v0
	v_or_b32_e32 v169, 0x1c000, v0
	v_add_u32_e32 v170, 0x1c400, v0
	v_add_u32_e32 v171, 0x1c800, v0
	v_add_u32_e32 v172, 0x1cc00, v0
	s_movk_i32 s72, 0x1600
	s_barrier
	s_branch .LBB0_1093

.LBB0_1096:
	ds_read_b128 v[174:177], v143
	ds_read_b128 v[178:181], v153
	ds_read_b128 v[182:185], v159
	ds_read_b128 v[186:189], v160
	ds_read_b128 v[190:193], v161
	ds_read_b128 v[198:201], v162
	ds_read_b128 v[202:205], v163
	ds_read_b128 v[206:209], v164
	s_add_u32 s48, s24, 0xfffc0080
	s_addc_u32 s49, s25, -1
	s_cmp_eq_u32 s55, 12
	s_cselect_b32 s51, s4, s49
	s_cselect_b32 s50, s5, s48
	s_cselect_b32 s49, s15, s54
	s_cselect_b32 s48, s27, s39
	s_mov_b32 m0, s65
	ds_read_b128 v[210:213], v141
	ds_read_b128 v[214:217], v141 offset:1024
	ds_read_b128 v[218:221], v141 offset:2048
	ds_read_b128 v[222:225], v141 offset:3072
	ds_read_b128 v[226:229], v141 offset:4096
	ds_read_b128 v[230:233], v141 offset:5120
	ds_read_b128 v[234:237], v141 offset:6144
	ds_read_b128 v[238:241], v141 offset:7168
	global_load_lds_dwordx4 v132, s[24:25]
	s_mov_b32 m0, s67
	s_nop 0
	global_load_lds_dwordx4 v134, s[24:25]
	s_waitcnt vmcnt(8)
	s_waitcnt lgkmcnt(0)
	s_barrier
	s_setprio 1
	s_waitcnt lgkmcnt(0)
	v_mfma_f32_16x16x32_bf16 v[124:127], v[174:177], v[210:213], v[124:127]
	v_mfma_f32_16x16x32_bf16 v[120:123], v[182:185], v[210:213], v[120:123]
	v_mfma_f32_16x16x32_bf16 v[108:111], v[174:177], v[218:221], v[108:111]
	v_mfma_f32_16x16x32_bf16 v[104:107], v[182:185], v[218:221], v[104:107]
	v_mfma_f32_16x16x32_bf16 v[92:95], v[174:177], v[226:229], v[92:95]
	v_mfma_f32_16x16x32_bf16 v[88:91], v[182:185], v[226:229], v[88:91]
	v_mfma_f32_16x16x32_bf16 v[76:79], v[174:177], v[234:237], v[76:79]
	v_mfma_f32_16x16x32_bf16 v[72:75], v[182:185], v[234:237], v[72:75]
	v_mfma_f32_16x16x32_bf16 v[124:127], v[178:181], v[214:217], v[124:127]
	v_mfma_f32_16x16x32_bf16 v[120:123], v[186:189], v[214:217], v[120:123]
	v_mfma_f32_16x16x32_bf16 v[108:111], v[178:181], v[222:225], v[108:111]
	v_mfma_f32_16x16x32_bf16 v[104:107], v[186:189], v[222:225], v[104:107]
	v_mfma_f32_16x16x32_bf16 v[92:95], v[178:181], v[230:233], v[92:95]
	v_mfma_f32_16x16x32_bf16 v[88:91], v[186:189], v[230:233], v[88:91]
	v_mfma_f32_16x16x32_bf16 v[76:79], v[178:181], v[238:241], v[76:79]
	v_mfma_f32_16x16x32_bf16 v[72:75], v[186:189], v[238:241], v[72:75]
	s_setprio 0
	s_setprio 1
	v_mfma_f32_16x16x32_bf16 v[116:119], v[190:193], v[210:213], v[116:119]
	v_mfma_f32_16x16x32_bf16 v[112:115], v[202:205], v[210:213], v[112:115]
	v_mfma_f32_16x16x32_bf16 v[100:103], v[190:193], v[218:221], v[100:103]
	v_mfma_f32_16x16x32_bf16 v[96:99], v[202:205], v[218:221], v[96:99]
	v_mfma_f32_16x16x32_bf16 v[84:87], v[190:193], v[226:229], v[84:87]
	v_mfma_f32_16x16x32_bf16 v[80:83], v[202:205], v[226:229], v[80:83]
	v_mfma_f32_16x16x32_bf16 v[68:71], v[190:193], v[234:237], v[68:71]
	v_mfma_f32_16x16x32_bf16 v[64:67], v[202:205], v[234:237], v[64:67]
	v_mfma_f32_16x16x32_bf16 v[116:119], v[198:201], v[214:217], v[116:119]
	v_mfma_f32_16x16x32_bf16 v[112:115], v[206:209], v[214:217], v[112:115]
	v_mfma_f32_16x16x32_bf16 v[100:103], v[198:201], v[222:225], v[100:103]
	v_mfma_f32_16x16x32_bf16 v[96:99], v[206:209], v[222:225], v[96:99]
	v_mfma_f32_16x16x32_bf16 v[84:87], v[198:201], v[230:233], v[84:87]
	v_mfma_f32_16x16x32_bf16 v[80:83], v[206:209], v[230:233], v[80:83]
	v_mfma_f32_16x16x32_bf16 v[68:71], v[198:201], v[238:241], v[68:71]
	v_mfma_f32_16x16x32_bf16 v[64:67], v[206:209], v[238:241], v[64:67]
	s_setprio 0
	s_barrier
	s_add_u32 s98, s48, s8
	s_addc_u32 s99, s49, s9
	s_add_u32 s100, s50, s8
	s_addc_u32 s101, s51, s9
	s_mov_b32 m0, s28
	s_add_u32 s68, s48, 0x40000
	ds_read_b128 v[210:213], v141 offset:16384
	ds_read_b128 v[214:217], v141 offset:17408
	ds_read_b128 v[218:221], v141 offset:18432
	ds_read_b128 v[222:225], v141 offset:19456
	ds_read_b128 v[226:229], v141 offset:20480
	ds_read_b128 v[230:233], v141 offset:21504
	ds_read_b128 v[234:237], v141 offset:22528
	ds_read_b128 v[238:241], v141 offset:23552
	global_load_lds_dwordx4 v130, s[48:49]
	s_mov_b32 m0, s29
	s_addc_u32 s69, s49, 0
	global_load_lds_dwordx4 v128, s[48:49]
	s_mov_b32 m0, s30
	s_nop 0
	global_load_lds_dwordx4 v130, s[68:69]
	s_mov_b32 m0, s31
	s_nop 0
	global_load_lds_dwordx4 v128, s[68:69]
	s_mov_b32 m0, s2
	s_nop 0
	global_load_lds_dwordx4 v130, s[50:51]
	s_mov_b32 m0, s33
	s_nop 0
	global_load_lds_dwordx4 v128, s[50:51]
	s_waitcnt vmcnt(8)
	s_waitcnt lgkmcnt(0)
	s_barrier
	s_setprio 1
	s_waitcnt lgkmcnt(0)
	v_mfma_f32_16x16x32_bf16 v[60:63], v[174:177], v[210:213], v[60:63]
	v_mfma_f32_16x16x32_bf16 v[56:59], v[182:185], v[210:213], v[56:59]
	v_mfma_f32_16x16x32_bf16 v[44:47], v[174:177], v[218:221], v[44:47]
	v_mfma_f32_16x16x32_bf16 v[40:43], v[182:185], v[218:221], v[40:43]
	v_mfma_f32_16x16x32_bf16 v[28:31], v[174:177], v[226:229], v[28:31]
	v_mfma_f32_16x16x32_bf16 v[24:27], v[182:185], v[226:229], v[24:27]
	v_mfma_f32_16x16x32_bf16 v[12:15], v[174:177], v[234:237], v[12:15]
	v_mfma_f32_16x16x32_bf16 v[8:11], v[182:185], v[234:237], v[8:11]
	v_mfma_f32_16x16x32_bf16 v[60:63], v[178:181], v[214:217], v[60:63]
	v_mfma_f32_16x16x32_bf16 v[56:59], v[186:189], v[214:217], v[56:59]
	v_mfma_f32_16x16x32_bf16 v[44:47], v[178:181], v[222:225], v[44:47]
	v_mfma_f32_16x16x32_bf16 v[40:43], v[186:189], v[222:225], v[40:43]
	v_mfma_f32_16x16x32_bf16 v[28:31], v[178:181], v[230:233], v[28:31]
	v_mfma_f32_16x16x32_bf16 v[24:27], v[186:189], v[230:233], v[24:27]
	v_mfma_f32_16x16x32_bf16 v[12:15], v[178:181], v[238:241], v[12:15]
	v_mfma_f32_16x16x32_bf16 v[8:11], v[186:189], v[238:241], v[8:11]
	s_setprio 0
	s_setprio 1
	v_mfma_f32_16x16x32_bf16 v[52:55], v[190:193], v[210:213], v[52:55]
	v_mfma_f32_16x16x32_bf16 v[48:51], v[202:205], v[210:213], v[48:51]
	v_mfma_f32_16x16x32_bf16 v[36:39], v[190:193], v[218:221], v[36:39]
	v_mfma_f32_16x16x32_bf16 v[32:35], v[202:205], v[218:221], v[32:35]
	v_mfma_f32_16x16x32_bf16 v[20:23], v[190:193], v[226:229], v[20:23]
	v_mfma_f32_16x16x32_bf16 v[16:19], v[202:205], v[226:229], v[16:19]
	v_mfma_f32_16x16x32_bf16 v[4:7], v[190:193], v[234:237], v[4:7]
	v_mfma_f32_16x16x32_bf16 v[0:3], v[202:205], v[234:237], v[0:3]
	v_mfma_f32_16x16x32_bf16 v[52:55], v[198:201], v[214:217], v[52:55]
	v_mfma_f32_16x16x32_bf16 v[48:51], v[206:209], v[214:217], v[48:51]
	v_mfma_f32_16x16x32_bf16 v[36:39], v[198:201], v[222:225], v[36:39]
	v_mfma_f32_16x16x32_bf16 v[32:35], v[206:209], v[222:225], v[32:35]
	v_mfma_f32_16x16x32_bf16 v[20:23], v[198:201], v[230:233], v[20:23]
	v_mfma_f32_16x16x32_bf16 v[16:19], v[206:209], v[230:233], v[16:19]
	v_mfma_f32_16x16x32_bf16 v[4:7], v[198:201], v[238:241], v[4:7]
	v_mfma_f32_16x16x32_bf16 v[0:3], v[206:209], v[238:241], v[0:3]
	s_setprio 0
	s_barrier
	ds_read_b128 v[174:177], v165
	ds_read_b128 v[178:181], v166
	ds_read_b128 v[182:185], v167
	ds_read_b128 v[186:189], v168
	ds_read_b128 v[190:193], v169
	ds_read_b128 v[198:201], v170
	ds_read_b128 v[202:205], v171
	ds_read_b128 v[206:209], v172
	s_add_u32 s50, s50, 0x40000
	s_addc_u32 s51, s51, 0
	s_mov_b32 m0, s34
	ds_read_b128 v[210:213], v141 offset:32768
	ds_read_b128 v[214:217], v141 offset:33792
	ds_read_b128 v[218:221], v141 offset:34816
	ds_read_b128 v[222:225], v141 offset:35840
	ds_read_b128 v[226:229], v141 offset:36864
	ds_read_b128 v[230:233], v141 offset:37888
	ds_read_b128 v[234:237], v141 offset:38912
	ds_read_b128 v[238:241], v141 offset:39936
	global_load_lds_dwordx4 v130, s[50:51]
	s_mov_b32 m0, s35
	s_nop 0
	global_load_lds_dwordx4 v128, s[50:51]
	s_waitcnt vmcnt(8)
	s_waitcnt lgkmcnt(0)
	s_barrier
	s_setprio 1
	s_waitcnt lgkmcnt(0)
	v_mfma_f32_16x16x32_bf16 v[124:127], v[174:177], v[210:213], v[124:127]
	v_mfma_f32_16x16x32_bf16 v[120:123], v[182:185], v[210:213], v[120:123]
	v_mfma_f32_16x16x32_bf16 v[108:111], v[174:177], v[218:221], v[108:111]
	v_mfma_f32_16x16x32_bf16 v[104:107], v[182:185], v[218:221], v[104:107]
	v_mfma_f32_16x16x32_bf16 v[92:95], v[174:177], v[226:229], v[92:95]
	v_mfma_f32_16x16x32_bf16 v[88:91], v[182:185], v[226:229], v[88:91]
	v_mfma_f32_16x16x32_bf16 v[76:79], v[174:177], v[234:237], v[76:79]
	v_mfma_f32_16x16x32_bf16 v[72:75], v[182:185], v[234:237], v[72:75]
	v_mfma_f32_16x16x32_bf16 v[124:127], v[178:181], v[214:217], v[124:127]
	v_mfma_f32_16x16x32_bf16 v[120:123], v[186:189], v[214:217], v[120:123]
	v_mfma_f32_16x16x32_bf16 v[108:111], v[178:181], v[222:225], v[108:111]
	v_mfma_f32_16x16x32_bf16 v[104:107], v[186:189], v[222:225], v[104:107]
	v_mfma_f32_16x16x32_bf16 v[92:95], v[178:181], v[230:233], v[92:95]
	v_mfma_f32_16x16x32_bf16 v[88:91], v[186:189], v[230:233], v[88:91]
	v_mfma_f32_16x16x32_bf16 v[76:79], v[178:181], v[238:241], v[76:79]
	v_mfma_f32_16x16x32_bf16 v[72:75], v[186:189], v[238:241], v[72:75]
	s_setprio 0
	s_setprio 1
	v_mfma_f32_16x16x32_bf16 v[116:119], v[190:193], v[210:213], v[116:119]
	v_mfma_f32_16x16x32_bf16 v[112:115], v[202:205], v[210:213], v[112:115]
	v_mfma_f32_16x16x32_bf16 v[100:103], v[190:193], v[218:221], v[100:103]
	v_mfma_f32_16x16x32_bf16 v[96:99], v[202:205], v[218:221], v[96:99]
	v_mfma_f32_16x16x32_bf16 v[84:87], v[190:193], v[226:229], v[84:87]
	v_mfma_f32_16x16x32_bf16 v[80:83], v[202:205], v[226:229], v[80:83]
	v_mfma_f32_16x16x32_bf16 v[68:71], v[190:193], v[234:237], v[68:71]
	v_mfma_f32_16x16x32_bf16 v[64:67], v[202:205], v[234:237], v[64:67]
	v_mfma_f32_16x16x32_bf16 v[116:119], v[198:201], v[214:217], v[116:119]
	v_mfma_f32_16x16x32_bf16 v[112:115], v[206:209], v[214:217], v[112:115]
	v_mfma_f32_16x16x32_bf16 v[100:103], v[198:201], v[222:225], v[100:103]
	v_mfma_f32_16x16x32_bf16 v[96:99], v[206:209], v[222:225], v[96:99]
	v_mfma_f32_16x16x32_bf16 v[84:87], v[198:201], v[230:233], v[84:87]
	v_mfma_f32_16x16x32_bf16 v[80:83], v[206:209], v[230:233], v[80:83]
	v_mfma_f32_16x16x32_bf16 v[68:71], v[198:201], v[238:241], v[68:71]
	v_mfma_f32_16x16x32_bf16 v[64:67], v[206:209], v[238:241], v[64:67]
	s_setprio 0
	s_barrier
	s_mov_b32 m0, s40
	s_add_u32 s48, s48, 0x40080
	ds_read_b128 v[210:213], v141 offset:49152
	ds_read_b128 v[214:217], v141 offset:50176
	ds_read_b128 v[218:221], v141 offset:51200
	ds_read_b128 v[222:225], v141 offset:52224
	ds_read_b128 v[226:229], v141 offset:53248
	ds_read_b128 v[230:233], v141 offset:54272
	ds_read_b128 v[234:237], v141 offset:55296
	ds_read_b128 v[238:241], v141 offset:56320
	global_load_lds_dwordx4 v130, s[98:99]
	s_mov_b32 m0, s41
	s_addc_u32 s49, s49, 0
	global_load_lds_dwordx4 v128, s[98:99]
	s_mov_b32 m0, s53
	s_nop 0
	global_load_lds_dwordx4 v130, s[48:49]
	s_mov_b32 m0, s60
	s_nop 0
	global_load_lds_dwordx4 v128, s[48:49]
	s_mov_b32 m0, s47
	s_nop 0
	global_load_lds_dwordx4 v130, s[100:101]
	s_mov_b32 m0, s52
	s_nop 0
	global_load_lds_dwordx4 v128, s[100:101]
	s_waitcnt vmcnt(8)
	s_waitcnt lgkmcnt(0)
	s_barrier
	s_setprio 1
	s_waitcnt lgkmcnt(0)
	v_mfma_f32_16x16x32_bf16 v[60:63], v[174:177], v[210:213], v[60:63]
	v_mfma_f32_16x16x32_bf16 v[56:59], v[182:185], v[210:213], v[56:59]
	v_mfma_f32_16x16x32_bf16 v[44:47], v[174:177], v[218:221], v[44:47]
	v_mfma_f32_16x16x32_bf16 v[40:43], v[182:185], v[218:221], v[40:43]
	v_mfma_f32_16x16x32_bf16 v[28:31], v[174:177], v[226:229], v[28:31]
	v_mfma_f32_16x16x32_bf16 v[24:27], v[182:185], v[226:229], v[24:27]
	v_mfma_f32_16x16x32_bf16 v[12:15], v[174:177], v[234:237], v[12:15]
	v_mfma_f32_16x16x32_bf16 v[8:11], v[182:185], v[234:237], v[8:11]
	v_mfma_f32_16x16x32_bf16 v[60:63], v[178:181], v[214:217], v[60:63]
	v_mfma_f32_16x16x32_bf16 v[56:59], v[186:189], v[214:217], v[56:59]
	v_mfma_f32_16x16x32_bf16 v[44:47], v[178:181], v[222:225], v[44:47]
	v_mfma_f32_16x16x32_bf16 v[40:43], v[186:189], v[222:225], v[40:43]
	v_mfma_f32_16x16x32_bf16 v[28:31], v[178:181], v[230:233], v[28:31]
	v_mfma_f32_16x16x32_bf16 v[24:27], v[186:189], v[230:233], v[24:27]
	v_mfma_f32_16x16x32_bf16 v[12:15], v[178:181], v[238:241], v[12:15]
	v_mfma_f32_16x16x32_bf16 v[8:11], v[186:189], v[238:241], v[8:11]
	s_setprio 0
	s_setprio 1
	v_mfma_f32_16x16x32_bf16 v[52:55], v[190:193], v[210:213], v[52:55]
	v_mfma_f32_16x16x32_bf16 v[48:51], v[202:205], v[210:213], v[48:51]
	v_mfma_f32_16x16x32_bf16 v[36:39], v[190:193], v[218:221], v[36:39]
	v_mfma_f32_16x16x32_bf16 v[32:35], v[202:205], v[218:221], v[32:35]
	v_mfma_f32_16x16x32_bf16 v[20:23], v[190:193], v[226:229], v[20:23]
	v_mfma_f32_16x16x32_bf16 v[16:19], v[202:205], v[226:229], v[16:19]
	v_mfma_f32_16x16x32_bf16 v[4:7], v[190:193], v[234:237], v[4:7]
	v_mfma_f32_16x16x32_bf16 v[0:3], v[202:205], v[234:237], v[0:3]
	v_mfma_f32_16x16x32_bf16 v[52:55], v[198:201], v[214:217], v[52:55]
	v_mfma_f32_16x16x32_bf16 v[48:51], v[206:209], v[214:217], v[48:51]
	v_mfma_f32_16x16x32_bf16 v[36:39], v[198:201], v[222:225], v[36:39]
	v_mfma_f32_16x16x32_bf16 v[32:35], v[206:209], v[222:225], v[32:35]
	v_mfma_f32_16x16x32_bf16 v[20:23], v[198:201], v[230:233], v[20:23]
	v_mfma_f32_16x16x32_bf16 v[16:19], v[206:209], v[230:233], v[16:19]
	v_mfma_f32_16x16x32_bf16 v[4:7], v[198:201], v[238:241], v[4:7]
	v_mfma_f32_16x16x32_bf16 v[0:3], v[206:209], v[238:241], v[0:3]
	s_setprio 0
	s_barrier
	s_add_i32 s55, s55, 2
	s_add_u32 s24, s24, 0x100
	s_addc_u32 s25, s25, 0
	s_add_u32 s39, s39, 0x100
	s_addc_u32 s54, s54, 0
	s_cmp_gt_u32 s55, 13
	s_cbranch_scc0 .LBB0_1096
	s_and_b64 vcc, exec, s[12:13]
	s_cbranch_vccz .LBB0_1099
	s_barrier

.LBB0_1162:
	s_lshl_b32 s12, s12, 5
	s_add_i32 s35, s6, 0x18000
	s_mov_b64 s[14:15], 0x80
	s_and_b32 s42, s12, 0x60
	v_lshl_add_u64 v[6:7], v[6:7], 0, s[14:15]
	s_mov_b32 m0, s35
	s_add_i32 s36, s6, 0x1a000
	s_lshl_b32 s26, s5, 13
	s_lshl_b32 s27, s42, 7
	s_waitcnt vmcnt(2)
	s_barrier
	global_load_lds_dwordx4 v[6:7], off
	v_lshl_add_u64 v[4:5], v[4:5], 0, s[14:15]
	s_mov_b32 m0, s36
	s_add_i32 s37, s6, 0x8000
	s_add_i32 s40, s6, 0xa000
	global_load_lds_dwordx4 v[4:5], off
	v_lshl_add_u64 v[0:1], v[0:1], 0, s[14:15]
	s_mov_b32 m0, s37
	s_add_u32 s12, s46, 0xb0080
	global_load_lds_dwordx4 v[0:1], off
	v_lshl_add_u64 v[0:1], v[2:3], 0, s[14:15]
	s_mov_b32 m0, s40
	s_addc_u32 s13, s47, 0
	s_add_i32 s41, s6, 0x1c000
	global_load_lds_dwordx4 v[0:1], off
	s_mov_b32 m0, s41
	s_add_i32 s43, s6, 0x1e000
	global_load_lds_dwordx4 v140, s[12:13]
	s_mov_b32 m0, s43
	s_sext_i32_i8 s39, s11
	global_load_lds_dwordx4 v142, s[12:13]
	v_bfe_u32 v0, v8, 4, 2
	v_and_b32_e32 v1, 15, v8
	v_lshlrev_b32_e32 v2, 4, v0
	v_lshl_or_b32 v153, s5, 6, v1
	v_lshl_or_b32 v1, v1, 6, v2
	v_lshlrev_b32_e32 v2, 2, v8
	v_and_b32_e32 v2, 32, v2
	v_bitop3_b32 v159, v1, s26, v2 bitop3:0xde
	v_bitop3_b32 v2, v1, s27, v2 bitop3:0xde
	v_lshl_or_b32 v182, v0, 2, s42
	v_lshrrev_b32_e32 v1, 1, v9
	v_mul_lo_u32 v0, v11, s4
	s_mov_b32 s5, 0xb000
	s_cmpk_lt_u32 s10, 0x100
	v_mad_u64_u32 v[0:1], s[10:11], v1, s5, v[0:1]
	v_or_b32_e32 v0, v0, v10
	s_mov_b64 s[12:13], 0xb0080
	v_add_lshl_u32 v0, v0, v12, 1
	v_mov_b32_e32 v1, v141
	v_lshl_add_u64 v[160:161], v[0:1], 0, s[12:13]
	v_lshrrev_b32_e32 v1, 1, v13
	v_mul_lo_u32 v0, v14, s4
	v_mad_u64_u32 v[0:1], s[4:5], v1, s5, v[0:1]
	s_waitcnt vmcnt(6)
	v_or_b32_e32 v0, v0, v15
	v_add_lshl_u32 v0, v0, v16, 1
	v_mov_b32_e32 v1, v141
	s_movk_i32 s52, 0x100
	s_cselect_b64 s[26:27], -1, 0
	s_ashr_i32 s53, s82, 31
	s_mov_b32 s54, s82
	v_lshl_add_u64 v[162:163], v[0:1], 0, s[12:13]
	s_mov_b32 s55, 0
	v_mov_b64_e32 v[164:165], 0x200
	v_mov_b64_e32 v[166:167], 0x1ff
	v_or_b32_e32 v183, 0x10000, v2
	v_add_u32_e32 v184, 0x10400, v2
	v_add_u32_e32 v185, 0x10800, v2
	v_add_u32_e32 v186, 0x10c00, v2
	v_or_b32_e32 v187, 0x14000, v2
	v_add_u32_e32 v188, 0x14400, v2
	v_add_u32_e32 v189, 0x14800, v2
	v_add_u32_e32 v190, 0x14c00, v2
	s_add_i32 s60, s6, 0xc000
	s_add_i32 s61, s6, 0xe000
	v_or_b32_e32 v191, 0x18000, v2
	v_add_u32_e32 v192, 0x18400, v2
	v_add_u32_e32 v193, 0x18800, v2
	v_add_u32_e32 v197, 0x18c00, v2
	v_or_b32_e32 v198, 0x1c000, v2
	v_add_u32_e32 v199, 0x1c400, v2
	v_add_u32_e32 v200, 0x1c800, v2
	v_add_u32_e32 v201, 0x1cc00, v2
	s_mov_b32 s64, 0x3e0f83e1
	s_movk_i32 s65, 0xdf00
	s_mov_b32 s42, 0x3fd744fd
	v_mov_b32_e32 v202, 0xffffff00
	s_barrier
	s_branch .LBB0_1165

.LBB0_1176:
	ds_read_b128 v[128:131], v183
	ds_read_b128 v[132:135], v184
	ds_read_b128 v[136:139], v185
	ds_read_b128 v[168:171], v186
	ds_read_b128 v[172:175], v187
	ds_read_b128 v[176:179], v188
	ds_read_b128 v[204:207], v189
	ds_read_b128 v[208:211], v190
	s_add_u32 s46, s24, 0x100
	s_addc_u32 s47, s25, 0
	s_cmp_eq_u32 s66, 40
	s_cselect_b32 s51, s13, s47
	s_cselect_b32 s50, s12, s46
	s_cselect_b32 s49, s45, s5
	s_cselect_b32 s48, s44, s4
	s_mov_b32 m0, s60
	ds_read_b128 v[212:215], v159
	ds_read_b128 v[216:219], v159 offset:1024
	ds_read_b128 v[220:223], v159 offset:2048
	ds_read_b128 v[224:227], v159 offset:3072
	ds_read_b128 v[228:231], v159 offset:4096
	ds_read_b128 v[232:235], v159 offset:5120
	ds_read_b128 v[236:239], v159 offset:6144
	ds_read_b128 v[240:243], v159 offset:7168
	global_load_lds_dwordx4 v160, s[24:25]
	s_mov_b32 m0, s61
	s_nop 0
	global_load_lds_dwordx4 v162, s[24:25]
	s_waitcnt vmcnt(8)
	s_waitcnt lgkmcnt(0)
	s_barrier
	s_setprio 1
	s_waitcnt lgkmcnt(0)
	v_mfma_f32_16x16x32_bf16 v[124:127], v[128:131], v[212:215], v[124:127]
	v_mfma_f32_16x16x32_bf16 v[120:123], v[136:139], v[212:215], v[120:123]
	v_mfma_f32_16x16x32_bf16 v[108:111], v[128:131], v[220:223], v[108:111]
	v_mfma_f32_16x16x32_bf16 v[104:107], v[136:139], v[220:223], v[104:107]
	v_mfma_f32_16x16x32_bf16 v[92:95], v[128:131], v[228:231], v[92:95]
	v_mfma_f32_16x16x32_bf16 v[88:91], v[136:139], v[228:231], v[88:91]
	v_mfma_f32_16x16x32_bf16 v[76:79], v[128:131], v[236:239], v[76:79]
	v_mfma_f32_16x16x32_bf16 v[72:75], v[136:139], v[236:239], v[72:75]
	v_mfma_f32_16x16x32_bf16 v[124:127], v[132:135], v[216:219], v[124:127]
	v_mfma_f32_16x16x32_bf16 v[120:123], v[168:171], v[216:219], v[120:123]
	v_mfma_f32_16x16x32_bf16 v[108:111], v[132:135], v[224:227], v[108:111]
	v_mfma_f32_16x16x32_bf16 v[104:107], v[168:171], v[224:227], v[104:107]
	v_mfma_f32_16x16x32_bf16 v[92:95], v[132:135], v[232:235], v[92:95]
	v_mfma_f32_16x16x32_bf16 v[88:91], v[168:171], v[232:235], v[88:91]
	v_mfma_f32_16x16x32_bf16 v[76:79], v[132:135], v[240:243], v[76:79]
	v_mfma_f32_16x16x32_bf16 v[72:75], v[168:171], v[240:243], v[72:75]
	s_setprio 0
	s_setprio 1
	v_mfma_f32_16x16x32_bf16 v[116:119], v[172:175], v[212:215], v[116:119]
	v_mfma_f32_16x16x32_bf16 v[112:115], v[204:207], v[212:215], v[112:115]
	v_mfma_f32_16x16x32_bf16 v[100:103], v[172:175], v[220:223], v[100:103]
	v_mfma_f32_16x16x32_bf16 v[96:99], v[204:207], v[220:223], v[96:99]
	v_mfma_f32_16x16x32_bf16 v[84:87], v[172:175], v[228:231], v[84:87]
	v_mfma_f32_16x16x32_bf16 v[80:83], v[204:207], v[228:231], v[80:83]
	v_mfma_f32_16x16x32_bf16 v[68:71], v[172:175], v[236:239], v[68:71]
	v_mfma_f32_16x16x32_bf16 v[64:67], v[204:207], v[236:239], v[64:67]
	v_mfma_f32_16x16x32_bf16 v[116:119], v[176:179], v[216:219], v[116:119]
	v_mfma_f32_16x16x32_bf16 v[112:115], v[208:211], v[216:219], v[112:115]
	v_mfma_f32_16x16x32_bf16 v[100:103], v[176:179], v[224:227], v[100:103]
	v_mfma_f32_16x16x32_bf16 v[96:99], v[208:211], v[224:227], v[96:99]
	v_mfma_f32_16x16x32_bf16 v[84:87], v[176:179], v[232:235], v[84:87]
	v_mfma_f32_16x16x32_bf16 v[80:83], v[208:211], v[232:235], v[80:83]
	v_mfma_f32_16x16x32_bf16 v[68:71], v[176:179], v[240:243], v[68:71]
	v_mfma_f32_16x16x32_bf16 v[64:67], v[208:211], v[240:243], v[64:67]
	s_setprio 0
	s_barrier
	s_add_u32 s98, s48, s14
	s_addc_u32 s99, s49, s15
	s_add_u32 s100, s50, s14
	s_addc_u32 s101, s51, s15
	s_mov_b32 m0, s7
	s_add_u32 s24, s48, 0xb0000
	ds_read_b128 v[212:215], v159 offset:16384
	ds_read_b128 v[216:219], v159 offset:17408
	ds_read_b128 v[220:223], v159 offset:18432
	ds_read_b128 v[224:227], v159 offset:19456
	ds_read_b128 v[228:231], v159 offset:20480
	ds_read_b128 v[232:235], v159 offset:21504
	ds_read_b128 v[236:239], v159 offset:22528
	ds_read_b128 v[240:243], v159 offset:23552
	global_load_lds_dwordx4 v140, s[48:49]
	s_mov_b32 m0, s28
	s_addc_u32 s25, s49, 0
	global_load_lds_dwordx4 v142, s[48:49]
	s_mov_b32 m0, s29
	s_nop 0
	global_load_lds_dwordx4 v140, s[24:25]
	s_mov_b32 m0, s30
	s_nop 0
	global_load_lds_dwordx4 v142, s[24:25]
	s_mov_b32 m0, s6
	s_nop 0
	global_load_lds_dwordx4 v140, s[50:51]
	s_mov_b32 m0, s31
	s_nop 0
	global_load_lds_dwordx4 v142, s[50:51]
	s_waitcnt vmcnt(8)
	s_waitcnt lgkmcnt(0)
	s_barrier
	s_setprio 1
	s_waitcnt lgkmcnt(0)
	v_mfma_f32_16x16x32_bf16 v[60:63], v[128:131], v[212:215], v[60:63]
	v_mfma_f32_16x16x32_bf16 v[56:59], v[136:139], v[212:215], v[56:59]
	v_mfma_f32_16x16x32_bf16 v[44:47], v[128:131], v[220:223], v[44:47]
	v_mfma_f32_16x16x32_bf16 v[40:43], v[136:139], v[220:223], v[40:43]
	v_mfma_f32_16x16x32_bf16 v[28:31], v[128:131], v[228:231], v[28:31]
	v_mfma_f32_16x16x32_bf16 v[24:27], v[136:139], v[228:231], v[24:27]
	v_mfma_f32_16x16x32_bf16 v[12:15], v[128:131], v[236:239], v[12:15]
	v_mfma_f32_16x16x32_bf16 v[8:11], v[136:139], v[236:239], v[8:11]
	v_mfma_f32_16x16x32_bf16 v[60:63], v[132:135], v[216:219], v[60:63]
	v_mfma_f32_16x16x32_bf16 v[56:59], v[168:171], v[216:219], v[56:59]
	v_mfma_f32_16x16x32_bf16 v[44:47], v[132:135], v[224:227], v[44:47]
	v_mfma_f32_16x16x32_bf16 v[40:43], v[168:171], v[224:227], v[40:43]
	v_mfma_f32_16x16x32_bf16 v[28:31], v[132:135], v[232:235], v[28:31]
	v_mfma_f32_16x16x32_bf16 v[24:27], v[168:171], v[232:235], v[24:27]
	v_mfma_f32_16x16x32_bf16 v[12:15], v[132:135], v[240:243], v[12:15]
	v_mfma_f32_16x16x32_bf16 v[8:11], v[168:171], v[240:243], v[8:11]
	s_setprio 0
	s_setprio 1
	v_mfma_f32_16x16x32_bf16 v[52:55], v[172:175], v[212:215], v[52:55]
	v_mfma_f32_16x16x32_bf16 v[48:51], v[204:207], v[212:215], v[48:51]
	v_mfma_f32_16x16x32_bf16 v[36:39], v[172:175], v[220:223], v[36:39]
	v_mfma_f32_16x16x32_bf16 v[32:35], v[204:207], v[220:223], v[32:35]
	v_mfma_f32_16x16x32_bf16 v[20:23], v[172:175], v[228:231], v[20:23]
	v_mfma_f32_16x16x32_bf16 v[16:19], v[204:207], v[228:231], v[16:19]
	v_mfma_f32_16x16x32_bf16 v[4:7], v[172:175], v[236:239], v[4:7]
	v_mfma_f32_16x16x32_bf16 v[0:3], v[204:207], v[236:239], v[0:3]
	v_mfma_f32_16x16x32_bf16 v[52:55], v[176:179], v[216:219], v[52:55]
	v_mfma_f32_16x16x32_bf16 v[48:51], v[208:211], v[216:219], v[48:51]
	v_mfma_f32_16x16x32_bf16 v[36:39], v[176:179], v[224:227], v[36:39]
	v_mfma_f32_16x16x32_bf16 v[32:35], v[208:211], v[224:227], v[32:35]
	v_mfma_f32_16x16x32_bf16 v[20:23], v[176:179], v[232:235], v[20:23]
	v_mfma_f32_16x16x32_bf16 v[16:19], v[208:211], v[232:235], v[16:19]
	v_mfma_f32_16x16x32_bf16 v[4:7], v[176:179], v[240:243], v[4:7]
	v_mfma_f32_16x16x32_bf16 v[0:3], v[208:211], v[240:243], v[0:3]
	s_setprio 0
	s_barrier
	ds_read_b128 v[128:131], v191
	ds_read_b128 v[132:135], v192
	ds_read_b128 v[136:139], v193
	ds_read_b128 v[168:171], v197
	ds_read_b128 v[172:175], v198
	ds_read_b128 v[176:179], v199
	ds_read_b128 v[204:207], v200
	ds_read_b128 v[208:211], v201
	s_add_u32 s24, s50, 0xb0000
	s_addc_u32 s25, s51, 0
	s_mov_b32 m0, s33
	ds_read_b128 v[212:215], v159 offset:32768
	ds_read_b128 v[216:219], v159 offset:33792
	ds_read_b128 v[220:223], v159 offset:34816
	ds_read_b128 v[224:227], v159 offset:35840
	ds_read_b128 v[228:231], v159 offset:36864
	ds_read_b128 v[232:235], v159 offset:37888
	ds_read_b128 v[236:239], v159 offset:38912
	ds_read_b128 v[240:243], v159 offset:39936
	global_load_lds_dwordx4 v140, s[24:25]
	s_mov_b32 m0, s34
	s_nop 0
	global_load_lds_dwordx4 v142, s[24:25]
	s_waitcnt vmcnt(8)
	s_waitcnt lgkmcnt(0)
	s_barrier
	s_setprio 1
	s_waitcnt lgkmcnt(0)
	v_mfma_f32_16x16x32_bf16 v[124:127], v[128:131], v[212:215], v[124:127]
	v_mfma_f32_16x16x32_bf16 v[120:123], v[136:139], v[212:215], v[120:123]
	v_mfma_f32_16x16x32_bf16 v[108:111], v[128:131], v[220:223], v[108:111]
	v_mfma_f32_16x16x32_bf16 v[104:107], v[136:139], v[220:223], v[104:107]
	v_mfma_f32_16x16x32_bf16 v[92:95], v[128:131], v[228:231], v[92:95]
	v_mfma_f32_16x16x32_bf16 v[88:91], v[136:139], v[228:231], v[88:91]
	v_mfma_f32_16x16x32_bf16 v[76:79], v[128:131], v[236:239], v[76:79]
	v_mfma_f32_16x16x32_bf16 v[72:75], v[136:139], v[236:239], v[72:75]
	v_mfma_f32_16x16x32_bf16 v[124:127], v[132:135], v[216:219], v[124:127]
	v_mfma_f32_16x16x32_bf16 v[120:123], v[168:171], v[216:219], v[120:123]
	v_mfma_f32_16x16x32_bf16 v[108:111], v[132:135], v[224:227], v[108:111]
	v_mfma_f32_16x16x32_bf16 v[104:107], v[168:171], v[224:227], v[104:107]
	v_mfma_f32_16x16x32_bf16 v[92:95], v[132:135], v[232:235], v[92:95]
	v_mfma_f32_16x16x32_bf16 v[88:91], v[168:171], v[232:235], v[88:91]
	v_mfma_f32_16x16x32_bf16 v[76:79], v[132:135], v[240:243], v[76:79]
	v_mfma_f32_16x16x32_bf16 v[72:75], v[168:171], v[240:243], v[72:75]
	s_setprio 0
	s_setprio 1
	v_mfma_f32_16x16x32_bf16 v[116:119], v[172:175], v[212:215], v[116:119]
	v_mfma_f32_16x16x32_bf16 v[112:115], v[204:207], v[212:215], v[112:115]
	v_mfma_f32_16x16x32_bf16 v[100:103], v[172:175], v[220:223], v[100:103]
	v_mfma_f32_16x16x32_bf16 v[96:99], v[204:207], v[220:223], v[96:99]
	v_mfma_f32_16x16x32_bf16 v[84:87], v[172:175], v[228:231], v[84:87]
	v_mfma_f32_16x16x32_bf16 v[80:83], v[204:207], v[228:231], v[80:83]
	v_mfma_f32_16x16x32_bf16 v[68:71], v[172:175], v[236:239], v[68:71]
	v_mfma_f32_16x16x32_bf16 v[64:67], v[204:207], v[236:239], v[64:67]
	v_mfma_f32_16x16x32_bf16 v[116:119], v[176:179], v[216:219], v[116:119]
	v_mfma_f32_16x16x32_bf16 v[112:115], v[208:211], v[216:219], v[112:115]
	v_mfma_f32_16x16x32_bf16 v[100:103], v[176:179], v[224:227], v[100:103]
	v_mfma_f32_16x16x32_bf16 v[96:99], v[208:211], v[224:227], v[96:99]
	v_mfma_f32_16x16x32_bf16 v[84:87], v[176:179], v[232:235], v[84:87]
	v_mfma_f32_16x16x32_bf16 v[80:83], v[208:211], v[232:235], v[80:83]
	v_mfma_f32_16x16x32_bf16 v[68:71], v[176:179], v[240:243], v[68:71]
	v_mfma_f32_16x16x32_bf16 v[64:67], v[208:211], v[240:243], v[64:67]
	s_setprio 0
	s_barrier
	s_mov_b32 m0, s35
	s_add_u32 s24, s48, 0xb0080
	ds_read_b128 v[212:215], v159 offset:49152
	ds_read_b128 v[216:219], v159 offset:50176
	ds_read_b128 v[220:223], v159 offset:51200
	ds_read_b128 v[224:227], v159 offset:52224
	ds_read_b128 v[228:231], v159 offset:53248
	ds_read_b128 v[232:235], v159 offset:54272
	ds_read_b128 v[236:239], v159 offset:55296
	ds_read_b128 v[240:243], v159 offset:56320
	global_load_lds_dwordx4 v140, s[98:99]
	s_mov_b32 m0, s36
	s_addc_u32 s25, s49, 0
	global_load_lds_dwordx4 v142, s[98:99]
	s_mov_b32 m0, s41
	s_nop 0
	global_load_lds_dwordx4 v140, s[24:25]
	s_mov_b32 m0, s43
	s_nop 0
	global_load_lds_dwordx4 v142, s[24:25]
	s_mov_b32 m0, s37
	s_nop 0
	global_load_lds_dwordx4 v140, s[100:101]
	s_mov_b32 m0, s40
	s_nop 0
	global_load_lds_dwordx4 v142, s[100:101]
	s_waitcnt vmcnt(8)
	s_waitcnt lgkmcnt(0)
	s_barrier
	s_setprio 1
	s_waitcnt lgkmcnt(0)
	v_mfma_f32_16x16x32_bf16 v[60:63], v[128:131], v[212:215], v[60:63]
	v_mfma_f32_16x16x32_bf16 v[56:59], v[136:139], v[212:215], v[56:59]
	v_mfma_f32_16x16x32_bf16 v[44:47], v[128:131], v[220:223], v[44:47]
	v_mfma_f32_16x16x32_bf16 v[40:43], v[136:139], v[220:223], v[40:43]
	v_mfma_f32_16x16x32_bf16 v[28:31], v[128:131], v[228:231], v[28:31]
	v_mfma_f32_16x16x32_bf16 v[24:27], v[136:139], v[228:231], v[24:27]
	v_mfma_f32_16x16x32_bf16 v[12:15], v[128:131], v[236:239], v[12:15]
	v_mfma_f32_16x16x32_bf16 v[8:11], v[136:139], v[236:239], v[8:11]
	v_mfma_f32_16x16x32_bf16 v[60:63], v[132:135], v[216:219], v[60:63]
	v_mfma_f32_16x16x32_bf16 v[56:59], v[168:171], v[216:219], v[56:59]
	v_mfma_f32_16x16x32_bf16 v[44:47], v[132:135], v[224:227], v[44:47]
	v_mfma_f32_16x16x32_bf16 v[40:43], v[168:171], v[224:227], v[40:43]
	v_mfma_f32_16x16x32_bf16 v[28:31], v[132:135], v[232:235], v[28:31]
	v_mfma_f32_16x16x32_bf16 v[24:27], v[168:171], v[232:235], v[24:27]
	v_mfma_f32_16x16x32_bf16 v[12:15], v[132:135], v[240:243], v[12:15]
	v_mfma_f32_16x16x32_bf16 v[8:11], v[168:171], v[240:243], v[8:11]
	s_setprio 0
	s_setprio 1
	v_mfma_f32_16x16x32_bf16 v[52:55], v[172:175], v[212:215], v[52:55]
	v_mfma_f32_16x16x32_bf16 v[48:51], v[204:207], v[212:215], v[48:51]
	v_mfma_f32_16x16x32_bf16 v[36:39], v[172:175], v[220:223], v[36:39]
	v_mfma_f32_16x16x32_bf16 v[32:35], v[204:207], v[220:223], v[32:35]
	v_mfma_f32_16x16x32_bf16 v[20:23], v[172:175], v[228:231], v[20:23]
	v_mfma_f32_16x16x32_bf16 v[16:19], v[204:207], v[228:231], v[16:19]
	v_mfma_f32_16x16x32_bf16 v[4:7], v[172:175], v[236:239], v[4:7]
	v_mfma_f32_16x16x32_bf16 v[0:3], v[204:207], v[236:239], v[0:3]
	v_mfma_f32_16x16x32_bf16 v[52:55], v[176:179], v[216:219], v[52:55]
	v_mfma_f32_16x16x32_bf16 v[48:51], v[208:211], v[216:219], v[48:51]
	v_mfma_f32_16x16x32_bf16 v[36:39], v[176:179], v[224:227], v[36:39]
	v_mfma_f32_16x16x32_bf16 v[32:35], v[208:211], v[224:227], v[32:35]
	v_mfma_f32_16x16x32_bf16 v[20:23], v[176:179], v[232:235], v[20:23]
	v_mfma_f32_16x16x32_bf16 v[16:19], v[208:211], v[232:235], v[16:19]
	v_mfma_f32_16x16x32_bf16 v[4:7], v[176:179], v[240:243], v[4:7]
	v_mfma_f32_16x16x32_bf16 v[0:3], v[208:211], v[240:243], v[0:3]
	s_setprio 0
	s_barrier
	s_add_i32 s66, s66, 2
	s_add_u32 s4, s4, 0x100
	s_addc_u32 s5, s5, 0
	s_cmp_gt_u32 s66, 41
	s_mov_b64 s[24:25], s[46:47]
	s_cbranch_scc0 .LBB0_1176
	s_mov_b64 s[88:89], s[78:79]
	s_and_b64 vcc, exec, s[26:27]
	s_cbranch_vccz .LBB0_1179
	s_barrier

.LBB0_1324:
	s_lshl_b32 s8, s8, 5
	s_add_i32 s34, s2, 0x18000
	s_mov_b64 s[38:39], 0x80
	s_and_b32 s13, s8, 0x60
	v_lshl_add_u64 v[6:7], v[6:7], 0, s[38:39]
	s_mov_b32 m0, s34
	s_add_i32 s35, s2, 0x1a000
	s_lshl_b32 s11, s5, 13
	s_lshl_b32 s42, s13, 7
	s_waitcnt vmcnt(2)
	s_barrier
	global_load_lds_dwordx4 v[6:7], off
	v_lshl_add_u64 v[4:5], v[4:5], 0, s[38:39]
	s_mov_b32 m0, s35
	s_add_i32 s36, s2, 0x8000
	s_add_i32 s37, s2, 0xa000
	global_load_lds_dwordx4 v[4:5], off
	v_lshl_add_u64 v[0:1], v[0:1], 0, s[38:39]
	s_mov_b32 m0, s36
	s_add_u32 s8, s24, 0x40080
	global_load_lds_dwordx4 v[0:1], off
	v_lshl_add_u64 v[0:1], v[2:3], 0, s[38:39]
	s_mov_b32 m0, s37
	s_addc_u32 s9, s25, 0
	s_add_i32 s40, s2, 0x1c000
	global_load_lds_dwordx4 v[0:1], off
	s_mov_b32 m0, s40
	s_add_i32 s41, s2, 0x1e000
	global_load_lds_dwordx4 v128, s[8:9]
	s_mov_b32 m0, s41
	s_cmpk_lt_u32 s4, 0x100
	global_load_lds_dwordx4 v130, s[8:9]
	v_bfe_u32 v1, v8, 4, 2
	v_and_b32_e32 v0, 15, v8
	v_lshlrev_b32_e32 v2, 4, v1
	v_lshl_or_b32 v153, s5, 6, v0
	v_lshl_or_b32 v0, v0, 6, v2
	v_lshlrev_b32_e32 v2, 2, v8
	v_lshl_or_b32 v166, v1, 2, s13
	v_lshlrev_b32_e32 v1, 14, v9
	v_and_b32_e32 v2, 32, v2
	v_and_b32_e32 v1, 0xffff8000, v1
	v_bitop3_b32 v159, v0, s11, v2 bitop3:0xde
	v_bitop3_b32 v0, v0, s42, v2 bitop3:0xde
	v_lshl_add_u32 v1, v10, 11, v1
	v_and_b32_e32 v2, 1, v9
	v_lshl_or_b32 v1, v2, 6, v1
	v_lshl_add_u32 v134, v11, 1, v1
	v_lshlrev_b32_e32 v1, 14, v12
	v_and_b32_e32 v1, 0xffff8000, v1
	s_waitcnt vmcnt(6)
	v_lshl_add_u32 v1, v13, 11, v1
	v_and_b32_e32 v2, 1, v12
	v_lshl_or_b32 v1, v2, 6, v1
	s_cselect_b64 s[42:43], -1, 0
	s_ashr_i32 s45, s82, 31
	s_mov_b32 s52, s82
	s_ashr_i32 s53, s3, 31
	v_mov_b32_e32 v135, v133
	v_lshl_add_u32 v136, v14, 1, v1
	v_mov_b32_e32 v137, v133
	s_mov_b32 s60, 0
	v_mov_b64_e32 v[138:139], 0x400
	v_mov_b64_e32 v[140:141], 0x3ff
	v_or_b32_e32 v167, 0x10000, v0
	v_add_u32_e32 v168, 0x10400, v0
	v_add_u32_e32 v169, 0x10800, v0
	v_add_u32_e32 v170, 0x10c00, v0
	v_or_b32_e32 v171, 0x14000, v0
	v_add_u32_e32 v172, 0x14400, v0
	v_add_u32_e32 v173, 0x14800, v0
	v_add_u32_e32 v174, 0x14c00, v0
	s_add_i32 s61, s2, 0xc000
	s_add_i32 s67, s2, 0xe000
	v_or_b32_e32 v175, 0x18000, v0
	v_add_u32_e32 v176, 0x18400, v0
	v_add_u32_e32 v177, 0x18800, v0
	v_add_u32_e32 v178, 0x18c00, v0
	v_or_b32_e32 v179, 0x1c000, v0
	v_add_u32_e32 v180, 0x1c400, v0
	v_add_u32_e32 v181, 0x1c800, v0
	v_add_u32_e32 v182, 0x1cc00, v0
	s_movk_i32 s74, 0x3ff
	s_mov_b32 s44, 0x3e000000
	s_barrier
	s_branch .LBB0_1327

.LBB0_1334:
	ds_read_b128 v[160:163], v167
	ds_read_b128 v[184:187], v168
	ds_read_b128 v[188:191], v169
	ds_read_b128 v[198:201], v170
	ds_read_b128 v[202:205], v171
	ds_read_b128 v[206:209], v172
	ds_read_b128 v[210:213], v173
	ds_read_b128 v[214:217], v174
	s_add_u32 s24, s14, 0xfffc0080
	s_addc_u32 s25, s15, -1
	s_cmp_eq_u32 s66, 12
	s_cselect_b32 s65, s4, s25
	s_cselect_b32 s64, s5, s24
	s_cselect_b32 s25, s11, s49
	s_cselect_b32 s24, s13, s47
	s_mov_b32 m0, s61
	ds_read_b128 v[218:221], v159
	ds_read_b128 v[222:225], v159 offset:1024
	ds_read_b128 v[226:229], v159 offset:2048
	ds_read_b128 v[230:233], v159 offset:3072
	ds_read_b128 v[234:237], v159 offset:4096
	ds_read_b128 v[238:241], v159 offset:5120
	ds_read_b128 v[242:245], v159 offset:6144
	ds_read_b128 v[246:249], v159 offset:7168
	global_load_lds_dwordx4 v134, s[14:15]
	s_mov_b32 m0, s67
	s_nop 0
	global_load_lds_dwordx4 v136, s[14:15]
	s_waitcnt vmcnt(8)
	s_waitcnt lgkmcnt(0)
	s_barrier
	s_setprio 1
	s_waitcnt lgkmcnt(0)
	v_mfma_f32_16x16x32_bf16 v[124:127], v[160:163], v[218:221], v[124:127]
	v_mfma_f32_16x16x32_bf16 v[120:123], v[188:191], v[218:221], v[120:123]
	v_mfma_f32_16x16x32_bf16 v[108:111], v[160:163], v[226:229], v[108:111]
	v_mfma_f32_16x16x32_bf16 v[104:107], v[188:191], v[226:229], v[104:107]
	v_mfma_f32_16x16x32_bf16 v[92:95], v[160:163], v[234:237], v[92:95]
	v_mfma_f32_16x16x32_bf16 v[88:91], v[188:191], v[234:237], v[88:91]
	v_mfma_f32_16x16x32_bf16 v[76:79], v[160:163], v[242:245], v[76:79]
	v_mfma_f32_16x16x32_bf16 v[72:75], v[188:191], v[242:245], v[72:75]
	v_mfma_f32_16x16x32_bf16 v[124:127], v[184:187], v[222:225], v[124:127]
	v_mfma_f32_16x16x32_bf16 v[120:123], v[198:201], v[222:225], v[120:123]
	v_mfma_f32_16x16x32_bf16 v[108:111], v[184:187], v[230:233], v[108:111]
	v_mfma_f32_16x16x32_bf16 v[104:107], v[198:201], v[230:233], v[104:107]
	v_mfma_f32_16x16x32_bf16 v[92:95], v[184:187], v[238:241], v[92:95]
	v_mfma_f32_16x16x32_bf16 v[88:91], v[198:201], v[238:241], v[88:91]
	v_mfma_f32_16x16x32_bf16 v[76:79], v[184:187], v[246:249], v[76:79]
	v_mfma_f32_16x16x32_bf16 v[72:75], v[198:201], v[246:249], v[72:75]
	s_setprio 0
	s_setprio 1
	v_mfma_f32_16x16x32_bf16 v[116:119], v[202:205], v[218:221], v[116:119]
	v_mfma_f32_16x16x32_bf16 v[112:115], v[210:213], v[218:221], v[112:115]
	v_mfma_f32_16x16x32_bf16 v[100:103], v[202:205], v[226:229], v[100:103]
	v_mfma_f32_16x16x32_bf16 v[96:99], v[210:213], v[226:229], v[96:99]
	v_mfma_f32_16x16x32_bf16 v[84:87], v[202:205], v[234:237], v[84:87]
	v_mfma_f32_16x16x32_bf16 v[80:83], v[210:213], v[234:237], v[80:83]
	v_mfma_f32_16x16x32_bf16 v[68:71], v[202:205], v[242:245], v[68:71]
	v_mfma_f32_16x16x32_bf16 v[64:67], v[210:213], v[242:245], v[64:67]
	v_mfma_f32_16x16x32_bf16 v[116:119], v[206:209], v[222:225], v[116:119]
	v_mfma_f32_16x16x32_bf16 v[112:115], v[214:217], v[222:225], v[112:115]
	v_mfma_f32_16x16x32_bf16 v[100:103], v[206:209], v[230:233], v[100:103]
	v_mfma_f32_16x16x32_bf16 v[96:99], v[214:217], v[230:233], v[96:99]
	v_mfma_f32_16x16x32_bf16 v[84:87], v[206:209], v[238:241], v[84:87]
	v_mfma_f32_16x16x32_bf16 v[80:83], v[214:217], v[238:241], v[80:83]
	v_mfma_f32_16x16x32_bf16 v[68:71], v[206:209], v[246:249], v[68:71]
	v_mfma_f32_16x16x32_bf16 v[64:67], v[214:217], v[246:249], v[64:67]
	s_setprio 0
	s_barrier
	s_add_u32 s98, s24, s38
	s_addc_u32 s99, s25, s39
	s_add_u32 s100, s64, s38
	s_addc_u32 s101, s65, s39
	s_mov_b32 m0, s6
	s_add_u32 s68, s24, 0x40000
	ds_read_b128 v[218:221], v159 offset:16384
	ds_read_b128 v[222:225], v159 offset:17408
	ds_read_b128 v[226:229], v159 offset:18432
	ds_read_b128 v[230:233], v159 offset:19456
	ds_read_b128 v[234:237], v159 offset:20480
	ds_read_b128 v[238:241], v159 offset:21504
	ds_read_b128 v[242:245], v159 offset:22528
	ds_read_b128 v[246:249], v159 offset:23552
	global_load_lds_dwordx4 v128, s[24:25]
	s_mov_b32 m0, s7
	s_addc_u32 s69, s25, 0
	global_load_lds_dwordx4 v130, s[24:25]
	s_mov_b32 m0, s28
	s_nop 0
	global_load_lds_dwordx4 v128, s[68:69]
	s_mov_b32 m0, s29
	s_nop 0
	global_load_lds_dwordx4 v130, s[68:69]
	s_mov_b32 m0, s2
	s_nop 0
	global_load_lds_dwordx4 v128, s[64:65]
	s_mov_b32 m0, s30
	s_nop 0
	global_load_lds_dwordx4 v130, s[64:65]
	s_waitcnt vmcnt(8)
	s_waitcnt lgkmcnt(0)
	s_barrier
	s_setprio 1
	s_waitcnt lgkmcnt(0)
	v_mfma_f32_16x16x32_bf16 v[60:63], v[160:163], v[218:221], v[60:63]
	v_mfma_f32_16x16x32_bf16 v[56:59], v[188:191], v[218:221], v[56:59]
	v_mfma_f32_16x16x32_bf16 v[44:47], v[160:163], v[226:229], v[44:47]
	v_mfma_f32_16x16x32_bf16 v[40:43], v[188:191], v[226:229], v[40:43]
	v_mfma_f32_16x16x32_bf16 v[28:31], v[160:163], v[234:237], v[28:31]
	v_mfma_f32_16x16x32_bf16 v[24:27], v[188:191], v[234:237], v[24:27]
	v_mfma_f32_16x16x32_bf16 v[12:15], v[160:163], v[242:245], v[12:15]
	v_mfma_f32_16x16x32_bf16 v[8:11], v[188:191], v[242:245], v[8:11]
	v_mfma_f32_16x16x32_bf16 v[60:63], v[184:187], v[222:225], v[60:63]
	v_mfma_f32_16x16x32_bf16 v[56:59], v[198:201], v[222:225], v[56:59]
	v_mfma_f32_16x16x32_bf16 v[44:47], v[184:187], v[230:233], v[44:47]
	v_mfma_f32_16x16x32_bf16 v[40:43], v[198:201], v[230:233], v[40:43]
	v_mfma_f32_16x16x32_bf16 v[28:31], v[184:187], v[238:241], v[28:31]
	v_mfma_f32_16x16x32_bf16 v[24:27], v[198:201], v[238:241], v[24:27]
	v_mfma_f32_16x16x32_bf16 v[12:15], v[184:187], v[246:249], v[12:15]
	v_mfma_f32_16x16x32_bf16 v[8:11], v[198:201], v[246:249], v[8:11]
	s_setprio 0
	s_setprio 1
	v_mfma_f32_16x16x32_bf16 v[52:55], v[202:205], v[218:221], v[52:55]
	v_mfma_f32_16x16x32_bf16 v[48:51], v[210:213], v[218:221], v[48:51]
	v_mfma_f32_16x16x32_bf16 v[36:39], v[202:205], v[226:229], v[36:39]
	v_mfma_f32_16x16x32_bf16 v[32:35], v[210:213], v[226:229], v[32:35]
	v_mfma_f32_16x16x32_bf16 v[20:23], v[202:205], v[234:237], v[20:23]
	v_mfma_f32_16x16x32_bf16 v[16:19], v[210:213], v[234:237], v[16:19]
	v_mfma_f32_16x16x32_bf16 v[4:7], v[202:205], v[242:245], v[4:7]
	v_mfma_f32_16x16x32_bf16 v[0:3], v[210:213], v[242:245], v[0:3]
	v_mfma_f32_16x16x32_bf16 v[52:55], v[206:209], v[222:225], v[52:55]
	v_mfma_f32_16x16x32_bf16 v[48:51], v[214:217], v[222:225], v[48:51]
	v_mfma_f32_16x16x32_bf16 v[36:39], v[206:209], v[230:233], v[36:39]
	v_mfma_f32_16x16x32_bf16 v[32:35], v[214:217], v[230:233], v[32:35]
	v_mfma_f32_16x16x32_bf16 v[20:23], v[206:209], v[238:241], v[20:23]
	v_mfma_f32_16x16x32_bf16 v[16:19], v[214:217], v[238:241], v[16:19]
	v_mfma_f32_16x16x32_bf16 v[4:7], v[206:209], v[246:249], v[4:7]
	v_mfma_f32_16x16x32_bf16 v[0:3], v[214:217], v[246:249], v[0:3]
	s_setprio 0
	s_barrier
	ds_read_b128 v[160:163], v175
	ds_read_b128 v[184:187], v176
	ds_read_b128 v[188:191], v177
	ds_read_b128 v[198:201], v178
	ds_read_b128 v[202:205], v179
	ds_read_b128 v[206:209], v180
	ds_read_b128 v[210:213], v181
	ds_read_b128 v[214:217], v182
	s_add_u32 s64, s64, 0x40000
	s_addc_u32 s65, s65, 0
	s_mov_b32 m0, s31
	ds_read_b128 v[218:221], v159 offset:32768
	ds_read_b128 v[222:225], v159 offset:33792
	ds_read_b128 v[226:229], v159 offset:34816
	ds_read_b128 v[230:233], v159 offset:35840
	ds_read_b128 v[234:237], v159 offset:36864
	ds_read_b128 v[238:241], v159 offset:37888
	ds_read_b128 v[242:245], v159 offset:38912
	ds_read_b128 v[246:249], v159 offset:39936
	global_load_lds_dwordx4 v128, s[64:65]
	s_mov_b32 m0, s33
	s_nop 0
	global_load_lds_dwordx4 v130, s[64:65]
	s_waitcnt vmcnt(8)
	s_waitcnt lgkmcnt(0)
	s_barrier
	s_setprio 1
	s_waitcnt lgkmcnt(0)
	v_mfma_f32_16x16x32_bf16 v[124:127], v[160:163], v[218:221], v[124:127]
	v_mfma_f32_16x16x32_bf16 v[120:123], v[188:191], v[218:221], v[120:123]
	v_mfma_f32_16x16x32_bf16 v[108:111], v[160:163], v[226:229], v[108:111]
	v_mfma_f32_16x16x32_bf16 v[104:107], v[188:191], v[226:229], v[104:107]
	v_mfma_f32_16x16x32_bf16 v[92:95], v[160:163], v[234:237], v[92:95]
	v_mfma_f32_16x16x32_bf16 v[88:91], v[188:191], v[234:237], v[88:91]
	v_mfma_f32_16x16x32_bf16 v[76:79], v[160:163], v[242:245], v[76:79]
	v_mfma_f32_16x16x32_bf16 v[72:75], v[188:191], v[242:245], v[72:75]
	v_mfma_f32_16x16x32_bf16 v[124:127], v[184:187], v[222:225], v[124:127]
	v_mfma_f32_16x16x32_bf16 v[120:123], v[198:201], v[222:225], v[120:123]
	v_mfma_f32_16x16x32_bf16 v[108:111], v[184:187], v[230:233], v[108:111]
	v_mfma_f32_16x16x32_bf16 v[104:107], v[198:201], v[230:233], v[104:107]
	v_mfma_f32_16x16x32_bf16 v[92:95], v[184:187], v[238:241], v[92:95]
	v_mfma_f32_16x16x32_bf16 v[88:91], v[198:201], v[238:241], v[88:91]
	v_mfma_f32_16x16x32_bf16 v[76:79], v[184:187], v[246:249], v[76:79]
	v_mfma_f32_16x16x32_bf16 v[72:75], v[198:201], v[246:249], v[72:75]
	s_setprio 0
	s_setprio 1
	v_mfma_f32_16x16x32_bf16 v[116:119], v[202:205], v[218:221], v[116:119]
	v_mfma_f32_16x16x32_bf16 v[112:115], v[210:213], v[218:221], v[112:115]
	v_mfma_f32_16x16x32_bf16 v[100:103], v[202:205], v[226:229], v[100:103]
	v_mfma_f32_16x16x32_bf16 v[96:99], v[210:213], v[226:229], v[96:99]
	v_mfma_f32_16x16x32_bf16 v[84:87], v[202:205], v[234:237], v[84:87]
	v_mfma_f32_16x16x32_bf16 v[80:83], v[210:213], v[234:237], v[80:83]
	v_mfma_f32_16x16x32_bf16 v[68:71], v[202:205], v[242:245], v[68:71]
	v_mfma_f32_16x16x32_bf16 v[64:67], v[210:213], v[242:245], v[64:67]
	v_mfma_f32_16x16x32_bf16 v[116:119], v[206:209], v[222:225], v[116:119]
	v_mfma_f32_16x16x32_bf16 v[112:115], v[214:217], v[222:225], v[112:115]
	v_mfma_f32_16x16x32_bf16 v[100:103], v[206:209], v[230:233], v[100:103]
	v_mfma_f32_16x16x32_bf16 v[96:99], v[214:217], v[230:233], v[96:99]
	v_mfma_f32_16x16x32_bf16 v[84:87], v[206:209], v[238:241], v[84:87]
	v_mfma_f32_16x16x32_bf16 v[80:83], v[214:217], v[238:241], v[80:83]
	v_mfma_f32_16x16x32_bf16 v[68:71], v[206:209], v[246:249], v[68:71]
	v_mfma_f32_16x16x32_bf16 v[64:67], v[214:217], v[246:249], v[64:67]
	s_setprio 0
	s_barrier
	s_mov_b32 m0, s34
	s_add_u32 s24, s24, 0x40080
	ds_read_b128 v[218:221], v159 offset:49152
	ds_read_b128 v[222:225], v159 offset:50176
	ds_read_b128 v[226:229], v159 offset:51200
	ds_read_b128 v[230:233], v159 offset:52224
	ds_read_b128 v[234:237], v159 offset:53248
	ds_read_b128 v[238:241], v159 offset:54272
	ds_read_b128 v[242:245], v159 offset:55296
	ds_read_b128 v[246:249], v159 offset:56320
	global_load_lds_dwordx4 v128, s[98:99]
	s_mov_b32 m0, s35
	s_addc_u32 s25, s25, 0
	global_load_lds_dwordx4 v130, s[98:99]
	s_mov_b32 m0, s40
	s_nop 0
	global_load_lds_dwordx4 v128, s[24:25]
	s_mov_b32 m0, s41
	s_nop 0
	global_load_lds_dwordx4 v130, s[24:25]
	s_mov_b32 m0, s36
	s_nop 0
	global_load_lds_dwordx4 v128, s[100:101]
	s_mov_b32 m0, s37
	s_nop 0
	global_load_lds_dwordx4 v130, s[100:101]
	s_waitcnt vmcnt(8)
	s_waitcnt lgkmcnt(0)
	s_barrier
	s_setprio 1
	s_waitcnt lgkmcnt(0)
	v_mfma_f32_16x16x32_bf16 v[60:63], v[160:163], v[218:221], v[60:63]
	v_mfma_f32_16x16x32_bf16 v[56:59], v[188:191], v[218:221], v[56:59]
	v_mfma_f32_16x16x32_bf16 v[44:47], v[160:163], v[226:229], v[44:47]
	v_mfma_f32_16x16x32_bf16 v[40:43], v[188:191], v[226:229], v[40:43]
	v_mfma_f32_16x16x32_bf16 v[28:31], v[160:163], v[234:237], v[28:31]
	v_mfma_f32_16x16x32_bf16 v[24:27], v[188:191], v[234:237], v[24:27]
	v_mfma_f32_16x16x32_bf16 v[12:15], v[160:163], v[242:245], v[12:15]
	v_mfma_f32_16x16x32_bf16 v[8:11], v[188:191], v[242:245], v[8:11]
	v_mfma_f32_16x16x32_bf16 v[60:63], v[184:187], v[222:225], v[60:63]
	v_mfma_f32_16x16x32_bf16 v[56:59], v[198:201], v[222:225], v[56:59]
	v_mfma_f32_16x16x32_bf16 v[44:47], v[184:187], v[230:233], v[44:47]
	v_mfma_f32_16x16x32_bf16 v[40:43], v[198:201], v[230:233], v[40:43]
	v_mfma_f32_16x16x32_bf16 v[28:31], v[184:187], v[238:241], v[28:31]
	v_mfma_f32_16x16x32_bf16 v[24:27], v[198:201], v[238:241], v[24:27]
	v_mfma_f32_16x16x32_bf16 v[12:15], v[184:187], v[246:249], v[12:15]
	v_mfma_f32_16x16x32_bf16 v[8:11], v[198:201], v[246:249], v[8:11]
	s_setprio 0
	s_setprio 1
	v_mfma_f32_16x16x32_bf16 v[52:55], v[202:205], v[218:221], v[52:55]
	v_mfma_f32_16x16x32_bf16 v[48:51], v[210:213], v[218:221], v[48:51]
	v_mfma_f32_16x16x32_bf16 v[36:39], v[202:205], v[226:229], v[36:39]
	v_mfma_f32_16x16x32_bf16 v[32:35], v[210:213], v[226:229], v[32:35]
	v_mfma_f32_16x16x32_bf16 v[20:23], v[202:205], v[234:237], v[20:23]
	v_mfma_f32_16x16x32_bf16 v[16:19], v[210:213], v[234:237], v[16:19]
	v_mfma_f32_16x16x32_bf16 v[4:7], v[202:205], v[242:245], v[4:7]
	v_mfma_f32_16x16x32_bf16 v[0:3], v[210:213], v[242:245], v[0:3]
	v_mfma_f32_16x16x32_bf16 v[52:55], v[206:209], v[222:225], v[52:55]
	v_mfma_f32_16x16x32_bf16 v[48:51], v[214:217], v[222:225], v[48:51]
	v_mfma_f32_16x16x32_bf16 v[36:39], v[206:209], v[230:233], v[36:39]
	v_mfma_f32_16x16x32_bf16 v[32:35], v[214:217], v[230:233], v[32:35]
	v_mfma_f32_16x16x32_bf16 v[20:23], v[206:209], v[238:241], v[20:23]
	v_mfma_f32_16x16x32_bf16 v[16:19], v[214:217], v[238:241], v[16:19]
	v_mfma_f32_16x16x32_bf16 v[4:7], v[206:209], v[246:249], v[4:7]
	v_mfma_f32_16x16x32_bf16 v[0:3], v[214:217], v[246:249], v[0:3]
	s_setprio 0
	s_barrier
	s_add_i32 s66, s66, 2
	s_add_u32 s14, s14, 0x100
	s_addc_u32 s15, s15, 0
	s_add_u32 s47, s47, 0x100
	s_addc_u32 s49, s49, 0
	s_cmp_gt_u32 s66, 13
	s_cbranch_scc0 .LBB0_1334
	s_and_b64 vcc, exec, s[42:43]
	s_cbranch_vccz .LBB0_1337
	s_barrier

.LBB0_1487:
	s_lshl_b32 s9, s9, 5
	s_add_i32 s40, s28, 0x18000
	s_mov_b64 s[10:11], 0x80
	s_and_b32 s39, s9, 0x60
	v_lshl_add_u64 v[6:7], v[6:7], 0, s[10:11]
	s_mov_b32 m0, s40
	s_add_i32 s41, s28, 0x1a000
	s_lshl_b32 s38, s5, 13
	s_lshl_b32 s9, s39, 7
	s_waitcnt vmcnt(2)
	s_barrier
	global_load_lds_dwordx4 v[6:7], off
	v_lshl_add_u64 v[4:5], v[4:5], 0, s[10:11]
	s_mov_b32 m0, s41
	s_add_i32 s49, s28, 0x8000
	s_add_i32 s52, s28, 0xa000
	global_load_lds_dwordx4 v[4:5], off
	v_lshl_add_u64 v[2:3], v[2:3], 0, s[10:11]
	s_mov_b32 m0, s49
	s_add_u32 s14, s50, 0x40080
	global_load_lds_dwordx4 v[2:3], off
	v_lshl_add_u64 v[0:1], v[0:1], 0, s[10:11]
	s_mov_b32 m0, s52
	s_addc_u32 s15, s51, 0
	s_add_i32 s53, s28, 0x1c000
	global_load_lds_dwordx4 v[0:1], off
	s_mov_b32 m0, s53
	s_add_i32 s60, s28, 0x1e000
	global_load_lds_dwordx4 v128, s[14:15]
	s_mov_b32 m0, s60
	s_sext_i32_i8 s85, s8
	global_load_lds_dwordx4 v130, s[14:15]
	v_bfe_u32 v0, v8, 4, 2
	v_lshlrev_b32_e32 v2, 4, v0
	v_lshl_or_b32 v153, v0, 2, s39
	v_lshlrev_b32_e32 v0, 13, v9
	v_and_b32_e32 v1, 15, v8
	v_and_b32_e32 v0, 0x7fffc000, v0
	v_lshl_or_b32 v142, s5, 6, v1
	v_lshl_or_b32 v1, v1, 6, v2
	v_lshlrev_b32_e32 v2, 2, v8
	v_lshl_add_u32 v0, v10, 10, v0
	v_and_b32_e32 v2, 32, v2
	v_or_b32_e32 v0, v0, v11
	v_bitop3_b32 v143, v1, s38, v2 bitop3:0xde
	v_bitop3_b32 v2, v1, s9, v2 bitop3:0xde
	s_mov_b64 s[8:9], 0x40080
	v_add_lshl_u32 v0, v0, v12, 1
	v_mov_b32_e32 v1, v129
	v_lshl_add_u64 v[132:133], v[0:1], 0, s[8:9]
	v_lshlrev_b32_e32 v0, 13, v13
	v_and_b32_e32 v0, 0x7fffc000, v0
	v_lshl_add_u32 v0, v14, 10, v0
	s_waitcnt vmcnt(6)
	v_or_b32_e32 v0, v0, v15
	s_cmpk_lt_u32 s4, 0x100
	v_add_lshl_u32 v0, v0, v16, 1
	s_mov_b32 s61, 0x8000
	s_cselect_b64 s[14:15], -1, 0
	s_ashr_i32 s66, s82, 31
	s_mov_b32 s67, s82
	v_lshl_add_u64 v[134:135], v[0:1], 0, s[8:9]
	s_mov_b32 s74, 0
	v_mov_b64_e32 v[136:137], 0x200
	v_mov_b64_e32 v[138:139], 0x1ff
	v_or_b32_e32 v159, 0x10000, v2
	v_add_u32_e32 v160, 0x10400, v2
	v_add_u32_e32 v161, 0x10800, v2
	v_add_u32_e32 v162, 0x10c00, v2
	v_or_b32_e32 v163, 0x14000, v2
	v_add_u32_e32 v164, 0x14400, v2
	v_add_u32_e32 v165, 0x14800, v2
	v_add_u32_e32 v166, 0x14c00, v2
	s_mov_b32 s75, 0xc000
	s_add_i32 s76, s28, 0xc000
	s_add_i32 s77, s28, 0xe000
	v_or_b32_e32 v167, 0x18000, v2
	v_add_u32_e32 v168, 0x18400, v2
	v_add_u32_e32 v169, 0x18800, v2
	v_add_u32_e32 v170, 0x18c00, v2
	v_or_b32_e32 v171, 0x1c000, v2
	v_add_u32_e32 v172, 0x1c400, v2
	v_add_u32_e32 v173, 0x1c800, v2
	v_add_u32_e32 v174, 0x1cc00, v2
	s_mov_b32 s80, 0x3e0f83e1
	s_movk_i32 s81, 0xdf00
	s_movk_i32 s84, 0x4200
	s_barrier
	s_branch .LBB0_1490

.LBB0_1497:
	ds_read_b128 v[176:179], v159
	ds_read_b128 v[180:183], v160
	ds_read_b128 v[184:187], v161
	ds_read_b128 v[188:191], v162
	ds_read_b128 v[198:201], v163
	ds_read_b128 v[202:205], v164
	ds_read_b128 v[206:209], v165
	ds_read_b128 v[210:213], v166
	s_add_u32 s50, s24, 0x100
	s_addc_u32 s51, s25, 0
	s_cmp_eq_u32 s68, 12
	s_cselect_b32 s65, s4, s51
	s_cselect_b32 s64, s5, s50
	s_cselect_b32 s55, s39, s87
	s_cselect_b32 s54, s43, s86
	s_mov_b32 m0, s76
	ds_read_b128 v[214:217], v143
	ds_read_b128 v[218:221], v143 offset:1024
	ds_read_b128 v[222:225], v143 offset:2048
	ds_read_b128 v[226:229], v143 offset:3072
	ds_read_b128 v[230:233], v143 offset:4096
	ds_read_b128 v[234:237], v143 offset:5120
	ds_read_b128 v[238:241], v143 offset:6144
	ds_read_b128 v[242:245], v143 offset:7168
	global_load_lds_dwordx4 v132, s[24:25]
	s_mov_b32 m0, s77
	s_nop 0
	global_load_lds_dwordx4 v134, s[24:25]
	s_waitcnt vmcnt(8)
	s_waitcnt lgkmcnt(0)
	s_barrier
	s_setprio 1
	s_waitcnt lgkmcnt(0)
	v_mfma_f32_16x16x32_bf16 v[124:127], v[176:179], v[214:217], v[124:127]
	v_mfma_f32_16x16x32_bf16 v[120:123], v[184:187], v[214:217], v[120:123]
	v_mfma_f32_16x16x32_bf16 v[108:111], v[176:179], v[222:225], v[108:111]
	v_mfma_f32_16x16x32_bf16 v[104:107], v[184:187], v[222:225], v[104:107]
	v_mfma_f32_16x16x32_bf16 v[92:95], v[176:179], v[230:233], v[92:95]
	v_mfma_f32_16x16x32_bf16 v[88:91], v[184:187], v[230:233], v[88:91]
	v_mfma_f32_16x16x32_bf16 v[76:79], v[176:179], v[238:241], v[76:79]
	v_mfma_f32_16x16x32_bf16 v[72:75], v[184:187], v[238:241], v[72:75]
	v_mfma_f32_16x16x32_bf16 v[124:127], v[180:183], v[218:221], v[124:127]
	v_mfma_f32_16x16x32_bf16 v[120:123], v[188:191], v[218:221], v[120:123]
	v_mfma_f32_16x16x32_bf16 v[108:111], v[180:183], v[226:229], v[108:111]
	v_mfma_f32_16x16x32_bf16 v[104:107], v[188:191], v[226:229], v[104:107]
	v_mfma_f32_16x16x32_bf16 v[92:95], v[180:183], v[234:237], v[92:95]
	v_mfma_f32_16x16x32_bf16 v[88:91], v[188:191], v[234:237], v[88:91]
	v_mfma_f32_16x16x32_bf16 v[76:79], v[180:183], v[242:245], v[76:79]
	v_mfma_f32_16x16x32_bf16 v[72:75], v[188:191], v[242:245], v[72:75]
	s_setprio 0
	s_setprio 1
	v_mfma_f32_16x16x32_bf16 v[116:119], v[198:201], v[214:217], v[116:119]
	v_mfma_f32_16x16x32_bf16 v[112:115], v[206:209], v[214:217], v[112:115]
	v_mfma_f32_16x16x32_bf16 v[100:103], v[198:201], v[222:225], v[100:103]
	v_mfma_f32_16x16x32_bf16 v[96:99], v[206:209], v[222:225], v[96:99]
	v_mfma_f32_16x16x32_bf16 v[84:87], v[198:201], v[230:233], v[84:87]
	v_mfma_f32_16x16x32_bf16 v[80:83], v[206:209], v[230:233], v[80:83]
	v_mfma_f32_16x16x32_bf16 v[68:71], v[198:201], v[238:241], v[68:71]
	v_mfma_f32_16x16x32_bf16 v[64:67], v[206:209], v[238:241], v[64:67]
	v_mfma_f32_16x16x32_bf16 v[116:119], v[202:205], v[218:221], v[116:119]
	v_mfma_f32_16x16x32_bf16 v[112:115], v[210:213], v[218:221], v[112:115]
	v_mfma_f32_16x16x32_bf16 v[100:103], v[202:205], v[226:229], v[100:103]
	v_mfma_f32_16x16x32_bf16 v[96:99], v[210:213], v[226:229], v[96:99]
	v_mfma_f32_16x16x32_bf16 v[84:87], v[202:205], v[234:237], v[84:87]
	v_mfma_f32_16x16x32_bf16 v[80:83], v[210:213], v[234:237], v[80:83]
	v_mfma_f32_16x16x32_bf16 v[68:71], v[202:205], v[242:245], v[68:71]
	v_mfma_f32_16x16x32_bf16 v[64:67], v[210:213], v[242:245], v[64:67]
	s_setprio 0
	s_barrier
	s_add_u32 s98, s54, s10
	s_addc_u32 s99, s55, s11
	s_add_u32 s100, s64, s10
	s_addc_u32 s101, s65, s11
	s_mov_b32 m0, s29
	s_add_u32 s24, s54, 0x40000
	ds_read_b128 v[214:217], v143 offset:16384
	ds_read_b128 v[218:221], v143 offset:17408
	ds_read_b128 v[222:225], v143 offset:18432
	ds_read_b128 v[226:229], v143 offset:19456
	ds_read_b128 v[230:233], v143 offset:20480
	ds_read_b128 v[234:237], v143 offset:21504
	ds_read_b128 v[238:241], v143 offset:22528
	ds_read_b128 v[242:245], v143 offset:23552
	global_load_lds_dwordx4 v128, s[54:55]
	s_mov_b32 m0, s30
	s_addc_u32 s25, s55, 0
	global_load_lds_dwordx4 v130, s[54:55]
	s_mov_b32 m0, s31
	s_nop 0
	global_load_lds_dwordx4 v128, s[24:25]
	s_mov_b32 m0, s33
	s_nop 0
	global_load_lds_dwordx4 v130, s[24:25]
	s_mov_b32 m0, s28
	s_nop 0
	global_load_lds_dwordx4 v128, s[64:65]
	s_mov_b32 m0, s34
	s_nop 0
	global_load_lds_dwordx4 v130, s[64:65]
	s_waitcnt vmcnt(8)
	s_waitcnt lgkmcnt(0)
	s_barrier
	s_setprio 1
	s_waitcnt lgkmcnt(0)
	v_mfma_f32_16x16x32_bf16 v[60:63], v[176:179], v[214:217], v[60:63]
	v_mfma_f32_16x16x32_bf16 v[56:59], v[184:187], v[214:217], v[56:59]
	v_mfma_f32_16x16x32_bf16 v[44:47], v[176:179], v[222:225], v[44:47]
	v_mfma_f32_16x16x32_bf16 v[40:43], v[184:187], v[222:225], v[40:43]
	v_mfma_f32_16x16x32_bf16 v[28:31], v[176:179], v[230:233], v[28:31]
	v_mfma_f32_16x16x32_bf16 v[24:27], v[184:187], v[230:233], v[24:27]
	v_mfma_f32_16x16x32_bf16 v[12:15], v[176:179], v[238:241], v[12:15]
	v_mfma_f32_16x16x32_bf16 v[8:11], v[184:187], v[238:241], v[8:11]
	v_mfma_f32_16x16x32_bf16 v[60:63], v[180:183], v[218:221], v[60:63]
	v_mfma_f32_16x16x32_bf16 v[56:59], v[188:191], v[218:221], v[56:59]
	v_mfma_f32_16x16x32_bf16 v[44:47], v[180:183], v[226:229], v[44:47]
	v_mfma_f32_16x16x32_bf16 v[40:43], v[188:191], v[226:229], v[40:43]
	v_mfma_f32_16x16x32_bf16 v[28:31], v[180:183], v[234:237], v[28:31]
	v_mfma_f32_16x16x32_bf16 v[24:27], v[188:191], v[234:237], v[24:27]
	v_mfma_f32_16x16x32_bf16 v[12:15], v[180:183], v[242:245], v[12:15]
	v_mfma_f32_16x16x32_bf16 v[8:11], v[188:191], v[242:245], v[8:11]
	s_setprio 0
	s_setprio 1
	v_mfma_f32_16x16x32_bf16 v[52:55], v[198:201], v[214:217], v[52:55]
	v_mfma_f32_16x16x32_bf16 v[48:51], v[206:209], v[214:217], v[48:51]
	v_mfma_f32_16x16x32_bf16 v[36:39], v[198:201], v[222:225], v[36:39]
	v_mfma_f32_16x16x32_bf16 v[32:35], v[206:209], v[222:225], v[32:35]
	v_mfma_f32_16x16x32_bf16 v[20:23], v[198:201], v[230:233], v[20:23]
	v_mfma_f32_16x16x32_bf16 v[16:19], v[206:209], v[230:233], v[16:19]
	v_mfma_f32_16x16x32_bf16 v[4:7], v[198:201], v[238:241], v[4:7]
	v_mfma_f32_16x16x32_bf16 v[0:3], v[206:209], v[238:241], v[0:3]
	v_mfma_f32_16x16x32_bf16 v[52:55], v[202:205], v[218:221], v[52:55]
	v_mfma_f32_16x16x32_bf16 v[48:51], v[210:213], v[218:221], v[48:51]
	v_mfma_f32_16x16x32_bf16 v[36:39], v[202:205], v[226:229], v[36:39]
	v_mfma_f32_16x16x32_bf16 v[32:35], v[210:213], v[226:229], v[32:35]
	v_mfma_f32_16x16x32_bf16 v[20:23], v[202:205], v[234:237], v[20:23]
	v_mfma_f32_16x16x32_bf16 v[16:19], v[210:213], v[234:237], v[16:19]
	v_mfma_f32_16x16x32_bf16 v[4:7], v[202:205], v[242:245], v[4:7]
	v_mfma_f32_16x16x32_bf16 v[0:3], v[210:213], v[242:245], v[0:3]
	s_setprio 0
	s_barrier
	ds_read_b128 v[176:179], v167
	ds_read_b128 v[180:183], v168
	ds_read_b128 v[184:187], v169
	ds_read_b128 v[188:191], v170
	ds_read_b128 v[198:201], v171
	ds_read_b128 v[202:205], v172
	ds_read_b128 v[206:209], v173
	ds_read_b128 v[210:213], v174
	s_add_u32 s24, s64, 0x40000
	s_addc_u32 s25, s65, 0
	s_mov_b32 m0, s35
	ds_read_b128 v[214:217], v143 offset:32768
	ds_read_b128 v[218:221], v143 offset:33792
	ds_read_b128 v[222:225], v143 offset:34816
	ds_read_b128 v[226:229], v143 offset:35840
	ds_read_b128 v[230:233], v143 offset:36864
	ds_read_b128 v[234:237], v143 offset:37888
	ds_read_b128 v[238:241], v143 offset:38912
	ds_read_b128 v[242:245], v143 offset:39936
	global_load_lds_dwordx4 v128, s[24:25]
	s_mov_b32 m0, s36
	s_nop 0
	global_load_lds_dwordx4 v130, s[24:25]
	s_waitcnt vmcnt(8)
	s_waitcnt lgkmcnt(0)
	s_barrier
	s_setprio 1
	s_waitcnt lgkmcnt(0)
	v_mfma_f32_16x16x32_bf16 v[124:127], v[176:179], v[214:217], v[124:127]
	v_mfma_f32_16x16x32_bf16 v[120:123], v[184:187], v[214:217], v[120:123]
	v_mfma_f32_16x16x32_bf16 v[108:111], v[176:179], v[222:225], v[108:111]
	v_mfma_f32_16x16x32_bf16 v[104:107], v[184:187], v[222:225], v[104:107]
	v_mfma_f32_16x16x32_bf16 v[92:95], v[176:179], v[230:233], v[92:95]
	v_mfma_f32_16x16x32_bf16 v[88:91], v[184:187], v[230:233], v[88:91]
	v_mfma_f32_16x16x32_bf16 v[76:79], v[176:179], v[238:241], v[76:79]
	v_mfma_f32_16x16x32_bf16 v[72:75], v[184:187], v[238:241], v[72:75]
	v_mfma_f32_16x16x32_bf16 v[124:127], v[180:183], v[218:221], v[124:127]
	v_mfma_f32_16x16x32_bf16 v[120:123], v[188:191], v[218:221], v[120:123]
	v_mfma_f32_16x16x32_bf16 v[108:111], v[180:183], v[226:229], v[108:111]
	v_mfma_f32_16x16x32_bf16 v[104:107], v[188:191], v[226:229], v[104:107]
	v_mfma_f32_16x16x32_bf16 v[92:95], v[180:183], v[234:237], v[92:95]
	v_mfma_f32_16x16x32_bf16 v[88:91], v[188:191], v[234:237], v[88:91]
	v_mfma_f32_16x16x32_bf16 v[76:79], v[180:183], v[242:245], v[76:79]
	v_mfma_f32_16x16x32_bf16 v[72:75], v[188:191], v[242:245], v[72:75]
	s_setprio 0
	s_setprio 1
	v_mfma_f32_16x16x32_bf16 v[116:119], v[198:201], v[214:217], v[116:119]
	v_mfma_f32_16x16x32_bf16 v[112:115], v[206:209], v[214:217], v[112:115]
	v_mfma_f32_16x16x32_bf16 v[100:103], v[198:201], v[222:225], v[100:103]
	v_mfma_f32_16x16x32_bf16 v[96:99], v[206:209], v[222:225], v[96:99]
	v_mfma_f32_16x16x32_bf16 v[84:87], v[198:201], v[230:233], v[84:87]
	v_mfma_f32_16x16x32_bf16 v[80:83], v[206:209], v[230:233], v[80:83]
	v_mfma_f32_16x16x32_bf16 v[68:71], v[198:201], v[238:241], v[68:71]
	v_mfma_f32_16x16x32_bf16 v[64:67], v[206:209], v[238:241], v[64:67]
	v_mfma_f32_16x16x32_bf16 v[116:119], v[202:205], v[218:221], v[116:119]
	v_mfma_f32_16x16x32_bf16 v[112:115], v[210:213], v[218:221], v[112:115]
	v_mfma_f32_16x16x32_bf16 v[100:103], v[202:205], v[226:229], v[100:103]
	v_mfma_f32_16x16x32_bf16 v[96:99], v[210:213], v[226:229], v[96:99]
	v_mfma_f32_16x16x32_bf16 v[84:87], v[202:205], v[234:237], v[84:87]
	v_mfma_f32_16x16x32_bf16 v[80:83], v[210:213], v[234:237], v[80:83]
	v_mfma_f32_16x16x32_bf16 v[68:71], v[202:205], v[242:245], v[68:71]
	v_mfma_f32_16x16x32_bf16 v[64:67], v[210:213], v[242:245], v[64:67]
	s_setprio 0
	s_barrier
	s_mov_b32 m0, s40
	s_add_u32 s24, s54, 0x40080
	ds_read_b128 v[214:217], v143 offset:49152
	ds_read_b128 v[218:221], v143 offset:50176
	ds_read_b128 v[222:225], v143 offset:51200
	ds_read_b128 v[226:229], v143 offset:52224
	ds_read_b128 v[230:233], v143 offset:53248
	ds_read_b128 v[234:237], v143 offset:54272
	ds_read_b128 v[238:241], v143 offset:55296
	ds_read_b128 v[242:245], v143 offset:56320
	global_load_lds_dwordx4 v128, s[98:99]
	s_mov_b32 m0, s41
	s_addc_u32 s25, s55, 0
	global_load_lds_dwordx4 v130, s[98:99]
	s_mov_b32 m0, s53
	s_nop 0
	global_load_lds_dwordx4 v128, s[24:25]
	s_mov_b32 m0, s60
	s_nop 0
	global_load_lds_dwordx4 v130, s[24:25]
	s_mov_b32 m0, s49
	s_nop 0
	global_load_lds_dwordx4 v128, s[100:101]
	s_mov_b32 m0, s52
	s_nop 0
	global_load_lds_dwordx4 v130, s[100:101]
	s_waitcnt vmcnt(8)
	s_waitcnt lgkmcnt(0)
	s_barrier
	s_setprio 1
	s_waitcnt lgkmcnt(0)
	v_mfma_f32_16x16x32_bf16 v[60:63], v[176:179], v[214:217], v[60:63]
	v_mfma_f32_16x16x32_bf16 v[56:59], v[184:187], v[214:217], v[56:59]
	v_mfma_f32_16x16x32_bf16 v[44:47], v[176:179], v[222:225], v[44:47]
	v_mfma_f32_16x16x32_bf16 v[40:43], v[184:187], v[222:225], v[40:43]
	v_mfma_f32_16x16x32_bf16 v[28:31], v[176:179], v[230:233], v[28:31]
	v_mfma_f32_16x16x32_bf16 v[24:27], v[184:187], v[230:233], v[24:27]
	v_mfma_f32_16x16x32_bf16 v[12:15], v[176:179], v[238:241], v[12:15]
	v_mfma_f32_16x16x32_bf16 v[8:11], v[184:187], v[238:241], v[8:11]
	v_mfma_f32_16x16x32_bf16 v[60:63], v[180:183], v[218:221], v[60:63]
	v_mfma_f32_16x16x32_bf16 v[56:59], v[188:191], v[218:221], v[56:59]
	v_mfma_f32_16x16x32_bf16 v[44:47], v[180:183], v[226:229], v[44:47]
	v_mfma_f32_16x16x32_bf16 v[40:43], v[188:191], v[226:229], v[40:43]
	v_mfma_f32_16x16x32_bf16 v[28:31], v[180:183], v[234:237], v[28:31]
	v_mfma_f32_16x16x32_bf16 v[24:27], v[188:191], v[234:237], v[24:27]
	v_mfma_f32_16x16x32_bf16 v[12:15], v[180:183], v[242:245], v[12:15]
	v_mfma_f32_16x16x32_bf16 v[8:11], v[188:191], v[242:245], v[8:11]
	s_setprio 0
	s_setprio 1
	v_mfma_f32_16x16x32_bf16 v[52:55], v[198:201], v[214:217], v[52:55]
	v_mfma_f32_16x16x32_bf16 v[48:51], v[206:209], v[214:217], v[48:51]
	v_mfma_f32_16x16x32_bf16 v[36:39], v[198:201], v[222:225], v[36:39]
	v_mfma_f32_16x16x32_bf16 v[32:35], v[206:209], v[222:225], v[32:35]
	v_mfma_f32_16x16x32_bf16 v[20:23], v[198:201], v[230:233], v[20:23]
	v_mfma_f32_16x16x32_bf16 v[16:19], v[206:209], v[230:233], v[16:19]
	v_mfma_f32_16x16x32_bf16 v[4:7], v[198:201], v[238:241], v[4:7]
	v_mfma_f32_16x16x32_bf16 v[0:3], v[206:209], v[238:241], v[0:3]
	v_mfma_f32_16x16x32_bf16 v[52:55], v[202:205], v[218:221], v[52:55]
	v_mfma_f32_16x16x32_bf16 v[48:51], v[210:213], v[218:221], v[48:51]
	v_mfma_f32_16x16x32_bf16 v[36:39], v[202:205], v[226:229], v[36:39]
	v_mfma_f32_16x16x32_bf16 v[32:35], v[210:213], v[226:229], v[32:35]
	v_mfma_f32_16x16x32_bf16 v[20:23], v[202:205], v[234:237], v[20:23]
	v_mfma_f32_16x16x32_bf16 v[16:19], v[210:213], v[234:237], v[16:19]
	v_mfma_f32_16x16x32_bf16 v[4:7], v[202:205], v[242:245], v[4:7]
	v_mfma_f32_16x16x32_bf16 v[0:3], v[210:213], v[242:245], v[0:3]
	s_setprio 0
	s_barrier
	s_add_i32 s68, s68, 2
	s_add_u32 s86, s86, 0x100
	s_addc_u32 s87, s87, 0
	s_cmp_gt_u32 s68, 13
	s_mov_b64 s[24:25], s[50:51]
	s_cbranch_scc0 .LBB0_1497
	s_and_b64 vcc, exec, s[14:15]
	s_cbranch_vccz .LBB0_1500
	s_barrier

.LBB0_1756:
	s_lshl_b32 s5, s5, 5
	s_add_i32 s35, s6, 0x18000
	s_mov_b64 s[38:39], 0x80
	s_and_b32 s46, s5, 0x60
	v_lshl_add_u64 v[6:7], v[6:7], 0, s[38:39]
	s_mov_b32 m0, s35
	s_add_i32 s36, s6, 0x1a000
	s_lshl_b32 s44, s4, 13
	s_lshl_b32 s5, s46, 7
	s_waitcnt vmcnt(2)
	s_barrier
	global_load_lds_dwordx4 v[6:7], off
	v_lshl_add_u64 v[4:5], v[4:5], 0, s[38:39]
	s_mov_b32 m0, s36
	s_add_i32 s37, s6, 0x8000
	s_add_i32 s40, s6, 0xa000
	global_load_lds_dwordx4 v[4:5], off
	v_lshl_add_u64 v[0:1], v[0:1], 0, s[38:39]
	s_mov_b32 m0, s37
	s_add_u32 s42, s74, 0x40080
	global_load_lds_dwordx4 v[0:1], off
	v_lshl_add_u64 v[0:1], v[2:3], 0, s[38:39]
	s_mov_b32 m0, s40
	s_addc_u32 s43, s75, 0
	s_add_i32 s41, s6, 0x1c000
	global_load_lds_dwordx4 v[0:1], off
	s_mov_b32 m0, s41
	s_add_i32 s45, s6, 0x1e000
	global_load_lds_dwordx4 v160, s[42:43]
	s_mov_b32 m0, s45
	s_cmpk_lt_u32 s9, 0x100
	global_load_lds_dwordx4 v162, s[42:43]
	v_bfe_u32 v0, v8, 4, 2
	v_lshlrev_b32_e32 v2, 4, v0
	v_lshl_or_b32 v198, v0, 2, s46
	v_lshlrev_b32_e32 v0, 13, v9
	v_and_b32_e32 v1, 15, v8
	v_and_b32_e32 v0, 0x7fffc000, v0
	v_lshl_or_b32 v153, s4, 6, v1
	v_lshl_or_b32 v1, v1, 6, v2
	v_lshlrev_b32_e32 v2, 2, v8
	v_lshl_add_u32 v0, v10, 10, v0
	v_and_b32_e32 v2, 32, v2
	v_or_b32_e32 v0, v0, v11
	v_bitop3_b32 v159, v1, s44, v2 bitop3:0xde
	v_bitop3_b32 v2, v1, s5, v2 bitop3:0xde
	s_mov_b64 s[4:5], 0x40080
	v_add_lshl_u32 v0, v0, v12, 1
	v_mov_b32_e32 v1, v161
	v_lshl_add_u64 v[164:165], v[0:1], 0, s[4:5]
	v_lshlrev_b32_e32 v0, 13, v13
	v_and_b32_e32 v0, 0x7fffc000, v0
	v_lshl_add_u32 v0, v14, 10, v0
	s_waitcnt vmcnt(6)
	v_or_b32_e32 v0, v0, v15
	v_add_lshl_u32 v0, v0, v16, 1
	s_sext_i32_i8 s66, s8
	s_movk_i32 s52, 0x100
	s_cselect_b64 s[42:43], -1, 0
	s_ashr_i32 s53, s82, 31
	s_mov_b32 s60, s82
	v_lshl_add_u64 v[166:167], v[0:1], 0, s[4:5]
	s_mov_b32 s61, 0
	v_mov_b64_e32 v[168:169], 0x200
	v_mov_b64_e32 v[170:171], 0x1ff
	v_or_b32_e32 v199, 0x10000, v2
	v_add_u32_e32 v200, 0x10400, v2
	v_add_u32_e32 v201, 0x10800, v2
	v_add_u32_e32 v202, 0x10c00, v2
	v_or_b32_e32 v203, 0x14000, v2
	v_add_u32_e32 v204, 0x14400, v2
	v_add_u32_e32 v205, 0x14800, v2
	v_add_u32_e32 v206, 0x14c00, v2
	s_add_i32 s65, s6, 0xc000
	s_add_i32 s67, s6, 0xe000
	v_or_b32_e32 v207, 0x18000, v2
	v_add_u32_e32 v208, 0x18400, v2
	v_add_u32_e32 v209, 0x18800, v2
	v_add_u32_e32 v210, 0x18c00, v2
	v_or_b32_e32 v211, 0x1c000, v2
	v_add_u32_e32 v212, 0x1c400, v2
	v_add_u32_e32 v213, 0x1c800, v2
	v_add_u32_e32 v214, 0x1cc00, v2
	s_mov_b32 s76, 0x3e0f83e1
	s_movk_i32 s77, 0xdf00
	s_mov_b32 s44, 0x3fd744fd
	v_mov_b32_e32 v215, 0xffffff00
	s_barrier
	s_branch .LBB0_1759

.LBB0_1766:
	ds_read_b128 v[128:131], v199
	ds_read_b128 v[132:135], v200
	ds_read_b128 v[136:139], v201
	ds_read_b128 v[140:143], v202
	ds_read_b128 v[172:175], v203
	ds_read_b128 v[176:179], v204
	ds_read_b128 v[180:183], v205
	ds_read_b128 v[184:187], v206
	s_add_u32 s74, s24, 0x100
	s_addc_u32 s75, s25, 0
	s_cmp_eq_u32 s68, 12
	s_cselect_b32 s85, s4, s75
	s_cselect_b32 s84, s5, s74
	s_cselect_b32 s81, s47, s87
	s_cselect_b32 s80, s49, s86
	s_mov_b32 m0, s65
	ds_read_b128 v[188:191], v159
	ds_read_b128 v[216:219], v159 offset:1024
	ds_read_b128 v[220:223], v159 offset:2048
	ds_read_b128 v[224:227], v159 offset:3072
	ds_read_b128 v[228:231], v159 offset:4096
	ds_read_b128 v[232:235], v159 offset:5120
	ds_read_b128 v[236:239], v159 offset:6144
	ds_read_b128 v[240:243], v159 offset:7168
	global_load_lds_dwordx4 v164, s[24:25]
	s_mov_b32 m0, s67
	s_nop 0
	global_load_lds_dwordx4 v166, s[24:25]
	s_waitcnt vmcnt(8)
	s_waitcnt lgkmcnt(0)
	s_barrier
	s_setprio 1
	s_waitcnt lgkmcnt(0)
	v_mfma_f32_16x16x32_bf16 v[124:127], v[128:131], v[188:191], v[124:127]
	v_mfma_f32_16x16x32_bf16 v[120:123], v[136:139], v[188:191], v[120:123]
	v_mfma_f32_16x16x32_bf16 v[108:111], v[128:131], v[220:223], v[108:111]
	v_mfma_f32_16x16x32_bf16 v[104:107], v[136:139], v[220:223], v[104:107]
	v_mfma_f32_16x16x32_bf16 v[92:95], v[128:131], v[228:231], v[92:95]
	v_mfma_f32_16x16x32_bf16 v[88:91], v[136:139], v[228:231], v[88:91]
	v_mfma_f32_16x16x32_bf16 v[76:79], v[128:131], v[236:239], v[76:79]
	v_mfma_f32_16x16x32_bf16 v[72:75], v[136:139], v[236:239], v[72:75]
	v_mfma_f32_16x16x32_bf16 v[124:127], v[132:135], v[216:219], v[124:127]
	v_mfma_f32_16x16x32_bf16 v[120:123], v[140:143], v[216:219], v[120:123]
	v_mfma_f32_16x16x32_bf16 v[108:111], v[132:135], v[224:227], v[108:111]
	v_mfma_f32_16x16x32_bf16 v[104:107], v[140:143], v[224:227], v[104:107]
	v_mfma_f32_16x16x32_bf16 v[92:95], v[132:135], v[232:235], v[92:95]
	v_mfma_f32_16x16x32_bf16 v[88:91], v[140:143], v[232:235], v[88:91]
	v_mfma_f32_16x16x32_bf16 v[76:79], v[132:135], v[240:243], v[76:79]
	v_mfma_f32_16x16x32_bf16 v[72:75], v[140:143], v[240:243], v[72:75]
	s_setprio 0
	s_setprio 1
	v_mfma_f32_16x16x32_bf16 v[116:119], v[172:175], v[188:191], v[116:119]
	v_mfma_f32_16x16x32_bf16 v[112:115], v[180:183], v[188:191], v[112:115]
	v_mfma_f32_16x16x32_bf16 v[100:103], v[172:175], v[220:223], v[100:103]
	v_mfma_f32_16x16x32_bf16 v[96:99], v[180:183], v[220:223], v[96:99]
	v_mfma_f32_16x16x32_bf16 v[84:87], v[172:175], v[228:231], v[84:87]
	v_mfma_f32_16x16x32_bf16 v[80:83], v[180:183], v[228:231], v[80:83]
	v_mfma_f32_16x16x32_bf16 v[68:71], v[172:175], v[236:239], v[68:71]
	v_mfma_f32_16x16x32_bf16 v[64:67], v[180:183], v[236:239], v[64:67]
	v_mfma_f32_16x16x32_bf16 v[116:119], v[176:179], v[216:219], v[116:119]
	v_mfma_f32_16x16x32_bf16 v[112:115], v[184:187], v[216:219], v[112:115]
	v_mfma_f32_16x16x32_bf16 v[100:103], v[176:179], v[224:227], v[100:103]
	v_mfma_f32_16x16x32_bf16 v[96:99], v[184:187], v[224:227], v[96:99]
	v_mfma_f32_16x16x32_bf16 v[84:87], v[176:179], v[232:235], v[84:87]
	v_mfma_f32_16x16x32_bf16 v[80:83], v[184:187], v[232:235], v[80:83]
	v_mfma_f32_16x16x32_bf16 v[68:71], v[176:179], v[240:243], v[68:71]
	v_mfma_f32_16x16x32_bf16 v[64:67], v[184:187], v[240:243], v[64:67]
	s_setprio 0
	s_barrier
	s_add_u32 s98, s80, s38
	s_addc_u32 s99, s81, s39
	s_add_u32 s100, s84, s38
	s_addc_u32 s101, s85, s39
	s_mov_b32 m0, s7
	s_add_u32 s24, s80, 0x40000
	ds_read_b128 v[188:191], v159 offset:16384
	ds_read_b128 v[216:219], v159 offset:17408
	ds_read_b128 v[220:223], v159 offset:18432
	ds_read_b128 v[224:227], v159 offset:19456
	ds_read_b128 v[228:231], v159 offset:20480
	ds_read_b128 v[232:235], v159 offset:21504
	ds_read_b128 v[236:239], v159 offset:22528
	ds_read_b128 v[240:243], v159 offset:23552
	global_load_lds_dwordx4 v160, s[80:81]
	s_mov_b32 m0, s28
	s_addc_u32 s25, s81, 0
	global_load_lds_dwordx4 v162, s[80:81]
	s_mov_b32 m0, s29
	s_nop 0
	global_load_lds_dwordx4 v160, s[24:25]
	s_mov_b32 m0, s30
	s_nop 0
	global_load_lds_dwordx4 v162, s[24:25]
	s_mov_b32 m0, s6
	s_nop 0
	global_load_lds_dwordx4 v160, s[84:85]
	s_mov_b32 m0, s31
	s_nop 0
	global_load_lds_dwordx4 v162, s[84:85]
	s_waitcnt vmcnt(8)
	s_waitcnt lgkmcnt(0)
	s_barrier
	s_setprio 1
	s_waitcnt lgkmcnt(0)
	v_mfma_f32_16x16x32_bf16 v[60:63], v[128:131], v[188:191], v[60:63]
	v_mfma_f32_16x16x32_bf16 v[56:59], v[136:139], v[188:191], v[56:59]
	v_mfma_f32_16x16x32_bf16 v[44:47], v[128:131], v[220:223], v[44:47]
	v_mfma_f32_16x16x32_bf16 v[40:43], v[136:139], v[220:223], v[40:43]
	v_mfma_f32_16x16x32_bf16 v[28:31], v[128:131], v[228:231], v[28:31]
	v_mfma_f32_16x16x32_bf16 v[24:27], v[136:139], v[228:231], v[24:27]
	v_mfma_f32_16x16x32_bf16 v[12:15], v[128:131], v[236:239], v[12:15]
	v_mfma_f32_16x16x32_bf16 v[8:11], v[136:139], v[236:239], v[8:11]
	v_mfma_f32_16x16x32_bf16 v[60:63], v[132:135], v[216:219], v[60:63]
	v_mfma_f32_16x16x32_bf16 v[56:59], v[140:143], v[216:219], v[56:59]
	v_mfma_f32_16x16x32_bf16 v[44:47], v[132:135], v[224:227], v[44:47]
	v_mfma_f32_16x16x32_bf16 v[40:43], v[140:143], v[224:227], v[40:43]
	v_mfma_f32_16x16x32_bf16 v[28:31], v[132:135], v[232:235], v[28:31]
	v_mfma_f32_16x16x32_bf16 v[24:27], v[140:143], v[232:235], v[24:27]
	v_mfma_f32_16x16x32_bf16 v[12:15], v[132:135], v[240:243], v[12:15]
	v_mfma_f32_16x16x32_bf16 v[8:11], v[140:143], v[240:243], v[8:11]
	s_setprio 0
	s_setprio 1
	v_mfma_f32_16x16x32_bf16 v[52:55], v[172:175], v[188:191], v[52:55]
	v_mfma_f32_16x16x32_bf16 v[48:51], v[180:183], v[188:191], v[48:51]
	v_mfma_f32_16x16x32_bf16 v[36:39], v[172:175], v[220:223], v[36:39]
	v_mfma_f32_16x16x32_bf16 v[32:35], v[180:183], v[220:223], v[32:35]
	v_mfma_f32_16x16x32_bf16 v[20:23], v[172:175], v[228:231], v[20:23]
	v_mfma_f32_16x16x32_bf16 v[16:19], v[180:183], v[228:231], v[16:19]
	v_mfma_f32_16x16x32_bf16 v[4:7], v[172:175], v[236:239], v[4:7]
	v_mfma_f32_16x16x32_bf16 v[0:3], v[180:183], v[236:239], v[0:3]
	v_mfma_f32_16x16x32_bf16 v[52:55], v[176:179], v[216:219], v[52:55]
	v_mfma_f32_16x16x32_bf16 v[48:51], v[184:187], v[216:219], v[48:51]
	v_mfma_f32_16x16x32_bf16 v[36:39], v[176:179], v[224:227], v[36:39]
	v_mfma_f32_16x16x32_bf16 v[32:35], v[184:187], v[224:227], v[32:35]
	v_mfma_f32_16x16x32_bf16 v[20:23], v[176:179], v[232:235], v[20:23]
	v_mfma_f32_16x16x32_bf16 v[16:19], v[184:187], v[232:235], v[16:19]
	v_mfma_f32_16x16x32_bf16 v[4:7], v[176:179], v[240:243], v[4:7]
	v_mfma_f32_16x16x32_bf16 v[0:3], v[184:187], v[240:243], v[0:3]
	s_setprio 0
	s_barrier
	ds_read_b128 v[128:131], v207
	ds_read_b128 v[132:135], v208
	ds_read_b128 v[136:139], v209
	ds_read_b128 v[140:143], v210
	ds_read_b128 v[172:175], v211
	ds_read_b128 v[176:179], v212
	ds_read_b128 v[180:183], v213
	ds_read_b128 v[184:187], v214
	s_add_u32 s24, s84, 0x40000
	s_addc_u32 s25, s85, 0
	s_mov_b32 m0, s33
	ds_read_b128 v[188:191], v159 offset:32768
	ds_read_b128 v[216:219], v159 offset:33792
	ds_read_b128 v[220:223], v159 offset:34816
	ds_read_b128 v[224:227], v159 offset:35840
	ds_read_b128 v[228:231], v159 offset:36864
	ds_read_b128 v[232:235], v159 offset:37888
	ds_read_b128 v[236:239], v159 offset:38912
	ds_read_b128 v[240:243], v159 offset:39936
	global_load_lds_dwordx4 v160, s[24:25]
	s_mov_b32 m0, s34
	s_nop 0
	global_load_lds_dwordx4 v162, s[24:25]
	s_waitcnt vmcnt(8)
	s_waitcnt lgkmcnt(0)
	s_barrier
	s_setprio 1
	s_waitcnt lgkmcnt(0)
	v_mfma_f32_16x16x32_bf16 v[124:127], v[128:131], v[188:191], v[124:127]
	v_mfma_f32_16x16x32_bf16 v[120:123], v[136:139], v[188:191], v[120:123]
	v_mfma_f32_16x16x32_bf16 v[108:111], v[128:131], v[220:223], v[108:111]
	v_mfma_f32_16x16x32_bf16 v[104:107], v[136:139], v[220:223], v[104:107]
	v_mfma_f32_16x16x32_bf16 v[92:95], v[128:131], v[228:231], v[92:95]
	v_mfma_f32_16x16x32_bf16 v[88:91], v[136:139], v[228:231], v[88:91]
	v_mfma_f32_16x16x32_bf16 v[76:79], v[128:131], v[236:239], v[76:79]
	v_mfma_f32_16x16x32_bf16 v[72:75], v[136:139], v[236:239], v[72:75]
	v_mfma_f32_16x16x32_bf16 v[124:127], v[132:135], v[216:219], v[124:127]
	v_mfma_f32_16x16x32_bf16 v[120:123], v[140:143], v[216:219], v[120:123]
	v_mfma_f32_16x16x32_bf16 v[108:111], v[132:135], v[224:227], v[108:111]
	v_mfma_f32_16x16x32_bf16 v[104:107], v[140:143], v[224:227], v[104:107]
	v_mfma_f32_16x16x32_bf16 v[92:95], v[132:135], v[232:235], v[92:95]
	v_mfma_f32_16x16x32_bf16 v[88:91], v[140:143], v[232:235], v[88:91]
	v_mfma_f32_16x16x32_bf16 v[76:79], v[132:135], v[240:243], v[76:79]
	v_mfma_f32_16x16x32_bf16 v[72:75], v[140:143], v[240:243], v[72:75]
	s_setprio 0
	s_setprio 1
	v_mfma_f32_16x16x32_bf16 v[116:119], v[172:175], v[188:191], v[116:119]
	v_mfma_f32_16x16x32_bf16 v[112:115], v[180:183], v[188:191], v[112:115]
	v_mfma_f32_16x16x32_bf16 v[100:103], v[172:175], v[220:223], v[100:103]
	v_mfma_f32_16x16x32_bf16 v[96:99], v[180:183], v[220:223], v[96:99]
	v_mfma_f32_16x16x32_bf16 v[84:87], v[172:175], v[228:231], v[84:87]
	v_mfma_f32_16x16x32_bf16 v[80:83], v[180:183], v[228:231], v[80:83]
	v_mfma_f32_16x16x32_bf16 v[68:71], v[172:175], v[236:239], v[68:71]
	v_mfma_f32_16x16x32_bf16 v[64:67], v[180:183], v[236:239], v[64:67]
	v_mfma_f32_16x16x32_bf16 v[116:119], v[176:179], v[216:219], v[116:119]
	v_mfma_f32_16x16x32_bf16 v[112:115], v[184:187], v[216:219], v[112:115]
	v_mfma_f32_16x16x32_bf16 v[100:103], v[176:179], v[224:227], v[100:103]
	v_mfma_f32_16x16x32_bf16 v[96:99], v[184:187], v[224:227], v[96:99]
	v_mfma_f32_16x16x32_bf16 v[84:87], v[176:179], v[232:235], v[84:87]
	v_mfma_f32_16x16x32_bf16 v[80:83], v[184:187], v[232:235], v[80:83]
	v_mfma_f32_16x16x32_bf16 v[68:71], v[176:179], v[240:243], v[68:71]
	v_mfma_f32_16x16x32_bf16 v[64:67], v[184:187], v[240:243], v[64:67]
	s_setprio 0
	s_barrier
	s_mov_b32 m0, s35
	s_add_u32 s24, s80, 0x40080
	ds_read_b128 v[188:191], v159 offset:49152
	ds_read_b128 v[216:219], v159 offset:50176
	ds_read_b128 v[220:223], v159 offset:51200
	ds_read_b128 v[224:227], v159 offset:52224
	ds_read_b128 v[228:231], v159 offset:53248
	ds_read_b128 v[232:235], v159 offset:54272
	ds_read_b128 v[236:239], v159 offset:55296
	ds_read_b128 v[240:243], v159 offset:56320
	global_load_lds_dwordx4 v160, s[98:99]
	s_mov_b32 m0, s36
	s_addc_u32 s25, s81, 0
	global_load_lds_dwordx4 v162, s[98:99]
	s_mov_b32 m0, s41
	s_nop 0
	global_load_lds_dwordx4 v160, s[24:25]
	s_mov_b32 m0, s45
	s_nop 0
	global_load_lds_dwordx4 v162, s[24:25]
	s_mov_b32 m0, s37
	s_nop 0
	global_load_lds_dwordx4 v160, s[100:101]
	s_mov_b32 m0, s40
	s_nop 0
	global_load_lds_dwordx4 v162, s[100:101]
	s_waitcnt vmcnt(8)
	s_waitcnt lgkmcnt(0)
	s_barrier
	s_setprio 1
	s_waitcnt lgkmcnt(0)
	v_mfma_f32_16x16x32_bf16 v[60:63], v[128:131], v[188:191], v[60:63]
	v_mfma_f32_16x16x32_bf16 v[56:59], v[136:139], v[188:191], v[56:59]
	v_mfma_f32_16x16x32_bf16 v[44:47], v[128:131], v[220:223], v[44:47]
	v_mfma_f32_16x16x32_bf16 v[40:43], v[136:139], v[220:223], v[40:43]
	v_mfma_f32_16x16x32_bf16 v[28:31], v[128:131], v[228:231], v[28:31]
	v_mfma_f32_16x16x32_bf16 v[24:27], v[136:139], v[228:231], v[24:27]
	v_mfma_f32_16x16x32_bf16 v[12:15], v[128:131], v[236:239], v[12:15]
	v_mfma_f32_16x16x32_bf16 v[8:11], v[136:139], v[236:239], v[8:11]
	v_mfma_f32_16x16x32_bf16 v[60:63], v[132:135], v[216:219], v[60:63]
	v_mfma_f32_16x16x32_bf16 v[56:59], v[140:143], v[216:219], v[56:59]
	v_mfma_f32_16x16x32_bf16 v[44:47], v[132:135], v[224:227], v[44:47]
	v_mfma_f32_16x16x32_bf16 v[40:43], v[140:143], v[224:227], v[40:43]
	v_mfma_f32_16x16x32_bf16 v[28:31], v[132:135], v[232:235], v[28:31]
	v_mfma_f32_16x16x32_bf16 v[24:27], v[140:143], v[232:235], v[24:27]
	v_mfma_f32_16x16x32_bf16 v[12:15], v[132:135], v[240:243], v[12:15]
	v_mfma_f32_16x16x32_bf16 v[8:11], v[140:143], v[240:243], v[8:11]
	s_setprio 0
	s_setprio 1
	v_mfma_f32_16x16x32_bf16 v[52:55], v[172:175], v[188:191], v[52:55]
	v_mfma_f32_16x16x32_bf16 v[48:51], v[180:183], v[188:191], v[48:51]
	v_mfma_f32_16x16x32_bf16 v[36:39], v[172:175], v[220:223], v[36:39]
	v_mfma_f32_16x16x32_bf16 v[32:35], v[180:183], v[220:223], v[32:35]
	v_mfma_f32_16x16x32_bf16 v[20:23], v[172:175], v[228:231], v[20:23]
	v_mfma_f32_16x16x32_bf16 v[16:19], v[180:183], v[228:231], v[16:19]
	v_mfma_f32_16x16x32_bf16 v[4:7], v[172:175], v[236:239], v[4:7]
	v_mfma_f32_16x16x32_bf16 v[0:3], v[180:183], v[236:239], v[0:3]
	v_mfma_f32_16x16x32_bf16 v[52:55], v[176:179], v[216:219], v[52:55]
	v_mfma_f32_16x16x32_bf16 v[48:51], v[184:187], v[216:219], v[48:51]
	v_mfma_f32_16x16x32_bf16 v[36:39], v[176:179], v[224:227], v[36:39]
	v_mfma_f32_16x16x32_bf16 v[32:35], v[184:187], v[224:227], v[32:35]
	v_mfma_f32_16x16x32_bf16 v[20:23], v[176:179], v[232:235], v[20:23]
	v_mfma_f32_16x16x32_bf16 v[16:19], v[184:187], v[232:235], v[16:19]
	v_mfma_f32_16x16x32_bf16 v[4:7], v[176:179], v[240:243], v[4:7]
	v_mfma_f32_16x16x32_bf16 v[0:3], v[184:187], v[240:243], v[0:3]
	s_setprio 0
	s_barrier
	s_add_i32 s68, s68, 2
	s_add_u32 s86, s86, 0x100
	s_addc_u32 s87, s87, 0
	s_cmp_gt_u32 s68, 13
	s_mov_b64 s[24:25], s[74:75]
	s_cbranch_scc0 .LBB0_1766
	s_and_b64 vcc, exec, s[42:43]
	s_cbranch_vccz .LBB0_1769
	s_barrier

.LBB0_1908:
	s_lshl_b32 s11, s11, 5
	s_add_i32 s36, s2, 0x18000
	s_mov_b64 s[12:13], 0x80
	s_and_b32 s35, s11, 0x60
	v_lshl_add_u64 v[6:7], v[6:7], 0, s[12:13]
	s_mov_b32 m0, s36
	s_add_i32 s37, s2, 0x1a000
	s_lshl_b32 s38, s5, 13
	s_lshl_b32 s11, s35, 7
	s_waitcnt vmcnt(2)
	s_barrier
	global_load_lds_dwordx4 v[6:7], off
	v_lshl_add_u64 v[4:5], v[4:5], 0, s[12:13]
	s_mov_b32 m0, s37
	s_add_i32 s47, s2, 0x8000
	s_add_i32 s52, s2, 0xa000
	global_load_lds_dwordx4 v[4:5], off
	v_lshl_add_u64 v[0:1], v[0:1], 0, s[12:13]
	s_mov_b32 m0, s47
	s_add_u32 s14, s48, 0x40080
	global_load_lds_dwordx4 v[0:1], off
	v_lshl_add_u64 v[0:1], v[2:3], 0, s[12:13]
	s_mov_b32 m0, s52
	s_addc_u32 s15, s49, 0
	s_add_i32 s53, s2, 0x1c000
	global_load_lds_dwordx4 v[0:1], off
	s_mov_b32 m0, s53
	s_add_i32 s54, s2, 0x1e000
	global_load_lds_dwordx4 v130, s[14:15]
	s_mov_b32 m0, s54
	s_cmpk_lt_u32 s4, 0x100
	global_load_lds_dwordx4 v128, s[14:15]
	v_bfe_u32 v1, v9, 4, 2
	v_and_b32_e32 v0, 15, v9
	v_lshlrev_b32_e32 v2, 4, v1
	v_lshl_or_b32 v140, s5, 6, v0
	v_lshl_or_b32 v0, v0, 6, v2
	v_lshlrev_b32_e32 v2, 2, v9
	v_lshlrev_b32_e32 v142, 2, v1
	v_lshlrev_b32_e32 v1, 14, v12
	v_and_b32_e32 v2, 32, v2
	v_and_b32_e32 v1, 0xffff8000, v1
	v_bitop3_b32 v141, v0, s38, v2 bitop3:0xde
	v_bitop3_b32 v0, v0, s11, v2 bitop3:0xde
	v_lshl_add_u32 v1, v13, 11, v1
	v_and_b32_e32 v2, 1, v12
	v_lshl_or_b32 v1, v2, 6, v1
	v_lshl_add_u32 v132, v14, 1, v1
	v_lshlrev_b32_e32 v1, 14, v8
	v_and_b32_e32 v1, 0xffff8000, v1
	s_waitcnt vmcnt(6)
	v_lshl_add_u32 v1, v10, 11, v1
	v_and_b32_e32 v2, 1, v8
	v_lshl_or_b32 v1, v2, 6, v1
	s_sext_i32_i16 s66, s10
	s_cselect_b64 s[14:15], -1, 0
	s_ashr_i32 s55, s82, 31
	s_mov_b32 s60, s82
	v_mov_b32_e32 v133, v131
	v_lshl_add_u32 v134, v11, 1, v1
	v_mov_b32_e32 v135, v131
	v_mov_b64_e32 v[136:137], 0xb58
	v_mov_b64_e32 v[138:139], 0xb57
	v_or_b32_e32 v143, 0x10000, v0
	v_add_u32_e32 v153, 0x10400, v0
	v_add_u32_e32 v159, 0x10800, v0
	v_add_u32_e32 v160, 0x10c00, v0
	v_or_b32_e32 v161, 0x14000, v0
	v_add_u32_e32 v162, 0x14400, v0
	v_add_u32_e32 v163, 0x14800, v0
	v_add_u32_e32 v164, 0x14c00, v0
	s_add_i32 s61, s2, 0xc000
	s_add_i32 s64, s2, 0xe000
	v_or_b32_e32 v165, 0x18000, v0
	v_add_u32_e32 v166, 0x18400, v0
	v_add_u32_e32 v167, 0x18800, v0
	v_add_u32_e32 v168, 0x18c00, v0
	v_or_b32_e32 v169, 0x1c000, v0
	v_add_u32_e32 v170, 0x1c400, v0
	v_add_u32_e32 v171, 0x1c800, v0
	v_add_u32_e32 v172, 0x1cc00, v0
	s_movk_i32 s65, 0x1600
	s_barrier
	s_branch .LBB0_1911

.LBB0_1914:
	ds_read_b128 v[174:177], v143
	ds_read_b128 v[178:181], v153
	ds_read_b128 v[182:185], v159
	ds_read_b128 v[186:189], v160
	ds_read_b128 v[190:193], v161
	ds_read_b128 v[198:201], v162
	ds_read_b128 v[202:205], v163
	ds_read_b128 v[206:209], v164
	s_add_u32 s48, s24, 0xfffc0080
	s_addc_u32 s49, s25, -1
	s_cmp_eq_u32 s75, 12
	s_cselect_b32 s51, s4, s49
	s_cselect_b32 s50, s5, s48
	s_cselect_b32 s49, s39, s74
	s_cselect_b32 s48, s41, s67
	s_mov_b32 m0, s61
	ds_read_b128 v[210:213], v141
	ds_read_b128 v[214:217], v141 offset:1024
	ds_read_b128 v[218:221], v141 offset:2048
	ds_read_b128 v[222:225], v141 offset:3072
	ds_read_b128 v[226:229], v141 offset:4096
	ds_read_b128 v[230:233], v141 offset:5120
	ds_read_b128 v[234:237], v141 offset:6144
	ds_read_b128 v[238:241], v141 offset:7168
	global_load_lds_dwordx4 v132, s[24:25]
	s_mov_b32 m0, s64
	s_nop 0
	global_load_lds_dwordx4 v134, s[24:25]
	s_waitcnt vmcnt(8)
	s_waitcnt lgkmcnt(0)
	s_barrier
	s_setprio 1
	s_waitcnt lgkmcnt(0)
	v_mfma_f32_16x16x32_bf16 v[124:127], v[174:177], v[210:213], v[124:127]
	v_mfma_f32_16x16x32_bf16 v[120:123], v[182:185], v[210:213], v[120:123]
	v_mfma_f32_16x16x32_bf16 v[108:111], v[174:177], v[218:221], v[108:111]
	v_mfma_f32_16x16x32_bf16 v[104:107], v[182:185], v[218:221], v[104:107]
	v_mfma_f32_16x16x32_bf16 v[92:95], v[174:177], v[226:229], v[92:95]
	v_mfma_f32_16x16x32_bf16 v[88:91], v[182:185], v[226:229], v[88:91]
	v_mfma_f32_16x16x32_bf16 v[76:79], v[174:177], v[234:237], v[76:79]
	v_mfma_f32_16x16x32_bf16 v[72:75], v[182:185], v[234:237], v[72:75]
	v_mfma_f32_16x16x32_bf16 v[124:127], v[178:181], v[214:217], v[124:127]
	v_mfma_f32_16x16x32_bf16 v[120:123], v[186:189], v[214:217], v[120:123]
	v_mfma_f32_16x16x32_bf16 v[108:111], v[178:181], v[222:225], v[108:111]
	v_mfma_f32_16x16x32_bf16 v[104:107], v[186:189], v[222:225], v[104:107]
	v_mfma_f32_16x16x32_bf16 v[92:95], v[178:181], v[230:233], v[92:95]
	v_mfma_f32_16x16x32_bf16 v[88:91], v[186:189], v[230:233], v[88:91]
	v_mfma_f32_16x16x32_bf16 v[76:79], v[178:181], v[238:241], v[76:79]
	v_mfma_f32_16x16x32_bf16 v[72:75], v[186:189], v[238:241], v[72:75]
	s_setprio 0
	s_setprio 1
	v_mfma_f32_16x16x32_bf16 v[116:119], v[190:193], v[210:213], v[116:119]
	v_mfma_f32_16x16x32_bf16 v[112:115], v[202:205], v[210:213], v[112:115]
	v_mfma_f32_16x16x32_bf16 v[100:103], v[190:193], v[218:221], v[100:103]
	v_mfma_f32_16x16x32_bf16 v[96:99], v[202:205], v[218:221], v[96:99]
	v_mfma_f32_16x16x32_bf16 v[84:87], v[190:193], v[226:229], v[84:87]
	v_mfma_f32_16x16x32_bf16 v[80:83], v[202:205], v[226:229], v[80:83]
	v_mfma_f32_16x16x32_bf16 v[68:71], v[190:193], v[234:237], v[68:71]
	v_mfma_f32_16x16x32_bf16 v[64:67], v[202:205], v[234:237], v[64:67]
	v_mfma_f32_16x16x32_bf16 v[116:119], v[198:201], v[214:217], v[116:119]
	v_mfma_f32_16x16x32_bf16 v[112:115], v[206:209], v[214:217], v[112:115]
	v_mfma_f32_16x16x32_bf16 v[100:103], v[198:201], v[222:225], v[100:103]
	v_mfma_f32_16x16x32_bf16 v[96:99], v[206:209], v[222:225], v[96:99]
	v_mfma_f32_16x16x32_bf16 v[84:87], v[198:201], v[230:233], v[84:87]
	v_mfma_f32_16x16x32_bf16 v[80:83], v[206:209], v[230:233], v[80:83]
	v_mfma_f32_16x16x32_bf16 v[68:71], v[198:201], v[238:241], v[68:71]
	v_mfma_f32_16x16x32_bf16 v[64:67], v[206:209], v[238:241], v[64:67]
	s_setprio 0
	s_barrier
	s_add_u32 s98, s48, s12
	s_addc_u32 s99, s49, s13
	s_add_u32 s100, s50, s12
	s_addc_u32 s101, s51, s13
	s_mov_b32 m0, s8
	s_add_u32 s68, s48, 0x40000
	ds_read_b128 v[210:213], v141 offset:16384
	ds_read_b128 v[214:217], v141 offset:17408
	ds_read_b128 v[218:221], v141 offset:18432
	ds_read_b128 v[222:225], v141 offset:19456
	ds_read_b128 v[226:229], v141 offset:20480
	ds_read_b128 v[230:233], v141 offset:21504
	ds_read_b128 v[234:237], v141 offset:22528
	ds_read_b128 v[238:241], v141 offset:23552
	global_load_lds_dwordx4 v130, s[48:49]
	s_mov_b32 m0, s9
	s_addc_u32 s69, s49, 0
	global_load_lds_dwordx4 v128, s[48:49]
	s_mov_b32 m0, s28
	s_nop 0
	global_load_lds_dwordx4 v130, s[68:69]
	s_mov_b32 m0, s29
	s_nop 0
	global_load_lds_dwordx4 v128, s[68:69]
	s_mov_b32 m0, s2
	s_nop 0
	global_load_lds_dwordx4 v130, s[50:51]
	s_mov_b32 m0, s30
	s_nop 0
	global_load_lds_dwordx4 v128, s[50:51]
	s_waitcnt vmcnt(8)
	s_waitcnt lgkmcnt(0)
	s_barrier
	s_setprio 1
	s_waitcnt lgkmcnt(0)
	v_mfma_f32_16x16x32_bf16 v[60:63], v[174:177], v[210:213], v[60:63]
	v_mfma_f32_16x16x32_bf16 v[56:59], v[182:185], v[210:213], v[56:59]
	v_mfma_f32_16x16x32_bf16 v[44:47], v[174:177], v[218:221], v[44:47]
	v_mfma_f32_16x16x32_bf16 v[40:43], v[182:185], v[218:221], v[40:43]
	v_mfma_f32_16x16x32_bf16 v[28:31], v[174:177], v[226:229], v[28:31]
	v_mfma_f32_16x16x32_bf16 v[24:27], v[182:185], v[226:229], v[24:27]
	v_mfma_f32_16x16x32_bf16 v[12:15], v[174:177], v[234:237], v[12:15]
	v_mfma_f32_16x16x32_bf16 v[8:11], v[182:185], v[234:237], v[8:11]
	v_mfma_f32_16x16x32_bf16 v[60:63], v[178:181], v[214:217], v[60:63]
	v_mfma_f32_16x16x32_bf16 v[56:59], v[186:189], v[214:217], v[56:59]
	v_mfma_f32_16x16x32_bf16 v[44:47], v[178:181], v[222:225], v[44:47]
	v_mfma_f32_16x16x32_bf16 v[40:43], v[186:189], v[222:225], v[40:43]
	v_mfma_f32_16x16x32_bf16 v[28:31], v[178:181], v[230:233], v[28:31]
	v_mfma_f32_16x16x32_bf16 v[24:27], v[186:189], v[230:233], v[24:27]
	v_mfma_f32_16x16x32_bf16 v[12:15], v[178:181], v[238:241], v[12:15]
	v_mfma_f32_16x16x32_bf16 v[8:11], v[186:189], v[238:241], v[8:11]
	s_setprio 0
	s_setprio 1
	v_mfma_f32_16x16x32_bf16 v[52:55], v[190:193], v[210:213], v[52:55]
	v_mfma_f32_16x16x32_bf16 v[48:51], v[202:205], v[210:213], v[48:51]
	v_mfma_f32_16x16x32_bf16 v[36:39], v[190:193], v[218:221], v[36:39]
	v_mfma_f32_16x16x32_bf16 v[32:35], v[202:205], v[218:221], v[32:35]
	v_mfma_f32_16x16x32_bf16 v[20:23], v[190:193], v[226:229], v[20:23]
	v_mfma_f32_16x16x32_bf16 v[16:19], v[202:205], v[226:229], v[16:19]
	v_mfma_f32_16x16x32_bf16 v[4:7], v[190:193], v[234:237], v[4:7]
	v_mfma_f32_16x16x32_bf16 v[0:3], v[202:205], v[234:237], v[0:3]
	v_mfma_f32_16x16x32_bf16 v[52:55], v[198:201], v[214:217], v[52:55]
	v_mfma_f32_16x16x32_bf16 v[48:51], v[206:209], v[214:217], v[48:51]
	v_mfma_f32_16x16x32_bf16 v[36:39], v[198:201], v[222:225], v[36:39]
	v_mfma_f32_16x16x32_bf16 v[32:35], v[206:209], v[222:225], v[32:35]
	v_mfma_f32_16x16x32_bf16 v[20:23], v[198:201], v[230:233], v[20:23]
	v_mfma_f32_16x16x32_bf16 v[16:19], v[206:209], v[230:233], v[16:19]
	v_mfma_f32_16x16x32_bf16 v[4:7], v[198:201], v[238:241], v[4:7]
	v_mfma_f32_16x16x32_bf16 v[0:3], v[206:209], v[238:241], v[0:3]
	s_setprio 0
	s_barrier
	ds_read_b128 v[174:177], v165
	ds_read_b128 v[178:181], v166
	ds_read_b128 v[182:185], v167
	ds_read_b128 v[186:189], v168
	ds_read_b128 v[190:193], v169
	ds_read_b128 v[198:201], v170
	ds_read_b128 v[202:205], v171
	ds_read_b128 v[206:209], v172
	s_add_u32 s50, s50, 0x40000
	s_addc_u32 s51, s51, 0
	s_mov_b32 m0, s31
	ds_read_b128 v[210:213], v141 offset:32768
	ds_read_b128 v[214:217], v141 offset:33792
	ds_read_b128 v[218:221], v141 offset:34816
	ds_read_b128 v[222:225], v141 offset:35840
	ds_read_b128 v[226:229], v141 offset:36864
	ds_read_b128 v[230:233], v141 offset:37888
	ds_read_b128 v[234:237], v141 offset:38912
	ds_read_b128 v[238:241], v141 offset:39936
	global_load_lds_dwordx4 v130, s[50:51]
	s_mov_b32 m0, s33
	s_nop 0
	global_load_lds_dwordx4 v128, s[50:51]
	s_waitcnt vmcnt(8)
	s_waitcnt lgkmcnt(0)
	s_barrier
	s_setprio 1
	s_waitcnt lgkmcnt(0)
	v_mfma_f32_16x16x32_bf16 v[124:127], v[174:177], v[210:213], v[124:127]
	v_mfma_f32_16x16x32_bf16 v[120:123], v[182:185], v[210:213], v[120:123]
	v_mfma_f32_16x16x32_bf16 v[108:111], v[174:177], v[218:221], v[108:111]
	v_mfma_f32_16x16x32_bf16 v[104:107], v[182:185], v[218:221], v[104:107]
	v_mfma_f32_16x16x32_bf16 v[92:95], v[174:177], v[226:229], v[92:95]
	v_mfma_f32_16x16x32_bf16 v[88:91], v[182:185], v[226:229], v[88:91]
	v_mfma_f32_16x16x32_bf16 v[76:79], v[174:177], v[234:237], v[76:79]
	v_mfma_f32_16x16x32_bf16 v[72:75], v[182:185], v[234:237], v[72:75]
	v_mfma_f32_16x16x32_bf16 v[124:127], v[178:181], v[214:217], v[124:127]
	v_mfma_f32_16x16x32_bf16 v[120:123], v[186:189], v[214:217], v[120:123]
	v_mfma_f32_16x16x32_bf16 v[108:111], v[178:181], v[222:225], v[108:111]
	v_mfma_f32_16x16x32_bf16 v[104:107], v[186:189], v[222:225], v[104:107]
	v_mfma_f32_16x16x32_bf16 v[92:95], v[178:181], v[230:233], v[92:95]
	v_mfma_f32_16x16x32_bf16 v[88:91], v[186:189], v[230:233], v[88:91]
	v_mfma_f32_16x16x32_bf16 v[76:79], v[178:181], v[238:241], v[76:79]
	v_mfma_f32_16x16x32_bf16 v[72:75], v[186:189], v[238:241], v[72:75]
	s_setprio 0
	s_setprio 1
	v_mfma_f32_16x16x32_bf16 v[116:119], v[190:193], v[210:213], v[116:119]
	v_mfma_f32_16x16x32_bf16 v[112:115], v[202:205], v[210:213], v[112:115]
	v_mfma_f32_16x16x32_bf16 v[100:103], v[190:193], v[218:221], v[100:103]
	v_mfma_f32_16x16x32_bf16 v[96:99], v[202:205], v[218:221], v[96:99]
	v_mfma_f32_16x16x32_bf16 v[84:87], v[190:193], v[226:229], v[84:87]
	v_mfma_f32_16x16x32_bf16 v[80:83], v[202:205], v[226:229], v[80:83]
	v_mfma_f32_16x16x32_bf16 v[68:71], v[190:193], v[234:237], v[68:71]
	v_mfma_f32_16x16x32_bf16 v[64:67], v[202:205], v[234:237], v[64:67]
	v_mfma_f32_16x16x32_bf16 v[116:119], v[198:201], v[214:217], v[116:119]
	v_mfma_f32_16x16x32_bf16 v[112:115], v[206:209], v[214:217], v[112:115]
	v_mfma_f32_16x16x32_bf16 v[100:103], v[198:201], v[222:225], v[100:103]
	v_mfma_f32_16x16x32_bf16 v[96:99], v[206:209], v[222:225], v[96:99]
	v_mfma_f32_16x16x32_bf16 v[84:87], v[198:201], v[230:233], v[84:87]
	v_mfma_f32_16x16x32_bf16 v[80:83], v[206:209], v[230:233], v[80:83]
	v_mfma_f32_16x16x32_bf16 v[68:71], v[198:201], v[238:241], v[68:71]
	v_mfma_f32_16x16x32_bf16 v[64:67], v[206:209], v[238:241], v[64:67]
	s_setprio 0
	s_barrier
	s_mov_b32 m0, s36
	s_add_u32 s48, s48, 0x40080
	ds_read_b128 v[210:213], v141 offset:49152
	ds_read_b128 v[214:217], v141 offset:50176
	ds_read_b128 v[218:221], v141 offset:51200
	ds_read_b128 v[222:225], v141 offset:52224
	ds_read_b128 v[226:229], v141 offset:53248
	ds_read_b128 v[230:233], v141 offset:54272
	ds_read_b128 v[234:237], v141 offset:55296
	ds_read_b128 v[238:241], v141 offset:56320
	global_load_lds_dwordx4 v130, s[98:99]
	s_mov_b32 m0, s37
	s_addc_u32 s49, s49, 0
	global_load_lds_dwordx4 v128, s[98:99]
	s_mov_b32 m0, s53
	s_nop 0
	global_load_lds_dwordx4 v130, s[48:49]
	s_mov_b32 m0, s54
	s_nop 0
	global_load_lds_dwordx4 v128, s[48:49]
	s_mov_b32 m0, s47
	s_nop 0
	global_load_lds_dwordx4 v130, s[100:101]
	s_mov_b32 m0, s52
	s_nop 0
	global_load_lds_dwordx4 v128, s[100:101]
	s_waitcnt vmcnt(8)
	s_waitcnt lgkmcnt(0)
	s_barrier
	s_setprio 1
	s_waitcnt lgkmcnt(0)
	v_mfma_f32_16x16x32_bf16 v[60:63], v[174:177], v[210:213], v[60:63]
	v_mfma_f32_16x16x32_bf16 v[56:59], v[182:185], v[210:213], v[56:59]
	v_mfma_f32_16x16x32_bf16 v[44:47], v[174:177], v[218:221], v[44:47]
	v_mfma_f32_16x16x32_bf16 v[40:43], v[182:185], v[218:221], v[40:43]
	v_mfma_f32_16x16x32_bf16 v[28:31], v[174:177], v[226:229], v[28:31]
	v_mfma_f32_16x16x32_bf16 v[24:27], v[182:185], v[226:229], v[24:27]
	v_mfma_f32_16x16x32_bf16 v[12:15], v[174:177], v[234:237], v[12:15]
	v_mfma_f32_16x16x32_bf16 v[8:11], v[182:185], v[234:237], v[8:11]
	v_mfma_f32_16x16x32_bf16 v[60:63], v[178:181], v[214:217], v[60:63]
	v_mfma_f32_16x16x32_bf16 v[56:59], v[186:189], v[214:217], v[56:59]
	v_mfma_f32_16x16x32_bf16 v[44:47], v[178:181], v[222:225], v[44:47]
	v_mfma_f32_16x16x32_bf16 v[40:43], v[186:189], v[222:225], v[40:43]
	v_mfma_f32_16x16x32_bf16 v[28:31], v[178:181], v[230:233], v[28:31]
	v_mfma_f32_16x16x32_bf16 v[24:27], v[186:189], v[230:233], v[24:27]
	v_mfma_f32_16x16x32_bf16 v[12:15], v[178:181], v[238:241], v[12:15]
	v_mfma_f32_16x16x32_bf16 v[8:11], v[186:189], v[238:241], v[8:11]
	s_setprio 0
	s_setprio 1
	v_mfma_f32_16x16x32_bf16 v[52:55], v[190:193], v[210:213], v[52:55]
	v_mfma_f32_16x16x32_bf16 v[48:51], v[202:205], v[210:213], v[48:51]
	v_mfma_f32_16x16x32_bf16 v[36:39], v[190:193], v[218:221], v[36:39]
	v_mfma_f32_16x16x32_bf16 v[32:35], v[202:205], v[218:221], v[32:35]
	v_mfma_f32_16x16x32_bf16 v[20:23], v[190:193], v[226:229], v[20:23]
	v_mfma_f32_16x16x32_bf16 v[16:19], v[202:205], v[226:229], v[16:19]
	v_mfma_f32_16x16x32_bf16 v[4:7], v[190:193], v[234:237], v[4:7]
	v_mfma_f32_16x16x32_bf16 v[0:3], v[202:205], v[234:237], v[0:3]
	v_mfma_f32_16x16x32_bf16 v[52:55], v[198:201], v[214:217], v[52:55]
	v_mfma_f32_16x16x32_bf16 v[48:51], v[206:209], v[214:217], v[48:51]
	v_mfma_f32_16x16x32_bf16 v[36:39], v[198:201], v[222:225], v[36:39]
	v_mfma_f32_16x16x32_bf16 v[32:35], v[206:209], v[222:225], v[32:35]
	v_mfma_f32_16x16x32_bf16 v[20:23], v[198:201], v[230:233], v[20:23]
	v_mfma_f32_16x16x32_bf16 v[16:19], v[206:209], v[230:233], v[16:19]
	v_mfma_f32_16x16x32_bf16 v[4:7], v[198:201], v[238:241], v[4:7]
	v_mfma_f32_16x16x32_bf16 v[0:3], v[206:209], v[238:241], v[0:3]
	s_setprio 0
	s_barrier
	s_add_i32 s75, s75, 2
	s_add_u32 s24, s24, 0x100
	s_addc_u32 s25, s25, 0
	s_add_u32 s67, s67, 0x100
	s_addc_u32 s74, s74, 0
	s_cmp_gt_u32 s75, 13
	s_cbranch_scc0 .LBB0_1914
	s_and_b64 vcc, exec, s[14:15]
	s_cbranch_vccz .LBB0_1917
	s_barrier

.LBB0_1980:
	s_lshl_b32 s12, s12, 5
	s_add_i32 s33, s6, 0x18000
	s_mov_b64 s[40:41], 0x80
	s_and_b32 s44, s12, 0x60
	v_lshl_add_u64 v[6:7], v[6:7], 0, s[40:41]
	s_mov_b32 m0, s33
	s_add_i32 s34, s6, 0x1a000
	s_lshl_b32 s42, s5, 13
	s_lshl_b32 s43, s44, 7
	s_waitcnt vmcnt(2)
	s_barrier
	global_load_lds_dwordx4 v[6:7], off
	v_lshl_add_u64 v[4:5], v[4:5], 0, s[40:41]
	s_mov_b32 m0, s34
	s_add_i32 s35, s6, 0x8000
	s_add_i32 s36, s6, 0xa000
	global_load_lds_dwordx4 v[4:5], off
	v_lshl_add_u64 v[0:1], v[0:1], 0, s[40:41]
	s_mov_b32 m0, s35
	s_add_u32 s12, s48, 0xb0080
	global_load_lds_dwordx4 v[0:1], off
	v_lshl_add_u64 v[0:1], v[2:3], 0, s[40:41]
	s_mov_b32 m0, s36
	s_addc_u32 s13, s49, 0
	s_add_i32 s37, s6, 0x1c000
	global_load_lds_dwordx4 v[0:1], off
	s_mov_b32 m0, s37
	s_add_i32 s45, s6, 0x1e000
	global_load_lds_dwordx4 v160, s[12:13]
	s_mov_b32 m0, s45
	s_sext_i32_i8 s77, s11
	global_load_lds_dwordx4 v162, s[12:13]
	v_bfe_u32 v0, v8, 4, 2
	v_and_b32_e32 v1, 15, v8
	v_lshlrev_b32_e32 v2, 4, v0
	v_lshl_or_b32 v153, s5, 6, v1
	v_lshl_or_b32 v1, v1, 6, v2
	v_lshlrev_b32_e32 v2, 2, v8
	v_and_b32_e32 v2, 32, v2
	v_bitop3_b32 v159, v1, s42, v2 bitop3:0xde
	v_bitop3_b32 v2, v1, s43, v2 bitop3:0xde
	v_lshl_or_b32 v198, v0, 2, s44
	v_lshrrev_b32_e32 v1, 1, v9
	v_mul_lo_u32 v0, v11, s4
	s_mov_b32 s5, 0xb000
	s_cmpk_lt_u32 s10, 0x100
	v_mad_u64_u32 v[0:1], s[10:11], v1, s5, v[0:1]
	v_or_b32_e32 v0, v0, v10
	s_mov_b64 s[12:13], 0xb0080
	v_add_lshl_u32 v0, v0, v12, 1
	v_mov_b32_e32 v1, v161
	v_lshl_add_u64 v[164:165], v[0:1], 0, s[12:13]
	v_lshrrev_b32_e32 v1, 1, v13
	v_mul_lo_u32 v0, v14, s4
	v_mad_u64_u32 v[0:1], s[4:5], v1, s5, v[0:1]
	s_waitcnt vmcnt(6)
	v_or_b32_e32 v0, v0, v15
	v_add_lshl_u32 v0, v0, v16, 1
	v_mov_b32_e32 v1, v161
	s_movk_i32 s52, 0x100
	s_cselect_b64 s[42:43], -1, 0
	s_ashr_i32 s53, s82, 31
	s_mov_b32 s60, s82
	v_lshl_add_u64 v[166:167], v[0:1], 0, s[12:13]
	s_mov_b32 s61, 0
	v_mov_b64_e32 v[168:169], 0x200
	v_mov_b64_e32 v[170:171], 0x1ff
	v_or_b32_e32 v199, 0x10000, v2
	v_add_u32_e32 v200, 0x10400, v2
	v_add_u32_e32 v201, 0x10800, v2
	v_add_u32_e32 v202, 0x10c00, v2
	v_or_b32_e32 v203, 0x14000, v2
	v_add_u32_e32 v204, 0x14400, v2
	v_add_u32_e32 v205, 0x14800, v2
	v_add_u32_e32 v206, 0x14c00, v2
	s_add_i32 s64, s6, 0xc000
	s_add_i32 s65, s6, 0xe000
	v_or_b32_e32 v207, 0x18000, v2
	v_add_u32_e32 v208, 0x18400, v2
	v_add_u32_e32 v209, 0x18800, v2
	v_add_u32_e32 v210, 0x18c00, v2
	v_or_b32_e32 v211, 0x1c000, v2
	v_add_u32_e32 v212, 0x1c400, v2
	v_add_u32_e32 v213, 0x1c800, v2
	v_add_u32_e32 v214, 0x1cc00, v2
	s_mov_b32 s67, 0x3e0f83e1
	s_movk_i32 s74, 0xdf00
	s_mov_b32 s44, 0x3fd744fd
	v_mov_b32_e32 v215, 0xffffff00
	s_barrier
	s_branch .LBB0_1983

.LBB0_1994:
	ds_read_b128 v[128:131], v199
	ds_read_b128 v[132:135], v200
	ds_read_b128 v[136:139], v201
	ds_read_b128 v[140:143], v202
	ds_read_b128 v[172:175], v203
	ds_read_b128 v[176:179], v204
	ds_read_b128 v[180:183], v205
	ds_read_b128 v[184:187], v206
	s_add_u32 s48, s24, 0x100
	s_addc_u32 s49, s25, 0
	s_cmp_eq_u32 s68, 40
	s_cselect_b32 s55, s13, s49
	s_cselect_b32 s54, s12, s48
	s_cselect_b32 s51, s47, s5
	s_cselect_b32 s50, s46, s4
	s_mov_b32 m0, s64
	ds_read_b128 v[188:191], v159
	ds_read_b128 v[216:219], v159 offset:1024
	ds_read_b128 v[220:223], v159 offset:2048
	ds_read_b128 v[224:227], v159 offset:3072
	ds_read_b128 v[228:231], v159 offset:4096
	ds_read_b128 v[232:235], v159 offset:5120
	ds_read_b128 v[236:239], v159 offset:6144
	ds_read_b128 v[240:243], v159 offset:7168
	global_load_lds_dwordx4 v164, s[24:25]
	s_mov_b32 m0, s65
	s_nop 0
	global_load_lds_dwordx4 v166, s[24:25]
	s_waitcnt vmcnt(8)
	s_waitcnt lgkmcnt(0)
	s_barrier
	s_setprio 1
	s_waitcnt lgkmcnt(0)
	v_mfma_f32_16x16x32_bf16 v[124:127], v[128:131], v[188:191], v[124:127]
	v_mfma_f32_16x16x32_bf16 v[120:123], v[136:139], v[188:191], v[120:123]
	v_mfma_f32_16x16x32_bf16 v[108:111], v[128:131], v[220:223], v[108:111]
	v_mfma_f32_16x16x32_bf16 v[104:107], v[136:139], v[220:223], v[104:107]
	v_mfma_f32_16x16x32_bf16 v[92:95], v[128:131], v[228:231], v[92:95]
	v_mfma_f32_16x16x32_bf16 v[88:91], v[136:139], v[228:231], v[88:91]
	v_mfma_f32_16x16x32_bf16 v[76:79], v[128:131], v[236:239], v[76:79]
	v_mfma_f32_16x16x32_bf16 v[72:75], v[136:139], v[236:239], v[72:75]
	v_mfma_f32_16x16x32_bf16 v[124:127], v[132:135], v[216:219], v[124:127]
	v_mfma_f32_16x16x32_bf16 v[120:123], v[140:143], v[216:219], v[120:123]
	v_mfma_f32_16x16x32_bf16 v[108:111], v[132:135], v[224:227], v[108:111]
	v_mfma_f32_16x16x32_bf16 v[104:107], v[140:143], v[224:227], v[104:107]
	v_mfma_f32_16x16x32_bf16 v[92:95], v[132:135], v[232:235], v[92:95]
	v_mfma_f32_16x16x32_bf16 v[88:91], v[140:143], v[232:235], v[88:91]
	v_mfma_f32_16x16x32_bf16 v[76:79], v[132:135], v[240:243], v[76:79]
	v_mfma_f32_16x16x32_bf16 v[72:75], v[140:143], v[240:243], v[72:75]
	s_setprio 0
	s_setprio 1
	v_mfma_f32_16x16x32_bf16 v[116:119], v[172:175], v[188:191], v[116:119]
	v_mfma_f32_16x16x32_bf16 v[112:115], v[180:183], v[188:191], v[112:115]
	v_mfma_f32_16x16x32_bf16 v[100:103], v[172:175], v[220:223], v[100:103]
	v_mfma_f32_16x16x32_bf16 v[96:99], v[180:183], v[220:223], v[96:99]
	v_mfma_f32_16x16x32_bf16 v[84:87], v[172:175], v[228:231], v[84:87]
	v_mfma_f32_16x16x32_bf16 v[80:83], v[180:183], v[228:231], v[80:83]
	v_mfma_f32_16x16x32_bf16 v[68:71], v[172:175], v[236:239], v[68:71]
	v_mfma_f32_16x16x32_bf16 v[64:67], v[180:183], v[236:239], v[64:67]
	v_mfma_f32_16x16x32_bf16 v[116:119], v[176:179], v[216:219], v[116:119]
	v_mfma_f32_16x16x32_bf16 v[112:115], v[184:187], v[216:219], v[112:115]
	v_mfma_f32_16x16x32_bf16 v[100:103], v[176:179], v[224:227], v[100:103]
	v_mfma_f32_16x16x32_bf16 v[96:99], v[184:187], v[224:227], v[96:99]
	v_mfma_f32_16x16x32_bf16 v[84:87], v[176:179], v[232:235], v[84:87]
	v_mfma_f32_16x16x32_bf16 v[80:83], v[184:187], v[232:235], v[80:83]
	v_mfma_f32_16x16x32_bf16 v[68:71], v[176:179], v[240:243], v[68:71]
	v_mfma_f32_16x16x32_bf16 v[64:67], v[184:187], v[240:243], v[64:67]
	s_setprio 0
	s_barrier
	s_add_u32 s98, s50, s40
	s_addc_u32 s99, s51, s41
	s_add_u32 s100, s54, s40
	s_addc_u32 s101, s55, s41
	s_mov_b32 m0, s7
	s_add_u32 s24, s50, 0xb0000
	ds_read_b128 v[188:191], v159 offset:16384
	ds_read_b128 v[216:219], v159 offset:17408
	ds_read_b128 v[220:223], v159 offset:18432
	ds_read_b128 v[224:227], v159 offset:19456
	ds_read_b128 v[228:231], v159 offset:20480
	ds_read_b128 v[232:235], v159 offset:21504
	ds_read_b128 v[236:239], v159 offset:22528
	ds_read_b128 v[240:243], v159 offset:23552
	global_load_lds_dwordx4 v160, s[50:51]
	s_mov_b32 m0, s8
	s_addc_u32 s25, s51, 0
	global_load_lds_dwordx4 v162, s[50:51]
	s_mov_b32 m0, s9
	s_nop 0
	global_load_lds_dwordx4 v160, s[24:25]
	s_mov_b32 m0, s28
	s_nop 0
	global_load_lds_dwordx4 v162, s[24:25]
	s_mov_b32 m0, s6
	s_nop 0
	global_load_lds_dwordx4 v160, s[54:55]
	s_mov_b32 m0, s29
	s_nop 0
	global_load_lds_dwordx4 v162, s[54:55]
	s_waitcnt vmcnt(8)
	s_waitcnt lgkmcnt(0)
	s_barrier
	s_setprio 1
	s_waitcnt lgkmcnt(0)
	v_mfma_f32_16x16x32_bf16 v[60:63], v[128:131], v[188:191], v[60:63]
	v_mfma_f32_16x16x32_bf16 v[56:59], v[136:139], v[188:191], v[56:59]
	v_mfma_f32_16x16x32_bf16 v[44:47], v[128:131], v[220:223], v[44:47]
	v_mfma_f32_16x16x32_bf16 v[40:43], v[136:139], v[220:223], v[40:43]
	v_mfma_f32_16x16x32_bf16 v[28:31], v[128:131], v[228:231], v[28:31]
	v_mfma_f32_16x16x32_bf16 v[24:27], v[136:139], v[228:231], v[24:27]
	v_mfma_f32_16x16x32_bf16 v[12:15], v[128:131], v[236:239], v[12:15]
	v_mfma_f32_16x16x32_bf16 v[8:11], v[136:139], v[236:239], v[8:11]
	v_mfma_f32_16x16x32_bf16 v[60:63], v[132:135], v[216:219], v[60:63]
	v_mfma_f32_16x16x32_bf16 v[56:59], v[140:143], v[216:219], v[56:59]
	v_mfma_f32_16x16x32_bf16 v[44:47], v[132:135], v[224:227], v[44:47]
	v_mfma_f32_16x16x32_bf16 v[40:43], v[140:143], v[224:227], v[40:43]
	v_mfma_f32_16x16x32_bf16 v[28:31], v[132:135], v[232:235], v[28:31]
	v_mfma_f32_16x16x32_bf16 v[24:27], v[140:143], v[232:235], v[24:27]
	v_mfma_f32_16x16x32_bf16 v[12:15], v[132:135], v[240:243], v[12:15]
	v_mfma_f32_16x16x32_bf16 v[8:11], v[140:143], v[240:243], v[8:11]
	s_setprio 0
	s_setprio 1
	v_mfma_f32_16x16x32_bf16 v[52:55], v[172:175], v[188:191], v[52:55]
	v_mfma_f32_16x16x32_bf16 v[48:51], v[180:183], v[188:191], v[48:51]
	v_mfma_f32_16x16x32_bf16 v[36:39], v[172:175], v[220:223], v[36:39]
	v_mfma_f32_16x16x32_bf16 v[32:35], v[180:183], v[220:223], v[32:35]
	v_mfma_f32_16x16x32_bf16 v[20:23], v[172:175], v[228:231], v[20:23]
	v_mfma_f32_16x16x32_bf16 v[16:19], v[180:183], v[228:231], v[16:19]
	v_mfma_f32_16x16x32_bf16 v[4:7], v[172:175], v[236:239], v[4:7]
	v_mfma_f32_16x16x32_bf16 v[0:3], v[180:183], v[236:239], v[0:3]
	v_mfma_f32_16x16x32_bf16 v[52:55], v[176:179], v[216:219], v[52:55]
	v_mfma_f32_16x16x32_bf16 v[48:51], v[184:187], v[216:219], v[48:51]
	v_mfma_f32_16x16x32_bf16 v[36:39], v[176:179], v[224:227], v[36:39]
	v_mfma_f32_16x16x32_bf16 v[32:35], v[184:187], v[224:227], v[32:35]
	v_mfma_f32_16x16x32_bf16 v[20:23], v[176:179], v[232:235], v[20:23]
	v_mfma_f32_16x16x32_bf16 v[16:19], v[184:187], v[232:235], v[16:19]
	v_mfma_f32_16x16x32_bf16 v[4:7], v[176:179], v[240:243], v[4:7]
	v_mfma_f32_16x16x32_bf16 v[0:3], v[184:187], v[240:243], v[0:3]
	s_setprio 0
	s_barrier
	ds_read_b128 v[128:131], v207
	ds_read_b128 v[132:135], v208
	ds_read_b128 v[136:139], v209
	ds_read_b128 v[140:143], v210
	ds_read_b128 v[172:175], v211
	ds_read_b128 v[176:179], v212
	ds_read_b128 v[180:183], v213
	ds_read_b128 v[184:187], v214
	s_add_u32 s24, s54, 0xb0000
	s_addc_u32 s25, s55, 0
	s_mov_b32 m0, s30
	ds_read_b128 v[188:191], v159 offset:32768
	ds_read_b128 v[216:219], v159 offset:33792
	ds_read_b128 v[220:223], v159 offset:34816
	ds_read_b128 v[224:227], v159 offset:35840
	ds_read_b128 v[228:231], v159 offset:36864
	ds_read_b128 v[232:235], v159 offset:37888
	ds_read_b128 v[236:239], v159 offset:38912
	ds_read_b128 v[240:243], v159 offset:39936
	global_load_lds_dwordx4 v160, s[24:25]
	s_mov_b32 m0, s31
	s_nop 0
	global_load_lds_dwordx4 v162, s[24:25]
	s_waitcnt vmcnt(8)
	s_waitcnt lgkmcnt(0)
	s_barrier
	s_setprio 1
	s_waitcnt lgkmcnt(0)
	v_mfma_f32_16x16x32_bf16 v[124:127], v[128:131], v[188:191], v[124:127]
	v_mfma_f32_16x16x32_bf16 v[120:123], v[136:139], v[188:191], v[120:123]
	v_mfma_f32_16x16x32_bf16 v[108:111], v[128:131], v[220:223], v[108:111]
	v_mfma_f32_16x16x32_bf16 v[104:107], v[136:139], v[220:223], v[104:107]
	v_mfma_f32_16x16x32_bf16 v[92:95], v[128:131], v[228:231], v[92:95]
	v_mfma_f32_16x16x32_bf16 v[88:91], v[136:139], v[228:231], v[88:91]
	v_mfma_f32_16x16x32_bf16 v[76:79], v[128:131], v[236:239], v[76:79]
	v_mfma_f32_16x16x32_bf16 v[72:75], v[136:139], v[236:239], v[72:75]
	v_mfma_f32_16x16x32_bf16 v[124:127], v[132:135], v[216:219], v[124:127]
	v_mfma_f32_16x16x32_bf16 v[120:123], v[140:143], v[216:219], v[120:123]
	v_mfma_f32_16x16x32_bf16 v[108:111], v[132:135], v[224:227], v[108:111]
	v_mfma_f32_16x16x32_bf16 v[104:107], v[140:143], v[224:227], v[104:107]
	v_mfma_f32_16x16x32_bf16 v[92:95], v[132:135], v[232:235], v[92:95]
	v_mfma_f32_16x16x32_bf16 v[88:91], v[140:143], v[232:235], v[88:91]
	v_mfma_f32_16x16x32_bf16 v[76:79], v[132:135], v[240:243], v[76:79]
	v_mfma_f32_16x16x32_bf16 v[72:75], v[140:143], v[240:243], v[72:75]
	s_setprio 0
	s_setprio 1
	v_mfma_f32_16x16x32_bf16 v[116:119], v[172:175], v[188:191], v[116:119]
	v_mfma_f32_16x16x32_bf16 v[112:115], v[180:183], v[188:191], v[112:115]
	v_mfma_f32_16x16x32_bf16 v[100:103], v[172:175], v[220:223], v[100:103]
	v_mfma_f32_16x16x32_bf16 v[96:99], v[180:183], v[220:223], v[96:99]
	v_mfma_f32_16x16x32_bf16 v[84:87], v[172:175], v[228:231], v[84:87]
	v_mfma_f32_16x16x32_bf16 v[80:83], v[180:183], v[228:231], v[80:83]
	v_mfma_f32_16x16x32_bf16 v[68:71], v[172:175], v[236:239], v[68:71]
	v_mfma_f32_16x16x32_bf16 v[64:67], v[180:183], v[236:239], v[64:67]
	v_mfma_f32_16x16x32_bf16 v[116:119], v[176:179], v[216:219], v[116:119]
	v_mfma_f32_16x16x32_bf16 v[112:115], v[184:187], v[216:219], v[112:115]
	v_mfma_f32_16x16x32_bf16 v[100:103], v[176:179], v[224:227], v[100:103]
	v_mfma_f32_16x16x32_bf16 v[96:99], v[184:187], v[224:227], v[96:99]
	v_mfma_f32_16x16x32_bf16 v[84:87], v[176:179], v[232:235], v[84:87]
	v_mfma_f32_16x16x32_bf16 v[80:83], v[184:187], v[232:235], v[80:83]
	v_mfma_f32_16x16x32_bf16 v[68:71], v[176:179], v[240:243], v[68:71]
	v_mfma_f32_16x16x32_bf16 v[64:67], v[184:187], v[240:243], v[64:67]
	s_setprio 0
	s_barrier
	s_mov_b32 m0, s33
	s_add_u32 s24, s50, 0xb0080
	ds_read_b128 v[188:191], v159 offset:49152
	ds_read_b128 v[216:219], v159 offset:50176
	ds_read_b128 v[220:223], v159 offset:51200
	ds_read_b128 v[224:227], v159 offset:52224
	ds_read_b128 v[228:231], v159 offset:53248
	ds_read_b128 v[232:235], v159 offset:54272
	ds_read_b128 v[236:239], v159 offset:55296
	ds_read_b128 v[240:243], v159 offset:56320
	global_load_lds_dwordx4 v160, s[98:99]
	s_mov_b32 m0, s34
	s_addc_u32 s25, s51, 0
	global_load_lds_dwordx4 v162, s[98:99]
	s_mov_b32 m0, s37
	s_nop 0
	global_load_lds_dwordx4 v160, s[24:25]
	s_mov_b32 m0, s45
	s_nop 0
	global_load_lds_dwordx4 v162, s[24:25]
	s_mov_b32 m0, s35
	s_nop 0
	global_load_lds_dwordx4 v160, s[100:101]
	s_mov_b32 m0, s36
	s_nop 0
	global_load_lds_dwordx4 v162, s[100:101]
	s_waitcnt vmcnt(8)
	s_waitcnt lgkmcnt(0)
	s_barrier
	s_setprio 1
	s_waitcnt lgkmcnt(0)
	v_mfma_f32_16x16x32_bf16 v[60:63], v[128:131], v[188:191], v[60:63]
	v_mfma_f32_16x16x32_bf16 v[56:59], v[136:139], v[188:191], v[56:59]
	v_mfma_f32_16x16x32_bf16 v[44:47], v[128:131], v[220:223], v[44:47]
	v_mfma_f32_16x16x32_bf16 v[40:43], v[136:139], v[220:223], v[40:43]
	v_mfma_f32_16x16x32_bf16 v[28:31], v[128:131], v[228:231], v[28:31]
	v_mfma_f32_16x16x32_bf16 v[24:27], v[136:139], v[228:231], v[24:27]
	v_mfma_f32_16x16x32_bf16 v[12:15], v[128:131], v[236:239], v[12:15]
	v_mfma_f32_16x16x32_bf16 v[8:11], v[136:139], v[236:239], v[8:11]
	v_mfma_f32_16x16x32_bf16 v[60:63], v[132:135], v[216:219], v[60:63]
	v_mfma_f32_16x16x32_bf16 v[56:59], v[140:143], v[216:219], v[56:59]
	v_mfma_f32_16x16x32_bf16 v[44:47], v[132:135], v[224:227], v[44:47]
	v_mfma_f32_16x16x32_bf16 v[40:43], v[140:143], v[224:227], v[40:43]
	v_mfma_f32_16x16x32_bf16 v[28:31], v[132:135], v[232:235], v[28:31]
	v_mfma_f32_16x16x32_bf16 v[24:27], v[140:143], v[232:235], v[24:27]
	v_mfma_f32_16x16x32_bf16 v[12:15], v[132:135], v[240:243], v[12:15]
	v_mfma_f32_16x16x32_bf16 v[8:11], v[140:143], v[240:243], v[8:11]
	s_setprio 0
	s_setprio 1
	v_mfma_f32_16x16x32_bf16 v[52:55], v[172:175], v[188:191], v[52:55]
	v_mfma_f32_16x16x32_bf16 v[48:51], v[180:183], v[188:191], v[48:51]
	v_mfma_f32_16x16x32_bf16 v[36:39], v[172:175], v[220:223], v[36:39]
	v_mfma_f32_16x16x32_bf16 v[32:35], v[180:183], v[220:223], v[32:35]
	v_mfma_f32_16x16x32_bf16 v[20:23], v[172:175], v[228:231], v[20:23]
	v_mfma_f32_16x16x32_bf16 v[16:19], v[180:183], v[228:231], v[16:19]
	v_mfma_f32_16x16x32_bf16 v[4:7], v[172:175], v[236:239], v[4:7]
	v_mfma_f32_16x16x32_bf16 v[0:3], v[180:183], v[236:239], v[0:3]
	v_mfma_f32_16x16x32_bf16 v[52:55], v[176:179], v[216:219], v[52:55]
	v_mfma_f32_16x16x32_bf16 v[48:51], v[184:187], v[216:219], v[48:51]
	v_mfma_f32_16x16x32_bf16 v[36:39], v[176:179], v[224:227], v[36:39]
	v_mfma_f32_16x16x32_bf16 v[32:35], v[184:187], v[224:227], v[32:35]
	v_mfma_f32_16x16x32_bf16 v[20:23], v[176:179], v[232:235], v[20:23]
	v_mfma_f32_16x16x32_bf16 v[16:19], v[184:187], v[232:235], v[16:19]
	v_mfma_f32_16x16x32_bf16 v[4:7], v[176:179], v[240:243], v[4:7]
	v_mfma_f32_16x16x32_bf16 v[0:3], v[184:187], v[240:243], v[0:3]
	s_setprio 0
	s_barrier
	s_add_i32 s68, s68, 2
	s_add_u32 s4, s4, 0x100
	s_addc_u32 s5, s5, 0
	s_cmp_gt_u32 s68, 41
	s_mov_b64 s[24:25], s[48:49]
	s_cbranch_scc0 .LBB0_1994
	s_and_b64 vcc, exec, s[42:43]
	s_cbranch_vccz .LBB0_1997
	s_barrier

.LBB0_2142:
	s_lshl_b32 s10, s10, 5
	s_add_i32 s31, s2, 0x18000
	s_mov_b64 s[42:43], 0x80
	s_and_b32 s15, s10, 0x60
	v_lshl_add_u64 v[6:7], v[6:7], 0, s[42:43]
	s_mov_b32 m0, s31
	s_add_i32 s33, s2, 0x1a000
	s_lshl_b32 s13, s5, 13
	s_lshl_b32 s24, s15, 7
	s_waitcnt vmcnt(2)
	s_barrier
	global_load_lds_dwordx4 v[6:7], off
	v_lshl_add_u64 v[4:5], v[4:5], 0, s[42:43]
	s_mov_b32 m0, s33
	s_add_i32 s34, s2, 0x8000
	s_add_i32 s35, s2, 0xa000
	global_load_lds_dwordx4 v[4:5], off
	v_lshl_add_u64 v[0:1], v[0:1], 0, s[42:43]
	s_mov_b32 m0, s34
	s_add_u32 s10, s18, 0x40080
	global_load_lds_dwordx4 v[0:1], off
	v_lshl_add_u64 v[0:1], v[2:3], 0, s[42:43]
	s_mov_b32 m0, s35
	s_addc_u32 s11, s19, 0
	s_add_i32 s36, s2, 0x1c000
	global_load_lds_dwordx4 v[0:1], off
	s_mov_b32 m0, s36
	s_add_i32 s37, s2, 0x1e000
	global_load_lds_dwordx4 v128, s[10:11]
	s_mov_b32 m0, s37
	s_cmpk_lt_u32 s4, 0x100
	global_load_lds_dwordx4 v130, s[10:11]
	v_bfe_u32 v1, v8, 4, 2
	v_and_b32_e32 v0, 15, v8
	v_lshlrev_b32_e32 v2, 4, v1
	v_lshl_or_b32 v153, s5, 6, v0
	v_lshl_or_b32 v0, v0, 6, v2
	v_lshlrev_b32_e32 v2, 2, v8
	v_lshl_or_b32 v168, v1, 2, s15
	v_lshlrev_b32_e32 v1, 14, v9
	v_and_b32_e32 v2, 32, v2
	v_and_b32_e32 v1, 0xffff8000, v1
	v_bitop3_b32 v159, v0, s13, v2 bitop3:0xde
	v_bitop3_b32 v0, v0, s24, v2 bitop3:0xde
	v_lshl_add_u32 v1, v10, 11, v1
	v_and_b32_e32 v2, 1, v9
	v_lshl_or_b32 v1, v2, 6, v1
	v_lshl_add_u32 v134, v11, 1, v1
	v_lshlrev_b32_e32 v1, 14, v12
	v_and_b32_e32 v1, 0xffff8000, v1
	s_waitcnt vmcnt(6)
	v_lshl_add_u32 v1, v13, 11, v1
	v_and_b32_e32 v2, 1, v12
	v_lshl_or_b32 v1, v2, 6, v1
	s_cselect_b64 s[44:45], -1, 0
	s_ashr_i32 s52, s82, 31
	s_mov_b32 s53, s82
	s_ashr_i32 s60, s3, 31
	v_mov_b32_e32 v135, v133
	v_lshl_add_u32 v136, v14, 1, v1
	v_mov_b32_e32 v137, v133
	s_mov_b32 s61, 0
	v_mov_b64_e32 v[138:139], 0x200
	v_mov_b64_e32 v[140:141], 0x1ff
	v_or_b32_e32 v169, 0x10000, v0
	v_add_u32_e32 v170, 0x10400, v0
	v_add_u32_e32 v171, 0x10800, v0
	v_add_u32_e32 v172, 0x10c00, v0
	v_or_b32_e32 v173, 0x14000, v0
	v_add_u32_e32 v174, 0x14400, v0
	v_add_u32_e32 v175, 0x14800, v0
	v_add_u32_e32 v176, 0x14c00, v0
	s_add_i32 s64, s2, 0xc000
	s_add_i32 s65, s2, 0xe000
	v_or_b32_e32 v177, 0x18000, v0
	v_add_u32_e32 v178, 0x18400, v0
	v_add_u32_e32 v179, 0x18800, v0
	v_add_u32_e32 v180, 0x18c00, v0
	v_or_b32_e32 v181, 0x1c000, v0
	v_add_u32_e32 v182, 0x1c400, v0
	v_add_u32_e32 v183, 0x1c800, v0
	v_add_u32_e32 v184, 0x1cc00, v0
	s_movk_i32 s67, 0x1ff
	s_movk_i32 s74, 0x320
	s_barrier
	s_branch .LBB0_2145

.LBB0_2152:
	ds_read_b128 v[160:163], v169
	ds_read_b128 v[164:167], v170
	ds_read_b128 v[186:189], v171
	ds_read_b128 v[190:193], v172
	ds_read_b128 v[198:201], v173
	ds_read_b128 v[202:205], v174
	ds_read_b128 v[206:209], v175
	ds_read_b128 v[210:213], v176
	s_add_u32 s18, s16, 0xfffc0080
	s_addc_u32 s19, s17, -1
	s_cmp_eq_u32 s66, 12
	s_cselect_b32 s25, s4, s19
	s_cselect_b32 s24, s5, s18
	s_cselect_b32 s19, s13, s49
	s_cselect_b32 s18, s15, s47
	s_mov_b32 m0, s64
	ds_read_b128 v[214:217], v159
	ds_read_b128 v[218:221], v159 offset:1024
	ds_read_b128 v[222:225], v159 offset:2048
	ds_read_b128 v[226:229], v159 offset:3072
	ds_read_b128 v[230:233], v159 offset:4096
	ds_read_b128 v[234:237], v159 offset:5120
	ds_read_b128 v[238:241], v159 offset:6144
	ds_read_b128 v[242:245], v159 offset:7168
	global_load_lds_dwordx4 v134, s[16:17]
	s_mov_b32 m0, s65
	s_nop 0
	global_load_lds_dwordx4 v136, s[16:17]
	s_waitcnt vmcnt(8)
	s_waitcnt lgkmcnt(0)
	s_barrier
	s_setprio 1
	s_waitcnt lgkmcnt(0)
	v_mfma_f32_16x16x32_bf16 v[124:127], v[160:163], v[214:217], v[124:127]
	v_mfma_f32_16x16x32_bf16 v[120:123], v[186:189], v[214:217], v[120:123]
	v_mfma_f32_16x16x32_bf16 v[108:111], v[160:163], v[222:225], v[108:111]
	v_mfma_f32_16x16x32_bf16 v[104:107], v[186:189], v[222:225], v[104:107]
	v_mfma_f32_16x16x32_bf16 v[92:95], v[160:163], v[230:233], v[92:95]
	v_mfma_f32_16x16x32_bf16 v[88:91], v[186:189], v[230:233], v[88:91]
	v_mfma_f32_16x16x32_bf16 v[76:79], v[160:163], v[238:241], v[76:79]
	v_mfma_f32_16x16x32_bf16 v[72:75], v[186:189], v[238:241], v[72:75]
	v_mfma_f32_16x16x32_bf16 v[124:127], v[164:167], v[218:221], v[124:127]
	v_mfma_f32_16x16x32_bf16 v[120:123], v[190:193], v[218:221], v[120:123]
	v_mfma_f32_16x16x32_bf16 v[108:111], v[164:167], v[226:229], v[108:111]
	v_mfma_f32_16x16x32_bf16 v[104:107], v[190:193], v[226:229], v[104:107]
	v_mfma_f32_16x16x32_bf16 v[92:95], v[164:167], v[234:237], v[92:95]
	v_mfma_f32_16x16x32_bf16 v[88:91], v[190:193], v[234:237], v[88:91]
	v_mfma_f32_16x16x32_bf16 v[76:79], v[164:167], v[242:245], v[76:79]
	v_mfma_f32_16x16x32_bf16 v[72:75], v[190:193], v[242:245], v[72:75]
	s_setprio 0
	s_setprio 1
	v_mfma_f32_16x16x32_bf16 v[116:119], v[198:201], v[214:217], v[116:119]
	v_mfma_f32_16x16x32_bf16 v[112:115], v[206:209], v[214:217], v[112:115]
	v_mfma_f32_16x16x32_bf16 v[100:103], v[198:201], v[222:225], v[100:103]
	v_mfma_f32_16x16x32_bf16 v[96:99], v[206:209], v[222:225], v[96:99]
	v_mfma_f32_16x16x32_bf16 v[84:87], v[198:201], v[230:233], v[84:87]
	v_mfma_f32_16x16x32_bf16 v[80:83], v[206:209], v[230:233], v[80:83]
	v_mfma_f32_16x16x32_bf16 v[68:71], v[198:201], v[238:241], v[68:71]
	v_mfma_f32_16x16x32_bf16 v[64:67], v[206:209], v[238:241], v[64:67]
	v_mfma_f32_16x16x32_bf16 v[116:119], v[202:205], v[218:221], v[116:119]
	v_mfma_f32_16x16x32_bf16 v[112:115], v[210:213], v[218:221], v[112:115]
	v_mfma_f32_16x16x32_bf16 v[100:103], v[202:205], v[226:229], v[100:103]
	v_mfma_f32_16x16x32_bf16 v[96:99], v[210:213], v[226:229], v[96:99]
	v_mfma_f32_16x16x32_bf16 v[84:87], v[202:205], v[234:237], v[84:87]
	v_mfma_f32_16x16x32_bf16 v[80:83], v[210:213], v[234:237], v[80:83]
	v_mfma_f32_16x16x32_bf16 v[68:71], v[202:205], v[242:245], v[68:71]
	v_mfma_f32_16x16x32_bf16 v[64:67], v[210:213], v[242:245], v[64:67]
	s_setprio 0
	s_barrier
	s_add_u32 s98, s18, s42
	s_addc_u32 s99, s19, s43
	s_add_u32 s100, s24, s42
	s_addc_u32 s101, s25, s43
	s_mov_b32 m0, s6
	s_add_u32 s68, s18, 0x40000
	ds_read_b128 v[214:217], v159 offset:16384
	ds_read_b128 v[218:221], v159 offset:17408
	ds_read_b128 v[222:225], v159 offset:18432
	ds_read_b128 v[226:229], v159 offset:19456
	ds_read_b128 v[230:233], v159 offset:20480
	ds_read_b128 v[234:237], v159 offset:21504
	ds_read_b128 v[238:241], v159 offset:22528
	ds_read_b128 v[242:245], v159 offset:23552
	global_load_lds_dwordx4 v128, s[18:19]
	s_mov_b32 m0, s7
	s_addc_u32 s69, s19, 0
	global_load_lds_dwordx4 v130, s[18:19]
	s_mov_b32 m0, s8
	s_nop 0
	global_load_lds_dwordx4 v128, s[68:69]
	s_mov_b32 m0, s9
	s_nop 0
	global_load_lds_dwordx4 v130, s[68:69]
	s_mov_b32 m0, s2
	s_nop 0
	global_load_lds_dwordx4 v128, s[24:25]
	s_mov_b32 m0, s28
	s_nop 0
	global_load_lds_dwordx4 v130, s[24:25]
	s_waitcnt vmcnt(8)
	s_waitcnt lgkmcnt(0)
	s_barrier
	s_setprio 1
	s_waitcnt lgkmcnt(0)
	v_mfma_f32_16x16x32_bf16 v[60:63], v[160:163], v[214:217], v[60:63]
	v_mfma_f32_16x16x32_bf16 v[56:59], v[186:189], v[214:217], v[56:59]
	v_mfma_f32_16x16x32_bf16 v[44:47], v[160:163], v[222:225], v[44:47]
	v_mfma_f32_16x16x32_bf16 v[40:43], v[186:189], v[222:225], v[40:43]
	v_mfma_f32_16x16x32_bf16 v[28:31], v[160:163], v[230:233], v[28:31]
	v_mfma_f32_16x16x32_bf16 v[24:27], v[186:189], v[230:233], v[24:27]
	v_mfma_f32_16x16x32_bf16 v[12:15], v[160:163], v[238:241], v[12:15]
	v_mfma_f32_16x16x32_bf16 v[8:11], v[186:189], v[238:241], v[8:11]
	v_mfma_f32_16x16x32_bf16 v[60:63], v[164:167], v[218:221], v[60:63]
	v_mfma_f32_16x16x32_bf16 v[56:59], v[190:193], v[218:221], v[56:59]
	v_mfma_f32_16x16x32_bf16 v[44:47], v[164:167], v[226:229], v[44:47]
	v_mfma_f32_16x16x32_bf16 v[40:43], v[190:193], v[226:229], v[40:43]
	v_mfma_f32_16x16x32_bf16 v[28:31], v[164:167], v[234:237], v[28:31]
	v_mfma_f32_16x16x32_bf16 v[24:27], v[190:193], v[234:237], v[24:27]
	v_mfma_f32_16x16x32_bf16 v[12:15], v[164:167], v[242:245], v[12:15]
	v_mfma_f32_16x16x32_bf16 v[8:11], v[190:193], v[242:245], v[8:11]
	s_setprio 0
	s_setprio 1
	v_mfma_f32_16x16x32_bf16 v[52:55], v[198:201], v[214:217], v[52:55]
	v_mfma_f32_16x16x32_bf16 v[48:51], v[206:209], v[214:217], v[48:51]
	v_mfma_f32_16x16x32_bf16 v[36:39], v[198:201], v[222:225], v[36:39]
	v_mfma_f32_16x16x32_bf16 v[32:35], v[206:209], v[222:225], v[32:35]
	v_mfma_f32_16x16x32_bf16 v[20:23], v[198:201], v[230:233], v[20:23]
	v_mfma_f32_16x16x32_bf16 v[16:19], v[206:209], v[230:233], v[16:19]
	v_mfma_f32_16x16x32_bf16 v[4:7], v[198:201], v[238:241], v[4:7]
	v_mfma_f32_16x16x32_bf16 v[0:3], v[206:209], v[238:241], v[0:3]
	v_mfma_f32_16x16x32_bf16 v[52:55], v[202:205], v[218:221], v[52:55]
	v_mfma_f32_16x16x32_bf16 v[48:51], v[210:213], v[218:221], v[48:51]
	v_mfma_f32_16x16x32_bf16 v[36:39], v[202:205], v[226:229], v[36:39]
	v_mfma_f32_16x16x32_bf16 v[32:35], v[210:213], v[226:229], v[32:35]
	v_mfma_f32_16x16x32_bf16 v[20:23], v[202:205], v[234:237], v[20:23]
	v_mfma_f32_16x16x32_bf16 v[16:19], v[210:213], v[234:237], v[16:19]
	v_mfma_f32_16x16x32_bf16 v[4:7], v[202:205], v[242:245], v[4:7]
	v_mfma_f32_16x16x32_bf16 v[0:3], v[210:213], v[242:245], v[0:3]
	s_setprio 0
	s_barrier
	ds_read_b128 v[160:163], v177
	ds_read_b128 v[164:167], v178
	ds_read_b128 v[186:189], v179
	ds_read_b128 v[190:193], v180
	ds_read_b128 v[198:201], v181
	ds_read_b128 v[202:205], v182
	ds_read_b128 v[206:209], v183
	ds_read_b128 v[210:213], v184
	s_add_u32 s24, s24, 0x40000
	s_addc_u32 s25, s25, 0
	s_mov_b32 m0, s29
	ds_read_b128 v[214:217], v159 offset:32768
	ds_read_b128 v[218:221], v159 offset:33792
	ds_read_b128 v[222:225], v159 offset:34816
	ds_read_b128 v[226:229], v159 offset:35840
	ds_read_b128 v[230:233], v159 offset:36864
	ds_read_b128 v[234:237], v159 offset:37888
	ds_read_b128 v[238:241], v159 offset:38912
	ds_read_b128 v[242:245], v159 offset:39936
	global_load_lds_dwordx4 v128, s[24:25]
	s_mov_b32 m0, s30
	s_nop 0
	global_load_lds_dwordx4 v130, s[24:25]
	s_waitcnt vmcnt(8)
	s_waitcnt lgkmcnt(0)
	s_barrier
	s_setprio 1
	s_waitcnt lgkmcnt(0)
	v_mfma_f32_16x16x32_bf16 v[124:127], v[160:163], v[214:217], v[124:127]
	v_mfma_f32_16x16x32_bf16 v[120:123], v[186:189], v[214:217], v[120:123]
	v_mfma_f32_16x16x32_bf16 v[108:111], v[160:163], v[222:225], v[108:111]
	v_mfma_f32_16x16x32_bf16 v[104:107], v[186:189], v[222:225], v[104:107]
	v_mfma_f32_16x16x32_bf16 v[92:95], v[160:163], v[230:233], v[92:95]
	v_mfma_f32_16x16x32_bf16 v[88:91], v[186:189], v[230:233], v[88:91]
	v_mfma_f32_16x16x32_bf16 v[76:79], v[160:163], v[238:241], v[76:79]
	v_mfma_f32_16x16x32_bf16 v[72:75], v[186:189], v[238:241], v[72:75]
	v_mfma_f32_16x16x32_bf16 v[124:127], v[164:167], v[218:221], v[124:127]
	v_mfma_f32_16x16x32_bf16 v[120:123], v[190:193], v[218:221], v[120:123]
	v_mfma_f32_16x16x32_bf16 v[108:111], v[164:167], v[226:229], v[108:111]
	v_mfma_f32_16x16x32_bf16 v[104:107], v[190:193], v[226:229], v[104:107]
	v_mfma_f32_16x16x32_bf16 v[92:95], v[164:167], v[234:237], v[92:95]
	v_mfma_f32_16x16x32_bf16 v[88:91], v[190:193], v[234:237], v[88:91]
	v_mfma_f32_16x16x32_bf16 v[76:79], v[164:167], v[242:245], v[76:79]
	v_mfma_f32_16x16x32_bf16 v[72:75], v[190:193], v[242:245], v[72:75]
	s_setprio 0
	s_setprio 1
	v_mfma_f32_16x16x32_bf16 v[116:119], v[198:201], v[214:217], v[116:119]
	v_mfma_f32_16x16x32_bf16 v[112:115], v[206:209], v[214:217], v[112:115]
	v_mfma_f32_16x16x32_bf16 v[100:103], v[198:201], v[222:225], v[100:103]
	v_mfma_f32_16x16x32_bf16 v[96:99], v[206:209], v[222:225], v[96:99]
	v_mfma_f32_16x16x32_bf16 v[84:87], v[198:201], v[230:233], v[84:87]
	v_mfma_f32_16x16x32_bf16 v[80:83], v[206:209], v[230:233], v[80:83]
	v_mfma_f32_16x16x32_bf16 v[68:71], v[198:201], v[238:241], v[68:71]
	v_mfma_f32_16x16x32_bf16 v[64:67], v[206:209], v[238:241], v[64:67]
	v_mfma_f32_16x16x32_bf16 v[116:119], v[202:205], v[218:221], v[116:119]
	v_mfma_f32_16x16x32_bf16 v[112:115], v[210:213], v[218:221], v[112:115]
	v_mfma_f32_16x16x32_bf16 v[100:103], v[202:205], v[226:229], v[100:103]
	v_mfma_f32_16x16x32_bf16 v[96:99], v[210:213], v[226:229], v[96:99]
	v_mfma_f32_16x16x32_bf16 v[84:87], v[202:205], v[234:237], v[84:87]
	v_mfma_f32_16x16x32_bf16 v[80:83], v[210:213], v[234:237], v[80:83]
	v_mfma_f32_16x16x32_bf16 v[68:71], v[202:205], v[242:245], v[68:71]
	v_mfma_f32_16x16x32_bf16 v[64:67], v[210:213], v[242:245], v[64:67]
	s_setprio 0
	s_barrier
	s_mov_b32 m0, s31
	s_add_u32 s18, s18, 0x40080
	ds_read_b128 v[214:217], v159 offset:49152
	ds_read_b128 v[218:221], v159 offset:50176
	ds_read_b128 v[222:225], v159 offset:51200
	ds_read_b128 v[226:229], v159 offset:52224
	ds_read_b128 v[230:233], v159 offset:53248
	ds_read_b128 v[234:237], v159 offset:54272
	ds_read_b128 v[238:241], v159 offset:55296
	ds_read_b128 v[242:245], v159 offset:56320
	global_load_lds_dwordx4 v128, s[98:99]
	s_mov_b32 m0, s33
	s_addc_u32 s19, s19, 0
	global_load_lds_dwordx4 v130, s[98:99]
	s_mov_b32 m0, s36
	s_nop 0
	global_load_lds_dwordx4 v128, s[18:19]
	s_mov_b32 m0, s37
	s_nop 0
	global_load_lds_dwordx4 v130, s[18:19]
	s_mov_b32 m0, s34
	s_nop 0
	global_load_lds_dwordx4 v128, s[100:101]
	s_mov_b32 m0, s35
	s_nop 0
	global_load_lds_dwordx4 v130, s[100:101]
	s_waitcnt vmcnt(8)
	s_waitcnt lgkmcnt(0)
	s_barrier
	s_setprio 1
	s_waitcnt lgkmcnt(0)
	v_mfma_f32_16x16x32_bf16 v[60:63], v[160:163], v[214:217], v[60:63]
	v_mfma_f32_16x16x32_bf16 v[56:59], v[186:189], v[214:217], v[56:59]
	v_mfma_f32_16x16x32_bf16 v[44:47], v[160:163], v[222:225], v[44:47]
	v_mfma_f32_16x16x32_bf16 v[40:43], v[186:189], v[222:225], v[40:43]
	v_mfma_f32_16x16x32_bf16 v[28:31], v[160:163], v[230:233], v[28:31]
	v_mfma_f32_16x16x32_bf16 v[24:27], v[186:189], v[230:233], v[24:27]
	v_mfma_f32_16x16x32_bf16 v[12:15], v[160:163], v[238:241], v[12:15]
	v_mfma_f32_16x16x32_bf16 v[8:11], v[186:189], v[238:241], v[8:11]
	v_mfma_f32_16x16x32_bf16 v[60:63], v[164:167], v[218:221], v[60:63]
	v_mfma_f32_16x16x32_bf16 v[56:59], v[190:193], v[218:221], v[56:59]
	v_mfma_f32_16x16x32_bf16 v[44:47], v[164:167], v[226:229], v[44:47]
	v_mfma_f32_16x16x32_bf16 v[40:43], v[190:193], v[226:229], v[40:43]
	v_mfma_f32_16x16x32_bf16 v[28:31], v[164:167], v[234:237], v[28:31]
	v_mfma_f32_16x16x32_bf16 v[24:27], v[190:193], v[234:237], v[24:27]
	v_mfma_f32_16x16x32_bf16 v[12:15], v[164:167], v[242:245], v[12:15]
	v_mfma_f32_16x16x32_bf16 v[8:11], v[190:193], v[242:245], v[8:11]
	s_setprio 0
	s_setprio 1
	v_mfma_f32_16x16x32_bf16 v[52:55], v[198:201], v[214:217], v[52:55]
	v_mfma_f32_16x16x32_bf16 v[48:51], v[206:209], v[214:217], v[48:51]
	v_mfma_f32_16x16x32_bf16 v[36:39], v[198:201], v[222:225], v[36:39]
	v_mfma_f32_16x16x32_bf16 v[32:35], v[206:209], v[222:225], v[32:35]
	v_mfma_f32_16x16x32_bf16 v[20:23], v[198:201], v[230:233], v[20:23]
	v_mfma_f32_16x16x32_bf16 v[16:19], v[206:209], v[230:233], v[16:19]
	v_mfma_f32_16x16x32_bf16 v[4:7], v[198:201], v[238:241], v[4:7]
	v_mfma_f32_16x16x32_bf16 v[0:3], v[206:209], v[238:241], v[0:3]
	v_mfma_f32_16x16x32_bf16 v[52:55], v[202:205], v[218:221], v[52:55]
	v_mfma_f32_16x16x32_bf16 v[48:51], v[210:213], v[218:221], v[48:51]
	v_mfma_f32_16x16x32_bf16 v[36:39], v[202:205], v[226:229], v[36:39]
	v_mfma_f32_16x16x32_bf16 v[32:35], v[210:213], v[226:229], v[32:35]
	v_mfma_f32_16x16x32_bf16 v[20:23], v[202:205], v[234:237], v[20:23]
	v_mfma_f32_16x16x32_bf16 v[16:19], v[210:213], v[234:237], v[16:19]
	v_mfma_f32_16x16x32_bf16 v[4:7], v[202:205], v[242:245], v[4:7]
	v_mfma_f32_16x16x32_bf16 v[0:3], v[210:213], v[242:245], v[0:3]
	s_setprio 0
	s_barrier
	s_add_i32 s66, s66, 2
	s_add_u32 s16, s16, 0x100
	s_addc_u32 s17, s17, 0
	s_add_u32 s47, s47, 0x100
	s_addc_u32 s49, s49, 0
	s_cmp_gt_u32 s66, 13
	s_cbranch_scc0 .LBB0_2152
	s_and_b64 vcc, exec, s[44:45]
	s_cbranch_vccz .LBB0_2155
	s_barrier

.LBB0_2524:
	s_lshl_b32 s10, s10, 5
	s_add_i32 s31, s2, 0x18000
	s_mov_b64 s[44:45], 0x80
	s_and_b32 s15, s10, 0x60
	v_lshl_add_u64 v[6:7], v[6:7], 0, s[44:45]
	s_mov_b32 m0, s31
	s_add_i32 s33, s2, 0x1a000
	s_lshl_b32 s13, s5, 13
	s_lshl_b32 s18, s15, 7
	s_waitcnt vmcnt(2)
	s_barrier
	global_load_lds_dwordx4 v[6:7], off
	v_lshl_add_u64 v[4:5], v[4:5], 0, s[44:45]
	s_mov_b32 m0, s33
	s_add_i32 s34, s2, 0x8000
	s_add_i32 s35, s2, 0xa000
	global_load_lds_dwordx4 v[4:5], off
	v_lshl_add_u64 v[0:1], v[0:1], 0, s[44:45]
	s_mov_b32 m0, s34
	s_add_u32 s10, s16, 0x20080
	global_load_lds_dwordx4 v[0:1], off
	v_lshl_add_u64 v[0:1], v[2:3], 0, s[44:45]
	s_mov_b32 m0, s35
	s_addc_u32 s11, s17, 0
	s_add_i32 s36, s2, 0x1c000
	global_load_lds_dwordx4 v[0:1], off
	s_mov_b32 m0, s36
	s_add_i32 s37, s2, 0x1e000
	global_load_lds_dwordx4 v128, s[10:11]
	s_mov_b32 m0, s37
	s_cmpk_lt_u32 s4, 0x100
	global_load_lds_dwordx4 v130, s[10:11]
	v_bfe_u32 v1, v8, 4, 2
	v_and_b32_e32 v0, 15, v8
	v_lshlrev_b32_e32 v2, 4, v1
	v_lshl_or_b32 v153, s5, 6, v0
	v_lshl_or_b32 v0, v0, 6, v2
	v_lshlrev_b32_e32 v2, 2, v8
	v_lshl_or_b32 v161, v1, 2, s15
	v_lshlrev_b32_e32 v1, 13, v9
	v_and_b32_e32 v2, 32, v2
	v_and_b32_e32 v1, 0xffffc000, v1
	v_bitop3_b32 v160, v0, s13, v2 bitop3:0xde
	v_bitop3_b32 v0, v0, s18, v2 bitop3:0xde
	v_lshl_add_u32 v1, v10, 10, v1
	v_and_b32_e32 v2, 1, v9
	v_lshl_or_b32 v1, v2, 6, v1
	v_lshl_add_u32 v132, v11, 1, v1
	v_lshlrev_b32_e32 v1, 13, v12
	v_and_b32_e32 v1, 0xffffc000, v1
	s_waitcnt vmcnt(6)
	v_lshl_add_u32 v1, v13, 10, v1
	v_and_b32_e32 v2, 1, v12
	v_lshl_or_b32 v1, v2, 6, v1
	s_movk_i32 s52, 0x60
	s_cselect_b64 s[46:47], -1, 0
	s_ashr_i32 s53, s82, 31
	s_mov_b32 s60, s82
	s_ashr_i32 s61, s3, 31
	v_mov_b32_e32 v133, v129
	v_lshl_add_u32 v134, v14, 1, v1
	v_mov_b32_e32 v135, v129
	s_mov_b32 s67, 0
	v_mov_b64_e32 v[136:137], 0x300
	v_mov_b64_e32 v[138:139], 0x2ff
	s_mov_b32 s76, 0x2aaaaaab
	v_or_b32_e32 v162, 0x10000, v0
	v_add_u32_e32 v163, 0x10400, v0
	v_add_u32_e32 v164, 0x10800, v0
	v_add_u32_e32 v165, 0x10c00, v0
	v_or_b32_e32 v166, 0x14000, v0
	v_add_u32_e32 v167, 0x14400, v0
	v_add_u32_e32 v168, 0x14800, v0
	v_add_u32_e32 v169, 0x14c00, v0
	s_add_i32 s77, s2, 0xc000
	s_add_i32 s78, s2, 0xe000
	v_or_b32_e32 v170, 0x18000, v0
	v_add_u32_e32 v171, 0x18400, v0
	v_add_u32_e32 v172, 0x18800, v0
	v_add_u32_e32 v173, 0x18c00, v0
	v_or_b32_e32 v174, 0x1c000, v0
	v_add_u32_e32 v175, 0x1c400, v0
	v_add_u32_e32 v176, 0x1c800, v0
	v_add_u32_e32 v177, 0x1cc00, v0
	s_mov_b32 s79, 0x3e0f83e1
	s_movk_i32 s80, 0xff
	s_movk_i32 s81, 0xc00
	s_barrier
	s_branch .LBB0_2527

.LBB0_2530:
	ds_read_b128 v[140:143], v162
	ds_read_b128 v[178:181], v163
	ds_read_b128 v[182:185], v164
	ds_read_b128 v[186:189], v165
	ds_read_b128 v[190:193], v166
	ds_read_b128 v[198:201], v167
	ds_read_b128 v[202:205], v168
	ds_read_b128 v[206:209], v169
	s_add_u32 s16, s0, 0xfffe0080
	s_addc_u32 s17, s1, -1
	s_cmp_eq_u32 s64, 4
	s_cselect_b32 s19, s4, s17
	s_cselect_b32 s18, s5, s16
	s_cselect_b32 s17, s13, s51
	s_cselect_b32 s16, s15, s49
	s_mov_b32 m0, s77
	ds_read_b128 v[210:213], v160
	ds_read_b128 v[214:217], v160 offset:1024
	ds_read_b128 v[218:221], v160 offset:2048
	ds_read_b128 v[222:225], v160 offset:3072
	ds_read_b128 v[226:229], v160 offset:4096
	ds_read_b128 v[230:233], v160 offset:5120
	ds_read_b128 v[234:237], v160 offset:6144
	ds_read_b128 v[238:241], v160 offset:7168
	global_load_lds_dwordx4 v132, s[0:1]
	s_mov_b32 m0, s78
	s_nop 0
	global_load_lds_dwordx4 v134, s[0:1]
	s_waitcnt vmcnt(8)
	s_waitcnt lgkmcnt(0)
	s_barrier
	s_setprio 1
	s_waitcnt lgkmcnt(0)
	v_mfma_f32_16x16x32_bf16 v[124:127], v[140:143], v[210:213], v[124:127]
	v_mfma_f32_16x16x32_bf16 v[120:123], v[182:185], v[210:213], v[120:123]
	v_mfma_f32_16x16x32_bf16 v[108:111], v[140:143], v[218:221], v[108:111]
	v_mfma_f32_16x16x32_bf16 v[104:107], v[182:185], v[218:221], v[104:107]
	v_mfma_f32_16x16x32_bf16 v[92:95], v[140:143], v[226:229], v[92:95]
	v_mfma_f32_16x16x32_bf16 v[88:91], v[182:185], v[226:229], v[88:91]
	v_mfma_f32_16x16x32_bf16 v[76:79], v[140:143], v[234:237], v[76:79]
	v_mfma_f32_16x16x32_bf16 v[72:75], v[182:185], v[234:237], v[72:75]
	v_mfma_f32_16x16x32_bf16 v[124:127], v[178:181], v[214:217], v[124:127]
	v_mfma_f32_16x16x32_bf16 v[120:123], v[186:189], v[214:217], v[120:123]
	v_mfma_f32_16x16x32_bf16 v[108:111], v[178:181], v[222:225], v[108:111]
	v_mfma_f32_16x16x32_bf16 v[104:107], v[186:189], v[222:225], v[104:107]
	v_mfma_f32_16x16x32_bf16 v[92:95], v[178:181], v[230:233], v[92:95]
	v_mfma_f32_16x16x32_bf16 v[88:91], v[186:189], v[230:233], v[88:91]
	v_mfma_f32_16x16x32_bf16 v[76:79], v[178:181], v[238:241], v[76:79]
	v_mfma_f32_16x16x32_bf16 v[72:75], v[186:189], v[238:241], v[72:75]
	s_setprio 0
	s_setprio 1
	v_mfma_f32_16x16x32_bf16 v[116:119], v[190:193], v[210:213], v[116:119]
	v_mfma_f32_16x16x32_bf16 v[112:115], v[202:205], v[210:213], v[112:115]
	v_mfma_f32_16x16x32_bf16 v[100:103], v[190:193], v[218:221], v[100:103]
	v_mfma_f32_16x16x32_bf16 v[96:99], v[202:205], v[218:221], v[96:99]
	v_mfma_f32_16x16x32_bf16 v[84:87], v[190:193], v[226:229], v[84:87]
	v_mfma_f32_16x16x32_bf16 v[80:83], v[202:205], v[226:229], v[80:83]
	v_mfma_f32_16x16x32_bf16 v[68:71], v[190:193], v[234:237], v[68:71]
	v_mfma_f32_16x16x32_bf16 v[64:67], v[202:205], v[234:237], v[64:67]
	v_mfma_f32_16x16x32_bf16 v[116:119], v[198:201], v[214:217], v[116:119]
	v_mfma_f32_16x16x32_bf16 v[112:115], v[206:209], v[214:217], v[112:115]
	v_mfma_f32_16x16x32_bf16 v[100:103], v[198:201], v[222:225], v[100:103]
	v_mfma_f32_16x16x32_bf16 v[96:99], v[206:209], v[222:225], v[96:99]
	v_mfma_f32_16x16x32_bf16 v[84:87], v[198:201], v[230:233], v[84:87]
	v_mfma_f32_16x16x32_bf16 v[80:83], v[206:209], v[230:233], v[80:83]
	v_mfma_f32_16x16x32_bf16 v[68:71], v[198:201], v[238:241], v[68:71]
	v_mfma_f32_16x16x32_bf16 v[64:67], v[206:209], v[238:241], v[64:67]
	s_setprio 0
	s_barrier
	s_add_u32 s98, s16, s44
	s_addc_u32 s99, s17, s45
	s_add_u32 s100, s18, s44
	s_addc_u32 s101, s19, s45
	s_mov_b32 m0, s6
	s_add_u32 s68, s16, 0x20000
	ds_read_b128 v[210:213], v160 offset:16384
	ds_read_b128 v[214:217], v160 offset:17408
	ds_read_b128 v[218:221], v160 offset:18432
	ds_read_b128 v[222:225], v160 offset:19456
	ds_read_b128 v[226:229], v160 offset:20480
	ds_read_b128 v[230:233], v160 offset:21504
	ds_read_b128 v[234:237], v160 offset:22528
	ds_read_b128 v[238:241], v160 offset:23552
	global_load_lds_dwordx4 v128, s[16:17]
	s_mov_b32 m0, s7
	s_addc_u32 s69, s17, 0
	global_load_lds_dwordx4 v130, s[16:17]
	s_mov_b32 m0, s8
	s_nop 0
	global_load_lds_dwordx4 v128, s[68:69]
	s_mov_b32 m0, s9
	s_nop 0
	global_load_lds_dwordx4 v130, s[68:69]
	s_mov_b32 m0, s2
	s_nop 0
	global_load_lds_dwordx4 v128, s[18:19]
	s_mov_b32 m0, s28
	s_nop 0
	global_load_lds_dwordx4 v130, s[18:19]
	s_waitcnt vmcnt(8)
	s_waitcnt lgkmcnt(0)
	s_barrier
	s_setprio 1
	s_waitcnt lgkmcnt(0)
	v_mfma_f32_16x16x32_bf16 v[60:63], v[140:143], v[210:213], v[60:63]
	v_mfma_f32_16x16x32_bf16 v[56:59], v[182:185], v[210:213], v[56:59]
	v_mfma_f32_16x16x32_bf16 v[44:47], v[140:143], v[218:221], v[44:47]
	v_mfma_f32_16x16x32_bf16 v[40:43], v[182:185], v[218:221], v[40:43]
	v_mfma_f32_16x16x32_bf16 v[28:31], v[140:143], v[226:229], v[28:31]
	v_mfma_f32_16x16x32_bf16 v[24:27], v[182:185], v[226:229], v[24:27]
	v_mfma_f32_16x16x32_bf16 v[12:15], v[140:143], v[234:237], v[12:15]
	v_mfma_f32_16x16x32_bf16 v[8:11], v[182:185], v[234:237], v[8:11]
	v_mfma_f32_16x16x32_bf16 v[60:63], v[178:181], v[214:217], v[60:63]
	v_mfma_f32_16x16x32_bf16 v[56:59], v[186:189], v[214:217], v[56:59]
	v_mfma_f32_16x16x32_bf16 v[44:47], v[178:181], v[222:225], v[44:47]
	v_mfma_f32_16x16x32_bf16 v[40:43], v[186:189], v[222:225], v[40:43]
	v_mfma_f32_16x16x32_bf16 v[28:31], v[178:181], v[230:233], v[28:31]
	v_mfma_f32_16x16x32_bf16 v[24:27], v[186:189], v[230:233], v[24:27]
	v_mfma_f32_16x16x32_bf16 v[12:15], v[178:181], v[238:241], v[12:15]
	v_mfma_f32_16x16x32_bf16 v[8:11], v[186:189], v[238:241], v[8:11]
	s_setprio 0
	s_setprio 1
	v_mfma_f32_16x16x32_bf16 v[52:55], v[190:193], v[210:213], v[52:55]
	v_mfma_f32_16x16x32_bf16 v[48:51], v[202:205], v[210:213], v[48:51]
	v_mfma_f32_16x16x32_bf16 v[36:39], v[190:193], v[218:221], v[36:39]
	v_mfma_f32_16x16x32_bf16 v[32:35], v[202:205], v[218:221], v[32:35]
	v_mfma_f32_16x16x32_bf16 v[20:23], v[190:193], v[226:229], v[20:23]
	v_mfma_f32_16x16x32_bf16 v[16:19], v[202:205], v[226:229], v[16:19]
	v_mfma_f32_16x16x32_bf16 v[4:7], v[190:193], v[234:237], v[4:7]
	v_mfma_f32_16x16x32_bf16 v[0:3], v[202:205], v[234:237], v[0:3]
	v_mfma_f32_16x16x32_bf16 v[52:55], v[198:201], v[214:217], v[52:55]
	v_mfma_f32_16x16x32_bf16 v[48:51], v[206:209], v[214:217], v[48:51]
	v_mfma_f32_16x16x32_bf16 v[36:39], v[198:201], v[222:225], v[36:39]
	v_mfma_f32_16x16x32_bf16 v[32:35], v[206:209], v[222:225], v[32:35]
	v_mfma_f32_16x16x32_bf16 v[20:23], v[198:201], v[230:233], v[20:23]
	v_mfma_f32_16x16x32_bf16 v[16:19], v[206:209], v[230:233], v[16:19]
	v_mfma_f32_16x16x32_bf16 v[4:7], v[198:201], v[238:241], v[4:7]
	v_mfma_f32_16x16x32_bf16 v[0:3], v[206:209], v[238:241], v[0:3]
	s_setprio 0
	s_barrier
	ds_read_b128 v[140:143], v170
	ds_read_b128 v[178:181], v171
	ds_read_b128 v[182:185], v172
	ds_read_b128 v[186:189], v173
	ds_read_b128 v[190:193], v174
	ds_read_b128 v[198:201], v175
	ds_read_b128 v[202:205], v176
	ds_read_b128 v[206:209], v177
	s_add_u32 s18, s18, 0x20000
	s_addc_u32 s19, s19, 0
	s_mov_b32 m0, s29
	ds_read_b128 v[210:213], v160 offset:32768
	ds_read_b128 v[214:217], v160 offset:33792
	ds_read_b128 v[218:221], v160 offset:34816
	ds_read_b128 v[222:225], v160 offset:35840
	ds_read_b128 v[226:229], v160 offset:36864
	ds_read_b128 v[230:233], v160 offset:37888
	ds_read_b128 v[234:237], v160 offset:38912
	ds_read_b128 v[238:241], v160 offset:39936
	global_load_lds_dwordx4 v128, s[18:19]
	s_mov_b32 m0, s30
	s_nop 0
	global_load_lds_dwordx4 v130, s[18:19]
	s_waitcnt vmcnt(8)
	s_waitcnt lgkmcnt(0)
	s_barrier
	s_setprio 1
	s_waitcnt lgkmcnt(0)
	v_mfma_f32_16x16x32_bf16 v[124:127], v[140:143], v[210:213], v[124:127]
	v_mfma_f32_16x16x32_bf16 v[120:123], v[182:185], v[210:213], v[120:123]
	v_mfma_f32_16x16x32_bf16 v[108:111], v[140:143], v[218:221], v[108:111]
	v_mfma_f32_16x16x32_bf16 v[104:107], v[182:185], v[218:221], v[104:107]
	v_mfma_f32_16x16x32_bf16 v[92:95], v[140:143], v[226:229], v[92:95]
	v_mfma_f32_16x16x32_bf16 v[88:91], v[182:185], v[226:229], v[88:91]
	v_mfma_f32_16x16x32_bf16 v[76:79], v[140:143], v[234:237], v[76:79]
	v_mfma_f32_16x16x32_bf16 v[72:75], v[182:185], v[234:237], v[72:75]
	v_mfma_f32_16x16x32_bf16 v[124:127], v[178:181], v[214:217], v[124:127]
	v_mfma_f32_16x16x32_bf16 v[120:123], v[186:189], v[214:217], v[120:123]
	v_mfma_f32_16x16x32_bf16 v[108:111], v[178:181], v[222:225], v[108:111]
	v_mfma_f32_16x16x32_bf16 v[104:107], v[186:189], v[222:225], v[104:107]
	v_mfma_f32_16x16x32_bf16 v[92:95], v[178:181], v[230:233], v[92:95]
	v_mfma_f32_16x16x32_bf16 v[88:91], v[186:189], v[230:233], v[88:91]
	v_mfma_f32_16x16x32_bf16 v[76:79], v[178:181], v[238:241], v[76:79]
	v_mfma_f32_16x16x32_bf16 v[72:75], v[186:189], v[238:241], v[72:75]
	s_setprio 0
	s_setprio 1
	v_mfma_f32_16x16x32_bf16 v[116:119], v[190:193], v[210:213], v[116:119]
	v_mfma_f32_16x16x32_bf16 v[112:115], v[202:205], v[210:213], v[112:115]
	v_mfma_f32_16x16x32_bf16 v[100:103], v[190:193], v[218:221], v[100:103]
	v_mfma_f32_16x16x32_bf16 v[96:99], v[202:205], v[218:221], v[96:99]
	v_mfma_f32_16x16x32_bf16 v[84:87], v[190:193], v[226:229], v[84:87]
	v_mfma_f32_16x16x32_bf16 v[80:83], v[202:205], v[226:229], v[80:83]
	v_mfma_f32_16x16x32_bf16 v[68:71], v[190:193], v[234:237], v[68:71]
	v_mfma_f32_16x16x32_bf16 v[64:67], v[202:205], v[234:237], v[64:67]
	v_mfma_f32_16x16x32_bf16 v[116:119], v[198:201], v[214:217], v[116:119]
	v_mfma_f32_16x16x32_bf16 v[112:115], v[206:209], v[214:217], v[112:115]
	v_mfma_f32_16x16x32_bf16 v[100:103], v[198:201], v[222:225], v[100:103]
	v_mfma_f32_16x16x32_bf16 v[96:99], v[206:209], v[222:225], v[96:99]
	v_mfma_f32_16x16x32_bf16 v[84:87], v[198:201], v[230:233], v[84:87]
	v_mfma_f32_16x16x32_bf16 v[80:83], v[206:209], v[230:233], v[80:83]
	v_mfma_f32_16x16x32_bf16 v[68:71], v[198:201], v[238:241], v[68:71]
	v_mfma_f32_16x16x32_bf16 v[64:67], v[206:209], v[238:241], v[64:67]
	s_setprio 0
	s_barrier
	s_mov_b32 m0, s31
	s_add_u32 s16, s16, 0x20080
	ds_read_b128 v[210:213], v160 offset:49152
	ds_read_b128 v[214:217], v160 offset:50176
	ds_read_b128 v[218:221], v160 offset:51200
	ds_read_b128 v[222:225], v160 offset:52224
	ds_read_b128 v[226:229], v160 offset:53248
	ds_read_b128 v[230:233], v160 offset:54272
	ds_read_b128 v[234:237], v160 offset:55296
	ds_read_b128 v[238:241], v160 offset:56320
	global_load_lds_dwordx4 v128, s[98:99]
	s_mov_b32 m0, s33
	s_addc_u32 s17, s17, 0
	global_load_lds_dwordx4 v130, s[98:99]
	s_mov_b32 m0, s36
	s_nop 0
	global_load_lds_dwordx4 v128, s[16:17]
	s_mov_b32 m0, s37
	s_nop 0
	global_load_lds_dwordx4 v130, s[16:17]
	s_mov_b32 m0, s34
	s_nop 0
	global_load_lds_dwordx4 v128, s[100:101]
	s_mov_b32 m0, s35
	s_nop 0
	global_load_lds_dwordx4 v130, s[100:101]
	s_waitcnt vmcnt(8)
	s_waitcnt lgkmcnt(0)
	s_barrier
	s_setprio 1
	s_waitcnt lgkmcnt(0)
	v_mfma_f32_16x16x32_bf16 v[60:63], v[140:143], v[210:213], v[60:63]
	v_mfma_f32_16x16x32_bf16 v[56:59], v[182:185], v[210:213], v[56:59]
	v_mfma_f32_16x16x32_bf16 v[44:47], v[140:143], v[218:221], v[44:47]
	v_mfma_f32_16x16x32_bf16 v[40:43], v[182:185], v[218:221], v[40:43]
	v_mfma_f32_16x16x32_bf16 v[28:31], v[140:143], v[226:229], v[28:31]
	v_mfma_f32_16x16x32_bf16 v[24:27], v[182:185], v[226:229], v[24:27]
	v_mfma_f32_16x16x32_bf16 v[12:15], v[140:143], v[234:237], v[12:15]
	v_mfma_f32_16x16x32_bf16 v[8:11], v[182:185], v[234:237], v[8:11]
	v_mfma_f32_16x16x32_bf16 v[60:63], v[178:181], v[214:217], v[60:63]
	v_mfma_f32_16x16x32_bf16 v[56:59], v[186:189], v[214:217], v[56:59]
	v_mfma_f32_16x16x32_bf16 v[44:47], v[178:181], v[222:225], v[44:47]
	v_mfma_f32_16x16x32_bf16 v[40:43], v[186:189], v[222:225], v[40:43]
	v_mfma_f32_16x16x32_bf16 v[28:31], v[178:181], v[230:233], v[28:31]
	v_mfma_f32_16x16x32_bf16 v[24:27], v[186:189], v[230:233], v[24:27]
	v_mfma_f32_16x16x32_bf16 v[12:15], v[178:181], v[238:241], v[12:15]
	v_mfma_f32_16x16x32_bf16 v[8:11], v[186:189], v[238:241], v[8:11]
	s_setprio 0
	s_setprio 1
	v_mfma_f32_16x16x32_bf16 v[52:55], v[190:193], v[210:213], v[52:55]
	v_mfma_f32_16x16x32_bf16 v[48:51], v[202:205], v[210:213], v[48:51]
	v_mfma_f32_16x16x32_bf16 v[36:39], v[190:193], v[218:221], v[36:39]
	v_mfma_f32_16x16x32_bf16 v[32:35], v[202:205], v[218:221], v[32:35]
	v_mfma_f32_16x16x32_bf16 v[20:23], v[190:193], v[226:229], v[20:23]
	v_mfma_f32_16x16x32_bf16 v[16:19], v[202:205], v[226:229], v[16:19]
	v_mfma_f32_16x16x32_bf16 v[4:7], v[190:193], v[234:237], v[4:7]
	v_mfma_f32_16x16x32_bf16 v[0:3], v[202:205], v[234:237], v[0:3]
	v_mfma_f32_16x16x32_bf16 v[52:55], v[198:201], v[214:217], v[52:55]
	v_mfma_f32_16x16x32_bf16 v[48:51], v[206:209], v[214:217], v[48:51]
	v_mfma_f32_16x16x32_bf16 v[36:39], v[198:201], v[222:225], v[36:39]
	v_mfma_f32_16x16x32_bf16 v[32:35], v[206:209], v[222:225], v[32:35]
	v_mfma_f32_16x16x32_bf16 v[20:23], v[198:201], v[230:233], v[20:23]
	v_mfma_f32_16x16x32_bf16 v[16:19], v[206:209], v[230:233], v[16:19]
	v_mfma_f32_16x16x32_bf16 v[4:7], v[198:201], v[238:241], v[4:7]
	v_mfma_f32_16x16x32_bf16 v[0:3], v[206:209], v[238:241], v[0:3]
	s_setprio 0
	s_barrier
	s_add_i32 s64, s64, 2
	s_add_u32 s0, s0, 0x100
	s_addc_u32 s1, s1, 0
	s_add_u32 s49, s49, 0x100
	s_addc_u32 s51, s51, 0
	s_cmp_gt_u32 s64, 5
	s_cbranch_scc0 .LBB0_2530
	s_and_b64 vcc, exec, s[46:47]
	s_cbranch_vccz .LBB0_2533
	s_barrier

.LBB0_2618:
	s_lshl_b32 s5, s5, 5
	s_add_i32 s33, s30, 0x18000
	s_mov_b64 s[16:17], 0x80
	s_and_b32 s5, s5, 0x60
	v_lshl_add_u64 v[6:7], v[6:7], 0, s[16:17]
	s_mov_b32 m0, s33
	s_add_i32 s9, s30, 0x1a000
	s_lshl_b32 s20, s4, 13
	s_lshl_b32 s21, s5, 7
	s_waitcnt vmcnt(2)
	s_barrier
	global_load_lds_dwordx4 v[6:7], off
	v_lshl_add_u64 v[4:5], v[4:5], 0, s[16:17]
	s_mov_b32 m0, s9
	s_add_i32 s8, s30, 0x8000
	s_add_i32 s53, s30, 0xa000
	global_load_lds_dwordx4 v[4:5], off
	v_lshl_add_u64 v[2:3], v[2:3], 0, s[16:17]
	s_mov_b32 m0, s8
	s_add_u32 s18, s46, 0x10080
	global_load_lds_dwordx4 v[2:3], off
	v_lshl_add_u64 v[0:1], v[0:1], 0, s[16:17]
	s_mov_b32 m0, s53
	s_addc_u32 s19, s47, 0
	s_add_i32 s52, s30, 0x1c000
	global_load_lds_dwordx4 v[0:1], off
	s_mov_b32 m0, s52
	s_add_i32 s61, s30, 0x1e000
	global_load_lds_dwordx4 v128, s[18:19]
	s_mov_b32 m0, s61
	s_cmpk_lt_u32 s11, 0x100
	global_load_lds_dwordx4 v130, s[18:19]
	v_bfe_u32 v0, v8, 4, 2
	v_and_b32_e32 v1, 15, v8
	v_lshlrev_b32_e32 v2, 4, v0
	v_lshl_or_b32 v138, s4, 6, v1
	v_lshl_or_b32 v1, v1, 6, v2
	v_lshlrev_b32_e32 v2, 2, v8
	v_and_b32_e32 v2, 32, v2
	s_waitcnt vmcnt(6)
	v_bitop3_b32 v139, v1, s20, v2 bitop3:0xde
	v_bitop3_b32 v1, v1, s21, v2 bitop3:0xde
	s_sext_i32_i8 s66, s10
	s_mov_b32 s76, 0x8000
	s_cselect_b64 s[18:19], -1, 0
	s_ashr_i32 s77, s82, 31
	s_mov_b32 s28, s82
	v_lshl_or_b32 v140, v0, 2, s5
	s_mov_b32 s29, 0
	v_mov_b64_e32 v[132:133], 0x200
	v_mov_b64_e32 v[134:135], 0x1ff
	s_mov_b32 s34, 0xc000
	s_add_i32 s35, s30, 0xc000
	s_add_i32 s60, s30, 0xe000
	v_or_b32_e32 v141, 0x10000, v1
	v_add_u32_e32 v142, 0x10400, v1
	v_add_u32_e32 v143, 0x10800, v1
	v_add_u32_e32 v153, 0x10c00, v1
	v_or_b32_e32 v158, 0x14000, v1
	v_add_u32_e32 v159, 0x14400, v1
	v_add_u32_e32 v160, 0x14800, v1
	v_add_u32_e32 v161, 0x14c00, v1
	v_or_b32_e32 v162, 0x18000, v1
	v_add_u32_e32 v163, 0x18400, v1
	v_add_u32_e32 v164, 0x18800, v1
	v_add_u32_e32 v165, 0x18c00, v1
	v_or_b32_e32 v166, 0x1c000, v1
	v_add_u32_e32 v167, 0x1c400, v1
	v_add_u32_e32 v168, 0x1c800, v1
	v_add_u32_e32 v169, 0x1cc00, v1
	s_mov_b32 s31, 0x3e0f83e1
	s_movk_i32 s36, 0xdf00
	s_movk_i32 s37, 0x4200
	s_barrier
	s_branch .LBB0_2621

.LBB0_2628:
	s_add_u32 s65, s48, s64
	s_addc_u32 s70, s49, 0
	s_add_u32 s71, s65, 0x100
	s_addc_u32 s74, s70, 0
	s_and_b64 s[68:69], s[54:55], exec
	s_cselect_b32 s75, s4, s74
	s_cselect_b32 s74, s5, s71
	s_add_u32 s64, s46, s64
	s_addc_u32 s68, s47, 0
	s_add_u32 s64, s64, 0x100
	ds_read_b128 v[170:173], v141
	ds_read_b128 v[174:177], v142
	ds_read_b128 v[178:181], v143
	ds_read_b128 v[182:185], v153
	ds_read_b128 v[186:189], v158
	ds_read_b128 v[190:193], v159
	ds_read_b128 v[196:199], v160
	ds_read_b128 v[200:203], v161
	s_addc_u32 s68, s68, 0
	s_and_b64 s[54:55], s[54:55], exec
	s_cselect_b32 s79, s21, s68
	s_cselect_b32 s78, s23, s64
	s_add_u32 s82, s65, 0x10080
	s_addc_u32 s83, s70, 0
	s_add_u32 s80, s78, 0x10000
	s_addc_u32 s81, s79, 0
	s_add_u32 s64, s74, 0x10000
	s_addc_u32 s65, s75, 0
	s_add_u32 s54, s78, 0x10080
	s_addc_u32 s55, s79, 0
	s_mov_b32 m0, s35
	ds_read_b128 v[204:207], v139
	ds_read_b128 v[208:211], v139 offset:1024
	ds_read_b128 v[212:215], v139 offset:2048
	ds_read_b128 v[216:219], v139 offset:3072
	ds_read_b128 v[220:223], v139 offset:4096
	ds_read_b128 v[224:227], v139 offset:5120
	ds_read_b128 v[228:231], v139 offset:6144
	ds_read_b128 v[232:235], v139 offset:7168
	global_load_lds_dwordx4 v128, s[82:83]
	s_mov_b32 m0, s60
	s_nop 0
	global_load_lds_dwordx4 v130, s[82:83]
	s_waitcnt vmcnt(8)
	s_waitcnt lgkmcnt(0)
	s_barrier
	s_setprio 1
	s_waitcnt lgkmcnt(0)
	v_mfma_f32_16x16x32_bf16 v[124:127], v[170:173], v[204:207], v[124:127]
	v_mfma_f32_16x16x32_bf16 v[120:123], v[178:181], v[204:207], v[120:123]
	v_mfma_f32_16x16x32_bf16 v[108:111], v[170:173], v[212:215], v[108:111]
	v_mfma_f32_16x16x32_bf16 v[104:107], v[178:181], v[212:215], v[104:107]
	v_mfma_f32_16x16x32_bf16 v[92:95], v[170:173], v[220:223], v[92:95]
	v_mfma_f32_16x16x32_bf16 v[88:91], v[178:181], v[220:223], v[88:91]
	v_mfma_f32_16x16x32_bf16 v[76:79], v[170:173], v[228:231], v[76:79]
	v_mfma_f32_16x16x32_bf16 v[72:75], v[178:181], v[228:231], v[72:75]
	v_mfma_f32_16x16x32_bf16 v[124:127], v[174:177], v[208:211], v[124:127]
	v_mfma_f32_16x16x32_bf16 v[120:123], v[182:185], v[208:211], v[120:123]
	v_mfma_f32_16x16x32_bf16 v[108:111], v[174:177], v[216:219], v[108:111]
	v_mfma_f32_16x16x32_bf16 v[104:107], v[182:185], v[216:219], v[104:107]
	v_mfma_f32_16x16x32_bf16 v[92:95], v[174:177], v[224:227], v[92:95]
	v_mfma_f32_16x16x32_bf16 v[88:91], v[182:185], v[224:227], v[88:91]
	v_mfma_f32_16x16x32_bf16 v[76:79], v[174:177], v[232:235], v[76:79]
	v_mfma_f32_16x16x32_bf16 v[72:75], v[182:185], v[232:235], v[72:75]
	s_setprio 0
	s_setprio 1
	v_mfma_f32_16x16x32_bf16 v[116:119], v[186:189], v[204:207], v[116:119]
	v_mfma_f32_16x16x32_bf16 v[112:115], v[196:199], v[204:207], v[112:115]
	v_mfma_f32_16x16x32_bf16 v[100:103], v[186:189], v[212:215], v[100:103]
	v_mfma_f32_16x16x32_bf16 v[96:99], v[196:199], v[212:215], v[96:99]
	v_mfma_f32_16x16x32_bf16 v[84:87], v[186:189], v[220:223], v[84:87]
	v_mfma_f32_16x16x32_bf16 v[80:83], v[196:199], v[220:223], v[80:83]
	v_mfma_f32_16x16x32_bf16 v[68:71], v[186:189], v[228:231], v[68:71]
	v_mfma_f32_16x16x32_bf16 v[64:67], v[196:199], v[228:231], v[64:67]
	v_mfma_f32_16x16x32_bf16 v[116:119], v[190:193], v[208:211], v[116:119]
	v_mfma_f32_16x16x32_bf16 v[112:115], v[200:203], v[208:211], v[112:115]
	v_mfma_f32_16x16x32_bf16 v[100:103], v[190:193], v[216:219], v[100:103]
	v_mfma_f32_16x16x32_bf16 v[96:99], v[200:203], v[216:219], v[96:99]
	v_mfma_f32_16x16x32_bf16 v[84:87], v[190:193], v[224:227], v[84:87]
	v_mfma_f32_16x16x32_bf16 v[80:83], v[200:203], v[224:227], v[80:83]
	v_mfma_f32_16x16x32_bf16 v[68:71], v[190:193], v[232:235], v[68:71]
	v_mfma_f32_16x16x32_bf16 v[64:67], v[200:203], v[232:235], v[64:67]
	s_setprio 0
	s_barrier
	s_add_u32 s98, s78, s16
	s_addc_u32 s99, s79, s17
	s_add_u32 s100, s74, s16
	s_addc_u32 s101, s75, s17
	s_mov_b32 m0, s45
	ds_read_b128 v[204:207], v139 offset:16384
	ds_read_b128 v[208:211], v139 offset:17408
	ds_read_b128 v[212:215], v139 offset:18432
	ds_read_b128 v[216:219], v139 offset:19456
	ds_read_b128 v[220:223], v139 offset:20480
	ds_read_b128 v[224:227], v139 offset:21504
	ds_read_b128 v[228:231], v139 offset:22528
	ds_read_b128 v[232:235], v139 offset:23552
	global_load_lds_dwordx4 v128, s[78:79]
	s_mov_b32 m0, s67
	s_nop 0
	global_load_lds_dwordx4 v130, s[78:79]
	s_mov_b32 m0, s84
	s_nop 0
	global_load_lds_dwordx4 v128, s[80:81]
	s_mov_b32 m0, s85
	s_nop 0
	global_load_lds_dwordx4 v130, s[80:81]
	s_mov_b32 m0, s30
	s_nop 0
	global_load_lds_dwordx4 v128, s[74:75]
	s_mov_b32 m0, s86
	s_nop 0
	global_load_lds_dwordx4 v130, s[74:75]
	s_waitcnt vmcnt(8)
	s_waitcnt lgkmcnt(0)
	s_barrier
	s_setprio 1
	s_waitcnt lgkmcnt(0)
	v_mfma_f32_16x16x32_bf16 v[60:63], v[170:173], v[204:207], v[60:63]
	v_mfma_f32_16x16x32_bf16 v[56:59], v[178:181], v[204:207], v[56:59]
	v_mfma_f32_16x16x32_bf16 v[44:47], v[170:173], v[212:215], v[44:47]
	v_mfma_f32_16x16x32_bf16 v[40:43], v[178:181], v[212:215], v[40:43]
	v_mfma_f32_16x16x32_bf16 v[28:31], v[170:173], v[220:223], v[28:31]
	v_mfma_f32_16x16x32_bf16 v[24:27], v[178:181], v[220:223], v[24:27]
	v_mfma_f32_16x16x32_bf16 v[12:15], v[170:173], v[228:231], v[12:15]
	v_mfma_f32_16x16x32_bf16 v[8:11], v[178:181], v[228:231], v[8:11]
	v_mfma_f32_16x16x32_bf16 v[60:63], v[174:177], v[208:211], v[60:63]
	v_mfma_f32_16x16x32_bf16 v[56:59], v[182:185], v[208:211], v[56:59]
	v_mfma_f32_16x16x32_bf16 v[44:47], v[174:177], v[216:219], v[44:47]
	v_mfma_f32_16x16x32_bf16 v[40:43], v[182:185], v[216:219], v[40:43]
	v_mfma_f32_16x16x32_bf16 v[28:31], v[174:177], v[224:227], v[28:31]
	v_mfma_f32_16x16x32_bf16 v[24:27], v[182:185], v[224:227], v[24:27]
	v_mfma_f32_16x16x32_bf16 v[12:15], v[174:177], v[232:235], v[12:15]
	v_mfma_f32_16x16x32_bf16 v[8:11], v[182:185], v[232:235], v[8:11]
	s_setprio 0
	s_setprio 1
	v_mfma_f32_16x16x32_bf16 v[52:55], v[186:189], v[204:207], v[52:55]
	v_mfma_f32_16x16x32_bf16 v[48:51], v[196:199], v[204:207], v[48:51]
	v_mfma_f32_16x16x32_bf16 v[36:39], v[186:189], v[212:215], v[36:39]
	v_mfma_f32_16x16x32_bf16 v[32:35], v[196:199], v[212:215], v[32:35]
	v_mfma_f32_16x16x32_bf16 v[20:23], v[186:189], v[220:223], v[20:23]
	v_mfma_f32_16x16x32_bf16 v[16:19], v[196:199], v[220:223], v[16:19]
	v_mfma_f32_16x16x32_bf16 v[4:7], v[186:189], v[228:231], v[4:7]
	v_mfma_f32_16x16x32_bf16 v[0:3], v[196:199], v[228:231], v[0:3]
	v_mfma_f32_16x16x32_bf16 v[52:55], v[190:193], v[208:211], v[52:55]
	v_mfma_f32_16x16x32_bf16 v[48:51], v[200:203], v[208:211], v[48:51]
	v_mfma_f32_16x16x32_bf16 v[36:39], v[190:193], v[216:219], v[36:39]
	v_mfma_f32_16x16x32_bf16 v[32:35], v[200:203], v[216:219], v[32:35]
	v_mfma_f32_16x16x32_bf16 v[20:23], v[190:193], v[224:227], v[20:23]
	v_mfma_f32_16x16x32_bf16 v[16:19], v[200:203], v[224:227], v[16:19]
	v_mfma_f32_16x16x32_bf16 v[4:7], v[190:193], v[232:235], v[4:7]
	v_mfma_f32_16x16x32_bf16 v[0:3], v[200:203], v[232:235], v[0:3]
	s_setprio 0
	s_barrier
	ds_read_b128 v[170:173], v162
	ds_read_b128 v[174:177], v163
	ds_read_b128 v[178:181], v164
	ds_read_b128 v[182:185], v165
	ds_read_b128 v[186:189], v166
	ds_read_b128 v[190:193], v167
	ds_read_b128 v[196:199], v168
	ds_read_b128 v[200:203], v169
	s_mov_b32 m0, s87
	ds_read_b128 v[204:207], v139 offset:32768
	ds_read_b128 v[208:211], v139 offset:33792
	ds_read_b128 v[212:215], v139 offset:34816
	ds_read_b128 v[216:219], v139 offset:35840
	ds_read_b128 v[220:223], v139 offset:36864
	ds_read_b128 v[224:227], v139 offset:37888
	ds_read_b128 v[228:231], v139 offset:38912
	ds_read_b128 v[232:235], v139 offset:39936
	global_load_lds_dwordx4 v128, s[64:65]
	s_mov_b32 m0, s90
	s_nop 0
	global_load_lds_dwordx4 v130, s[64:65]
	s_waitcnt vmcnt(8)
	s_waitcnt lgkmcnt(0)
	s_barrier
	s_setprio 1
	s_waitcnt lgkmcnt(0)
	v_mfma_f32_16x16x32_bf16 v[124:127], v[170:173], v[204:207], v[124:127]
	v_mfma_f32_16x16x32_bf16 v[120:123], v[178:181], v[204:207], v[120:123]
	v_mfma_f32_16x16x32_bf16 v[108:111], v[170:173], v[212:215], v[108:111]
	v_mfma_f32_16x16x32_bf16 v[104:107], v[178:181], v[212:215], v[104:107]
	v_mfma_f32_16x16x32_bf16 v[92:95], v[170:173], v[220:223], v[92:95]
	v_mfma_f32_16x16x32_bf16 v[88:91], v[178:181], v[220:223], v[88:91]
	v_mfma_f32_16x16x32_bf16 v[76:79], v[170:173], v[228:231], v[76:79]
	v_mfma_f32_16x16x32_bf16 v[72:75], v[178:181], v[228:231], v[72:75]
	v_mfma_f32_16x16x32_bf16 v[124:127], v[174:177], v[208:211], v[124:127]
	v_mfma_f32_16x16x32_bf16 v[120:123], v[182:185], v[208:211], v[120:123]
	v_mfma_f32_16x16x32_bf16 v[108:111], v[174:177], v[216:219], v[108:111]
	v_mfma_f32_16x16x32_bf16 v[104:107], v[182:185], v[216:219], v[104:107]
	v_mfma_f32_16x16x32_bf16 v[92:95], v[174:177], v[224:227], v[92:95]
	v_mfma_f32_16x16x32_bf16 v[88:91], v[182:185], v[224:227], v[88:91]
	v_mfma_f32_16x16x32_bf16 v[76:79], v[174:177], v[232:235], v[76:79]
	v_mfma_f32_16x16x32_bf16 v[72:75], v[182:185], v[232:235], v[72:75]
	s_setprio 0
	s_setprio 1
	v_mfma_f32_16x16x32_bf16 v[116:119], v[186:189], v[204:207], v[116:119]
	v_mfma_f32_16x16x32_bf16 v[112:115], v[196:199], v[204:207], v[112:115]
	v_mfma_f32_16x16x32_bf16 v[100:103], v[186:189], v[212:215], v[100:103]
	v_mfma_f32_16x16x32_bf16 v[96:99], v[196:199], v[212:215], v[96:99]
	v_mfma_f32_16x16x32_bf16 v[84:87], v[186:189], v[220:223], v[84:87]
	v_mfma_f32_16x16x32_bf16 v[80:83], v[196:199], v[220:223], v[80:83]
	v_mfma_f32_16x16x32_bf16 v[68:71], v[186:189], v[228:231], v[68:71]
	v_mfma_f32_16x16x32_bf16 v[64:67], v[196:199], v[228:231], v[64:67]
	v_mfma_f32_16x16x32_bf16 v[116:119], v[190:193], v[208:211], v[116:119]
	v_mfma_f32_16x16x32_bf16 v[112:115], v[200:203], v[208:211], v[112:115]
	v_mfma_f32_16x16x32_bf16 v[100:103], v[190:193], v[216:219], v[100:103]
	v_mfma_f32_16x16x32_bf16 v[96:99], v[200:203], v[216:219], v[96:99]
	v_mfma_f32_16x16x32_bf16 v[84:87], v[190:193], v[224:227], v[84:87]
	v_mfma_f32_16x16x32_bf16 v[80:83], v[200:203], v[224:227], v[80:83]
	v_mfma_f32_16x16x32_bf16 v[68:71], v[190:193], v[232:235], v[68:71]
	v_mfma_f32_16x16x32_bf16 v[64:67], v[200:203], v[232:235], v[64:67]
	s_setprio 0
	s_barrier
	s_mov_b32 m0, s33
	ds_read_b128 v[204:207], v139 offset:49152
	ds_read_b128 v[208:211], v139 offset:50176
	ds_read_b128 v[212:215], v139 offset:51200
	ds_read_b128 v[216:219], v139 offset:52224
	ds_read_b128 v[220:223], v139 offset:53248
	ds_read_b128 v[224:227], v139 offset:54272
	ds_read_b128 v[228:231], v139 offset:55296
	ds_read_b128 v[232:235], v139 offset:56320
	global_load_lds_dwordx4 v128, s[98:99]
	s_mov_b32 m0, s9
	s_nop 0
	global_load_lds_dwordx4 v130, s[98:99]
	s_mov_b32 m0, s52
	s_nop 0
	global_load_lds_dwordx4 v128, s[54:55]
	s_mov_b32 m0, s61
	s_nop 0
	global_load_lds_dwordx4 v130, s[54:55]
	s_mov_b32 m0, s8
	s_nop 0
	global_load_lds_dwordx4 v128, s[100:101]
	s_mov_b32 m0, s53
	s_nop 0
	global_load_lds_dwordx4 v130, s[100:101]
	s_waitcnt vmcnt(8)
	s_waitcnt lgkmcnt(0)
	s_barrier
	s_setprio 1
	s_waitcnt lgkmcnt(0)
	v_mfma_f32_16x16x32_bf16 v[60:63], v[170:173], v[204:207], v[60:63]
	v_mfma_f32_16x16x32_bf16 v[56:59], v[178:181], v[204:207], v[56:59]
	v_mfma_f32_16x16x32_bf16 v[44:47], v[170:173], v[212:215], v[44:47]
	v_mfma_f32_16x16x32_bf16 v[40:43], v[178:181], v[212:215], v[40:43]
	v_mfma_f32_16x16x32_bf16 v[28:31], v[170:173], v[220:223], v[28:31]
	v_mfma_f32_16x16x32_bf16 v[24:27], v[178:181], v[220:223], v[24:27]
	v_mfma_f32_16x16x32_bf16 v[12:15], v[170:173], v[228:231], v[12:15]
	v_mfma_f32_16x16x32_bf16 v[8:11], v[178:181], v[228:231], v[8:11]
	v_mfma_f32_16x16x32_bf16 v[60:63], v[174:177], v[208:211], v[60:63]
	v_mfma_f32_16x16x32_bf16 v[56:59], v[182:185], v[208:211], v[56:59]
	v_mfma_f32_16x16x32_bf16 v[44:47], v[174:177], v[216:219], v[44:47]
	v_mfma_f32_16x16x32_bf16 v[40:43], v[182:185], v[216:219], v[40:43]
	v_mfma_f32_16x16x32_bf16 v[28:31], v[174:177], v[224:227], v[28:31]
	v_mfma_f32_16x16x32_bf16 v[24:27], v[182:185], v[224:227], v[24:27]
	v_mfma_f32_16x16x32_bf16 v[12:15], v[174:177], v[232:235], v[12:15]
	v_mfma_f32_16x16x32_bf16 v[8:11], v[182:185], v[232:235], v[8:11]
	s_setprio 0
	s_setprio 1
	v_mfma_f32_16x16x32_bf16 v[52:55], v[186:189], v[204:207], v[52:55]
	v_mfma_f32_16x16x32_bf16 v[48:51], v[196:199], v[204:207], v[48:51]
	v_mfma_f32_16x16x32_bf16 v[36:39], v[186:189], v[212:215], v[36:39]
	v_mfma_f32_16x16x32_bf16 v[32:35], v[196:199], v[212:215], v[32:35]
	v_mfma_f32_16x16x32_bf16 v[20:23], v[186:189], v[220:223], v[20:23]
	v_mfma_f32_16x16x32_bf16 v[16:19], v[196:199], v[220:223], v[16:19]
	v_mfma_f32_16x16x32_bf16 v[4:7], v[186:189], v[228:231], v[4:7]
	v_mfma_f32_16x16x32_bf16 v[0:3], v[196:199], v[228:231], v[0:3]
	v_mfma_f32_16x16x32_bf16 v[52:55], v[190:193], v[208:211], v[52:55]
	v_mfma_f32_16x16x32_bf16 v[48:51], v[200:203], v[208:211], v[48:51]
	v_mfma_f32_16x16x32_bf16 v[36:39], v[190:193], v[216:219], v[36:39]
	v_mfma_f32_16x16x32_bf16 v[32:35], v[200:203], v[216:219], v[32:35]
	v_mfma_f32_16x16x32_bf16 v[20:23], v[190:193], v[224:227], v[20:23]
	v_mfma_f32_16x16x32_bf16 v[16:19], v[200:203], v[224:227], v[16:19]
	v_mfma_f32_16x16x32_bf16 v[4:7], v[190:193], v[232:235], v[4:7]
	v_mfma_f32_16x16x32_bf16 v[0:3], v[200:203], v[232:235], v[0:3]
	s_setprio 0
	s_barrier
	s_movk_i32 s64, 0x100
	s_andn2_b64 vcc, exec, s[50:51]
	s_mov_b64 s[54:55], -1
	s_mov_b64 s[50:51], 0
	s_cbranch_vccz .LBB0_2628
	s_and_b64 vcc, exec, s[18:19]
	s_cbranch_vccz .LBB0_2631
	s_barrier

.LBB0_2791:
	s_lshl_b32 s5, s5, 5
	s_add_i32 s31, s6, 0x18000
	s_mov_b64 s[18:19], 0x80
	s_and_b32 s24, s5, 0x60
	v_lshl_add_u64 v[6:7], v[6:7], 0, s[18:19]
	s_mov_b32 m0, s31
	s_add_i32 s33, s6, 0x1a000
	s_lshl_b32 s22, s4, 13
	s_lshl_b32 s5, s24, 7
	s_waitcnt vmcnt(2)
	s_barrier
	global_load_lds_dwordx4 v[6:7], off
	v_lshl_add_u64 v[4:5], v[4:5], 0, s[18:19]
	s_mov_b32 m0, s33
	s_add_i32 s34, s6, 0x8000
	s_add_i32 s35, s6, 0xa000
	global_load_lds_dwordx4 v[4:5], off
	v_lshl_add_u64 v[0:1], v[0:1], 0, s[18:19]
	s_mov_b32 m0, s34
	s_add_u32 s20, s46, 0x40080
	global_load_lds_dwordx4 v[0:1], off
	v_lshl_add_u64 v[0:1], v[2:3], 0, s[18:19]
	s_mov_b32 m0, s35
	s_addc_u32 s21, s47, 0
	s_add_i32 s36, s6, 0x1c000
	global_load_lds_dwordx4 v[0:1], off
	s_mov_b32 m0, s36
	s_add_i32 s37, s6, 0x1e000
	global_load_lds_dwordx4 v158, s[20:21]
	s_mov_b32 m0, s37
	s_cmpk_lt_u32 s11, 0x100
	global_load_lds_dwordx4 v160, s[20:21]
	v_bfe_u32 v0, v8, 4, 2
	v_lshlrev_b32_e32 v2, 4, v0
	v_lshl_or_b32 v193, v0, 2, s24
	v_lshlrev_b32_e32 v0, 13, v9
	v_and_b32_e32 v1, 15, v8
	v_and_b32_e32 v0, 0x7fffc000, v0
	v_lshl_or_b32 v153, s4, 6, v1
	v_lshl_or_b32 v1, v1, 6, v2
	v_lshlrev_b32_e32 v2, 2, v8
	v_lshl_add_u32 v0, v10, 10, v0
	v_and_b32_e32 v2, 32, v2
	v_or_b32_e32 v0, v0, v11
	v_bitop3_b32 v192, v1, s22, v2 bitop3:0xde
	v_bitop3_b32 v2, v1, s5, v2 bitop3:0xde
	s_mov_b64 s[4:5], 0x40080
	v_add_lshl_u32 v0, v0, v12, 1
	v_mov_b32_e32 v1, v159
	v_lshl_add_u64 v[162:163], v[0:1], 0, s[4:5]
	v_lshlrev_b32_e32 v0, 13, v13
	v_and_b32_e32 v0, 0x7fffc000, v0
	v_lshl_add_u32 v0, v14, 10, v0
	s_waitcnt vmcnt(6)
	v_or_b32_e32 v0, v0, v15
	v_add_lshl_u32 v0, v0, v16, 1
	s_sext_i32_i8 s65, s10
	s_movk_i32 s43, 0x100
	s_cselect_b64 s[20:21], -1, 0
	s_ashr_i32 s52, s82, 31
	s_mov_b32 s53, s82
	v_lshl_add_u64 v[164:165], v[0:1], 0, s[4:5]
	s_mov_b32 s54, 0
	v_mov_b64_e32 v[166:167], 0x200
	v_mov_b64_e32 v[168:169], 0x1ff
	v_or_b32_e32 v195, 0x10000, v2
	v_add_u32_e32 v196, 0x10400, v2
	v_add_u32_e32 v197, 0x10800, v2
	v_add_u32_e32 v198, 0x10c00, v2
	v_or_b32_e32 v199, 0x14000, v2
	v_add_u32_e32 v200, 0x14400, v2
	v_add_u32_e32 v201, 0x14800, v2
	v_add_u32_e32 v202, 0x14c00, v2
	s_add_i32 s55, s6, 0xc000
	s_add_i32 s60, s6, 0xe000
	v_or_b32_e32 v203, 0x18000, v2
	v_add_u32_e32 v204, 0x18400, v2
	v_add_u32_e32 v205, 0x18800, v2
	v_add_u32_e32 v206, 0x18c00, v2
	v_or_b32_e32 v207, 0x1c000, v2
	v_add_u32_e32 v208, 0x1c400, v2
	v_add_u32_e32 v209, 0x1c800, v2
	v_add_u32_e32 v210, 0x1cc00, v2
	s_mov_b32 s61, 0x3e0f83e1
	s_movk_i32 s64, 0xdf00
	s_mov_b32 s22, 0x3fd744fd
	v_mov_b32_e32 v211, 0xffffff00
	s_barrier
	s_branch .LBB0_2794

.LBB0_2801:
	ds_read_b128 v[128:131], v195
	ds_read_b128 v[132:135], v196
	ds_read_b128 v[136:139], v197
	ds_read_b128 v[140:143], v198
	ds_read_b128 v[170:173], v199
	ds_read_b128 v[174:177], v200
	ds_read_b128 v[178:181], v201
	ds_read_b128 v[182:185], v202
	s_add_u32 s46, s44, 0x100
	s_addc_u32 s47, s45, 0
	s_cmp_eq_u32 s68, 12
	s_cselect_b32 s51, s4, s47
	s_cselect_b32 s50, s5, s46
	s_cselect_b32 s49, s25, s67
	s_cselect_b32 s48, s27, s66
	s_mov_b32 m0, s55
	ds_read_b128 v[186:189], v192
	ds_read_b128 v[212:215], v192 offset:1024
	ds_read_b128 v[216:219], v192 offset:2048
	ds_read_b128 v[220:223], v192 offset:3072
	ds_read_b128 v[224:227], v192 offset:4096
	ds_read_b128 v[228:231], v192 offset:5120
	ds_read_b128 v[232:235], v192 offset:6144
	ds_read_b128 v[236:239], v192 offset:7168
	global_load_lds_dwordx4 v162, s[44:45]
	s_mov_b32 m0, s60
	s_nop 0
	global_load_lds_dwordx4 v164, s[44:45]
	s_waitcnt vmcnt(8)
	s_waitcnt lgkmcnt(0)
	s_barrier
	s_setprio 1
	s_waitcnt lgkmcnt(0)
	v_mfma_f32_16x16x32_bf16 v[124:127], v[128:131], v[186:189], v[124:127]
	v_mfma_f32_16x16x32_bf16 v[120:123], v[136:139], v[186:189], v[120:123]
	v_mfma_f32_16x16x32_bf16 v[108:111], v[128:131], v[216:219], v[108:111]
	v_mfma_f32_16x16x32_bf16 v[104:107], v[136:139], v[216:219], v[104:107]
	v_mfma_f32_16x16x32_bf16 v[92:95], v[128:131], v[224:227], v[92:95]
	v_mfma_f32_16x16x32_bf16 v[88:91], v[136:139], v[224:227], v[88:91]
	v_mfma_f32_16x16x32_bf16 v[76:79], v[128:131], v[232:235], v[76:79]
	v_mfma_f32_16x16x32_bf16 v[72:75], v[136:139], v[232:235], v[72:75]
	v_mfma_f32_16x16x32_bf16 v[124:127], v[132:135], v[212:215], v[124:127]
	v_mfma_f32_16x16x32_bf16 v[120:123], v[140:143], v[212:215], v[120:123]
	v_mfma_f32_16x16x32_bf16 v[108:111], v[132:135], v[220:223], v[108:111]
	v_mfma_f32_16x16x32_bf16 v[104:107], v[140:143], v[220:223], v[104:107]
	v_mfma_f32_16x16x32_bf16 v[92:95], v[132:135], v[228:231], v[92:95]
	v_mfma_f32_16x16x32_bf16 v[88:91], v[140:143], v[228:231], v[88:91]
	v_mfma_f32_16x16x32_bf16 v[76:79], v[132:135], v[236:239], v[76:79]
	v_mfma_f32_16x16x32_bf16 v[72:75], v[140:143], v[236:239], v[72:75]
	s_setprio 0
	s_setprio 1
	v_mfma_f32_16x16x32_bf16 v[116:119], v[170:173], v[186:189], v[116:119]
	v_mfma_f32_16x16x32_bf16 v[112:115], v[178:181], v[186:189], v[112:115]
	v_mfma_f32_16x16x32_bf16 v[100:103], v[170:173], v[216:219], v[100:103]
	v_mfma_f32_16x16x32_bf16 v[96:99], v[178:181], v[216:219], v[96:99]
	v_mfma_f32_16x16x32_bf16 v[84:87], v[170:173], v[224:227], v[84:87]
	v_mfma_f32_16x16x32_bf16 v[80:83], v[178:181], v[224:227], v[80:83]
	v_mfma_f32_16x16x32_bf16 v[68:71], v[170:173], v[232:235], v[68:71]
	v_mfma_f32_16x16x32_bf16 v[64:67], v[178:181], v[232:235], v[64:67]
	v_mfma_f32_16x16x32_bf16 v[116:119], v[174:177], v[212:215], v[116:119]
	v_mfma_f32_16x16x32_bf16 v[112:115], v[182:185], v[212:215], v[112:115]
	v_mfma_f32_16x16x32_bf16 v[100:103], v[174:177], v[220:223], v[100:103]
	v_mfma_f32_16x16x32_bf16 v[96:99], v[182:185], v[220:223], v[96:99]
	v_mfma_f32_16x16x32_bf16 v[84:87], v[174:177], v[228:231], v[84:87]
	v_mfma_f32_16x16x32_bf16 v[80:83], v[182:185], v[228:231], v[80:83]
	v_mfma_f32_16x16x32_bf16 v[68:71], v[174:177], v[236:239], v[68:71]
	v_mfma_f32_16x16x32_bf16 v[64:67], v[182:185], v[236:239], v[64:67]
	s_setprio 0
	s_barrier
	s_add_u32 s98, s48, s18
	s_addc_u32 s99, s49, s19
	s_add_u32 s100, s50, s18
	s_addc_u32 s101, s51, s19
	s_mov_b32 m0, s7
	s_add_u32 s44, s48, 0x40000
	ds_read_b128 v[186:189], v192 offset:16384
	ds_read_b128 v[212:215], v192 offset:17408
	ds_read_b128 v[216:219], v192 offset:18432
	ds_read_b128 v[220:223], v192 offset:19456
	ds_read_b128 v[224:227], v192 offset:20480
	ds_read_b128 v[228:231], v192 offset:21504
	ds_read_b128 v[232:235], v192 offset:22528
	ds_read_b128 v[236:239], v192 offset:23552
	global_load_lds_dwordx4 v158, s[48:49]
	s_mov_b32 m0, s8
	s_addc_u32 s45, s49, 0
	global_load_lds_dwordx4 v160, s[48:49]
	s_mov_b32 m0, s9
	s_nop 0
	global_load_lds_dwordx4 v158, s[44:45]
	s_mov_b32 m0, s23
	s_nop 0
	global_load_lds_dwordx4 v160, s[44:45]
	s_mov_b32 m0, s6
	s_nop 0
	global_load_lds_dwordx4 v158, s[50:51]
	s_mov_b32 m0, s28
	s_nop 0
	global_load_lds_dwordx4 v160, s[50:51]
	s_waitcnt vmcnt(8)
	s_waitcnt lgkmcnt(0)
	s_barrier
	s_setprio 1
	s_waitcnt lgkmcnt(0)
	v_mfma_f32_16x16x32_bf16 v[60:63], v[128:131], v[186:189], v[60:63]
	v_mfma_f32_16x16x32_bf16 v[56:59], v[136:139], v[186:189], v[56:59]
	v_mfma_f32_16x16x32_bf16 v[44:47], v[128:131], v[216:219], v[44:47]
	v_mfma_f32_16x16x32_bf16 v[40:43], v[136:139], v[216:219], v[40:43]
	v_mfma_f32_16x16x32_bf16 v[28:31], v[128:131], v[224:227], v[28:31]
	v_mfma_f32_16x16x32_bf16 v[24:27], v[136:139], v[224:227], v[24:27]
	v_mfma_f32_16x16x32_bf16 v[12:15], v[128:131], v[232:235], v[12:15]
	v_mfma_f32_16x16x32_bf16 v[8:11], v[136:139], v[232:235], v[8:11]
	v_mfma_f32_16x16x32_bf16 v[60:63], v[132:135], v[212:215], v[60:63]
	v_mfma_f32_16x16x32_bf16 v[56:59], v[140:143], v[212:215], v[56:59]
	v_mfma_f32_16x16x32_bf16 v[44:47], v[132:135], v[220:223], v[44:47]
	v_mfma_f32_16x16x32_bf16 v[40:43], v[140:143], v[220:223], v[40:43]
	v_mfma_f32_16x16x32_bf16 v[28:31], v[132:135], v[228:231], v[28:31]
	v_mfma_f32_16x16x32_bf16 v[24:27], v[140:143], v[228:231], v[24:27]
	v_mfma_f32_16x16x32_bf16 v[12:15], v[132:135], v[236:239], v[12:15]
	v_mfma_f32_16x16x32_bf16 v[8:11], v[140:143], v[236:239], v[8:11]
	s_setprio 0
	s_setprio 1
	v_mfma_f32_16x16x32_bf16 v[52:55], v[170:173], v[186:189], v[52:55]
	v_mfma_f32_16x16x32_bf16 v[48:51], v[178:181], v[186:189], v[48:51]
	v_mfma_f32_16x16x32_bf16 v[36:39], v[170:173], v[216:219], v[36:39]
	v_mfma_f32_16x16x32_bf16 v[32:35], v[178:181], v[216:219], v[32:35]
	v_mfma_f32_16x16x32_bf16 v[20:23], v[170:173], v[224:227], v[20:23]
	v_mfma_f32_16x16x32_bf16 v[16:19], v[178:181], v[224:227], v[16:19]
	v_mfma_f32_16x16x32_bf16 v[4:7], v[170:173], v[232:235], v[4:7]
	v_mfma_f32_16x16x32_bf16 v[0:3], v[178:181], v[232:235], v[0:3]
	v_mfma_f32_16x16x32_bf16 v[52:55], v[174:177], v[212:215], v[52:55]
	v_mfma_f32_16x16x32_bf16 v[48:51], v[182:185], v[212:215], v[48:51]
	v_mfma_f32_16x16x32_bf16 v[36:39], v[174:177], v[220:223], v[36:39]
	v_mfma_f32_16x16x32_bf16 v[32:35], v[182:185], v[220:223], v[32:35]
	v_mfma_f32_16x16x32_bf16 v[20:23], v[174:177], v[228:231], v[20:23]
	v_mfma_f32_16x16x32_bf16 v[16:19], v[182:185], v[228:231], v[16:19]
	v_mfma_f32_16x16x32_bf16 v[4:7], v[174:177], v[236:239], v[4:7]
	v_mfma_f32_16x16x32_bf16 v[0:3], v[182:185], v[236:239], v[0:3]
	s_setprio 0
	s_barrier
	ds_read_b128 v[128:131], v203
	ds_read_b128 v[132:135], v204
	ds_read_b128 v[136:139], v205
	ds_read_b128 v[140:143], v206
	ds_read_b128 v[170:173], v207
	ds_read_b128 v[174:177], v208
	ds_read_b128 v[178:181], v209
	ds_read_b128 v[182:185], v210
	s_add_u32 s44, s50, 0x40000
	s_addc_u32 s45, s51, 0
	s_mov_b32 m0, s29
	ds_read_b128 v[186:189], v192 offset:32768
	ds_read_b128 v[212:215], v192 offset:33792
	ds_read_b128 v[216:219], v192 offset:34816
	ds_read_b128 v[220:223], v192 offset:35840
	ds_read_b128 v[224:227], v192 offset:36864
	ds_read_b128 v[228:231], v192 offset:37888
	ds_read_b128 v[232:235], v192 offset:38912
	ds_read_b128 v[236:239], v192 offset:39936
	global_load_lds_dwordx4 v158, s[44:45]
	s_mov_b32 m0, s30
	s_nop 0
	global_load_lds_dwordx4 v160, s[44:45]
	s_waitcnt vmcnt(8)
	s_waitcnt lgkmcnt(0)
	s_barrier
	s_setprio 1
	s_waitcnt lgkmcnt(0)
	v_mfma_f32_16x16x32_bf16 v[124:127], v[128:131], v[186:189], v[124:127]
	v_mfma_f32_16x16x32_bf16 v[120:123], v[136:139], v[186:189], v[120:123]
	v_mfma_f32_16x16x32_bf16 v[108:111], v[128:131], v[216:219], v[108:111]
	v_mfma_f32_16x16x32_bf16 v[104:107], v[136:139], v[216:219], v[104:107]
	v_mfma_f32_16x16x32_bf16 v[92:95], v[128:131], v[224:227], v[92:95]
	v_mfma_f32_16x16x32_bf16 v[88:91], v[136:139], v[224:227], v[88:91]
	v_mfma_f32_16x16x32_bf16 v[76:79], v[128:131], v[232:235], v[76:79]
	v_mfma_f32_16x16x32_bf16 v[72:75], v[136:139], v[232:235], v[72:75]
	v_mfma_f32_16x16x32_bf16 v[124:127], v[132:135], v[212:215], v[124:127]
	v_mfma_f32_16x16x32_bf16 v[120:123], v[140:143], v[212:215], v[120:123]
	v_mfma_f32_16x16x32_bf16 v[108:111], v[132:135], v[220:223], v[108:111]
	v_mfma_f32_16x16x32_bf16 v[104:107], v[140:143], v[220:223], v[104:107]
	v_mfma_f32_16x16x32_bf16 v[92:95], v[132:135], v[228:231], v[92:95]
	v_mfma_f32_16x16x32_bf16 v[88:91], v[140:143], v[228:231], v[88:91]
	v_mfma_f32_16x16x32_bf16 v[76:79], v[132:135], v[236:239], v[76:79]
	v_mfma_f32_16x16x32_bf16 v[72:75], v[140:143], v[236:239], v[72:75]
	s_setprio 0
	s_setprio 1
	v_mfma_f32_16x16x32_bf16 v[116:119], v[170:173], v[186:189], v[116:119]
	v_mfma_f32_16x16x32_bf16 v[112:115], v[178:181], v[186:189], v[112:115]
	v_mfma_f32_16x16x32_bf16 v[100:103], v[170:173], v[216:219], v[100:103]
	v_mfma_f32_16x16x32_bf16 v[96:99], v[178:181], v[216:219], v[96:99]
	v_mfma_f32_16x16x32_bf16 v[84:87], v[170:173], v[224:227], v[84:87]
	v_mfma_f32_16x16x32_bf16 v[80:83], v[178:181], v[224:227], v[80:83]
	v_mfma_f32_16x16x32_bf16 v[68:71], v[170:173], v[232:235], v[68:71]
	v_mfma_f32_16x16x32_bf16 v[64:67], v[178:181], v[232:235], v[64:67]
	v_mfma_f32_16x16x32_bf16 v[116:119], v[174:177], v[212:215], v[116:119]
	v_mfma_f32_16x16x32_bf16 v[112:115], v[182:185], v[212:215], v[112:115]
	v_mfma_f32_16x16x32_bf16 v[100:103], v[174:177], v[220:223], v[100:103]
	v_mfma_f32_16x16x32_bf16 v[96:99], v[182:185], v[220:223], v[96:99]
	v_mfma_f32_16x16x32_bf16 v[84:87], v[174:177], v[228:231], v[84:87]
	v_mfma_f32_16x16x32_bf16 v[80:83], v[182:185], v[228:231], v[80:83]
	v_mfma_f32_16x16x32_bf16 v[68:71], v[174:177], v[236:239], v[68:71]
	v_mfma_f32_16x16x32_bf16 v[64:67], v[182:185], v[236:239], v[64:67]
	s_setprio 0
	s_barrier
	s_mov_b32 m0, s31
	s_add_u32 s44, s48, 0x40080
	ds_read_b128 v[186:189], v192 offset:49152
	ds_read_b128 v[212:215], v192 offset:50176
	ds_read_b128 v[216:219], v192 offset:51200
	ds_read_b128 v[220:223], v192 offset:52224
	ds_read_b128 v[224:227], v192 offset:53248
	ds_read_b128 v[228:231], v192 offset:54272
	ds_read_b128 v[232:235], v192 offset:55296
	ds_read_b128 v[236:239], v192 offset:56320
	global_load_lds_dwordx4 v158, s[98:99]
	s_mov_b32 m0, s33
	s_addc_u32 s45, s49, 0
	global_load_lds_dwordx4 v160, s[98:99]
	s_mov_b32 m0, s36
	s_nop 0
	global_load_lds_dwordx4 v158, s[44:45]
	s_mov_b32 m0, s37
	s_nop 0
	global_load_lds_dwordx4 v160, s[44:45]
	s_mov_b32 m0, s34
	s_nop 0
	global_load_lds_dwordx4 v158, s[100:101]
	s_mov_b32 m0, s35
	s_nop 0
	global_load_lds_dwordx4 v160, s[100:101]
	s_waitcnt vmcnt(8)
	s_waitcnt lgkmcnt(0)
	s_barrier
	s_setprio 1
	s_waitcnt lgkmcnt(0)
	v_mfma_f32_16x16x32_bf16 v[60:63], v[128:131], v[186:189], v[60:63]
	v_mfma_f32_16x16x32_bf16 v[56:59], v[136:139], v[186:189], v[56:59]
	v_mfma_f32_16x16x32_bf16 v[44:47], v[128:131], v[216:219], v[44:47]
	v_mfma_f32_16x16x32_bf16 v[40:43], v[136:139], v[216:219], v[40:43]
	v_mfma_f32_16x16x32_bf16 v[28:31], v[128:131], v[224:227], v[28:31]
	v_mfma_f32_16x16x32_bf16 v[24:27], v[136:139], v[224:227], v[24:27]
	v_mfma_f32_16x16x32_bf16 v[12:15], v[128:131], v[232:235], v[12:15]
	v_mfma_f32_16x16x32_bf16 v[8:11], v[136:139], v[232:235], v[8:11]
	v_mfma_f32_16x16x32_bf16 v[60:63], v[132:135], v[212:215], v[60:63]
	v_mfma_f32_16x16x32_bf16 v[56:59], v[140:143], v[212:215], v[56:59]
	v_mfma_f32_16x16x32_bf16 v[44:47], v[132:135], v[220:223], v[44:47]
	v_mfma_f32_16x16x32_bf16 v[40:43], v[140:143], v[220:223], v[40:43]
	v_mfma_f32_16x16x32_bf16 v[28:31], v[132:135], v[228:231], v[28:31]
	v_mfma_f32_16x16x32_bf16 v[24:27], v[140:143], v[228:231], v[24:27]
	v_mfma_f32_16x16x32_bf16 v[12:15], v[132:135], v[236:239], v[12:15]
	v_mfma_f32_16x16x32_bf16 v[8:11], v[140:143], v[236:239], v[8:11]
	s_setprio 0
	s_setprio 1
	v_mfma_f32_16x16x32_bf16 v[52:55], v[170:173], v[186:189], v[52:55]
	v_mfma_f32_16x16x32_bf16 v[48:51], v[178:181], v[186:189], v[48:51]
	v_mfma_f32_16x16x32_bf16 v[36:39], v[170:173], v[216:219], v[36:39]
	v_mfma_f32_16x16x32_bf16 v[32:35], v[178:181], v[216:219], v[32:35]
	v_mfma_f32_16x16x32_bf16 v[20:23], v[170:173], v[224:227], v[20:23]
	v_mfma_f32_16x16x32_bf16 v[16:19], v[178:181], v[224:227], v[16:19]
	v_mfma_f32_16x16x32_bf16 v[4:7], v[170:173], v[232:235], v[4:7]
	v_mfma_f32_16x16x32_bf16 v[0:3], v[178:181], v[232:235], v[0:3]
	v_mfma_f32_16x16x32_bf16 v[52:55], v[174:177], v[212:215], v[52:55]
	v_mfma_f32_16x16x32_bf16 v[48:51], v[182:185], v[212:215], v[48:51]
	v_mfma_f32_16x16x32_bf16 v[36:39], v[174:177], v[220:223], v[36:39]
	v_mfma_f32_16x16x32_bf16 v[32:35], v[182:185], v[220:223], v[32:35]
	v_mfma_f32_16x16x32_bf16 v[20:23], v[174:177], v[228:231], v[20:23]
	v_mfma_f32_16x16x32_bf16 v[16:19], v[182:185], v[228:231], v[16:19]
	v_mfma_f32_16x16x32_bf16 v[4:7], v[174:177], v[236:239], v[4:7]
	v_mfma_f32_16x16x32_bf16 v[0:3], v[182:185], v[236:239], v[0:3]
	s_setprio 0
	s_barrier
	s_add_i32 s68, s68, 2
	s_add_u32 s66, s66, 0x100
	s_addc_u32 s67, s67, 0
	s_cmp_gt_u32 s68, 13
	s_mov_b64 s[44:45], s[46:47]
	s_cbranch_scc0 .LBB0_2801
	s_and_b64 vcc, exec, s[20:21]
	s_cbranch_vccz .LBB0_2804
	s_barrier

.LBB0_2943:
	s_lshl_b32 s9, s9, 5
	s_add_i32 s39, s2, 0x18000
	s_mov_b64 s[10:11], 0x80
	s_and_b32 s38, s9, 0x60
	v_lshl_add_u64 v[6:7], v[6:7], 0, s[10:11]
	s_mov_b32 m0, s39
	s_add_i32 s40, s2, 0x1a000
	s_lshl_b32 s14, s5, 13
	s_lshl_b32 s9, s38, 7
	s_waitcnt vmcnt(2)
	s_barrier
	global_load_lds_dwordx4 v[6:7], off
	v_lshl_add_u64 v[4:5], v[4:5], 0, s[10:11]
	s_mov_b32 m0, s40
	s_add_i32 s41, s2, 0x8000
	s_add_i32 s42, s2, 0xa000
	global_load_lds_dwordx4 v[4:5], off
	v_lshl_add_u64 v[0:1], v[0:1], 0, s[10:11]
	s_mov_b32 m0, s41
	s_add_u32 s12, s26, 0x40080
	global_load_lds_dwordx4 v[0:1], off
	v_lshl_add_u64 v[0:1], v[2:3], 0, s[10:11]
	s_mov_b32 m0, s42
	s_addc_u32 s13, s27, 0
	s_add_i32 s43, s2, 0x1c000
	global_load_lds_dwordx4 v[0:1], off
	s_mov_b32 m0, s43
	s_add_i32 s44, s2, 0x1e000
	global_load_lds_dwordx4 v130, s[12:13]
	s_mov_b32 m0, s44
	s_cmpk_lt_u32 s4, 0x100
	global_load_lds_dwordx4 v128, s[12:13]
	v_bfe_u32 v1, v9, 4, 2
	v_and_b32_e32 v0, 15, v9
	v_lshlrev_b32_e32 v2, 4, v1
	v_lshl_or_b32 v140, s5, 6, v0
	v_lshl_or_b32 v0, v0, 6, v2
	v_lshlrev_b32_e32 v2, 2, v9
	v_lshlrev_b32_e32 v142, 2, v1
	v_lshlrev_b32_e32 v1, 14, v12
	v_and_b32_e32 v2, 32, v2
	v_and_b32_e32 v1, 0xffff8000, v1
	v_bitop3_b32 v141, v0, s14, v2 bitop3:0xde
	v_bitop3_b32 v0, v0, s9, v2 bitop3:0xde
	v_lshl_add_u32 v1, v13, 11, v1
	v_and_b32_e32 v2, 1, v12
	v_lshl_or_b32 v1, v2, 6, v1
	s_waitcnt vmcnt(0)
	v_lshl_add_u32 v132, v14, 1, v1
	v_lshlrev_b32_e32 v1, 14, v8
	v_and_b32_e32 v1, 0xffff8000, v1
	s_waitcnt vmcnt(6)
	v_lshl_add_u32 v1, v10, 11, v1
	v_and_b32_e32 v2, 1, v8
	v_lshl_or_b32 v1, v2, 6, v1
	s_sext_i32_i16 s50, s8
	s_cselect_b64 s[12:13], -1, 0
	s_ashr_i32 s45, s82, 31
	s_mov_b32 s46, s82
	v_mov_b32_e32 v133, v131
	v_lshl_add_u32 v134, v11, 1, v1
	v_mov_b32_e32 v135, v131
	v_mov_b64_e32 v[136:137], 0xb58
	v_mov_b64_e32 v[138:139], 0xb57
	v_or_b32_e32 v143, 0x10000, v0
	v_add_u32_e32 v153, 0x10400, v0
	v_add_u32_e32 v158, 0x10800, v0
	v_add_u32_e32 v159, 0x10c00, v0
	v_or_b32_e32 v160, 0x14000, v0
	v_add_u32_e32 v161, 0x14400, v0
	v_add_u32_e32 v162, 0x14800, v0
	v_add_u32_e32 v163, 0x14c00, v0
	s_add_i32 s47, s2, 0xc000
	s_add_i32 s48, s2, 0xe000
	v_or_b32_e32 v164, 0x18000, v0
	v_add_u32_e32 v165, 0x18400, v0
	v_add_u32_e32 v166, 0x18800, v0
	v_add_u32_e32 v167, 0x18c00, v0
	v_or_b32_e32 v168, 0x1c000, v0
	v_add_u32_e32 v169, 0x1c400, v0
	v_add_u32_e32 v170, 0x1c800, v0
	v_add_u32_e32 v171, 0x1cc00, v0
	s_movk_i32 s49, 0x1600
	s_barrier
	s_branch .LBB0_2946

.LBB0_2949:
	ds_read_b128 v[172:175], v143
	ds_read_b128 v[176:179], v153
	ds_read_b128 v[180:183], v158
	ds_read_b128 v[184:187], v159
	ds_read_b128 v[188:191], v160
	ds_read_b128 v[196:199], v161
	ds_read_b128 v[200:203], v162
	ds_read_b128 v[204:207], v163
	s_add_u32 s26, s24, 0xfffc0080
	s_addc_u32 s27, s25, -1
	s_cmp_eq_u32 s53, 12
	s_cselect_b32 s37, s4, s27
	s_cselect_b32 s36, s5, s26
	s_cselect_b32 s27, s15, s52
	s_cselect_b32 s26, s17, s51
	s_mov_b32 m0, s47
	ds_read_b128 v[208:211], v141
	ds_read_b128 v[212:215], v141 offset:1024
	ds_read_b128 v[216:219], v141 offset:2048
	ds_read_b128 v[220:223], v141 offset:3072
	ds_read_b128 v[224:227], v141 offset:4096
	ds_read_b128 v[228:231], v141 offset:5120
	ds_read_b128 v[232:235], v141 offset:6144
	ds_read_b128 v[236:239], v141 offset:7168
	global_load_lds_dwordx4 v132, s[24:25]
	s_mov_b32 m0, s48
	s_nop 0
	global_load_lds_dwordx4 v134, s[24:25]
	s_waitcnt vmcnt(8)
	s_waitcnt lgkmcnt(0)
	s_barrier
	s_setprio 1
	s_waitcnt lgkmcnt(0)
	v_mfma_f32_16x16x32_bf16 v[124:127], v[172:175], v[208:211], v[124:127]
	v_mfma_f32_16x16x32_bf16 v[120:123], v[180:183], v[208:211], v[120:123]
	v_mfma_f32_16x16x32_bf16 v[108:111], v[172:175], v[216:219], v[108:111]
	v_mfma_f32_16x16x32_bf16 v[104:107], v[180:183], v[216:219], v[104:107]
	v_mfma_f32_16x16x32_bf16 v[92:95], v[172:175], v[224:227], v[92:95]
	v_mfma_f32_16x16x32_bf16 v[88:91], v[180:183], v[224:227], v[88:91]
	v_mfma_f32_16x16x32_bf16 v[76:79], v[172:175], v[232:235], v[76:79]
	v_mfma_f32_16x16x32_bf16 v[72:75], v[180:183], v[232:235], v[72:75]
	v_mfma_f32_16x16x32_bf16 v[124:127], v[176:179], v[212:215], v[124:127]
	v_mfma_f32_16x16x32_bf16 v[120:123], v[184:187], v[212:215], v[120:123]
	v_mfma_f32_16x16x32_bf16 v[108:111], v[176:179], v[220:223], v[108:111]
	v_mfma_f32_16x16x32_bf16 v[104:107], v[184:187], v[220:223], v[104:107]
	v_mfma_f32_16x16x32_bf16 v[92:95], v[176:179], v[228:231], v[92:95]
	v_mfma_f32_16x16x32_bf16 v[88:91], v[184:187], v[228:231], v[88:91]
	v_mfma_f32_16x16x32_bf16 v[76:79], v[176:179], v[236:239], v[76:79]
	v_mfma_f32_16x16x32_bf16 v[72:75], v[184:187], v[236:239], v[72:75]
	s_setprio 0
	s_setprio 1
	v_mfma_f32_16x16x32_bf16 v[116:119], v[188:191], v[208:211], v[116:119]
	v_mfma_f32_16x16x32_bf16 v[112:115], v[200:203], v[208:211], v[112:115]
	v_mfma_f32_16x16x32_bf16 v[100:103], v[188:191], v[216:219], v[100:103]
	v_mfma_f32_16x16x32_bf16 v[96:99], v[200:203], v[216:219], v[96:99]
	v_mfma_f32_16x16x32_bf16 v[84:87], v[188:191], v[224:227], v[84:87]
	v_mfma_f32_16x16x32_bf16 v[80:83], v[200:203], v[224:227], v[80:83]
	v_mfma_f32_16x16x32_bf16 v[68:71], v[188:191], v[232:235], v[68:71]
	v_mfma_f32_16x16x32_bf16 v[64:67], v[200:203], v[232:235], v[64:67]
	v_mfma_f32_16x16x32_bf16 v[116:119], v[196:199], v[212:215], v[116:119]
	v_mfma_f32_16x16x32_bf16 v[112:115], v[204:207], v[212:215], v[112:115]
	v_mfma_f32_16x16x32_bf16 v[100:103], v[196:199], v[220:223], v[100:103]
	v_mfma_f32_16x16x32_bf16 v[96:99], v[204:207], v[220:223], v[96:99]
	v_mfma_f32_16x16x32_bf16 v[84:87], v[196:199], v[228:231], v[84:87]
	v_mfma_f32_16x16x32_bf16 v[80:83], v[204:207], v[228:231], v[80:83]
	v_mfma_f32_16x16x32_bf16 v[68:71], v[196:199], v[236:239], v[68:71]
	v_mfma_f32_16x16x32_bf16 v[64:67], v[204:207], v[236:239], v[64:67]
	s_setprio 0
	s_barrier
	s_add_u32 s98, s26, s10
	s_addc_u32 s99, s27, s11
	s_add_u32 s100, s36, s10
	s_addc_u32 s101, s37, s11
	s_mov_b32 m0, s23
	s_add_u32 s54, s26, 0x40000
	ds_read_b128 v[208:211], v141 offset:16384
	ds_read_b128 v[212:215], v141 offset:17408
	ds_read_b128 v[216:219], v141 offset:18432
	ds_read_b128 v[220:223], v141 offset:19456
	ds_read_b128 v[224:227], v141 offset:20480
	ds_read_b128 v[228:231], v141 offset:21504
	ds_read_b128 v[232:235], v141 offset:22528
	ds_read_b128 v[236:239], v141 offset:23552
	global_load_lds_dwordx4 v130, s[26:27]
	s_mov_b32 m0, s28
	s_addc_u32 s55, s27, 0
	global_load_lds_dwordx4 v128, s[26:27]
	s_mov_b32 m0, s29
	s_nop 0
	global_load_lds_dwordx4 v130, s[54:55]
	s_mov_b32 m0, s30
	s_nop 0
	global_load_lds_dwordx4 v128, s[54:55]
	s_mov_b32 m0, s2
	s_nop 0
	global_load_lds_dwordx4 v130, s[36:37]
	s_mov_b32 m0, s31
	s_nop 0
	global_load_lds_dwordx4 v128, s[36:37]
	s_waitcnt vmcnt(8)
	s_waitcnt lgkmcnt(0)
	s_barrier
	s_setprio 1
	s_waitcnt lgkmcnt(0)
	v_mfma_f32_16x16x32_bf16 v[60:63], v[172:175], v[208:211], v[60:63]
	v_mfma_f32_16x16x32_bf16 v[56:59], v[180:183], v[208:211], v[56:59]
	v_mfma_f32_16x16x32_bf16 v[44:47], v[172:175], v[216:219], v[44:47]
	v_mfma_f32_16x16x32_bf16 v[40:43], v[180:183], v[216:219], v[40:43]
	v_mfma_f32_16x16x32_bf16 v[28:31], v[172:175], v[224:227], v[28:31]
	v_mfma_f32_16x16x32_bf16 v[24:27], v[180:183], v[224:227], v[24:27]
	v_mfma_f32_16x16x32_bf16 v[12:15], v[172:175], v[232:235], v[12:15]
	v_mfma_f32_16x16x32_bf16 v[8:11], v[180:183], v[232:235], v[8:11]
	v_mfma_f32_16x16x32_bf16 v[60:63], v[176:179], v[212:215], v[60:63]
	v_mfma_f32_16x16x32_bf16 v[56:59], v[184:187], v[212:215], v[56:59]
	v_mfma_f32_16x16x32_bf16 v[44:47], v[176:179], v[220:223], v[44:47]
	v_mfma_f32_16x16x32_bf16 v[40:43], v[184:187], v[220:223], v[40:43]
	v_mfma_f32_16x16x32_bf16 v[28:31], v[176:179], v[228:231], v[28:31]
	v_mfma_f32_16x16x32_bf16 v[24:27], v[184:187], v[228:231], v[24:27]
	v_mfma_f32_16x16x32_bf16 v[12:15], v[176:179], v[236:239], v[12:15]
	v_mfma_f32_16x16x32_bf16 v[8:11], v[184:187], v[236:239], v[8:11]
	s_setprio 0
	s_setprio 1
	v_mfma_f32_16x16x32_bf16 v[52:55], v[188:191], v[208:211], v[52:55]
	v_mfma_f32_16x16x32_bf16 v[48:51], v[200:203], v[208:211], v[48:51]
	v_mfma_f32_16x16x32_bf16 v[36:39], v[188:191], v[216:219], v[36:39]
	v_mfma_f32_16x16x32_bf16 v[32:35], v[200:203], v[216:219], v[32:35]
	v_mfma_f32_16x16x32_bf16 v[20:23], v[188:191], v[224:227], v[20:23]
	v_mfma_f32_16x16x32_bf16 v[16:19], v[200:203], v[224:227], v[16:19]
	v_mfma_f32_16x16x32_bf16 v[4:7], v[188:191], v[232:235], v[4:7]
	v_mfma_f32_16x16x32_bf16 v[0:3], v[200:203], v[232:235], v[0:3]
	v_mfma_f32_16x16x32_bf16 v[52:55], v[196:199], v[212:215], v[52:55]
	v_mfma_f32_16x16x32_bf16 v[48:51], v[204:207], v[212:215], v[48:51]
	v_mfma_f32_16x16x32_bf16 v[36:39], v[196:199], v[220:223], v[36:39]
	v_mfma_f32_16x16x32_bf16 v[32:35], v[204:207], v[220:223], v[32:35]
	v_mfma_f32_16x16x32_bf16 v[20:23], v[196:199], v[228:231], v[20:23]
	v_mfma_f32_16x16x32_bf16 v[16:19], v[204:207], v[228:231], v[16:19]
	v_mfma_f32_16x16x32_bf16 v[4:7], v[196:199], v[236:239], v[4:7]
	v_mfma_f32_16x16x32_bf16 v[0:3], v[204:207], v[236:239], v[0:3]
	s_setprio 0
	s_barrier
	ds_read_b128 v[172:175], v164
	ds_read_b128 v[176:179], v165
	ds_read_b128 v[180:183], v166
	ds_read_b128 v[184:187], v167
	ds_read_b128 v[188:191], v168
	ds_read_b128 v[196:199], v169
	ds_read_b128 v[200:203], v170
	ds_read_b128 v[204:207], v171
	s_add_u32 s36, s36, 0x40000
	s_addc_u32 s37, s37, 0
	s_mov_b32 m0, s33
	ds_read_b128 v[208:211], v141 offset:32768
	ds_read_b128 v[212:215], v141 offset:33792
	ds_read_b128 v[216:219], v141 offset:34816
	ds_read_b128 v[220:223], v141 offset:35840
	ds_read_b128 v[224:227], v141 offset:36864
	ds_read_b128 v[228:231], v141 offset:37888
	ds_read_b128 v[232:235], v141 offset:38912
	ds_read_b128 v[236:239], v141 offset:39936
	global_load_lds_dwordx4 v130, s[36:37]
	s_mov_b32 m0, s34
	s_nop 0
	global_load_lds_dwordx4 v128, s[36:37]
	s_waitcnt vmcnt(8)
	s_waitcnt lgkmcnt(0)
	s_barrier
	s_setprio 1
	s_waitcnt lgkmcnt(0)
	v_mfma_f32_16x16x32_bf16 v[124:127], v[172:175], v[208:211], v[124:127]
	v_mfma_f32_16x16x32_bf16 v[120:123], v[180:183], v[208:211], v[120:123]
	v_mfma_f32_16x16x32_bf16 v[108:111], v[172:175], v[216:219], v[108:111]
	v_mfma_f32_16x16x32_bf16 v[104:107], v[180:183], v[216:219], v[104:107]
	v_mfma_f32_16x16x32_bf16 v[92:95], v[172:175], v[224:227], v[92:95]
	v_mfma_f32_16x16x32_bf16 v[88:91], v[180:183], v[224:227], v[88:91]
	v_mfma_f32_16x16x32_bf16 v[76:79], v[172:175], v[232:235], v[76:79]
	v_mfma_f32_16x16x32_bf16 v[72:75], v[180:183], v[232:235], v[72:75]
	v_mfma_f32_16x16x32_bf16 v[124:127], v[176:179], v[212:215], v[124:127]
	v_mfma_f32_16x16x32_bf16 v[120:123], v[184:187], v[212:215], v[120:123]
	v_mfma_f32_16x16x32_bf16 v[108:111], v[176:179], v[220:223], v[108:111]
	v_mfma_f32_16x16x32_bf16 v[104:107], v[184:187], v[220:223], v[104:107]
	v_mfma_f32_16x16x32_bf16 v[92:95], v[176:179], v[228:231], v[92:95]
	v_mfma_f32_16x16x32_bf16 v[88:91], v[184:187], v[228:231], v[88:91]
	v_mfma_f32_16x16x32_bf16 v[76:79], v[176:179], v[236:239], v[76:79]
	v_mfma_f32_16x16x32_bf16 v[72:75], v[184:187], v[236:239], v[72:75]
	s_setprio 0
	s_setprio 1
	v_mfma_f32_16x16x32_bf16 v[116:119], v[188:191], v[208:211], v[116:119]
	v_mfma_f32_16x16x32_bf16 v[112:115], v[200:203], v[208:211], v[112:115]
	v_mfma_f32_16x16x32_bf16 v[100:103], v[188:191], v[216:219], v[100:103]
	v_mfma_f32_16x16x32_bf16 v[96:99], v[200:203], v[216:219], v[96:99]
	v_mfma_f32_16x16x32_bf16 v[84:87], v[188:191], v[224:227], v[84:87]
	v_mfma_f32_16x16x32_bf16 v[80:83], v[200:203], v[224:227], v[80:83]
	v_mfma_f32_16x16x32_bf16 v[68:71], v[188:191], v[232:235], v[68:71]
	v_mfma_f32_16x16x32_bf16 v[64:67], v[200:203], v[232:235], v[64:67]
	v_mfma_f32_16x16x32_bf16 v[116:119], v[196:199], v[212:215], v[116:119]
	v_mfma_f32_16x16x32_bf16 v[112:115], v[204:207], v[212:215], v[112:115]
	v_mfma_f32_16x16x32_bf16 v[100:103], v[196:199], v[220:223], v[100:103]
	v_mfma_f32_16x16x32_bf16 v[96:99], v[204:207], v[220:223], v[96:99]
	v_mfma_f32_16x16x32_bf16 v[84:87], v[196:199], v[228:231], v[84:87]
	v_mfma_f32_16x16x32_bf16 v[80:83], v[204:207], v[228:231], v[80:83]
	v_mfma_f32_16x16x32_bf16 v[68:71], v[196:199], v[236:239], v[68:71]
	v_mfma_f32_16x16x32_bf16 v[64:67], v[204:207], v[236:239], v[64:67]
	s_setprio 0
	s_barrier
	s_mov_b32 m0, s39
	s_add_u32 s26, s26, 0x40080
	ds_read_b128 v[208:211], v141 offset:49152
	ds_read_b128 v[212:215], v141 offset:50176
	ds_read_b128 v[216:219], v141 offset:51200
	ds_read_b128 v[220:223], v141 offset:52224
	ds_read_b128 v[224:227], v141 offset:53248
	ds_read_b128 v[228:231], v141 offset:54272
	ds_read_b128 v[232:235], v141 offset:55296
	ds_read_b128 v[236:239], v141 offset:56320
	global_load_lds_dwordx4 v130, s[98:99]
	s_mov_b32 m0, s40
	s_addc_u32 s27, s27, 0
	global_load_lds_dwordx4 v128, s[98:99]
	s_mov_b32 m0, s43
	s_nop 0
	global_load_lds_dwordx4 v130, s[26:27]
	s_mov_b32 m0, s44
	s_nop 0
	global_load_lds_dwordx4 v128, s[26:27]
	s_mov_b32 m0, s41
	s_nop 0
	global_load_lds_dwordx4 v130, s[100:101]
	s_mov_b32 m0, s42
	s_nop 0
	global_load_lds_dwordx4 v128, s[100:101]
	s_waitcnt vmcnt(8)
	s_waitcnt lgkmcnt(0)
	s_barrier
	s_setprio 1
	s_waitcnt lgkmcnt(0)
	v_mfma_f32_16x16x32_bf16 v[60:63], v[172:175], v[208:211], v[60:63]
	v_mfma_f32_16x16x32_bf16 v[56:59], v[180:183], v[208:211], v[56:59]
	v_mfma_f32_16x16x32_bf16 v[44:47], v[172:175], v[216:219], v[44:47]
	v_mfma_f32_16x16x32_bf16 v[40:43], v[180:183], v[216:219], v[40:43]
	v_mfma_f32_16x16x32_bf16 v[28:31], v[172:175], v[224:227], v[28:31]
	v_mfma_f32_16x16x32_bf16 v[24:27], v[180:183], v[224:227], v[24:27]
	v_mfma_f32_16x16x32_bf16 v[12:15], v[172:175], v[232:235], v[12:15]
	v_mfma_f32_16x16x32_bf16 v[8:11], v[180:183], v[232:235], v[8:11]
	v_mfma_f32_16x16x32_bf16 v[60:63], v[176:179], v[212:215], v[60:63]
	v_mfma_f32_16x16x32_bf16 v[56:59], v[184:187], v[212:215], v[56:59]
	v_mfma_f32_16x16x32_bf16 v[44:47], v[176:179], v[220:223], v[44:47]
	v_mfma_f32_16x16x32_bf16 v[40:43], v[184:187], v[220:223], v[40:43]
	v_mfma_f32_16x16x32_bf16 v[28:31], v[176:179], v[228:231], v[28:31]
	v_mfma_f32_16x16x32_bf16 v[24:27], v[184:187], v[228:231], v[24:27]
	v_mfma_f32_16x16x32_bf16 v[12:15], v[176:179], v[236:239], v[12:15]
	v_mfma_f32_16x16x32_bf16 v[8:11], v[184:187], v[236:239], v[8:11]
	s_setprio 0
	s_setprio 1
	v_mfma_f32_16x16x32_bf16 v[52:55], v[188:191], v[208:211], v[52:55]
	v_mfma_f32_16x16x32_bf16 v[48:51], v[200:203], v[208:211], v[48:51]
	v_mfma_f32_16x16x32_bf16 v[36:39], v[188:191], v[216:219], v[36:39]
	v_mfma_f32_16x16x32_bf16 v[32:35], v[200:203], v[216:219], v[32:35]
	v_mfma_f32_16x16x32_bf16 v[20:23], v[188:191], v[224:227], v[20:23]
	v_mfma_f32_16x16x32_bf16 v[16:19], v[200:203], v[224:227], v[16:19]
	v_mfma_f32_16x16x32_bf16 v[4:7], v[188:191], v[232:235], v[4:7]
	v_mfma_f32_16x16x32_bf16 v[0:3], v[200:203], v[232:235], v[0:3]
	v_mfma_f32_16x16x32_bf16 v[52:55], v[196:199], v[212:215], v[52:55]
	v_mfma_f32_16x16x32_bf16 v[48:51], v[204:207], v[212:215], v[48:51]
	v_mfma_f32_16x16x32_bf16 v[36:39], v[196:199], v[220:223], v[36:39]
	v_mfma_f32_16x16x32_bf16 v[32:35], v[204:207], v[220:223], v[32:35]
	v_mfma_f32_16x16x32_bf16 v[20:23], v[196:199], v[228:231], v[20:23]
	v_mfma_f32_16x16x32_bf16 v[16:19], v[204:207], v[228:231], v[16:19]
	v_mfma_f32_16x16x32_bf16 v[4:7], v[196:199], v[236:239], v[4:7]
	v_mfma_f32_16x16x32_bf16 v[0:3], v[204:207], v[236:239], v[0:3]
	s_setprio 0
	s_barrier
	s_add_i32 s53, s53, 2
	s_add_u32 s24, s24, 0x100
	s_addc_u32 s25, s25, 0
	s_add_u32 s51, s51, 0x100
	s_addc_u32 s52, s52, 0
	s_cmp_gt_u32 s53, 13
	s_cbranch_scc0 .LBB0_2949
	s_and_b64 vcc, exec, s[12:13]
	s_cbranch_vccz .LBB0_2952
	s_barrier

.LBB0_3015:
	s_lshl_b32 s10, s10, 5
	s_add_i32 s40, s6, 0x18000
	s_mov_b64 s[18:19], 0x80
	s_and_b32 s22, s10, 0x60
	v_lshl_add_u64 v[6:7], v[6:7], 0, s[18:19]
	s_mov_b32 m0, s40
	s_add_i32 s41, s6, 0x1a000
	s_lshl_b32 s20, s5, 13
	s_lshl_b32 s21, s22, 7
	s_waitcnt vmcnt(2)
	s_barrier
	global_load_lds_dwordx4 v[6:7], off
	v_lshl_add_u64 v[4:5], v[4:5], 0, s[18:19]
	s_mov_b32 m0, s41
	s_add_i32 s42, s6, 0x8000
	s_add_i32 s43, s6, 0xa000
	global_load_lds_dwordx4 v[4:5], off
	v_lshl_add_u64 v[0:1], v[0:1], 0, s[18:19]
	s_mov_b32 m0, s42
	s_add_u32 s10, s34, 0xb0080
	global_load_lds_dwordx4 v[0:1], off
	v_lshl_add_u64 v[0:1], v[2:3], 0, s[18:19]
	s_mov_b32 m0, s43
	s_addc_u32 s11, s35, 0
	s_add_i32 s44, s6, 0x1c000
	global_load_lds_dwordx4 v[0:1], off
	s_mov_b32 m0, s44
	s_add_i32 s45, s6, 0x1e000
	global_load_lds_dwordx4 v158, s[10:11]
	s_mov_b32 m0, s45
	s_sext_i32_i8 s61, s9
	global_load_lds_dwordx4 v160, s[10:11]
	v_bfe_u32 v0, v8, 4, 2
	v_and_b32_e32 v1, 15, v8
	v_lshlrev_b32_e32 v2, 4, v0
	v_lshl_or_b32 v153, s5, 6, v1
	v_lshl_or_b32 v1, v1, 6, v2
	v_lshlrev_b32_e32 v2, 2, v8
	v_and_b32_e32 v2, 32, v2
	v_bitop3_b32 v192, v1, s20, v2 bitop3:0xde
	v_bitop3_b32 v2, v1, s21, v2 bitop3:0xde
	v_lshl_or_b32 v193, v0, 2, s22
	v_lshrrev_b32_e32 v1, 1, v9
	v_mul_lo_u32 v0, v11, s4
	s_mov_b32 s5, 0xb000
	s_cmpk_lt_u32 s8, 0x100
	v_mad_u64_u32 v[0:1], s[8:9], v1, s5, v[0:1]
	v_or_b32_e32 v0, v0, v10
	s_mov_b64 s[10:11], 0xb0080
	v_add_lshl_u32 v0, v0, v12, 1
	v_mov_b32_e32 v1, v159
	v_lshl_add_u64 v[162:163], v[0:1], 0, s[10:11]
	v_lshrrev_b32_e32 v1, 1, v13
	v_mul_lo_u32 v0, v14, s4
	v_mad_u64_u32 v[0:1], s[4:5], v1, s5, v[0:1]
	s_waitcnt vmcnt(6)
	v_or_b32_e32 v0, v0, v15
	v_add_lshl_u32 v0, v0, v16, 1
	v_mov_b32_e32 v1, v159
	s_movk_i32 s46, 0x100
	s_cselect_b64 s[20:21], -1, 0
	s_ashr_i32 s47, s82, 31
	s_mov_b32 s48, s82
	v_lshl_add_u64 v[164:165], v[0:1], 0, s[10:11]
	s_mov_b32 s49, 0
	v_mov_b64_e32 v[166:167], 0x200
	v_mov_b64_e32 v[168:169], 0x1ff
	v_or_b32_e32 v195, 0x10000, v2
	v_add_u32_e32 v196, 0x10400, v2
	v_add_u32_e32 v197, 0x10800, v2
	v_add_u32_e32 v198, 0x10c00, v2
	v_or_b32_e32 v199, 0x14000, v2
	v_add_u32_e32 v200, 0x14400, v2
	v_add_u32_e32 v201, 0x14800, v2
	v_add_u32_e32 v202, 0x14c00, v2
	s_add_i32 s50, s6, 0xc000
	s_add_i32 s51, s6, 0xe000
	v_or_b32_e32 v203, 0x18000, v2
	v_add_u32_e32 v204, 0x18400, v2
	v_add_u32_e32 v205, 0x18800, v2
	v_add_u32_e32 v206, 0x18c00, v2
	v_or_b32_e32 v207, 0x1c000, v2
	v_add_u32_e32 v208, 0x1c400, v2
	v_add_u32_e32 v209, 0x1c800, v2
	v_add_u32_e32 v210, 0x1cc00, v2
	s_mov_b32 s52, 0x3e0f83e1
	s_movk_i32 s53, 0xdf00
	s_mov_b32 s22, 0x3fd744fd
	v_mov_b32_e32 v211, 0xffffff00
	s_barrier
	s_branch .LBB0_3018

.LBB0_3029:
	ds_read_b128 v[128:131], v195
	ds_read_b128 v[132:135], v196
	ds_read_b128 v[136:139], v197
	ds_read_b128 v[140:143], v198
	ds_read_b128 v[170:173], v199
	ds_read_b128 v[174:177], v200
	ds_read_b128 v[178:181], v201
	ds_read_b128 v[182:185], v202
	s_add_u32 s34, s26, 0x100
	s_addc_u32 s35, s27, 0
	s_cmp_eq_u32 s64, 40
	s_cselect_b32 s39, s11, s35
	s_cselect_b32 s38, s10, s34
	s_cselect_b32 s37, s25, s5
	s_cselect_b32 s36, s24, s4
	s_mov_b32 m0, s50
	ds_read_b128 v[186:189], v192
	ds_read_b128 v[212:215], v192 offset:1024
	ds_read_b128 v[216:219], v192 offset:2048
	ds_read_b128 v[220:223], v192 offset:3072
	ds_read_b128 v[224:227], v192 offset:4096
	ds_read_b128 v[228:231], v192 offset:5120
	ds_read_b128 v[232:235], v192 offset:6144
	ds_read_b128 v[236:239], v192 offset:7168
	global_load_lds_dwordx4 v162, s[26:27]
	s_mov_b32 m0, s51
	s_nop 0
	global_load_lds_dwordx4 v164, s[26:27]
	s_waitcnt vmcnt(8)
	s_waitcnt lgkmcnt(0)
	s_barrier
	s_setprio 1
	s_waitcnt lgkmcnt(0)
	v_mfma_f32_16x16x32_bf16 v[124:127], v[128:131], v[186:189], v[124:127]
	v_mfma_f32_16x16x32_bf16 v[120:123], v[136:139], v[186:189], v[120:123]
	v_mfma_f32_16x16x32_bf16 v[108:111], v[128:131], v[216:219], v[108:111]
	v_mfma_f32_16x16x32_bf16 v[104:107], v[136:139], v[216:219], v[104:107]
	v_mfma_f32_16x16x32_bf16 v[92:95], v[128:131], v[224:227], v[92:95]
	v_mfma_f32_16x16x32_bf16 v[88:91], v[136:139], v[224:227], v[88:91]
	v_mfma_f32_16x16x32_bf16 v[76:79], v[128:131], v[232:235], v[76:79]
	v_mfma_f32_16x16x32_bf16 v[72:75], v[136:139], v[232:235], v[72:75]
	v_mfma_f32_16x16x32_bf16 v[124:127], v[132:135], v[212:215], v[124:127]
	v_mfma_f32_16x16x32_bf16 v[120:123], v[140:143], v[212:215], v[120:123]
	v_mfma_f32_16x16x32_bf16 v[108:111], v[132:135], v[220:223], v[108:111]
	v_mfma_f32_16x16x32_bf16 v[104:107], v[140:143], v[220:223], v[104:107]
	v_mfma_f32_16x16x32_bf16 v[92:95], v[132:135], v[228:231], v[92:95]
	v_mfma_f32_16x16x32_bf16 v[88:91], v[140:143], v[228:231], v[88:91]
	v_mfma_f32_16x16x32_bf16 v[76:79], v[132:135], v[236:239], v[76:79]
	v_mfma_f32_16x16x32_bf16 v[72:75], v[140:143], v[236:239], v[72:75]
	s_setprio 0
	s_setprio 1
	v_mfma_f32_16x16x32_bf16 v[116:119], v[170:173], v[186:189], v[116:119]
	v_mfma_f32_16x16x32_bf16 v[112:115], v[178:181], v[186:189], v[112:115]
	v_mfma_f32_16x16x32_bf16 v[100:103], v[170:173], v[216:219], v[100:103]
	v_mfma_f32_16x16x32_bf16 v[96:99], v[178:181], v[216:219], v[96:99]
	v_mfma_f32_16x16x32_bf16 v[84:87], v[170:173], v[224:227], v[84:87]
	v_mfma_f32_16x16x32_bf16 v[80:83], v[178:181], v[224:227], v[80:83]
	v_mfma_f32_16x16x32_bf16 v[68:71], v[170:173], v[232:235], v[68:71]
	v_mfma_f32_16x16x32_bf16 v[64:67], v[178:181], v[232:235], v[64:67]
	v_mfma_f32_16x16x32_bf16 v[116:119], v[174:177], v[212:215], v[116:119]
	v_mfma_f32_16x16x32_bf16 v[112:115], v[182:185], v[212:215], v[112:115]
	v_mfma_f32_16x16x32_bf16 v[100:103], v[174:177], v[220:223], v[100:103]
	v_mfma_f32_16x16x32_bf16 v[96:99], v[182:185], v[220:223], v[96:99]
	v_mfma_f32_16x16x32_bf16 v[84:87], v[174:177], v[228:231], v[84:87]
	v_mfma_f32_16x16x32_bf16 v[80:83], v[182:185], v[228:231], v[80:83]
	v_mfma_f32_16x16x32_bf16 v[68:71], v[174:177], v[236:239], v[68:71]
	v_mfma_f32_16x16x32_bf16 v[64:67], v[182:185], v[236:239], v[64:67]
	s_setprio 0
	s_barrier
	s_add_u32 s98, s36, s18
	s_addc_u32 s99, s37, s19
	s_add_u32 s100, s38, s18
	s_addc_u32 s101, s39, s19
	s_mov_b32 m0, s7
	s_add_u32 s26, s36, 0xb0000
	ds_read_b128 v[186:189], v192 offset:16384
	ds_read_b128 v[212:215], v192 offset:17408
	ds_read_b128 v[216:219], v192 offset:18432
	ds_read_b128 v[220:223], v192 offset:19456
	ds_read_b128 v[224:227], v192 offset:20480
	ds_read_b128 v[228:231], v192 offset:21504
	ds_read_b128 v[232:235], v192 offset:22528
	ds_read_b128 v[236:239], v192 offset:23552
	global_load_lds_dwordx4 v158, s[36:37]
	s_mov_b32 m0, s23
	s_addc_u32 s27, s37, 0
	global_load_lds_dwordx4 v160, s[36:37]
	s_mov_b32 m0, s28
	s_nop 0
	global_load_lds_dwordx4 v158, s[26:27]
	s_mov_b32 m0, s29
	s_nop 0
	global_load_lds_dwordx4 v160, s[26:27]
	s_mov_b32 m0, s6
	s_nop 0
	global_load_lds_dwordx4 v158, s[38:39]
	s_mov_b32 m0, s30
	s_nop 0
	global_load_lds_dwordx4 v160, s[38:39]
	s_waitcnt vmcnt(8)
	s_waitcnt lgkmcnt(0)
	s_barrier
	s_setprio 1
	s_waitcnt lgkmcnt(0)
	v_mfma_f32_16x16x32_bf16 v[60:63], v[128:131], v[186:189], v[60:63]
	v_mfma_f32_16x16x32_bf16 v[56:59], v[136:139], v[186:189], v[56:59]
	v_mfma_f32_16x16x32_bf16 v[44:47], v[128:131], v[216:219], v[44:47]
	v_mfma_f32_16x16x32_bf16 v[40:43], v[136:139], v[216:219], v[40:43]
	v_mfma_f32_16x16x32_bf16 v[28:31], v[128:131], v[224:227], v[28:31]
	v_mfma_f32_16x16x32_bf16 v[24:27], v[136:139], v[224:227], v[24:27]
	v_mfma_f32_16x16x32_bf16 v[12:15], v[128:131], v[232:235], v[12:15]
	v_mfma_f32_16x16x32_bf16 v[8:11], v[136:139], v[232:235], v[8:11]
	v_mfma_f32_16x16x32_bf16 v[60:63], v[132:135], v[212:215], v[60:63]
	v_mfma_f32_16x16x32_bf16 v[56:59], v[140:143], v[212:215], v[56:59]
	v_mfma_f32_16x16x32_bf16 v[44:47], v[132:135], v[220:223], v[44:47]
	v_mfma_f32_16x16x32_bf16 v[40:43], v[140:143], v[220:223], v[40:43]
	v_mfma_f32_16x16x32_bf16 v[28:31], v[132:135], v[228:231], v[28:31]
	v_mfma_f32_16x16x32_bf16 v[24:27], v[140:143], v[228:231], v[24:27]
	v_mfma_f32_16x16x32_bf16 v[12:15], v[132:135], v[236:239], v[12:15]
	v_mfma_f32_16x16x32_bf16 v[8:11], v[140:143], v[236:239], v[8:11]
	s_setprio 0
	s_setprio 1
	v_mfma_f32_16x16x32_bf16 v[52:55], v[170:173], v[186:189], v[52:55]
	v_mfma_f32_16x16x32_bf16 v[48:51], v[178:181], v[186:189], v[48:51]
	v_mfma_f32_16x16x32_bf16 v[36:39], v[170:173], v[216:219], v[36:39]
	v_mfma_f32_16x16x32_bf16 v[32:35], v[178:181], v[216:219], v[32:35]
	v_mfma_f32_16x16x32_bf16 v[20:23], v[170:173], v[224:227], v[20:23]
	v_mfma_f32_16x16x32_bf16 v[16:19], v[178:181], v[224:227], v[16:19]
	v_mfma_f32_16x16x32_bf16 v[4:7], v[170:173], v[232:235], v[4:7]
	v_mfma_f32_16x16x32_bf16 v[0:3], v[178:181], v[232:235], v[0:3]
	v_mfma_f32_16x16x32_bf16 v[52:55], v[174:177], v[212:215], v[52:55]
	v_mfma_f32_16x16x32_bf16 v[48:51], v[182:185], v[212:215], v[48:51]
	v_mfma_f32_16x16x32_bf16 v[36:39], v[174:177], v[220:223], v[36:39]
	v_mfma_f32_16x16x32_bf16 v[32:35], v[182:185], v[220:223], v[32:35]
	v_mfma_f32_16x16x32_bf16 v[20:23], v[174:177], v[228:231], v[20:23]
	v_mfma_f32_16x16x32_bf16 v[16:19], v[182:185], v[228:231], v[16:19]
	v_mfma_f32_16x16x32_bf16 v[4:7], v[174:177], v[236:239], v[4:7]
	v_mfma_f32_16x16x32_bf16 v[0:3], v[182:185], v[236:239], v[0:3]
	s_setprio 0
	s_barrier
	ds_read_b128 v[128:131], v203
	ds_read_b128 v[132:135], v204
	ds_read_b128 v[136:139], v205
	ds_read_b128 v[140:143], v206
	ds_read_b128 v[170:173], v207
	ds_read_b128 v[174:177], v208
	ds_read_b128 v[178:181], v209
	ds_read_b128 v[182:185], v210
	s_add_u32 s26, s38, 0xb0000
	s_addc_u32 s27, s39, 0
	s_mov_b32 m0, s31
	ds_read_b128 v[186:189], v192 offset:32768
	ds_read_b128 v[212:215], v192 offset:33792
	ds_read_b128 v[216:219], v192 offset:34816
	ds_read_b128 v[220:223], v192 offset:35840
	ds_read_b128 v[224:227], v192 offset:36864
	ds_read_b128 v[228:231], v192 offset:37888
	ds_read_b128 v[232:235], v192 offset:38912
	ds_read_b128 v[236:239], v192 offset:39936
	global_load_lds_dwordx4 v158, s[26:27]
	s_mov_b32 m0, s33
	s_nop 0
	global_load_lds_dwordx4 v160, s[26:27]
	s_waitcnt vmcnt(8)
	s_waitcnt lgkmcnt(0)
	s_barrier
	s_setprio 1
	s_waitcnt lgkmcnt(0)
	v_mfma_f32_16x16x32_bf16 v[124:127], v[128:131], v[186:189], v[124:127]
	v_mfma_f32_16x16x32_bf16 v[120:123], v[136:139], v[186:189], v[120:123]
	v_mfma_f32_16x16x32_bf16 v[108:111], v[128:131], v[216:219], v[108:111]
	v_mfma_f32_16x16x32_bf16 v[104:107], v[136:139], v[216:219], v[104:107]
	v_mfma_f32_16x16x32_bf16 v[92:95], v[128:131], v[224:227], v[92:95]
	v_mfma_f32_16x16x32_bf16 v[88:91], v[136:139], v[224:227], v[88:91]
	v_mfma_f32_16x16x32_bf16 v[76:79], v[128:131], v[232:235], v[76:79]
	v_mfma_f32_16x16x32_bf16 v[72:75], v[136:139], v[232:235], v[72:75]
	v_mfma_f32_16x16x32_bf16 v[124:127], v[132:135], v[212:215], v[124:127]
	v_mfma_f32_16x16x32_bf16 v[120:123], v[140:143], v[212:215], v[120:123]
	v_mfma_f32_16x16x32_bf16 v[108:111], v[132:135], v[220:223], v[108:111]
	v_mfma_f32_16x16x32_bf16 v[104:107], v[140:143], v[220:223], v[104:107]
	v_mfma_f32_16x16x32_bf16 v[92:95], v[132:135], v[228:231], v[92:95]
	v_mfma_f32_16x16x32_bf16 v[88:91], v[140:143], v[228:231], v[88:91]
	v_mfma_f32_16x16x32_bf16 v[76:79], v[132:135], v[236:239], v[76:79]
	v_mfma_f32_16x16x32_bf16 v[72:75], v[140:143], v[236:239], v[72:75]
	s_setprio 0
	s_setprio 1
	v_mfma_f32_16x16x32_bf16 v[116:119], v[170:173], v[186:189], v[116:119]
	v_mfma_f32_16x16x32_bf16 v[112:115], v[178:181], v[186:189], v[112:115]
	v_mfma_f32_16x16x32_bf16 v[100:103], v[170:173], v[216:219], v[100:103]
	v_mfma_f32_16x16x32_bf16 v[96:99], v[178:181], v[216:219], v[96:99]
	v_mfma_f32_16x16x32_bf16 v[84:87], v[170:173], v[224:227], v[84:87]
	v_mfma_f32_16x16x32_bf16 v[80:83], v[178:181], v[224:227], v[80:83]
	v_mfma_f32_16x16x32_bf16 v[68:71], v[170:173], v[232:235], v[68:71]
	v_mfma_f32_16x16x32_bf16 v[64:67], v[178:181], v[232:235], v[64:67]
	v_mfma_f32_16x16x32_bf16 v[116:119], v[174:177], v[212:215], v[116:119]
	v_mfma_f32_16x16x32_bf16 v[112:115], v[182:185], v[212:215], v[112:115]
	v_mfma_f32_16x16x32_bf16 v[100:103], v[174:177], v[220:223], v[100:103]
	v_mfma_f32_16x16x32_bf16 v[96:99], v[182:185], v[220:223], v[96:99]
	v_mfma_f32_16x16x32_bf16 v[84:87], v[174:177], v[228:231], v[84:87]
	v_mfma_f32_16x16x32_bf16 v[80:83], v[182:185], v[228:231], v[80:83]
	v_mfma_f32_16x16x32_bf16 v[68:71], v[174:177], v[236:239], v[68:71]
	v_mfma_f32_16x16x32_bf16 v[64:67], v[182:185], v[236:239], v[64:67]
	s_setprio 0
	s_barrier
	s_mov_b32 m0, s40
	s_add_u32 s26, s36, 0xb0080
	ds_read_b128 v[186:189], v192 offset:49152
	ds_read_b128 v[212:215], v192 offset:50176
	ds_read_b128 v[216:219], v192 offset:51200
	ds_read_b128 v[220:223], v192 offset:52224
	ds_read_b128 v[224:227], v192 offset:53248
	ds_read_b128 v[228:231], v192 offset:54272
	ds_read_b128 v[232:235], v192 offset:55296
	ds_read_b128 v[236:239], v192 offset:56320
	global_load_lds_dwordx4 v158, s[98:99]
	s_mov_b32 m0, s41
	s_addc_u32 s27, s37, 0
	global_load_lds_dwordx4 v160, s[98:99]
	s_mov_b32 m0, s44
	s_nop 0
	global_load_lds_dwordx4 v158, s[26:27]
	s_mov_b32 m0, s45
	s_nop 0
	global_load_lds_dwordx4 v160, s[26:27]
	s_mov_b32 m0, s42
	s_nop 0
	global_load_lds_dwordx4 v158, s[100:101]
	s_mov_b32 m0, s43
	s_nop 0
	global_load_lds_dwordx4 v160, s[100:101]
	s_waitcnt vmcnt(8)
	s_waitcnt lgkmcnt(0)
	s_barrier
	s_setprio 1
	s_waitcnt lgkmcnt(0)
	v_mfma_f32_16x16x32_bf16 v[60:63], v[128:131], v[186:189], v[60:63]
	v_mfma_f32_16x16x32_bf16 v[56:59], v[136:139], v[186:189], v[56:59]
	v_mfma_f32_16x16x32_bf16 v[44:47], v[128:131], v[216:219], v[44:47]
	v_mfma_f32_16x16x32_bf16 v[40:43], v[136:139], v[216:219], v[40:43]
	v_mfma_f32_16x16x32_bf16 v[28:31], v[128:131], v[224:227], v[28:31]
	v_mfma_f32_16x16x32_bf16 v[24:27], v[136:139], v[224:227], v[24:27]
	v_mfma_f32_16x16x32_bf16 v[12:15], v[128:131], v[232:235], v[12:15]
	v_mfma_f32_16x16x32_bf16 v[8:11], v[136:139], v[232:235], v[8:11]
	v_mfma_f32_16x16x32_bf16 v[60:63], v[132:135], v[212:215], v[60:63]
	v_mfma_f32_16x16x32_bf16 v[56:59], v[140:143], v[212:215], v[56:59]
	v_mfma_f32_16x16x32_bf16 v[44:47], v[132:135], v[220:223], v[44:47]
	v_mfma_f32_16x16x32_bf16 v[40:43], v[140:143], v[220:223], v[40:43]
	v_mfma_f32_16x16x32_bf16 v[28:31], v[132:135], v[228:231], v[28:31]
	v_mfma_f32_16x16x32_bf16 v[24:27], v[140:143], v[228:231], v[24:27]
	v_mfma_f32_16x16x32_bf16 v[12:15], v[132:135], v[236:239], v[12:15]
	v_mfma_f32_16x16x32_bf16 v[8:11], v[140:143], v[236:239], v[8:11]
	s_setprio 0
	s_setprio 1
	v_mfma_f32_16x16x32_bf16 v[52:55], v[170:173], v[186:189], v[52:55]
	v_mfma_f32_16x16x32_bf16 v[48:51], v[178:181], v[186:189], v[48:51]
	v_mfma_f32_16x16x32_bf16 v[36:39], v[170:173], v[216:219], v[36:39]
	v_mfma_f32_16x16x32_bf16 v[32:35], v[178:181], v[216:219], v[32:35]
	v_mfma_f32_16x16x32_bf16 v[20:23], v[170:173], v[224:227], v[20:23]
	v_mfma_f32_16x16x32_bf16 v[16:19], v[178:181], v[224:227], v[16:19]
	v_mfma_f32_16x16x32_bf16 v[4:7], v[170:173], v[232:235], v[4:7]
	v_mfma_f32_16x16x32_bf16 v[0:3], v[178:181], v[232:235], v[0:3]
	v_mfma_f32_16x16x32_bf16 v[52:55], v[174:177], v[212:215], v[52:55]
	v_mfma_f32_16x16x32_bf16 v[48:51], v[182:185], v[212:215], v[48:51]
	v_mfma_f32_16x16x32_bf16 v[36:39], v[174:177], v[220:223], v[36:39]
	v_mfma_f32_16x16x32_bf16 v[32:35], v[182:185], v[220:223], v[32:35]
	v_mfma_f32_16x16x32_bf16 v[20:23], v[174:177], v[228:231], v[20:23]
	v_mfma_f32_16x16x32_bf16 v[16:19], v[182:185], v[228:231], v[16:19]
	v_mfma_f32_16x16x32_bf16 v[4:7], v[174:177], v[236:239], v[4:7]
	v_mfma_f32_16x16x32_bf16 v[0:3], v[182:185], v[236:239], v[0:3]
	s_setprio 0
	s_barrier
	s_add_i32 s64, s64, 2
	s_add_u32 s4, s4, 0x100
	s_addc_u32 s5, s5, 0
	s_cmp_gt_u32 s64, 41
	s_mov_b64 s[26:27], s[34:35]
	s_cbranch_scc0 .LBB0_3029
	s_and_b64 vcc, exec, s[20:21]
	s_cbranch_vccz .LBB0_3032
	s_barrier

.LBB0_3173:
	s_lshl_b32 s8, s8, 5
	s_add_i32 s40, s2, 0x18000
	s_mov_b64 s[16:17], 0x80
	s_and_b32 s13, s8, 0x60
	v_lshl_add_u64 v[6:7], v[6:7], 0, s[16:17]
	s_mov_b32 m0, s40
	s_add_i32 s41, s2, 0x1a000
	s_lshl_b32 s11, s5, 13
	s_lshl_b32 s18, s13, 7
	s_waitcnt vmcnt(2)
	s_barrier
	global_load_lds_dwordx4 v[6:7], off
	v_lshl_add_u64 v[4:5], v[4:5], 0, s[16:17]
	s_mov_b32 m0, s41
	s_add_i32 s42, s2, 0x8000
	s_add_i32 s43, s2, 0xa000
	global_load_lds_dwordx4 v[4:5], off
	v_lshl_add_u64 v[0:1], v[0:1], 0, s[16:17]
	s_mov_b32 m0, s42
	s_add_u32 s8, s34, 0x40080
	global_load_lds_dwordx4 v[0:1], off
	v_lshl_add_u64 v[0:1], v[2:3], 0, s[16:17]
	s_mov_b32 m0, s43
	s_addc_u32 s9, s35, 0
	s_add_i32 s44, s2, 0x1c000
	global_load_lds_dwordx4 v[0:1], off
	s_mov_b32 m0, s44
	s_add_i32 s45, s2, 0x1e000
	global_load_lds_dwordx4 v128, s[8:9]
	s_mov_b32 m0, s45
	s_cmpk_lt_u32 s4, 0x100
	global_load_lds_dwordx4 v130, s[8:9]
	v_bfe_u32 v1, v8, 4, 2
	v_and_b32_e32 v0, 15, v8
	v_lshlrev_b32_e32 v2, 4, v1
	v_lshl_or_b32 v147, s5, 6, v0
	v_lshl_or_b32 v0, v0, 6, v2
	v_lshlrev_b32_e32 v2, 2, v8
	v_lshl_or_b32 v153, v1, 2, s13
	v_lshlrev_b32_e32 v1, 14, v9
	v_and_b32_e32 v2, 32, v2
	v_and_b32_e32 v1, 0xffff8000, v1
	v_bitop3_b32 v149, v0, s11, v2 bitop3:0xde
	v_bitop3_b32 v0, v0, s18, v2 bitop3:0xde
	v_lshl_add_u32 v1, v10, 11, v1
	v_and_b32_e32 v2, 1, v9
	v_lshl_or_b32 v1, v2, 6, v1
	v_lshl_add_u32 v132, v11, 1, v1
	v_lshlrev_b32_e32 v1, 14, v12
	v_and_b32_e32 v1, 0xffff8000, v1
	s_waitcnt vmcnt(6)
	v_lshl_add_u32 v1, v13, 11, v1
	v_and_b32_e32 v2, 1, v12
	v_lshl_or_b32 v1, v2, 6, v1
	s_cselect_b64 s[18:19], -1, 0
	s_ashr_i32 s46, s82, 31
	s_mov_b32 s47, s82
	s_ashr_i32 s48, s3, 31
	v_mov_b32_e32 v133, v129
	v_lshl_add_u32 v134, v14, 1, v1
	v_mov_b32_e32 v135, v129
	s_mov_b32 s49, 0
	v_mov_b64_e32 v[136:137], 0xa50
	v_mov_b64_e32 v[138:139], 0xa4f
	s_movk_i32 s50, 0x14b
	v_or_b32_e32 v154, 0x10000, v0
	v_add_u32_e32 v155, 0x10400, v0
	v_add_u32_e32 v156, 0x10800, v0
	v_add_u32_e32 v157, 0x10c00, v0
	v_or_b32_e32 v158, 0x14000, v0
	v_add_u32_e32 v159, 0x14400, v0
	v_add_u32_e32 v160, 0x14800, v0
	v_add_u32_e32 v161, 0x14c00, v0
	s_add_i32 s51, s2, 0xc000
	s_add_i32 s52, s2, 0xe000
	v_or_b32_e32 v162, 0x18000, v0
	v_add_u32_e32 v163, 0x18400, v0
	v_add_u32_e32 v164, 0x18800, v0
	v_add_u32_e32 v165, 0x18c00, v0
	v_or_b32_e32 v166, 0x1c000, v0
	v_add_u32_e32 v167, 0x1c400, v0
	v_add_u32_e32 v168, 0x1c800, v0
	v_add_u32_e32 v169, 0x1cc00, v0
	s_mov_b32 s20, 0x3db504f3
	s_movk_i32 s53, 0x2800
	s_barrier
	s_branch .LBB0_3176

.LBB0_3179:
	ds_read_b128 v[140:143], v154
	ds_read_b128 v[170:173], v155
	ds_read_b128 v[174:177], v156
	ds_read_b128 v[178:181], v157
	ds_read_b128 v[182:185], v158
	ds_read_b128 v[186:189], v159
	ds_read_b128 v[190:193], v160
	ds_read_b128 v[194:197], v161
	s_add_u32 s34, s14, 0xfffc0080
	s_addc_u32 s35, s15, -1
	s_cmp_eq_u32 s54, 12
	s_cselect_b32 s37, s4, s35
	s_cselect_b32 s36, s5, s34
	s_cselect_b32 s35, s11, s25
	s_cselect_b32 s34, s13, s23
	s_mov_b32 m0, s51
	ds_read_b128 v[198:201], v149
	ds_read_b128 v[202:205], v149 offset:1024
	ds_read_b128 v[206:209], v149 offset:2048
	ds_read_b128 v[210:213], v149 offset:3072
	ds_read_b128 v[214:217], v149 offset:4096
	ds_read_b128 v[218:221], v149 offset:5120
	ds_read_b128 v[222:225], v149 offset:6144
	ds_read_b128 v[226:229], v149 offset:7168
	global_load_lds_dwordx4 v132, s[14:15]
	s_mov_b32 m0, s52
	s_nop 0
	global_load_lds_dwordx4 v134, s[14:15]
	s_waitcnt vmcnt(8)
	s_waitcnt lgkmcnt(0)
	s_barrier
	s_setprio 1
	s_waitcnt lgkmcnt(0)
	v_mfma_f32_16x16x32_bf16 v[124:127], v[140:143], v[198:201], v[124:127]
	v_mfma_f32_16x16x32_bf16 v[120:123], v[174:177], v[198:201], v[120:123]
	v_mfma_f32_16x16x32_bf16 v[108:111], v[140:143], v[206:209], v[108:111]
	v_mfma_f32_16x16x32_bf16 v[104:107], v[174:177], v[206:209], v[104:107]
	v_mfma_f32_16x16x32_bf16 v[92:95], v[140:143], v[214:217], v[92:95]
	v_mfma_f32_16x16x32_bf16 v[88:91], v[174:177], v[214:217], v[88:91]
	v_mfma_f32_16x16x32_bf16 v[76:79], v[140:143], v[222:225], v[76:79]
	v_mfma_f32_16x16x32_bf16 v[72:75], v[174:177], v[222:225], v[72:75]
	v_mfma_f32_16x16x32_bf16 v[124:127], v[170:173], v[202:205], v[124:127]
	v_mfma_f32_16x16x32_bf16 v[120:123], v[178:181], v[202:205], v[120:123]
	v_mfma_f32_16x16x32_bf16 v[108:111], v[170:173], v[210:213], v[108:111]
	v_mfma_f32_16x16x32_bf16 v[104:107], v[178:181], v[210:213], v[104:107]
	v_mfma_f32_16x16x32_bf16 v[92:95], v[170:173], v[218:221], v[92:95]
	v_mfma_f32_16x16x32_bf16 v[88:91], v[178:181], v[218:221], v[88:91]
	v_mfma_f32_16x16x32_bf16 v[76:79], v[170:173], v[226:229], v[76:79]
	v_mfma_f32_16x16x32_bf16 v[72:75], v[178:181], v[226:229], v[72:75]
	s_setprio 0
	s_setprio 1
	v_mfma_f32_16x16x32_bf16 v[116:119], v[182:185], v[198:201], v[116:119]
	v_mfma_f32_16x16x32_bf16 v[112:115], v[190:193], v[198:201], v[112:115]
	v_mfma_f32_16x16x32_bf16 v[100:103], v[182:185], v[206:209], v[100:103]
	v_mfma_f32_16x16x32_bf16 v[96:99], v[190:193], v[206:209], v[96:99]
	v_mfma_f32_16x16x32_bf16 v[84:87], v[182:185], v[214:217], v[84:87]
	v_mfma_f32_16x16x32_bf16 v[80:83], v[190:193], v[214:217], v[80:83]
	v_mfma_f32_16x16x32_bf16 v[68:71], v[182:185], v[222:225], v[68:71]
	v_mfma_f32_16x16x32_bf16 v[64:67], v[190:193], v[222:225], v[64:67]
	v_mfma_f32_16x16x32_bf16 v[116:119], v[186:189], v[202:205], v[116:119]
	v_mfma_f32_16x16x32_bf16 v[112:115], v[194:197], v[202:205], v[112:115]
	v_mfma_f32_16x16x32_bf16 v[100:103], v[186:189], v[210:213], v[100:103]
	v_mfma_f32_16x16x32_bf16 v[96:99], v[194:197], v[210:213], v[96:99]
	v_mfma_f32_16x16x32_bf16 v[84:87], v[186:189], v[218:221], v[84:87]
	v_mfma_f32_16x16x32_bf16 v[80:83], v[194:197], v[218:221], v[80:83]
	v_mfma_f32_16x16x32_bf16 v[68:71], v[186:189], v[226:229], v[68:71]
	v_mfma_f32_16x16x32_bf16 v[64:67], v[194:197], v[226:229], v[64:67]
	s_setprio 0
	s_barrier
	s_add_u32 s98, s34, s16
	s_addc_u32 s99, s35, s17
	s_add_u32 s100, s36, s16
	s_addc_u32 s101, s37, s17
	s_mov_b32 m0, s6
	s_add_u32 s60, s34, 0x40000
	ds_read_b128 v[198:201], v149 offset:16384
	ds_read_b128 v[202:205], v149 offset:17408
	ds_read_b128 v[206:209], v149 offset:18432
	ds_read_b128 v[210:213], v149 offset:19456
	ds_read_b128 v[214:217], v149 offset:20480
	ds_read_b128 v[218:221], v149 offset:21504
	ds_read_b128 v[222:225], v149 offset:22528
	ds_read_b128 v[226:229], v149 offset:23552
	global_load_lds_dwordx4 v128, s[34:35]
	s_mov_b32 m0, s7
	s_addc_u32 s61, s35, 0
	global_load_lds_dwordx4 v130, s[34:35]
	s_mov_b32 m0, s21
	s_nop 0
	global_load_lds_dwordx4 v128, s[60:61]
	s_mov_b32 m0, s28
	s_nop 0
	global_load_lds_dwordx4 v130, s[60:61]
	s_mov_b32 m0, s2
	s_nop 0
	global_load_lds_dwordx4 v128, s[36:37]
	s_mov_b32 m0, s29
	s_nop 0
	global_load_lds_dwordx4 v130, s[36:37]
	s_waitcnt vmcnt(8)
	s_waitcnt lgkmcnt(0)
	s_barrier
	s_setprio 1
	s_waitcnt lgkmcnt(0)
	v_mfma_f32_16x16x32_bf16 v[60:63], v[140:143], v[198:201], v[60:63]
	v_mfma_f32_16x16x32_bf16 v[56:59], v[174:177], v[198:201], v[56:59]
	v_mfma_f32_16x16x32_bf16 v[44:47], v[140:143], v[206:209], v[44:47]
	v_mfma_f32_16x16x32_bf16 v[40:43], v[174:177], v[206:209], v[40:43]
	v_mfma_f32_16x16x32_bf16 v[28:31], v[140:143], v[214:217], v[28:31]
	v_mfma_f32_16x16x32_bf16 v[24:27], v[174:177], v[214:217], v[24:27]
	v_mfma_f32_16x16x32_bf16 v[12:15], v[140:143], v[222:225], v[12:15]
	v_mfma_f32_16x16x32_bf16 v[8:11], v[174:177], v[222:225], v[8:11]
	v_mfma_f32_16x16x32_bf16 v[60:63], v[170:173], v[202:205], v[60:63]
	v_mfma_f32_16x16x32_bf16 v[56:59], v[178:181], v[202:205], v[56:59]
	v_mfma_f32_16x16x32_bf16 v[44:47], v[170:173], v[210:213], v[44:47]
	v_mfma_f32_16x16x32_bf16 v[40:43], v[178:181], v[210:213], v[40:43]
	v_mfma_f32_16x16x32_bf16 v[28:31], v[170:173], v[218:221], v[28:31]
	v_mfma_f32_16x16x32_bf16 v[24:27], v[178:181], v[218:221], v[24:27]
	v_mfma_f32_16x16x32_bf16 v[12:15], v[170:173], v[226:229], v[12:15]
	v_mfma_f32_16x16x32_bf16 v[8:11], v[178:181], v[226:229], v[8:11]
	s_setprio 0
	s_setprio 1
	v_mfma_f32_16x16x32_bf16 v[52:55], v[182:185], v[198:201], v[52:55]
	v_mfma_f32_16x16x32_bf16 v[48:51], v[190:193], v[198:201], v[48:51]
	v_mfma_f32_16x16x32_bf16 v[36:39], v[182:185], v[206:209], v[36:39]
	v_mfma_f32_16x16x32_bf16 v[32:35], v[190:193], v[206:209], v[32:35]
	v_mfma_f32_16x16x32_bf16 v[20:23], v[182:185], v[214:217], v[20:23]
	v_mfma_f32_16x16x32_bf16 v[16:19], v[190:193], v[214:217], v[16:19]
	v_mfma_f32_16x16x32_bf16 v[4:7], v[182:185], v[222:225], v[4:7]
	v_mfma_f32_16x16x32_bf16 v[0:3], v[190:193], v[222:225], v[0:3]
	v_mfma_f32_16x16x32_bf16 v[52:55], v[186:189], v[202:205], v[52:55]
	v_mfma_f32_16x16x32_bf16 v[48:51], v[194:197], v[202:205], v[48:51]
	v_mfma_f32_16x16x32_bf16 v[36:39], v[186:189], v[210:213], v[36:39]
	v_mfma_f32_16x16x32_bf16 v[32:35], v[194:197], v[210:213], v[32:35]
	v_mfma_f32_16x16x32_bf16 v[20:23], v[186:189], v[218:221], v[20:23]
	v_mfma_f32_16x16x32_bf16 v[16:19], v[194:197], v[218:221], v[16:19]
	v_mfma_f32_16x16x32_bf16 v[4:7], v[186:189], v[226:229], v[4:7]
	v_mfma_f32_16x16x32_bf16 v[0:3], v[194:197], v[226:229], v[0:3]
	s_setprio 0
	s_barrier
	ds_read_b128 v[140:143], v162
	ds_read_b128 v[170:173], v163
	ds_read_b128 v[174:177], v164
	ds_read_b128 v[178:181], v165
	ds_read_b128 v[182:185], v166
	ds_read_b128 v[186:189], v167
	ds_read_b128 v[190:193], v168
	ds_read_b128 v[194:197], v169
	s_add_u32 s36, s36, 0x40000
	s_addc_u32 s37, s37, 0
	s_mov_b32 m0, s33
	ds_read_b128 v[198:201], v149 offset:32768
	ds_read_b128 v[202:205], v149 offset:33792
	ds_read_b128 v[206:209], v149 offset:34816
	ds_read_b128 v[210:213], v149 offset:35840
	ds_read_b128 v[214:217], v149 offset:36864
	ds_read_b128 v[218:221], v149 offset:37888
	ds_read_b128 v[222:225], v149 offset:38912
	ds_read_b128 v[226:229], v149 offset:39936
	global_load_lds_dwordx4 v128, s[36:37]
	s_mov_b32 m0, s38
	s_nop 0
	global_load_lds_dwordx4 v130, s[36:37]
	s_waitcnt vmcnt(8)
	s_waitcnt lgkmcnt(0)
	s_barrier
	s_setprio 1
	s_waitcnt lgkmcnt(0)
	v_mfma_f32_16x16x32_bf16 v[124:127], v[140:143], v[198:201], v[124:127]
	v_mfma_f32_16x16x32_bf16 v[120:123], v[174:177], v[198:201], v[120:123]
	v_mfma_f32_16x16x32_bf16 v[108:111], v[140:143], v[206:209], v[108:111]
	v_mfma_f32_16x16x32_bf16 v[104:107], v[174:177], v[206:209], v[104:107]
	v_mfma_f32_16x16x32_bf16 v[92:95], v[140:143], v[214:217], v[92:95]
	v_mfma_f32_16x16x32_bf16 v[88:91], v[174:177], v[214:217], v[88:91]
	v_mfma_f32_16x16x32_bf16 v[76:79], v[140:143], v[222:225], v[76:79]
	v_mfma_f32_16x16x32_bf16 v[72:75], v[174:177], v[222:225], v[72:75]
	v_mfma_f32_16x16x32_bf16 v[124:127], v[170:173], v[202:205], v[124:127]
	v_mfma_f32_16x16x32_bf16 v[120:123], v[178:181], v[202:205], v[120:123]
	v_mfma_f32_16x16x32_bf16 v[108:111], v[170:173], v[210:213], v[108:111]
	v_mfma_f32_16x16x32_bf16 v[104:107], v[178:181], v[210:213], v[104:107]
	v_mfma_f32_16x16x32_bf16 v[92:95], v[170:173], v[218:221], v[92:95]
	v_mfma_f32_16x16x32_bf16 v[88:91], v[178:181], v[218:221], v[88:91]
	v_mfma_f32_16x16x32_bf16 v[76:79], v[170:173], v[226:229], v[76:79]
	v_mfma_f32_16x16x32_bf16 v[72:75], v[178:181], v[226:229], v[72:75]
	s_setprio 0
	s_setprio 1
	v_mfma_f32_16x16x32_bf16 v[116:119], v[182:185], v[198:201], v[116:119]
	v_mfma_f32_16x16x32_bf16 v[112:115], v[190:193], v[198:201], v[112:115]
	v_mfma_f32_16x16x32_bf16 v[100:103], v[182:185], v[206:209], v[100:103]
	v_mfma_f32_16x16x32_bf16 v[96:99], v[190:193], v[206:209], v[96:99]
	v_mfma_f32_16x16x32_bf16 v[84:87], v[182:185], v[214:217], v[84:87]
	v_mfma_f32_16x16x32_bf16 v[80:83], v[190:193], v[214:217], v[80:83]
	v_mfma_f32_16x16x32_bf16 v[68:71], v[182:185], v[222:225], v[68:71]
	v_mfma_f32_16x16x32_bf16 v[64:67], v[190:193], v[222:225], v[64:67]
	v_mfma_f32_16x16x32_bf16 v[116:119], v[186:189], v[202:205], v[116:119]
	v_mfma_f32_16x16x32_bf16 v[112:115], v[194:197], v[202:205], v[112:115]
	v_mfma_f32_16x16x32_bf16 v[100:103], v[186:189], v[210:213], v[100:103]
	v_mfma_f32_16x16x32_bf16 v[96:99], v[194:197], v[210:213], v[96:99]
	v_mfma_f32_16x16x32_bf16 v[84:87], v[186:189], v[218:221], v[84:87]
	v_mfma_f32_16x16x32_bf16 v[80:83], v[194:197], v[218:221], v[80:83]
	v_mfma_f32_16x16x32_bf16 v[68:71], v[186:189], v[226:229], v[68:71]
	v_mfma_f32_16x16x32_bf16 v[64:67], v[194:197], v[226:229], v[64:67]
	s_setprio 0
	s_barrier
	s_mov_b32 m0, s40
	s_add_u32 s34, s34, 0x40080
	ds_read_b128 v[198:201], v149 offset:49152
	ds_read_b128 v[202:205], v149 offset:50176
	ds_read_b128 v[206:209], v149 offset:51200
	ds_read_b128 v[210:213], v149 offset:52224
	ds_read_b128 v[214:217], v149 offset:53248
	ds_read_b128 v[218:221], v149 offset:54272
	ds_read_b128 v[222:225], v149 offset:55296
	ds_read_b128 v[226:229], v149 offset:56320
	global_load_lds_dwordx4 v128, s[98:99]
	s_mov_b32 m0, s41
	s_addc_u32 s35, s35, 0
	global_load_lds_dwordx4 v130, s[98:99]
	s_mov_b32 m0, s44
	s_nop 0
	global_load_lds_dwordx4 v128, s[34:35]
	s_mov_b32 m0, s45
	s_nop 0
	global_load_lds_dwordx4 v130, s[34:35]
	s_mov_b32 m0, s42
	s_nop 0
	global_load_lds_dwordx4 v128, s[100:101]
	s_mov_b32 m0, s43
	s_nop 0
	global_load_lds_dwordx4 v130, s[100:101]
	s_waitcnt vmcnt(8)
	s_waitcnt lgkmcnt(0)
	s_barrier
	s_setprio 1
	s_waitcnt lgkmcnt(0)
	v_mfma_f32_16x16x32_bf16 v[60:63], v[140:143], v[198:201], v[60:63]
	v_mfma_f32_16x16x32_bf16 v[56:59], v[174:177], v[198:201], v[56:59]
	v_mfma_f32_16x16x32_bf16 v[44:47], v[140:143], v[206:209], v[44:47]
	v_mfma_f32_16x16x32_bf16 v[40:43], v[174:177], v[206:209], v[40:43]
	v_mfma_f32_16x16x32_bf16 v[28:31], v[140:143], v[214:217], v[28:31]
	v_mfma_f32_16x16x32_bf16 v[24:27], v[174:177], v[214:217], v[24:27]
	v_mfma_f32_16x16x32_bf16 v[12:15], v[140:143], v[222:225], v[12:15]
	v_mfma_f32_16x16x32_bf16 v[8:11], v[174:177], v[222:225], v[8:11]
	v_mfma_f32_16x16x32_bf16 v[60:63], v[170:173], v[202:205], v[60:63]
	v_mfma_f32_16x16x32_bf16 v[56:59], v[178:181], v[202:205], v[56:59]
	v_mfma_f32_16x16x32_bf16 v[44:47], v[170:173], v[210:213], v[44:47]
	v_mfma_f32_16x16x32_bf16 v[40:43], v[178:181], v[210:213], v[40:43]
	v_mfma_f32_16x16x32_bf16 v[28:31], v[170:173], v[218:221], v[28:31]
	v_mfma_f32_16x16x32_bf16 v[24:27], v[178:181], v[218:221], v[24:27]
	v_mfma_f32_16x16x32_bf16 v[12:15], v[170:173], v[226:229], v[12:15]
	v_mfma_f32_16x16x32_bf16 v[8:11], v[178:181], v[226:229], v[8:11]
	s_setprio 0
	s_setprio 1
	v_mfma_f32_16x16x32_bf16 v[52:55], v[182:185], v[198:201], v[52:55]
	v_mfma_f32_16x16x32_bf16 v[48:51], v[190:193], v[198:201], v[48:51]
	v_mfma_f32_16x16x32_bf16 v[36:39], v[182:185], v[206:209], v[36:39]
	v_mfma_f32_16x16x32_bf16 v[32:35], v[190:193], v[206:209], v[32:35]
	v_mfma_f32_16x16x32_bf16 v[20:23], v[182:185], v[214:217], v[20:23]
	v_mfma_f32_16x16x32_bf16 v[16:19], v[190:193], v[214:217], v[16:19]
	v_mfma_f32_16x16x32_bf16 v[4:7], v[182:185], v[222:225], v[4:7]
	v_mfma_f32_16x16x32_bf16 v[0:3], v[190:193], v[222:225], v[0:3]
	v_mfma_f32_16x16x32_bf16 v[52:55], v[186:189], v[202:205], v[52:55]
	v_mfma_f32_16x16x32_bf16 v[48:51], v[194:197], v[202:205], v[48:51]
	v_mfma_f32_16x16x32_bf16 v[36:39], v[186:189], v[210:213], v[36:39]
	v_mfma_f32_16x16x32_bf16 v[32:35], v[194:197], v[210:213], v[32:35]
	v_mfma_f32_16x16x32_bf16 v[20:23], v[186:189], v[218:221], v[20:23]
	v_mfma_f32_16x16x32_bf16 v[16:19], v[194:197], v[218:221], v[16:19]
	v_mfma_f32_16x16x32_bf16 v[4:7], v[186:189], v[226:229], v[4:7]
	v_mfma_f32_16x16x32_bf16 v[0:3], v[194:197], v[226:229], v[0:3]
	s_setprio 0
	s_barrier
	s_add_i32 s54, s54, 2
	s_add_u32 s14, s14, 0x100
	s_addc_u32 s15, s15, 0
	s_add_u32 s23, s23, 0x100
	s_addc_u32 s25, s25, 0
	s_cmp_gt_u32 s54, 13
	s_cbranch_scc0 .LBB0_3179
	s_and_b64 vcc, exec, s[18:19]
	s_cbranch_vccz .LBB0_3182
	s_barrier

.LBB0_3524:
	v_readlane_b32 s64, v254, 59
	s_add_u32 s8, s90, 0x5c000
	v_readlane_b32 s76, v255, 7
	v_readlane_b32 s77, v255, 8
	s_addc_u32 s9, s91, 0
	v_readlane_b32 s78, v255, 9
	v_readlane_b32 s79, v255, 10
	s_mov_b64 s[12:13], s[76:77]
	s_add_u32 s10, s12, 0x5000
	s_mov_b64 s[14:15], s[78:79]
	s_addc_u32 s11, s13, 0
	s_add_u32 s12, s14, 0x5000
	s_addc_u32 s13, s15, 0
	s_lshl_b32 s7, s7, 5
	s_add_i32 s45, s19, 0x18000
	s_mov_b64 s[14:15], 0x80
	s_and_b32 s20, s7, 0x60
	v_lshl_add_u64 v[6:7], v[6:7], 0, s[14:15]
	s_mov_b32 m0, s45
	s_add_i32 s46, s19, 0x1a000
	s_lshl_b32 s18, s5, 13
	s_lshl_b32 s7, s20, 7
	s_waitcnt vmcnt(2)
	s_barrier
	global_load_lds_dwordx4 v[6:7], off
	v_lshl_add_u64 v[4:5], v[4:5], 0, s[14:15]
	s_mov_b32 m0, s46
	s_add_i32 s47, s19, 0x8000
	s_add_i32 s48, s19, 0xa000
	global_load_lds_dwordx4 v[4:5], off
	v_lshl_add_u64 v[0:1], v[0:1], 0, s[14:15]
	s_mov_b32 m0, s47
	s_add_u32 s16, s34, 0x40080
	global_load_lds_dwordx4 v[0:1], off
	v_lshl_add_u64 v[0:1], v[2:3], 0, s[14:15]
	s_mov_b32 m0, s48
	s_addc_u32 s17, s35, 0
	s_add_i32 s49, s19, 0x1c000
	global_load_lds_dwordx4 v[0:1], off
	s_mov_b32 m0, s49
	s_add_i32 s50, s19, 0x1e000
	global_load_lds_dwordx4 v154, s[16:17]
	s_mov_b32 m0, s50
	v_readlane_b32 s65, v254, 60
	global_load_lds_dwordx4 v156, s[16:17]
	v_bfe_u32 v0, v8, 4, 2
	v_lshlrev_b32_e32 v2, 4, v0
	v_lshl_or_b32 v153, v0, 2, s20
	v_lshlrev_b32_e32 v0, 13, v9
	v_and_b32_e32 v1, 15, v8
	v_and_b32_e32 v0, 0x7fffc000, v0
	v_lshl_or_b32 v147, s5, 6, v1
	v_lshl_or_b32 v1, v1, 6, v2
	v_lshlrev_b32_e32 v2, 2, v8
	v_lshl_add_u32 v0, v10, 10, v0
	v_and_b32_e32 v2, 32, v2
	v_or_b32_e32 v0, v0, v11
	s_sext_i32_i8 s65, s6
	v_bitop3_b32 v149, v1, s18, v2 bitop3:0xde
	v_bitop3_b32 v2, v1, s7, v2 bitop3:0xde
	s_mov_b64 s[6:7], 0x40080
	v_add_lshl_u32 v0, v0, v12, 1
	v_mov_b32_e32 v1, v155
	v_lshl_add_u64 v[158:159], v[0:1], 0, s[6:7]
	v_lshlrev_b32_e32 v0, 13, v13
	v_and_b32_e32 v0, 0x7fffc000, v0
	v_lshl_add_u32 v0, v14, 10, v0
	v_readlane_b32 s70, v255, 1
	v_readlane_b32 s71, v255, 2
	s_waitcnt vmcnt(6)
	v_or_b32_e32 v0, v0, v15
	s_cmpk_lt_u32 s4, 0x100
	v_add_lshl_u32 v0, v0, v16, 1
	v_readlane_b32 s70, v255, 21
	s_movk_i32 s51, 0x100
	s_cselect_b64 s[16:17], -1, 0
	s_ashr_i32 s52, s82, 31
	s_mov_b32 s53, s82
	v_lshl_add_u64 v[160:161], v[0:1], 0, s[6:7]
	s_mov_b32 s54, 0
	v_mov_b64_e32 v[162:163], 0x200
	v_mov_b64_e32 v[164:165], 0x1ff
	v_or_b32_e32 v188, 0x10000, v2
	v_add_u32_e32 v189, 0x10400, v2
	v_add_u32_e32 v190, 0x10800, v2
	v_add_u32_e32 v191, 0x10c00, v2
	v_or_b32_e32 v192, 0x14000, v2
	v_add_u32_e32 v193, 0x14400, v2
	v_add_u32_e32 v194, 0x14800, v2
	v_add_u32_e32 v195, 0x14c00, v2
	s_add_i32 s55, s19, 0xc000
	s_add_i32 s60, s19, 0xe000
	v_or_b32_e32 v196, 0x18000, v2
	v_add_u32_e32 v197, 0x18400, v2
	v_add_u32_e32 v198, 0x18800, v2
	v_add_u32_e32 v199, 0x18c00, v2
	v_or_b32_e32 v200, 0x1c000, v2
	v_add_u32_e32 v201, 0x1c400, v2
	v_add_u32_e32 v202, 0x1c800, v2
	v_add_u32_e32 v203, 0x1cc00, v2
	s_mov_b32 s61, 0x3e0f83e1
	s_movk_i32 s64, 0xdf00
	s_mov_b32 s18, 0x3fd744fd
	v_mov_b32_e32 v204, 0xffffff00
	v_readlane_b32 s71, v255, 22
	v_readlane_b32 s66, v254, 61
	v_readlane_b32 s67, v254, 62
	v_readlane_b32 s68, v254, 63
	v_readlane_b32 s69, v255, 0
	v_readlane_b32 s72, v255, 3
	v_readlane_b32 s73, v255, 4
	v_readlane_b32 s74, v255, 5
	v_readlane_b32 s75, v255, 6
	s_barrier
	s_branch .LBB0_3527

.LBB0_3534:
	ds_read_b128 v[128:131], v188
	ds_read_b128 v[132:135], v189
	ds_read_b128 v[136:139], v190
	ds_read_b128 v[140:143], v191
	ds_read_b128 v[166:169], v192
	ds_read_b128 v[170:173], v193
	ds_read_b128 v[174:177], v194
	ds_read_b128 v[178:181], v195
	s_add_u32 s34, s30, 0x100
	s_addc_u32 s35, s31, 0
	s_cmp_eq_u32 s68, 12
	s_cselect_b32 s39, s4, s35
	s_cselect_b32 s38, s5, s34
	s_cselect_b32 s37, s21, s67
	s_cselect_b32 s36, s23, s66
	s_mov_b32 m0, s55
	ds_read_b128 v[182:185], v149
	ds_read_b128 v[206:209], v149 offset:1024
	ds_read_b128 v[210:213], v149 offset:2048
	ds_read_b128 v[214:217], v149 offset:3072
	ds_read_b128 v[218:221], v149 offset:4096
	ds_read_b128 v[222:225], v149 offset:5120
	ds_read_b128 v[226:229], v149 offset:6144
	ds_read_b128 v[230:233], v149 offset:7168
	global_load_lds_dwordx4 v158, s[30:31]
	s_mov_b32 m0, s60
	s_nop 0
	global_load_lds_dwordx4 v160, s[30:31]
	s_waitcnt vmcnt(8)
	s_waitcnt lgkmcnt(0)
	s_barrier
	s_setprio 1
	s_waitcnt lgkmcnt(0)
	v_mfma_f32_16x16x32_bf16 v[124:127], v[128:131], v[182:185], v[124:127]
	v_mfma_f32_16x16x32_bf16 v[120:123], v[136:139], v[182:185], v[120:123]
	v_mfma_f32_16x16x32_bf16 v[108:111], v[128:131], v[210:213], v[108:111]
	v_mfma_f32_16x16x32_bf16 v[104:107], v[136:139], v[210:213], v[104:107]
	v_mfma_f32_16x16x32_bf16 v[92:95], v[128:131], v[218:221], v[92:95]
	v_mfma_f32_16x16x32_bf16 v[88:91], v[136:139], v[218:221], v[88:91]
	v_mfma_f32_16x16x32_bf16 v[76:79], v[128:131], v[226:229], v[76:79]
	v_mfma_f32_16x16x32_bf16 v[72:75], v[136:139], v[226:229], v[72:75]
	v_mfma_f32_16x16x32_bf16 v[124:127], v[132:135], v[206:209], v[124:127]
	v_mfma_f32_16x16x32_bf16 v[120:123], v[140:143], v[206:209], v[120:123]
	v_mfma_f32_16x16x32_bf16 v[108:111], v[132:135], v[214:217], v[108:111]
	v_mfma_f32_16x16x32_bf16 v[104:107], v[140:143], v[214:217], v[104:107]
	v_mfma_f32_16x16x32_bf16 v[92:95], v[132:135], v[222:225], v[92:95]
	v_mfma_f32_16x16x32_bf16 v[88:91], v[140:143], v[222:225], v[88:91]
	v_mfma_f32_16x16x32_bf16 v[76:79], v[132:135], v[230:233], v[76:79]
	v_mfma_f32_16x16x32_bf16 v[72:75], v[140:143], v[230:233], v[72:75]
	s_setprio 0
	s_setprio 1
	v_mfma_f32_16x16x32_bf16 v[116:119], v[166:169], v[182:185], v[116:119]
	v_mfma_f32_16x16x32_bf16 v[112:115], v[174:177], v[182:185], v[112:115]
	v_mfma_f32_16x16x32_bf16 v[100:103], v[166:169], v[210:213], v[100:103]
	v_mfma_f32_16x16x32_bf16 v[96:99], v[174:177], v[210:213], v[96:99]
	v_mfma_f32_16x16x32_bf16 v[84:87], v[166:169], v[218:221], v[84:87]
	v_mfma_f32_16x16x32_bf16 v[80:83], v[174:177], v[218:221], v[80:83]
	v_mfma_f32_16x16x32_bf16 v[68:71], v[166:169], v[226:229], v[68:71]
	v_mfma_f32_16x16x32_bf16 v[64:67], v[174:177], v[226:229], v[64:67]
	v_mfma_f32_16x16x32_bf16 v[116:119], v[170:173], v[206:209], v[116:119]
	v_mfma_f32_16x16x32_bf16 v[112:115], v[178:181], v[206:209], v[112:115]
	v_mfma_f32_16x16x32_bf16 v[100:103], v[170:173], v[214:217], v[100:103]
	v_mfma_f32_16x16x32_bf16 v[96:99], v[178:181], v[214:217], v[96:99]
	v_mfma_f32_16x16x32_bf16 v[84:87], v[170:173], v[222:225], v[84:87]
	v_mfma_f32_16x16x32_bf16 v[80:83], v[178:181], v[222:225], v[80:83]
	v_mfma_f32_16x16x32_bf16 v[68:71], v[170:173], v[230:233], v[68:71]
	v_mfma_f32_16x16x32_bf16 v[64:67], v[178:181], v[230:233], v[64:67]
	s_setprio 0
	s_barrier
	s_add_u32 s98, s36, s14
	s_addc_u32 s99, s37, s15
	s_add_u32 s100, s38, s14
	s_addc_u32 s101, s39, s15
	s_mov_b32 m0, s29
	s_add_u32 s30, s36, 0x40000
	ds_read_b128 v[182:185], v149 offset:16384
	ds_read_b128 v[206:209], v149 offset:17408
	ds_read_b128 v[210:213], v149 offset:18432
	ds_read_b128 v[214:217], v149 offset:19456
	ds_read_b128 v[218:221], v149 offset:20480
	ds_read_b128 v[222:225], v149 offset:21504
	ds_read_b128 v[226:229], v149 offset:22528
	ds_read_b128 v[230:233], v149 offset:23552
	global_load_lds_dwordx4 v154, s[36:37]
	s_mov_b32 m0, s33
	s_addc_u32 s31, s37, 0
	global_load_lds_dwordx4 v156, s[36:37]
	s_mov_b32 m0, s40
	s_nop 0
	global_load_lds_dwordx4 v154, s[30:31]
	s_mov_b32 m0, s41
	s_nop 0
	global_load_lds_dwordx4 v156, s[30:31]
	s_mov_b32 m0, s19
	s_nop 0
	global_load_lds_dwordx4 v154, s[38:39]
	s_mov_b32 m0, s42
	s_nop 0
	global_load_lds_dwordx4 v156, s[38:39]
	s_waitcnt vmcnt(8)
	s_waitcnt lgkmcnt(0)
	s_barrier
	s_setprio 1
	s_waitcnt lgkmcnt(0)
	v_mfma_f32_16x16x32_bf16 v[60:63], v[128:131], v[182:185], v[60:63]
	v_mfma_f32_16x16x32_bf16 v[56:59], v[136:139], v[182:185], v[56:59]
	v_mfma_f32_16x16x32_bf16 v[44:47], v[128:131], v[210:213], v[44:47]
	v_mfma_f32_16x16x32_bf16 v[40:43], v[136:139], v[210:213], v[40:43]
	v_mfma_f32_16x16x32_bf16 v[28:31], v[128:131], v[218:221], v[28:31]
	v_mfma_f32_16x16x32_bf16 v[24:27], v[136:139], v[218:221], v[24:27]
	v_mfma_f32_16x16x32_bf16 v[12:15], v[128:131], v[226:229], v[12:15]
	v_mfma_f32_16x16x32_bf16 v[8:11], v[136:139], v[226:229], v[8:11]
	v_mfma_f32_16x16x32_bf16 v[60:63], v[132:135], v[206:209], v[60:63]
	v_mfma_f32_16x16x32_bf16 v[56:59], v[140:143], v[206:209], v[56:59]
	v_mfma_f32_16x16x32_bf16 v[44:47], v[132:135], v[214:217], v[44:47]
	v_mfma_f32_16x16x32_bf16 v[40:43], v[140:143], v[214:217], v[40:43]
	v_mfma_f32_16x16x32_bf16 v[28:31], v[132:135], v[222:225], v[28:31]
	v_mfma_f32_16x16x32_bf16 v[24:27], v[140:143], v[222:225], v[24:27]
	v_mfma_f32_16x16x32_bf16 v[12:15], v[132:135], v[230:233], v[12:15]
	v_mfma_f32_16x16x32_bf16 v[8:11], v[140:143], v[230:233], v[8:11]
	s_setprio 0
	s_setprio 1
	v_mfma_f32_16x16x32_bf16 v[52:55], v[166:169], v[182:185], v[52:55]
	v_mfma_f32_16x16x32_bf16 v[48:51], v[174:177], v[182:185], v[48:51]
	v_mfma_f32_16x16x32_bf16 v[36:39], v[166:169], v[210:213], v[36:39]
	v_mfma_f32_16x16x32_bf16 v[32:35], v[174:177], v[210:213], v[32:35]
	v_mfma_f32_16x16x32_bf16 v[20:23], v[166:169], v[218:221], v[20:23]
	v_mfma_f32_16x16x32_bf16 v[16:19], v[174:177], v[218:221], v[16:19]
	v_mfma_f32_16x16x32_bf16 v[4:7], v[166:169], v[226:229], v[4:7]
	v_mfma_f32_16x16x32_bf16 v[0:3], v[174:177], v[226:229], v[0:3]
	v_mfma_f32_16x16x32_bf16 v[52:55], v[170:173], v[206:209], v[52:55]
	v_mfma_f32_16x16x32_bf16 v[48:51], v[178:181], v[206:209], v[48:51]
	v_mfma_f32_16x16x32_bf16 v[36:39], v[170:173], v[214:217], v[36:39]
	v_mfma_f32_16x16x32_bf16 v[32:35], v[178:181], v[214:217], v[32:35]
	v_mfma_f32_16x16x32_bf16 v[20:23], v[170:173], v[222:225], v[20:23]
	v_mfma_f32_16x16x32_bf16 v[16:19], v[178:181], v[222:225], v[16:19]
	v_mfma_f32_16x16x32_bf16 v[4:7], v[170:173], v[230:233], v[4:7]
	v_mfma_f32_16x16x32_bf16 v[0:3], v[178:181], v[230:233], v[0:3]
	s_setprio 0
	s_barrier
	ds_read_b128 v[128:131], v196
	ds_read_b128 v[132:135], v197
	ds_read_b128 v[136:139], v198
	ds_read_b128 v[140:143], v199
	ds_read_b128 v[166:169], v200
	ds_read_b128 v[170:173], v201
	ds_read_b128 v[174:177], v202
	ds_read_b128 v[178:181], v203
	s_add_u32 s30, s38, 0x40000
	s_addc_u32 s31, s39, 0
	s_mov_b32 m0, s43
	ds_read_b128 v[182:185], v149 offset:32768
	ds_read_b128 v[206:209], v149 offset:33792
	ds_read_b128 v[210:213], v149 offset:34816
	ds_read_b128 v[214:217], v149 offset:35840
	ds_read_b128 v[218:221], v149 offset:36864
	ds_read_b128 v[222:225], v149 offset:37888
	ds_read_b128 v[226:229], v149 offset:38912
	ds_read_b128 v[230:233], v149 offset:39936
	global_load_lds_dwordx4 v154, s[30:31]
	s_mov_b32 m0, s44
	s_nop 0
	global_load_lds_dwordx4 v156, s[30:31]
	s_waitcnt vmcnt(8)
	s_waitcnt lgkmcnt(0)
	s_barrier
	s_setprio 1
	s_waitcnt lgkmcnt(0)
	v_mfma_f32_16x16x32_bf16 v[124:127], v[128:131], v[182:185], v[124:127]
	v_mfma_f32_16x16x32_bf16 v[120:123], v[136:139], v[182:185], v[120:123]
	v_mfma_f32_16x16x32_bf16 v[108:111], v[128:131], v[210:213], v[108:111]
	v_mfma_f32_16x16x32_bf16 v[104:107], v[136:139], v[210:213], v[104:107]
	v_mfma_f32_16x16x32_bf16 v[92:95], v[128:131], v[218:221], v[92:95]
	v_mfma_f32_16x16x32_bf16 v[88:91], v[136:139], v[218:221], v[88:91]
	v_mfma_f32_16x16x32_bf16 v[76:79], v[128:131], v[226:229], v[76:79]
	v_mfma_f32_16x16x32_bf16 v[72:75], v[136:139], v[226:229], v[72:75]
	v_mfma_f32_16x16x32_bf16 v[124:127], v[132:135], v[206:209], v[124:127]
	v_mfma_f32_16x16x32_bf16 v[120:123], v[140:143], v[206:209], v[120:123]
	v_mfma_f32_16x16x32_bf16 v[108:111], v[132:135], v[214:217], v[108:111]
	v_mfma_f32_16x16x32_bf16 v[104:107], v[140:143], v[214:217], v[104:107]
	v_mfma_f32_16x16x32_bf16 v[92:95], v[132:135], v[222:225], v[92:95]
	v_mfma_f32_16x16x32_bf16 v[88:91], v[140:143], v[222:225], v[88:91]
	v_mfma_f32_16x16x32_bf16 v[76:79], v[132:135], v[230:233], v[76:79]
	v_mfma_f32_16x16x32_bf16 v[72:75], v[140:143], v[230:233], v[72:75]
	s_setprio 0
	s_setprio 1
	v_mfma_f32_16x16x32_bf16 v[116:119], v[166:169], v[182:185], v[116:119]
	v_mfma_f32_16x16x32_bf16 v[112:115], v[174:177], v[182:185], v[112:115]
	v_mfma_f32_16x16x32_bf16 v[100:103], v[166:169], v[210:213], v[100:103]
	v_mfma_f32_16x16x32_bf16 v[96:99], v[174:177], v[210:213], v[96:99]
	v_mfma_f32_16x16x32_bf16 v[84:87], v[166:169], v[218:221], v[84:87]
	v_mfma_f32_16x16x32_bf16 v[80:83], v[174:177], v[218:221], v[80:83]
	v_mfma_f32_16x16x32_bf16 v[68:71], v[166:169], v[226:229], v[68:71]
	v_mfma_f32_16x16x32_bf16 v[64:67], v[174:177], v[226:229], v[64:67]
	v_mfma_f32_16x16x32_bf16 v[116:119], v[170:173], v[206:209], v[116:119]
	v_mfma_f32_16x16x32_bf16 v[112:115], v[178:181], v[206:209], v[112:115]
	v_mfma_f32_16x16x32_bf16 v[100:103], v[170:173], v[214:217], v[100:103]
	v_mfma_f32_16x16x32_bf16 v[96:99], v[178:181], v[214:217], v[96:99]
	v_mfma_f32_16x16x32_bf16 v[84:87], v[170:173], v[222:225], v[84:87]
	v_mfma_f32_16x16x32_bf16 v[80:83], v[178:181], v[222:225], v[80:83]
	v_mfma_f32_16x16x32_bf16 v[68:71], v[170:173], v[230:233], v[68:71]
	v_mfma_f32_16x16x32_bf16 v[64:67], v[178:181], v[230:233], v[64:67]
	s_setprio 0
	s_barrier
	s_mov_b32 m0, s45
	s_add_u32 s30, s36, 0x40080
	ds_read_b128 v[182:185], v149 offset:49152
	ds_read_b128 v[206:209], v149 offset:50176
	ds_read_b128 v[210:213], v149 offset:51200
	ds_read_b128 v[214:217], v149 offset:52224
	ds_read_b128 v[218:221], v149 offset:53248
	ds_read_b128 v[222:225], v149 offset:54272
	ds_read_b128 v[226:229], v149 offset:55296
	ds_read_b128 v[230:233], v149 offset:56320
	global_load_lds_dwordx4 v154, s[98:99]
	s_mov_b32 m0, s46
	s_addc_u32 s31, s37, 0
	global_load_lds_dwordx4 v156, s[98:99]
	s_mov_b32 m0, s49
	s_nop 0
	global_load_lds_dwordx4 v154, s[30:31]
	s_mov_b32 m0, s50
	s_nop 0
	global_load_lds_dwordx4 v156, s[30:31]
	s_mov_b32 m0, s47
	s_nop 0
	global_load_lds_dwordx4 v154, s[100:101]
	s_mov_b32 m0, s48
	s_nop 0
	global_load_lds_dwordx4 v156, s[100:101]
	s_waitcnt vmcnt(8)
	s_waitcnt lgkmcnt(0)
	s_barrier
	s_setprio 1
	s_waitcnt lgkmcnt(0)
	v_mfma_f32_16x16x32_bf16 v[60:63], v[128:131], v[182:185], v[60:63]
	v_mfma_f32_16x16x32_bf16 v[56:59], v[136:139], v[182:185], v[56:59]
	v_mfma_f32_16x16x32_bf16 v[44:47], v[128:131], v[210:213], v[44:47]
	v_mfma_f32_16x16x32_bf16 v[40:43], v[136:139], v[210:213], v[40:43]
	v_mfma_f32_16x16x32_bf16 v[28:31], v[128:131], v[218:221], v[28:31]
	v_mfma_f32_16x16x32_bf16 v[24:27], v[136:139], v[218:221], v[24:27]
	v_mfma_f32_16x16x32_bf16 v[12:15], v[128:131], v[226:229], v[12:15]
	v_mfma_f32_16x16x32_bf16 v[8:11], v[136:139], v[226:229], v[8:11]
	v_mfma_f32_16x16x32_bf16 v[60:63], v[132:135], v[206:209], v[60:63]
	v_mfma_f32_16x16x32_bf16 v[56:59], v[140:143], v[206:209], v[56:59]
	v_mfma_f32_16x16x32_bf16 v[44:47], v[132:135], v[214:217], v[44:47]
	v_mfma_f32_16x16x32_bf16 v[40:43], v[140:143], v[214:217], v[40:43]
	v_mfma_f32_16x16x32_bf16 v[28:31], v[132:135], v[222:225], v[28:31]
	v_mfma_f32_16x16x32_bf16 v[24:27], v[140:143], v[222:225], v[24:27]
	v_mfma_f32_16x16x32_bf16 v[12:15], v[132:135], v[230:233], v[12:15]
	v_mfma_f32_16x16x32_bf16 v[8:11], v[140:143], v[230:233], v[8:11]
	s_setprio 0
	s_setprio 1
	v_mfma_f32_16x16x32_bf16 v[52:55], v[166:169], v[182:185], v[52:55]
	v_mfma_f32_16x16x32_bf16 v[48:51], v[174:177], v[182:185], v[48:51]
	v_mfma_f32_16x16x32_bf16 v[36:39], v[166:169], v[210:213], v[36:39]
	v_mfma_f32_16x16x32_bf16 v[32:35], v[174:177], v[210:213], v[32:35]
	v_mfma_f32_16x16x32_bf16 v[20:23], v[166:169], v[218:221], v[20:23]
	v_mfma_f32_16x16x32_bf16 v[16:19], v[174:177], v[218:221], v[16:19]
	v_mfma_f32_16x16x32_bf16 v[4:7], v[166:169], v[226:229], v[4:7]
	v_mfma_f32_16x16x32_bf16 v[0:3], v[174:177], v[226:229], v[0:3]
	v_mfma_f32_16x16x32_bf16 v[52:55], v[170:173], v[206:209], v[52:55]
	v_mfma_f32_16x16x32_bf16 v[48:51], v[178:181], v[206:209], v[48:51]
	v_mfma_f32_16x16x32_bf16 v[36:39], v[170:173], v[214:217], v[36:39]
	v_mfma_f32_16x16x32_bf16 v[32:35], v[178:181], v[214:217], v[32:35]
	v_mfma_f32_16x16x32_bf16 v[20:23], v[170:173], v[222:225], v[20:23]
	v_mfma_f32_16x16x32_bf16 v[16:19], v[178:181], v[222:225], v[16:19]
	v_mfma_f32_16x16x32_bf16 v[4:7], v[170:173], v[230:233], v[4:7]
	v_mfma_f32_16x16x32_bf16 v[0:3], v[178:181], v[230:233], v[0:3]
	s_setprio 0
	s_barrier
	s_add_i32 s68, s68, 2
	s_add_u32 s66, s66, 0x100
	s_addc_u32 s67, s67, 0
	s_cmp_gt_u32 s68, 13
	s_mov_b64 s[30:31], s[34:35]
	s_cbranch_scc0 .LBB0_3534
	s_and_b64 vcc, exec, s[16:17]
	s_cbranch_vccz .LBB0_3537
	s_barrier

.LBB0_3657:
	s_lshl_b32 s7, s7, 5
	s_add_i32 s39, s2, 0x18000
	s_mov_b64 s[8:9], 0x80
	s_and_b32 s38, s7, 0x60
	v_lshl_add_u64 v[6:7], v[6:7], 0, s[8:9]
	s_mov_b32 m0, s39
	s_add_i32 s40, s2, 0x1a000
	s_lshl_b32 s12, s5, 13
	s_lshl_b32 s7, s38, 7
	s_waitcnt vmcnt(2)
	s_barrier
	global_load_lds_dwordx4 v[6:7], off
	v_lshl_add_u64 v[4:5], v[4:5], 0, s[8:9]
	s_mov_b32 m0, s40
	s_add_i32 s41, s2, 0x8000
	s_add_i32 s42, s2, 0xa000
	global_load_lds_dwordx4 v[4:5], off
	v_lshl_add_u64 v[0:1], v[0:1], 0, s[8:9]
	s_mov_b32 m0, s41
	s_add_u32 s10, s24, 0x40080
	global_load_lds_dwordx4 v[0:1], off
	v_lshl_add_u64 v[0:1], v[2:3], 0, s[8:9]
	s_mov_b32 m0, s42
	s_addc_u32 s11, s25, 0
	s_add_i32 s43, s2, 0x1c000
	global_load_lds_dwordx4 v[0:1], off
	s_mov_b32 m0, s43
	s_add_i32 s44, s2, 0x1e000
	global_load_lds_dwordx4 v130, s[10:11]
	s_mov_b32 m0, s44
	s_cmpk_lt_u32 s4, 0x100
	global_load_lds_dwordx4 v128, s[10:11]
	v_bfe_u32 v1, v9, 4, 2
	v_and_b32_e32 v0, 15, v9
	v_lshlrev_b32_e32 v2, 4, v1
	v_lshl_or_b32 v140, s5, 6, v0
	v_lshl_or_b32 v0, v0, 6, v2
	v_lshlrev_b32_e32 v2, 2, v9
	v_lshlrev_b32_e32 v142, 2, v1
	v_lshlrev_b32_e32 v1, 14, v12
	v_and_b32_e32 v2, 32, v2
	v_and_b32_e32 v1, 0xffff8000, v1
	v_bitop3_b32 v141, v0, s12, v2 bitop3:0xde
	v_bitop3_b32 v0, v0, s7, v2 bitop3:0xde
	v_lshl_add_u32 v1, v13, 11, v1
	v_and_b32_e32 v2, 1, v12
	v_lshl_or_b32 v1, v2, 6, v1
	v_lshl_add_u32 v132, v14, 1, v1
	v_lshlrev_b32_e32 v1, 14, v8
	v_and_b32_e32 v1, 0xffff8000, v1
	s_waitcnt vmcnt(6)
	v_lshl_add_u32 v1, v10, 11, v1
	v_and_b32_e32 v2, 1, v8
	v_lshl_or_b32 v1, v2, 6, v1
	s_sext_i32_i16 s50, s6
	s_cselect_b64 s[10:11], -1, 0
	s_ashr_i32 s45, s82, 31
	s_mov_b32 s46, s82
	v_mov_b32_e32 v133, v131
	v_lshl_add_u32 v134, v11, 1, v1
	v_mov_b32_e32 v135, v131
	v_mov_b64_e32 v[136:137], 0xb00
	v_mov_b64_e32 v[138:139], 0xaff
	v_or_b32_e32 v143, 0x10000, v0
	v_add_u32_e32 v147, 0x10400, v0
	v_add_u32_e32 v148, 0x10800, v0
	v_add_u32_e32 v149, 0x10c00, v0
	v_or_b32_e32 v151, 0x14000, v0
	v_add_u32_e32 v153, 0x14400, v0
	v_add_u32_e32 v154, 0x14800, v0
	v_add_u32_e32 v155, 0x14c00, v0
	s_add_i32 s47, s2, 0xc000
	s_add_i32 s48, s2, 0xe000
	v_or_b32_e32 v156, 0x18000, v0
	v_add_u32_e32 v157, 0x18400, v0
	v_add_u32_e32 v158, 0x18800, v0
	v_add_u32_e32 v159, 0x18c00, v0
	v_or_b32_e32 v160, 0x1c000, v0
	v_add_u32_e32 v161, 0x1c400, v0
	v_add_u32_e32 v162, 0x1c800, v0
	v_add_u32_e32 v163, 0x1cc00, v0
	s_movk_i32 s49, 0x1600
	s_barrier
	s_branch .LBB0_3660

.LBB0_3663:
	ds_read_b128 v[164:167], v143
	ds_read_b128 v[168:171], v147
	ds_read_b128 v[172:175], v148
	ds_read_b128 v[176:179], v149
	ds_read_b128 v[180:183], v151
	ds_read_b128 v[184:187], v153
	ds_read_b128 v[188:191], v154
	ds_read_b128 v[192:195], v155
	s_add_u32 s24, s22, 0xfffc0080
	s_addc_u32 s25, s23, -1
	s_cmp_eq_u32 s53, 12
	s_cselect_b32 s27, s4, s25
	s_cselect_b32 s26, s5, s24
	s_cselect_b32 s25, s13, s52
	s_cselect_b32 s24, s15, s51
	s_mov_b32 m0, s47
	ds_read_b128 v[196:199], v141
	ds_read_b128 v[200:203], v141 offset:1024
	ds_read_b128 v[204:207], v141 offset:2048
	ds_read_b128 v[208:211], v141 offset:3072
	ds_read_b128 v[212:215], v141 offset:4096
	ds_read_b128 v[216:219], v141 offset:5120
	ds_read_b128 v[220:223], v141 offset:6144
	ds_read_b128 v[224:227], v141 offset:7168
	global_load_lds_dwordx4 v132, s[22:23]
	s_mov_b32 m0, s48
	s_nop 0
	global_load_lds_dwordx4 v134, s[22:23]
	s_waitcnt vmcnt(8)
	s_waitcnt lgkmcnt(0)
	s_barrier
	s_setprio 1
	s_waitcnt lgkmcnt(0)
	v_mfma_f32_16x16x32_bf16 v[124:127], v[164:167], v[196:199], v[124:127]
	v_mfma_f32_16x16x32_bf16 v[120:123], v[172:175], v[196:199], v[120:123]
	v_mfma_f32_16x16x32_bf16 v[108:111], v[164:167], v[204:207], v[108:111]
	v_mfma_f32_16x16x32_bf16 v[104:107], v[172:175], v[204:207], v[104:107]
	v_mfma_f32_16x16x32_bf16 v[92:95], v[164:167], v[212:215], v[92:95]
	v_mfma_f32_16x16x32_bf16 v[88:91], v[172:175], v[212:215], v[88:91]
	v_mfma_f32_16x16x32_bf16 v[76:79], v[164:167], v[220:223], v[76:79]
	v_mfma_f32_16x16x32_bf16 v[72:75], v[172:175], v[220:223], v[72:75]
	v_mfma_f32_16x16x32_bf16 v[124:127], v[168:171], v[200:203], v[124:127]
	v_mfma_f32_16x16x32_bf16 v[120:123], v[176:179], v[200:203], v[120:123]
	v_mfma_f32_16x16x32_bf16 v[108:111], v[168:171], v[208:211], v[108:111]
	v_mfma_f32_16x16x32_bf16 v[104:107], v[176:179], v[208:211], v[104:107]
	v_mfma_f32_16x16x32_bf16 v[92:95], v[168:171], v[216:219], v[92:95]
	v_mfma_f32_16x16x32_bf16 v[88:91], v[176:179], v[216:219], v[88:91]
	v_mfma_f32_16x16x32_bf16 v[76:79], v[168:171], v[224:227], v[76:79]
	v_mfma_f32_16x16x32_bf16 v[72:75], v[176:179], v[224:227], v[72:75]
	s_setprio 0
	s_setprio 1
	v_mfma_f32_16x16x32_bf16 v[116:119], v[180:183], v[196:199], v[116:119]
	v_mfma_f32_16x16x32_bf16 v[112:115], v[188:191], v[196:199], v[112:115]
	v_mfma_f32_16x16x32_bf16 v[100:103], v[180:183], v[204:207], v[100:103]
	v_mfma_f32_16x16x32_bf16 v[96:99], v[188:191], v[204:207], v[96:99]
	v_mfma_f32_16x16x32_bf16 v[84:87], v[180:183], v[212:215], v[84:87]
	v_mfma_f32_16x16x32_bf16 v[80:83], v[188:191], v[212:215], v[80:83]
	v_mfma_f32_16x16x32_bf16 v[68:71], v[180:183], v[220:223], v[68:71]
	v_mfma_f32_16x16x32_bf16 v[64:67], v[188:191], v[220:223], v[64:67]
	v_mfma_f32_16x16x32_bf16 v[116:119], v[184:187], v[200:203], v[116:119]
	v_mfma_f32_16x16x32_bf16 v[112:115], v[192:195], v[200:203], v[112:115]
	v_mfma_f32_16x16x32_bf16 v[100:103], v[184:187], v[208:211], v[100:103]
	v_mfma_f32_16x16x32_bf16 v[96:99], v[192:195], v[208:211], v[96:99]
	v_mfma_f32_16x16x32_bf16 v[84:87], v[184:187], v[216:219], v[84:87]
	v_mfma_f32_16x16x32_bf16 v[80:83], v[192:195], v[216:219], v[80:83]
	v_mfma_f32_16x16x32_bf16 v[68:71], v[184:187], v[224:227], v[68:71]
	v_mfma_f32_16x16x32_bf16 v[64:67], v[192:195], v[224:227], v[64:67]
	s_setprio 0
	s_barrier
	s_add_u32 s98, s24, s8
	s_addc_u32 s99, s25, s9
	s_add_u32 s100, s26, s8
	s_addc_u32 s101, s27, s9
	s_mov_b32 m0, s21
	s_add_u32 s54, s24, 0x40000
	ds_read_b128 v[196:199], v141 offset:16384
	ds_read_b128 v[200:203], v141 offset:17408
	ds_read_b128 v[204:207], v141 offset:18432
	ds_read_b128 v[208:211], v141 offset:19456
	ds_read_b128 v[212:215], v141 offset:20480
	ds_read_b128 v[216:219], v141 offset:21504
	ds_read_b128 v[220:223], v141 offset:22528
	ds_read_b128 v[224:227], v141 offset:23552
	global_load_lds_dwordx4 v130, s[24:25]
	s_mov_b32 m0, s30
	s_addc_u32 s55, s25, 0
	global_load_lds_dwordx4 v128, s[24:25]
	s_mov_b32 m0, s31
	s_nop 0
	global_load_lds_dwordx4 v130, s[54:55]
	s_mov_b32 m0, s33
	s_nop 0
	global_load_lds_dwordx4 v128, s[54:55]
	s_mov_b32 m0, s2
	s_nop 0
	global_load_lds_dwordx4 v130, s[26:27]
	s_mov_b32 m0, s34
	s_nop 0
	global_load_lds_dwordx4 v128, s[26:27]
	s_waitcnt vmcnt(8)
	s_waitcnt lgkmcnt(0)
	s_barrier
	s_setprio 1
	s_waitcnt lgkmcnt(0)
	v_mfma_f32_16x16x32_bf16 v[60:63], v[164:167], v[196:199], v[60:63]
	v_mfma_f32_16x16x32_bf16 v[56:59], v[172:175], v[196:199], v[56:59]
	v_mfma_f32_16x16x32_bf16 v[44:47], v[164:167], v[204:207], v[44:47]
	v_mfma_f32_16x16x32_bf16 v[40:43], v[172:175], v[204:207], v[40:43]
	v_mfma_f32_16x16x32_bf16 v[28:31], v[164:167], v[212:215], v[28:31]
	v_mfma_f32_16x16x32_bf16 v[24:27], v[172:175], v[212:215], v[24:27]
	v_mfma_f32_16x16x32_bf16 v[12:15], v[164:167], v[220:223], v[12:15]
	v_mfma_f32_16x16x32_bf16 v[8:11], v[172:175], v[220:223], v[8:11]
	v_mfma_f32_16x16x32_bf16 v[60:63], v[168:171], v[200:203], v[60:63]
	v_mfma_f32_16x16x32_bf16 v[56:59], v[176:179], v[200:203], v[56:59]
	v_mfma_f32_16x16x32_bf16 v[44:47], v[168:171], v[208:211], v[44:47]
	v_mfma_f32_16x16x32_bf16 v[40:43], v[176:179], v[208:211], v[40:43]
	v_mfma_f32_16x16x32_bf16 v[28:31], v[168:171], v[216:219], v[28:31]
	v_mfma_f32_16x16x32_bf16 v[24:27], v[176:179], v[216:219], v[24:27]
	v_mfma_f32_16x16x32_bf16 v[12:15], v[168:171], v[224:227], v[12:15]
	v_mfma_f32_16x16x32_bf16 v[8:11], v[176:179], v[224:227], v[8:11]
	s_setprio 0
	s_setprio 1
	v_mfma_f32_16x16x32_bf16 v[52:55], v[180:183], v[196:199], v[52:55]
	v_mfma_f32_16x16x32_bf16 v[48:51], v[188:191], v[196:199], v[48:51]
	v_mfma_f32_16x16x32_bf16 v[36:39], v[180:183], v[204:207], v[36:39]
	v_mfma_f32_16x16x32_bf16 v[32:35], v[188:191], v[204:207], v[32:35]
	v_mfma_f32_16x16x32_bf16 v[20:23], v[180:183], v[212:215], v[20:23]
	v_mfma_f32_16x16x32_bf16 v[16:19], v[188:191], v[212:215], v[16:19]
	v_mfma_f32_16x16x32_bf16 v[4:7], v[180:183], v[220:223], v[4:7]
	v_mfma_f32_16x16x32_bf16 v[0:3], v[188:191], v[220:223], v[0:3]
	v_mfma_f32_16x16x32_bf16 v[52:55], v[184:187], v[200:203], v[52:55]
	v_mfma_f32_16x16x32_bf16 v[48:51], v[192:195], v[200:203], v[48:51]
	v_mfma_f32_16x16x32_bf16 v[36:39], v[184:187], v[208:211], v[36:39]
	v_mfma_f32_16x16x32_bf16 v[32:35], v[192:195], v[208:211], v[32:35]
	v_mfma_f32_16x16x32_bf16 v[20:23], v[184:187], v[216:219], v[20:23]
	v_mfma_f32_16x16x32_bf16 v[16:19], v[192:195], v[216:219], v[16:19]
	v_mfma_f32_16x16x32_bf16 v[4:7], v[184:187], v[224:227], v[4:7]
	v_mfma_f32_16x16x32_bf16 v[0:3], v[192:195], v[224:227], v[0:3]
	s_setprio 0
	s_barrier
	ds_read_b128 v[164:167], v156
	ds_read_b128 v[168:171], v157
	ds_read_b128 v[172:175], v158
	ds_read_b128 v[176:179], v159
	ds_read_b128 v[180:183], v160
	ds_read_b128 v[184:187], v161
	ds_read_b128 v[188:191], v162
	ds_read_b128 v[192:195], v163
	s_add_u32 s26, s26, 0x40000
	s_addc_u32 s27, s27, 0
	s_mov_b32 m0, s35
	ds_read_b128 v[196:199], v141 offset:32768
	ds_read_b128 v[200:203], v141 offset:33792
	ds_read_b128 v[204:207], v141 offset:34816
	ds_read_b128 v[208:211], v141 offset:35840
	ds_read_b128 v[212:215], v141 offset:36864
	ds_read_b128 v[216:219], v141 offset:37888
	ds_read_b128 v[220:223], v141 offset:38912
	ds_read_b128 v[224:227], v141 offset:39936
	global_load_lds_dwordx4 v130, s[26:27]
	s_mov_b32 m0, s36
	s_nop 0
	global_load_lds_dwordx4 v128, s[26:27]
	s_waitcnt vmcnt(8)
	s_waitcnt lgkmcnt(0)
	s_barrier
	s_setprio 1
	s_waitcnt lgkmcnt(0)
	v_mfma_f32_16x16x32_bf16 v[124:127], v[164:167], v[196:199], v[124:127]
	v_mfma_f32_16x16x32_bf16 v[120:123], v[172:175], v[196:199], v[120:123]
	v_mfma_f32_16x16x32_bf16 v[108:111], v[164:167], v[204:207], v[108:111]
	v_mfma_f32_16x16x32_bf16 v[104:107], v[172:175], v[204:207], v[104:107]
	v_mfma_f32_16x16x32_bf16 v[92:95], v[164:167], v[212:215], v[92:95]
	v_mfma_f32_16x16x32_bf16 v[88:91], v[172:175], v[212:215], v[88:91]
	v_mfma_f32_16x16x32_bf16 v[76:79], v[164:167], v[220:223], v[76:79]
	v_mfma_f32_16x16x32_bf16 v[72:75], v[172:175], v[220:223], v[72:75]
	v_mfma_f32_16x16x32_bf16 v[124:127], v[168:171], v[200:203], v[124:127]
	v_mfma_f32_16x16x32_bf16 v[120:123], v[176:179], v[200:203], v[120:123]
	v_mfma_f32_16x16x32_bf16 v[108:111], v[168:171], v[208:211], v[108:111]
	v_mfma_f32_16x16x32_bf16 v[104:107], v[176:179], v[208:211], v[104:107]
	v_mfma_f32_16x16x32_bf16 v[92:95], v[168:171], v[216:219], v[92:95]
	v_mfma_f32_16x16x32_bf16 v[88:91], v[176:179], v[216:219], v[88:91]
	v_mfma_f32_16x16x32_bf16 v[76:79], v[168:171], v[224:227], v[76:79]
	v_mfma_f32_16x16x32_bf16 v[72:75], v[176:179], v[224:227], v[72:75]
	s_setprio 0
	s_setprio 1
	v_mfma_f32_16x16x32_bf16 v[116:119], v[180:183], v[196:199], v[116:119]
	v_mfma_f32_16x16x32_bf16 v[112:115], v[188:191], v[196:199], v[112:115]
	v_mfma_f32_16x16x32_bf16 v[100:103], v[180:183], v[204:207], v[100:103]
	v_mfma_f32_16x16x32_bf16 v[96:99], v[188:191], v[204:207], v[96:99]
	v_mfma_f32_16x16x32_bf16 v[84:87], v[180:183], v[212:215], v[84:87]
	v_mfma_f32_16x16x32_bf16 v[80:83], v[188:191], v[212:215], v[80:83]
	v_mfma_f32_16x16x32_bf16 v[68:71], v[180:183], v[220:223], v[68:71]
	v_mfma_f32_16x16x32_bf16 v[64:67], v[188:191], v[220:223], v[64:67]
	v_mfma_f32_16x16x32_bf16 v[116:119], v[184:187], v[200:203], v[116:119]
	v_mfma_f32_16x16x32_bf16 v[112:115], v[192:195], v[200:203], v[112:115]
	v_mfma_f32_16x16x32_bf16 v[100:103], v[184:187], v[208:211], v[100:103]
	v_mfma_f32_16x16x32_bf16 v[96:99], v[192:195], v[208:211], v[96:99]
	v_mfma_f32_16x16x32_bf16 v[84:87], v[184:187], v[216:219], v[84:87]
	v_mfma_f32_16x16x32_bf16 v[80:83], v[192:195], v[216:219], v[80:83]
	v_mfma_f32_16x16x32_bf16 v[68:71], v[184:187], v[224:227], v[68:71]
	v_mfma_f32_16x16x32_bf16 v[64:67], v[192:195], v[224:227], v[64:67]
	s_setprio 0
	s_barrier
	s_mov_b32 m0, s39
	s_add_u32 s24, s24, 0x40080
	ds_read_b128 v[196:199], v141 offset:49152
	ds_read_b128 v[200:203], v141 offset:50176
	ds_read_b128 v[204:207], v141 offset:51200
	ds_read_b128 v[208:211], v141 offset:52224
	ds_read_b128 v[212:215], v141 offset:53248
	ds_read_b128 v[216:219], v141 offset:54272
	ds_read_b128 v[220:223], v141 offset:55296
	ds_read_b128 v[224:227], v141 offset:56320
	global_load_lds_dwordx4 v130, s[98:99]
	s_mov_b32 m0, s40
	s_addc_u32 s25, s25, 0
	global_load_lds_dwordx4 v128, s[98:99]
	s_mov_b32 m0, s43
	s_nop 0
	global_load_lds_dwordx4 v130, s[24:25]
	s_mov_b32 m0, s44
	s_nop 0
	global_load_lds_dwordx4 v128, s[24:25]
	s_mov_b32 m0, s41
	s_nop 0
	global_load_lds_dwordx4 v130, s[100:101]
	s_mov_b32 m0, s42
	s_nop 0
	global_load_lds_dwordx4 v128, s[100:101]
	s_waitcnt vmcnt(8)
	s_waitcnt lgkmcnt(0)
	s_barrier
	s_setprio 1
	s_waitcnt lgkmcnt(0)
	v_mfma_f32_16x16x32_bf16 v[60:63], v[164:167], v[196:199], v[60:63]
	v_mfma_f32_16x16x32_bf16 v[56:59], v[172:175], v[196:199], v[56:59]
	v_mfma_f32_16x16x32_bf16 v[44:47], v[164:167], v[204:207], v[44:47]
	v_mfma_f32_16x16x32_bf16 v[40:43], v[172:175], v[204:207], v[40:43]
	v_mfma_f32_16x16x32_bf16 v[28:31], v[164:167], v[212:215], v[28:31]
	v_mfma_f32_16x16x32_bf16 v[24:27], v[172:175], v[212:215], v[24:27]
	v_mfma_f32_16x16x32_bf16 v[12:15], v[164:167], v[220:223], v[12:15]
	v_mfma_f32_16x16x32_bf16 v[8:11], v[172:175], v[220:223], v[8:11]
	v_mfma_f32_16x16x32_bf16 v[60:63], v[168:171], v[200:203], v[60:63]
	v_mfma_f32_16x16x32_bf16 v[56:59], v[176:179], v[200:203], v[56:59]
	v_mfma_f32_16x16x32_bf16 v[44:47], v[168:171], v[208:211], v[44:47]
	v_mfma_f32_16x16x32_bf16 v[40:43], v[176:179], v[208:211], v[40:43]
	v_mfma_f32_16x16x32_bf16 v[28:31], v[168:171], v[216:219], v[28:31]
	v_mfma_f32_16x16x32_bf16 v[24:27], v[176:179], v[216:219], v[24:27]
	v_mfma_f32_16x16x32_bf16 v[12:15], v[168:171], v[224:227], v[12:15]
	v_mfma_f32_16x16x32_bf16 v[8:11], v[176:179], v[224:227], v[8:11]
	s_setprio 0
	s_setprio 1
	v_mfma_f32_16x16x32_bf16 v[52:55], v[180:183], v[196:199], v[52:55]
	v_mfma_f32_16x16x32_bf16 v[48:51], v[188:191], v[196:199], v[48:51]
	v_mfma_f32_16x16x32_bf16 v[36:39], v[180:183], v[204:207], v[36:39]
	v_mfma_f32_16x16x32_bf16 v[32:35], v[188:191], v[204:207], v[32:35]
	v_mfma_f32_16x16x32_bf16 v[20:23], v[180:183], v[212:215], v[20:23]
	v_mfma_f32_16x16x32_bf16 v[16:19], v[188:191], v[212:215], v[16:19]
	v_mfma_f32_16x16x32_bf16 v[4:7], v[180:183], v[220:223], v[4:7]
	v_mfma_f32_16x16x32_bf16 v[0:3], v[188:191], v[220:223], v[0:3]
	v_mfma_f32_16x16x32_bf16 v[52:55], v[184:187], v[200:203], v[52:55]
	v_mfma_f32_16x16x32_bf16 v[48:51], v[192:195], v[200:203], v[48:51]
	v_mfma_f32_16x16x32_bf16 v[36:39], v[184:187], v[208:211], v[36:39]
	v_mfma_f32_16x16x32_bf16 v[32:35], v[192:195], v[208:211], v[32:35]
	v_mfma_f32_16x16x32_bf16 v[20:23], v[184:187], v[216:219], v[20:23]
	v_mfma_f32_16x16x32_bf16 v[16:19], v[192:195], v[216:219], v[16:19]
	v_mfma_f32_16x16x32_bf16 v[4:7], v[184:187], v[224:227], v[4:7]
	v_mfma_f32_16x16x32_bf16 v[0:3], v[192:195], v[224:227], v[0:3]
	s_setprio 0
	s_barrier
	s_add_i32 s53, s53, 2
	s_add_u32 s22, s22, 0x100
	s_addc_u32 s23, s23, 0
	s_add_u32 s51, s51, 0x100
	s_addc_u32 s52, s52, 0
	s_cmp_gt_u32 s53, 13
	s_cbranch_scc0 .LBB0_3663
	s_and_b64 vcc, exec, s[10:11]
	s_cbranch_vccz .LBB0_3666
	s_barrier

.LBB0_3729:
	v_readlane_b32 s64, v254, 59
	s_add_u32 s10, s90, 0x5f000
	v_readlane_b32 s76, v255, 7
	v_readlane_b32 s77, v255, 8
	s_addc_u32 s11, s91, 0
	v_readlane_b32 s78, v255, 9
	v_readlane_b32 s79, v255, 10
	s_mov_b64 s[12:13], s[76:77]
	s_add_u32 s12, s12, 0x6000
	s_mov_b64 s[14:15], s[78:79]
	s_addc_u32 s13, s13, 0
	s_add_u32 s14, s14, 0x6000
	s_addc_u32 s15, s15, 0
	s_lshl_b32 s16, s16, 5
	s_and_b32 s28, s16, 0x60
	s_add_i32 s38, s4, 0x18000
	s_mov_b64 s[16:17], 0x80
	v_lshl_add_u64 v[6:7], v[6:7], 0, s[16:17]
	s_mov_b32 m0, s38
	s_add_i32 s39, s4, 0x1a000
	s_lshl_b32 s20, s1, 13
	s_lshl_b32 s22, s28, 7
	s_waitcnt vmcnt(2)
	s_barrier
	global_load_lds_dwordx4 v[6:7], off
	v_lshl_add_u64 v[4:5], v[4:5], 0, s[16:17]
	s_mov_b32 m0, s39
	s_add_i32 s40, s4, 0x8000
	s_add_i32 s41, s4, 0xa000
	global_load_lds_dwordx4 v[4:5], off
	v_lshl_add_u64 v[0:1], v[0:1], 0, s[16:17]
	s_mov_b32 m0, s40
	s_add_u32 s18, s26, 0xb0080
	global_load_lds_dwordx4 v[0:1], off
	v_lshl_add_u64 v[0:1], v[2:3], 0, s[16:17]
	s_mov_b32 m0, s41
	s_addc_u32 s19, s27, 0
	s_add_i32 s42, s4, 0x1c000
	global_load_lds_dwordx4 v[0:1], off
	s_mov_b32 m0, s42
	s_add_i32 s43, s4, 0x1e000
	global_load_lds_dwordx4 v148, s[18:19]
	s_mov_b32 m0, s43
	s_sext_i32_i8 s55, s7
	global_load_lds_dwordx4 v154, s[18:19]
	v_bfe_u32 v0, v146, 4, 2
	v_and_b32_e32 v1, 15, v146
	v_lshlrev_b32_e32 v2, 4, v0
	v_lshl_or_b32 v151, s1, 6, v1
	v_lshl_or_b32 v1, v1, 6, v2
	v_lshlrev_b32_e32 v2, 2, v146
	v_and_b32_e32 v2, 32, v2
	v_bitop3_b32 v153, v1, s20, v2 bitop3:0xde
	v_bitop3_b32 v2, v1, s22, v2 bitop3:0xde
	v_lshl_or_b32 v184, v0, 2, s28
	v_lshrrev_b32_e32 v1, 1, v8
	v_mul_lo_u32 v0, v10, s0
	s_mov_b32 s1, 0xb000
	s_cmpk_lt_u32 s6, 0x100
	v_mad_u64_u32 v[0:1], s[6:7], v1, s1, v[0:1]
	v_or_b32_e32 v0, v0, v9
	s_mov_b64 s[22:23], 0xb0080
	v_add_lshl_u32 v0, v0, v11, 1
	v_mov_b32_e32 v1, v149
	v_lshl_add_u64 v[146:147], v[0:1], 0, s[22:23]
	v_lshrrev_b32_e32 v1, 1, v12
	v_mul_lo_u32 v0, v13, s0
	v_mad_u64_u32 v[0:1], s[0:1], v1, s1, v[0:1]
	v_readlane_b32 s70, v255, 1
	v_readlane_b32 s71, v255, 2
	s_waitcnt vmcnt(6)
	v_or_b32_e32 v0, v0, v14
	v_add_lshl_u32 v0, v0, v15, 1
	v_mov_b32_e32 v1, v149
	v_readlane_b32 s70, v255, 21
	s_movk_i32 s44, 0x100
	s_cselect_b64 s[18:19], -1, 0
	s_ashr_i32 s45, s82, 31
	s_mov_b32 s46, s82
	v_lshl_add_u64 v[156:157], v[0:1], 0, s[22:23]
	s_mov_b32 s47, 0
	v_mov_b64_e32 v[158:159], 0x200
	v_mov_b64_e32 v[160:161], 0x1ff
	v_or_b32_e32 v185, 0x10000, v2
	v_add_u32_e32 v186, 0x10400, v2
	v_add_u32_e32 v187, 0x10800, v2
	v_add_u32_e32 v188, 0x10c00, v2
	v_or_b32_e32 v189, 0x14000, v2
	v_add_u32_e32 v190, 0x14400, v2
	v_add_u32_e32 v191, 0x14800, v2
	v_add_u32_e32 v192, 0x14c00, v2
	s_add_i32 s48, s4, 0xc000
	s_add_i32 s49, s4, 0xe000
	v_or_b32_e32 v193, 0x18000, v2
	v_add_u32_e32 v194, 0x18400, v2
	v_add_u32_e32 v195, 0x18800, v2
	v_add_u32_e32 v196, 0x18c00, v2
	v_or_b32_e32 v197, 0x1c000, v2
	v_add_u32_e32 v198, 0x1c400, v2
	v_add_u32_e32 v199, 0x1c800, v2
	v_add_u32_e32 v200, 0x1cc00, v2
	s_mov_b32 s50, 0x3e0f83e1
	s_movk_i32 s51, 0xdf00
	s_mov_b32 s20, 0x3fd744fd
	v_mov_b32_e32 v201, 0xffffff00
	v_readlane_b32 s71, v255, 22
	v_readlane_b32 s65, v254, 60
	v_readlane_b32 s66, v254, 61
	v_readlane_b32 s67, v254, 62
	v_readlane_b32 s68, v254, 63
	v_readlane_b32 s69, v255, 0
	v_readlane_b32 s72, v255, 3
	v_readlane_b32 s73, v255, 4
	v_readlane_b32 s74, v255, 5
	v_readlane_b32 s75, v255, 6
	s_barrier
	s_branch .LBB0_3732

.LBB0_3743:
	ds_read_b128 v[128:131], v185
	ds_read_b128 v[132:135], v186
	ds_read_b128 v[136:139], v187
	ds_read_b128 v[140:143], v188
	ds_read_b128 v[162:165], v189
	ds_read_b128 v[166:169], v190
	ds_read_b128 v[170:173], v191
	ds_read_b128 v[174:177], v192
	s_add_u32 s26, s24, 0x100
	s_addc_u32 s27, s25, 0
	s_cmp_eq_u32 s60, 40
	s_cselect_b32 s31, s7, s27
	s_cselect_b32 s30, s6, s26
	s_cselect_b32 s29, s23, s59
	s_cselect_b32 s28, s22, s58
	s_mov_b32 m0, s48
	ds_read_b128 v[178:181], v153
	ds_read_b128 v[202:205], v153 offset:1024
	ds_read_b128 v[206:209], v153 offset:2048
	ds_read_b128 v[210:213], v153 offset:3072
	ds_read_b128 v[214:217], v153 offset:4096
	ds_read_b128 v[218:221], v153 offset:5120
	ds_read_b128 v[222:225], v153 offset:6144
	ds_read_b128 v[226:229], v153 offset:7168
	global_load_lds_dwordx4 v146, s[24:25]
	s_mov_b32 m0, s49
	s_nop 0
	global_load_lds_dwordx4 v156, s[24:25]
	s_waitcnt vmcnt(8)
	s_waitcnt lgkmcnt(0)
	s_barrier
	s_setprio 1
	s_waitcnt lgkmcnt(0)
	v_mfma_f32_16x16x32_bf16 v[124:127], v[128:131], v[178:181], v[124:127]
	v_mfma_f32_16x16x32_bf16 v[120:123], v[136:139], v[178:181], v[120:123]
	v_mfma_f32_16x16x32_bf16 v[108:111], v[128:131], v[206:209], v[108:111]
	v_mfma_f32_16x16x32_bf16 v[104:107], v[136:139], v[206:209], v[104:107]
	v_mfma_f32_16x16x32_bf16 v[92:95], v[128:131], v[214:217], v[92:95]
	v_mfma_f32_16x16x32_bf16 v[88:91], v[136:139], v[214:217], v[88:91]
	v_mfma_f32_16x16x32_bf16 v[76:79], v[128:131], v[222:225], v[76:79]
	v_mfma_f32_16x16x32_bf16 v[72:75], v[136:139], v[222:225], v[72:75]
	v_mfma_f32_16x16x32_bf16 v[124:127], v[132:135], v[202:205], v[124:127]
	v_mfma_f32_16x16x32_bf16 v[120:123], v[140:143], v[202:205], v[120:123]
	v_mfma_f32_16x16x32_bf16 v[108:111], v[132:135], v[210:213], v[108:111]
	v_mfma_f32_16x16x32_bf16 v[104:107], v[140:143], v[210:213], v[104:107]
	v_mfma_f32_16x16x32_bf16 v[92:95], v[132:135], v[218:221], v[92:95]
	v_mfma_f32_16x16x32_bf16 v[88:91], v[140:143], v[218:221], v[88:91]
	v_mfma_f32_16x16x32_bf16 v[76:79], v[132:135], v[226:229], v[76:79]
	v_mfma_f32_16x16x32_bf16 v[72:75], v[140:143], v[226:229], v[72:75]
	s_setprio 0
	s_setprio 1
	v_mfma_f32_16x16x32_bf16 v[116:119], v[162:165], v[178:181], v[116:119]
	v_mfma_f32_16x16x32_bf16 v[112:115], v[170:173], v[178:181], v[112:115]
	v_mfma_f32_16x16x32_bf16 v[100:103], v[162:165], v[206:209], v[100:103]
	v_mfma_f32_16x16x32_bf16 v[96:99], v[170:173], v[206:209], v[96:99]
	v_mfma_f32_16x16x32_bf16 v[84:87], v[162:165], v[214:217], v[84:87]
	v_mfma_f32_16x16x32_bf16 v[80:83], v[170:173], v[214:217], v[80:83]
	v_mfma_f32_16x16x32_bf16 v[68:71], v[162:165], v[222:225], v[68:71]
	v_mfma_f32_16x16x32_bf16 v[64:67], v[170:173], v[222:225], v[64:67]
	v_mfma_f32_16x16x32_bf16 v[116:119], v[166:169], v[202:205], v[116:119]
	v_mfma_f32_16x16x32_bf16 v[112:115], v[174:177], v[202:205], v[112:115]
	v_mfma_f32_16x16x32_bf16 v[100:103], v[166:169], v[210:213], v[100:103]
	v_mfma_f32_16x16x32_bf16 v[96:99], v[174:177], v[210:213], v[96:99]
	v_mfma_f32_16x16x32_bf16 v[84:87], v[166:169], v[218:221], v[84:87]
	v_mfma_f32_16x16x32_bf16 v[80:83], v[174:177], v[218:221], v[80:83]
	v_mfma_f32_16x16x32_bf16 v[68:71], v[166:169], v[226:229], v[68:71]
	v_mfma_f32_16x16x32_bf16 v[64:67], v[174:177], v[226:229], v[64:67]
	s_setprio 0
	s_barrier
	s_add_u32 s98, s28, s16
	s_addc_u32 s99, s29, s17
	s_add_u32 s100, s30, s16
	s_addc_u32 s101, s31, s17
	s_mov_b32 m0, s5
	s_add_u32 s24, s28, 0xb0000
	ds_read_b128 v[178:181], v153 offset:16384
	ds_read_b128 v[202:205], v153 offset:17408
	ds_read_b128 v[206:209], v153 offset:18432
	ds_read_b128 v[210:213], v153 offset:19456
	ds_read_b128 v[214:217], v153 offset:20480
	ds_read_b128 v[218:221], v153 offset:21504
	ds_read_b128 v[222:225], v153 offset:22528
	ds_read_b128 v[226:229], v153 offset:23552
	global_load_lds_dwordx4 v148, s[28:29]
	s_mov_b32 m0, s21
	s_addc_u32 s25, s29, 0
	global_load_lds_dwordx4 v154, s[28:29]
	s_mov_b32 m0, s33
	s_nop 0
	global_load_lds_dwordx4 v148, s[24:25]
	s_mov_b32 m0, s34
	s_nop 0
	global_load_lds_dwordx4 v154, s[24:25]
	s_mov_b32 m0, s4
	s_nop 0
	global_load_lds_dwordx4 v148, s[30:31]
	s_mov_b32 m0, s35
	s_nop 0
	global_load_lds_dwordx4 v154, s[30:31]
	s_waitcnt vmcnt(8)
	s_waitcnt lgkmcnt(0)
	s_barrier
	s_setprio 1
	s_waitcnt lgkmcnt(0)
	v_mfma_f32_16x16x32_bf16 v[60:63], v[128:131], v[178:181], v[60:63]
	v_mfma_f32_16x16x32_bf16 v[56:59], v[136:139], v[178:181], v[56:59]
	v_mfma_f32_16x16x32_bf16 v[44:47], v[128:131], v[206:209], v[44:47]
	v_mfma_f32_16x16x32_bf16 v[40:43], v[136:139], v[206:209], v[40:43]
	v_mfma_f32_16x16x32_bf16 v[28:31], v[128:131], v[214:217], v[28:31]
	v_mfma_f32_16x16x32_bf16 v[24:27], v[136:139], v[214:217], v[24:27]
	v_mfma_f32_16x16x32_bf16 v[12:15], v[128:131], v[222:225], v[12:15]
	v_mfma_f32_16x16x32_bf16 v[8:11], v[136:139], v[222:225], v[8:11]
	v_mfma_f32_16x16x32_bf16 v[60:63], v[132:135], v[202:205], v[60:63]
	v_mfma_f32_16x16x32_bf16 v[56:59], v[140:143], v[202:205], v[56:59]
	v_mfma_f32_16x16x32_bf16 v[44:47], v[132:135], v[210:213], v[44:47]
	v_mfma_f32_16x16x32_bf16 v[40:43], v[140:143], v[210:213], v[40:43]
	v_mfma_f32_16x16x32_bf16 v[28:31], v[132:135], v[218:221], v[28:31]
	v_mfma_f32_16x16x32_bf16 v[24:27], v[140:143], v[218:221], v[24:27]
	v_mfma_f32_16x16x32_bf16 v[12:15], v[132:135], v[226:229], v[12:15]
	v_mfma_f32_16x16x32_bf16 v[8:11], v[140:143], v[226:229], v[8:11]
	s_setprio 0
	s_setprio 1
	v_mfma_f32_16x16x32_bf16 v[52:55], v[162:165], v[178:181], v[52:55]
	v_mfma_f32_16x16x32_bf16 v[48:51], v[170:173], v[178:181], v[48:51]
	v_mfma_f32_16x16x32_bf16 v[36:39], v[162:165], v[206:209], v[36:39]
	v_mfma_f32_16x16x32_bf16 v[32:35], v[170:173], v[206:209], v[32:35]
	v_mfma_f32_16x16x32_bf16 v[20:23], v[162:165], v[214:217], v[20:23]
	v_mfma_f32_16x16x32_bf16 v[16:19], v[170:173], v[214:217], v[16:19]
	v_mfma_f32_16x16x32_bf16 v[4:7], v[162:165], v[222:225], v[4:7]
	v_mfma_f32_16x16x32_bf16 v[0:3], v[170:173], v[222:225], v[0:3]
	v_mfma_f32_16x16x32_bf16 v[52:55], v[166:169], v[202:205], v[52:55]
	v_mfma_f32_16x16x32_bf16 v[48:51], v[174:177], v[202:205], v[48:51]
	v_mfma_f32_16x16x32_bf16 v[36:39], v[166:169], v[210:213], v[36:39]
	v_mfma_f32_16x16x32_bf16 v[32:35], v[174:177], v[210:213], v[32:35]
	v_mfma_f32_16x16x32_bf16 v[20:23], v[166:169], v[218:221], v[20:23]
	v_mfma_f32_16x16x32_bf16 v[16:19], v[174:177], v[218:221], v[16:19]
	v_mfma_f32_16x16x32_bf16 v[4:7], v[166:169], v[226:229], v[4:7]
	v_mfma_f32_16x16x32_bf16 v[0:3], v[174:177], v[226:229], v[0:3]
	s_setprio 0
	s_barrier
	ds_read_b128 v[128:131], v193
	ds_read_b128 v[132:135], v194
	ds_read_b128 v[136:139], v195
	ds_read_b128 v[140:143], v196
	ds_read_b128 v[162:165], v197
	ds_read_b128 v[166:169], v198
	ds_read_b128 v[170:173], v199
	ds_read_b128 v[174:177], v200
	s_add_u32 s24, s30, 0xb0000
	s_addc_u32 s25, s31, 0
	s_mov_b32 m0, s36
	ds_read_b128 v[178:181], v153 offset:32768
	ds_read_b128 v[202:205], v153 offset:33792
	ds_read_b128 v[206:209], v153 offset:34816
	ds_read_b128 v[210:213], v153 offset:35840
	ds_read_b128 v[214:217], v153 offset:36864
	ds_read_b128 v[218:221], v153 offset:37888
	ds_read_b128 v[222:225], v153 offset:38912
	ds_read_b128 v[226:229], v153 offset:39936
	global_load_lds_dwordx4 v148, s[24:25]
	s_mov_b32 m0, s37
	s_nop 0
	global_load_lds_dwordx4 v154, s[24:25]
	s_waitcnt vmcnt(8)
	s_waitcnt lgkmcnt(0)
	s_barrier
	s_setprio 1
	s_waitcnt lgkmcnt(0)
	v_mfma_f32_16x16x32_bf16 v[124:127], v[128:131], v[178:181], v[124:127]
	v_mfma_f32_16x16x32_bf16 v[120:123], v[136:139], v[178:181], v[120:123]
	v_mfma_f32_16x16x32_bf16 v[108:111], v[128:131], v[206:209], v[108:111]
	v_mfma_f32_16x16x32_bf16 v[104:107], v[136:139], v[206:209], v[104:107]
	v_mfma_f32_16x16x32_bf16 v[92:95], v[128:131], v[214:217], v[92:95]
	v_mfma_f32_16x16x32_bf16 v[88:91], v[136:139], v[214:217], v[88:91]
	v_mfma_f32_16x16x32_bf16 v[76:79], v[128:131], v[222:225], v[76:79]
	v_mfma_f32_16x16x32_bf16 v[72:75], v[136:139], v[222:225], v[72:75]
	v_mfma_f32_16x16x32_bf16 v[124:127], v[132:135], v[202:205], v[124:127]
	v_mfma_f32_16x16x32_bf16 v[120:123], v[140:143], v[202:205], v[120:123]
	v_mfma_f32_16x16x32_bf16 v[108:111], v[132:135], v[210:213], v[108:111]
	v_mfma_f32_16x16x32_bf16 v[104:107], v[140:143], v[210:213], v[104:107]
	v_mfma_f32_16x16x32_bf16 v[92:95], v[132:135], v[218:221], v[92:95]
	v_mfma_f32_16x16x32_bf16 v[88:91], v[140:143], v[218:221], v[88:91]
	v_mfma_f32_16x16x32_bf16 v[76:79], v[132:135], v[226:229], v[76:79]
	v_mfma_f32_16x16x32_bf16 v[72:75], v[140:143], v[226:229], v[72:75]
	s_setprio 0
	s_setprio 1
	v_mfma_f32_16x16x32_bf16 v[116:119], v[162:165], v[178:181], v[116:119]
	v_mfma_f32_16x16x32_bf16 v[112:115], v[170:173], v[178:181], v[112:115]
	v_mfma_f32_16x16x32_bf16 v[100:103], v[162:165], v[206:209], v[100:103]
	v_mfma_f32_16x16x32_bf16 v[96:99], v[170:173], v[206:209], v[96:99]
	v_mfma_f32_16x16x32_bf16 v[84:87], v[162:165], v[214:217], v[84:87]
	v_mfma_f32_16x16x32_bf16 v[80:83], v[170:173], v[214:217], v[80:83]
	v_mfma_f32_16x16x32_bf16 v[68:71], v[162:165], v[222:225], v[68:71]
	v_mfma_f32_16x16x32_bf16 v[64:67], v[170:173], v[222:225], v[64:67]
	v_mfma_f32_16x16x32_bf16 v[116:119], v[166:169], v[202:205], v[116:119]
	v_mfma_f32_16x16x32_bf16 v[112:115], v[174:177], v[202:205], v[112:115]
	v_mfma_f32_16x16x32_bf16 v[100:103], v[166:169], v[210:213], v[100:103]
	v_mfma_f32_16x16x32_bf16 v[96:99], v[174:177], v[210:213], v[96:99]
	v_mfma_f32_16x16x32_bf16 v[84:87], v[166:169], v[218:221], v[84:87]
	v_mfma_f32_16x16x32_bf16 v[80:83], v[174:177], v[218:221], v[80:83]
	v_mfma_f32_16x16x32_bf16 v[68:71], v[166:169], v[226:229], v[68:71]
	v_mfma_f32_16x16x32_bf16 v[64:67], v[174:177], v[226:229], v[64:67]
	s_setprio 0
	s_barrier
	s_mov_b32 m0, s38
	s_add_u32 s24, s28, 0xb0080
	ds_read_b128 v[178:181], v153 offset:49152
	ds_read_b128 v[202:205], v153 offset:50176
	ds_read_b128 v[206:209], v153 offset:51200
	ds_read_b128 v[210:213], v153 offset:52224
	ds_read_b128 v[214:217], v153 offset:53248
	ds_read_b128 v[218:221], v153 offset:54272
	ds_read_b128 v[222:225], v153 offset:55296
	ds_read_b128 v[226:229], v153 offset:56320
	global_load_lds_dwordx4 v148, s[98:99]
	s_mov_b32 m0, s39
	s_addc_u32 s25, s29, 0
	global_load_lds_dwordx4 v154, s[98:99]
	s_mov_b32 m0, s42
	s_nop 0
	global_load_lds_dwordx4 v148, s[24:25]
	s_mov_b32 m0, s43
	s_nop 0
	global_load_lds_dwordx4 v154, s[24:25]
	s_mov_b32 m0, s40
	s_nop 0
	global_load_lds_dwordx4 v148, s[100:101]
	s_mov_b32 m0, s41
	s_nop 0
	global_load_lds_dwordx4 v154, s[100:101]
	s_waitcnt vmcnt(8)
	s_waitcnt lgkmcnt(0)
	s_barrier
	s_setprio 1
	s_waitcnt lgkmcnt(0)
	v_mfma_f32_16x16x32_bf16 v[60:63], v[128:131], v[178:181], v[60:63]
	v_mfma_f32_16x16x32_bf16 v[56:59], v[136:139], v[178:181], v[56:59]
	v_mfma_f32_16x16x32_bf16 v[44:47], v[128:131], v[206:209], v[44:47]
	v_mfma_f32_16x16x32_bf16 v[40:43], v[136:139], v[206:209], v[40:43]
	v_mfma_f32_16x16x32_bf16 v[28:31], v[128:131], v[214:217], v[28:31]
	v_mfma_f32_16x16x32_bf16 v[24:27], v[136:139], v[214:217], v[24:27]
	v_mfma_f32_16x16x32_bf16 v[12:15], v[128:131], v[222:225], v[12:15]
	v_mfma_f32_16x16x32_bf16 v[8:11], v[136:139], v[222:225], v[8:11]
	v_mfma_f32_16x16x32_bf16 v[60:63], v[132:135], v[202:205], v[60:63]
	v_mfma_f32_16x16x32_bf16 v[56:59], v[140:143], v[202:205], v[56:59]
	v_mfma_f32_16x16x32_bf16 v[44:47], v[132:135], v[210:213], v[44:47]
	v_mfma_f32_16x16x32_bf16 v[40:43], v[140:143], v[210:213], v[40:43]
	v_mfma_f32_16x16x32_bf16 v[28:31], v[132:135], v[218:221], v[28:31]
	v_mfma_f32_16x16x32_bf16 v[24:27], v[140:143], v[218:221], v[24:27]
	v_mfma_f32_16x16x32_bf16 v[12:15], v[132:135], v[226:229], v[12:15]
	v_mfma_f32_16x16x32_bf16 v[8:11], v[140:143], v[226:229], v[8:11]
	s_setprio 0
	s_setprio 1
	v_mfma_f32_16x16x32_bf16 v[52:55], v[162:165], v[178:181], v[52:55]
	v_mfma_f32_16x16x32_bf16 v[48:51], v[170:173], v[178:181], v[48:51]
	v_mfma_f32_16x16x32_bf16 v[36:39], v[162:165], v[206:209], v[36:39]
	v_mfma_f32_16x16x32_bf16 v[32:35], v[170:173], v[206:209], v[32:35]
	v_mfma_f32_16x16x32_bf16 v[20:23], v[162:165], v[214:217], v[20:23]
	v_mfma_f32_16x16x32_bf16 v[16:19], v[170:173], v[214:217], v[16:19]
	v_mfma_f32_16x16x32_bf16 v[4:7], v[162:165], v[222:225], v[4:7]
	v_mfma_f32_16x16x32_bf16 v[0:3], v[170:173], v[222:225], v[0:3]
	v_mfma_f32_16x16x32_bf16 v[52:55], v[166:169], v[202:205], v[52:55]
	v_mfma_f32_16x16x32_bf16 v[48:51], v[174:177], v[202:205], v[48:51]
	v_mfma_f32_16x16x32_bf16 v[36:39], v[166:169], v[210:213], v[36:39]
	v_mfma_f32_16x16x32_bf16 v[32:35], v[174:177], v[210:213], v[32:35]
	v_mfma_f32_16x16x32_bf16 v[20:23], v[166:169], v[218:221], v[20:23]
	v_mfma_f32_16x16x32_bf16 v[16:19], v[174:177], v[218:221], v[16:19]
	v_mfma_f32_16x16x32_bf16 v[4:7], v[166:169], v[226:229], v[4:7]
	v_mfma_f32_16x16x32_bf16 v[0:3], v[174:177], v[226:229], v[0:3]
	s_setprio 0
	s_barrier
	s_add_i32 s60, s60, 2
	s_add_u32 s58, s58, 0x100
	s_addc_u32 s59, s59, 0
	s_cmp_gt_u32 s60, 41
	s_mov_b64 s[24:25], s[26:27]
	s_cbranch_scc0 .LBB0_3743
	s_and_b64 vcc, exec, s[18:19]
	s_cbranch_vccz .LBB0_3746
	s_barrier

	.amdhsa_kernel _Z4mega6Params
		.amdhsa_group_segment_fixed_size 155536
		.amdhsa_private_segment_fixed_size 0
		.amdhsa_kernarg_size 480
		.amdhsa_user_sgpr_count 2
		.amdhsa_user_sgpr_dispatch_ptr 0
		.amdhsa_user_sgpr_queue_ptr 0
		.amdhsa_user_sgpr_kernarg_segment_ptr 1
		.amdhsa_user_sgpr_dispatch_id 0
		.amdhsa_user_sgpr_kernarg_preload_length 0
		.amdhsa_user_sgpr_kernarg_preload_offset 0
		.amdhsa_user_sgpr_private_segment_size 0
		.amdhsa_uses_dynamic_stack 0
		.amdhsa_enable_private_segment 0
		.amdhsa_system_sgpr_workgroup_id_x 1
		.amdhsa_system_sgpr_workgroup_id_y 0
		.amdhsa_system_sgpr_workgroup_id_z 0
		.amdhsa_system_sgpr_workgroup_info 0
		.amdhsa_system_vgpr_workitem_id 2
		.amdhsa_next_free_vgpr 256
		.amdhsa_next_free_sgpr 102
		.amdhsa_accum_offset 256
		.amdhsa_reserve_vcc 1
		.amdhsa_float_round_mode_32 0
		.amdhsa_float_round_mode_16_64 0
		.amdhsa_float_denorm_mode_32 3
		.amdhsa_float_denorm_mode_16_64 3
		.amdhsa_dx10_clamp 1
		.amdhsa_ieee_mode 1
		.amdhsa_fp16_overflow 0
		.amdhsa_tg_split 0
		.amdhsa_exception_fp_ieee_invalid_op 0
		.amdhsa_exception_fp_denorm_src 0
		.amdhsa_exception_fp_ieee_div_zero 0
		.amdhsa_exception_fp_ieee_overflow 0
		.amdhsa_exception_fp_ieee_underflow 0
		.amdhsa_exception_fp_ieee_inexact 0
		.amdhsa_exception_int_div_zero 0
	.end_amdhsa_kernel

amdhsa.kernels:
  - .agpr_count:     0
    .args:
      - .offset:         0
        .size:           224
        .value_kind:     by_value
      - .offset:         224
        .size:           4
        .value_kind:     hidden_block_count_x
      - .offset:         228
        .size:           4
        .value_kind:     hidden_block_count_y
      - .offset:         232
        .size:           4
        .value_kind:     hidden_block_count_z
      - .offset:         236
        .size:           2
        .value_kind:     hidden_group_size_x
      - .offset:         238
        .size:           2
        .value_kind:     hidden_group_size_y
      - .offset:         240
        .size:           2
        .value_kind:     hidden_group_size_z
      - .offset:         242
        .size:           2
        .value_kind:     hidden_remainder_x
      - .offset:         244
        .size:           2
        .value_kind:     hidden_remainder_y
      - .offset:         246
        .size:           2
        .value_kind:     hidden_remainder_z
      - .offset:         264
        .size:           8
        .value_kind:     hidden_global_offset_x
      - .offset:         272
        .size:           8
        .value_kind:     hidden_global_offset_y
      - .offset:         280
        .size:           8
        .value_kind:     hidden_global_offset_z
      - .offset:         288
        .size:           2
        .value_kind:     hidden_grid_dims
      - .offset:         312
        .size:           8
        .value_kind:     hidden_multigrid_sync_arg
    .group_segment_fixed_size: 155536
    .kernarg_segment_align: 8
    .kernarg_segment_size: 480
    .language:       OpenCL C
    .language_version:
      - 2
      - 0
    .max_flat_workgroup_size: 512
    .name:           _Z4mega6Params
    .private_segment_fixed_size: 0
    .sgpr_count:     108
    .sgpr_spill_count: 117
    .symbol:         _Z4mega6Params.kd
    .uniform_work_group_size: 1
    .uses_dynamic_stack: false
    .vgpr_count:     256
    .vgpr_spill_count: 0
    .wavefront_size: 64
